# v53 + M0 save/restore and the trailing s_nop removed around every LDS-DMA issue in the GEMM loops (398 sites, -3 SALU each)
# baseline (speedup 1.0000x reference)
; template <class Prob, class Epi, bool I8 = false, bool ALIGN_EPI = true, bool SP2 = true>
; __device__ __forceinline__ void gemm_phase(LAS unsigned char* lds, int wave, const Prob& P, const Epi& E) {
;     const int tid_ = wave * 64 + mk_lane();
;     const int tid = tid_, wid = __builtin_amdgcn_readfirstlane(tid >> 6), lane = tid & 63, wr = wid >> 2, wc = wid & 3, fr = lane & 15, fq = lane >> 4;
;     const int K = P.K, nt = K / BK;
;     unsigned voffA[2], voffB[2];
; #pragma unroll
;     for (int i = 0; i < 2; ++i) { int R, C; stage_rc(tid * 16 + i * 8192, R, C); const int Rb = (R & ~31) + perm32(R & 31);
;         voffA[i] = P.a_rowoff(R) + (unsigned)C * 2u; voffB[i] = P.b_rowoff(Rb) + (unsigned)C * 2u; }
;     const size_t kstep = (size_t)(BK * 2);
;     const size_t hstepA = P.a_hstep(), hstepB = P.b_hstep();
;     const unsigned ldsw = (unsigned)wid * 1024u;
;     const unsigned ldsb = (unsigned)(size_t)lds + ldsw;
;     const int aoff = lds_byte(wr * 64 + fr, fq * 8), boff = lds_byte(wc * 32 + fr, fq * 8);
;     ...
;     Unit cur, nxt; int ui = 0;
;     if (!P.next(0, cur)) return;
;     Acc acc;
; #pragma unroll
;     for (int a = 0; a < 2; ++a)
; #pragma unroll
;         for (int b = 0; b < 2; ++b)
; #pragma unroll
;             for (int m = 0; m < 4; ++m)
; #pragma unroll
;                 for (int n = 0; n < 2; ++n) acc[a][b][m][n] = (f32x4){0.f, 0.f, 0.f, 0.f};
;     h16x8 At[4][2], B0[2][2], B1[2][2];
;     const char* cA = P.a_tile(cur); const char* cB = P.b_tile(cur);
;     if constexpr (SP2) {
;         PG8_STAGE(PG8_SB(0, 0), cB, voffB); PG8_STAGE(PG8_SB(0, 1), cB + hstepB, voffB); PG8_STAGE(PG8_SA(0, 0), cA, voffA); PG8_STAGE(PG8_SA(0, 1), cA + hstepA, voffA);
;         if (wr == 1) PG8_BAR;
;         PG8_WAIT_V(2); PG8_BAR;
;         PG8_STAGE(PG8_SB(1, 0), cB + kstep, voffB); PG8_STAGE(PG8_SA(1, 0), cA + kstep, voffA); PG8_STAGE(PG8_SB(1, 1), cB + hstepB + kstep, voffB);
;         PG8_WAIT_V(6); PG8_BAR;
;     } else {
;         PG8_STAGE(PG8_SB(0, 0), cB, voffB); PG8_STAGE(PG8_SA(0, 0), cA, voffA); PG8_STAGE(PG8_SB(0, 1), cB + hstepB, voffB); PG8_STAGE(PG8_SA(0, 1), cA + hstepA, voffA);
;         if (wr == 1) PG8_BAR;
;         PG8_WAIT_V(4); PG8_BAR;
;         PG8_STAGE(PG8_SB(1, 0), cB + kstep, voffB); PG8_STAGE(PG8_SA(1, 0), cA + kstep, voffA); PG8_STAGE(PG8_SB(1, 1), cB + hstepB + kstep, voffB);
;         PG8_WAIT_V(6); PG8_BAR;
.LBB0_215:
	s_mov_b64 s[52:53], 0
	s_add_u32 s30, s96, s52
	s_addc_u32 s31, s97, s53
	s_add_u32 s54, s30, 0x1b200000
	s_mov_b64 s[14:15], -1
	s_addc_u32 s55, s31, 0
	v_writelane_b32 v253, s0, 63
	s_and_b64 vcc, exec, s[0:1]
	s_nop 0
	v_writelane_b32 v255, s1, 0
	s_cbranch_vccnz .LBB0_526
	v_readlane_b32 s0, v254, 42
	v_readlane_b32 s4, v254, 43
	s_add_u32 s26, s30, 0x2d200000
	v_mbcnt_lo_u32_b32 v0, -1, 0
	v_mbcnt_hi_u32_b32 v0, -1, v0
	v_readlane_b32 s5, v254, 44
	v_add_u32_e32 v1, s0, v0
	s_addc_u32 s27, s31, 0
	v_readfirstlane_b32 s0, v1
	s_and_b64 vcc, exec, s[4:5]
	s_cbranch_vccz .LBB0_232
	v_ashrrev_i32_e32 v3, 31, v1
	v_lshrrev_b32_e32 v3, 26, v3
	v_lshlrev_b32_e32 v2, 4, v1
	v_add_u32_e32 v3, v1, v3
	v_bfe_i32 v1, v1, 27, 1
	v_lshrrev_b32_e32 v1, 22, v1
	v_add_u32_e32 v1, v2, v1
	v_and_b32_e32 v1, 0xfffffc00, v1
	v_sub_u32_e32 v1, v2, v1
	v_lshrrev_b32_e32 v4, 4, v1
	v_bitop3_b32 v1, v4, v1, 32 bitop3:0x6c
	s_add_u32 s2, s30, 0x5200000
	v_ashrrev_i32_e32 v5, 31, v1
	s_addc_u32 s19, s31, 0
	v_readlane_b32 s4, v254, 51
	v_ashrrev_i32_e32 v3, 6, v3
	v_lshrrev_b32_e32 v5, 26, v5
	v_readlane_b32 s5, v254, 52
	s_add_u32 s1, s54, s4
	v_lshlrev_b32_e32 v4, 3, v3
	v_add_u32_e32 v5, v1, v5
	s_addc_u32 s4, s55, s5
	v_readlane_b32 s5, v254, 48
	v_and_b32_e32 v4, -16, v4
	v_ashrrev_i32_e32 v6, 6, v5
	v_and_b32_e32 v5, 0xc0, v5
	s_add_u32 s44, s1, s5
	v_add_u32_e32 v4, v6, v4
	v_sub_u32_e32 v1, v1, v5
	v_mov_b32_e32 v8, 1
	s_addc_u32 s45, s4, 0
	v_lshlrev_b32_e32 v3, 5, v3
	v_ashrrev_i16_sdwa v1, v8, sext(v1) dst_sel:DWORD dst_unused:UNUSED_PAD src0_sel:DWORD src1_sel:BYTE_0
	v_lshlrev_b32_e32 v5, 1, v4
	v_lshrrev_b32_e32 v7, 2, v4
	v_and_b32_e32 v6, 3, v6
	s_mov_b32 s4, 0xfffe0
	v_and_b32_e32 v3, 32, v3
	v_bfe_i32 v1, v1, 0, 16
	v_and_b32_e32 v5, 24, v5
	v_and_b32_e32 v7, 4, v7
	v_and_or_b32 v6, v4, s4, v6
	v_or3_b32 v5, v6, v7, v5
	v_add_lshl_u32 v1, v3, v1, 1
	v_lshl_add_u32 v128, v4, 10, v1
	v_lshl_add_u32 v129, v5, 12, v1
	v_add_u32_e32 v1, 0x2000, v2
	v_ashrrev_i32_e32 v2, 31, v1
	v_lshrrev_b32_e32 v2, 22, v2
	v_add_u32_e32 v2, v1, v2
	v_ashrrev_i32_e32 v2, 10, v2
	v_mul_i32_i24_e32 v3, 0x400, v2
	v_sub_u32_e32 v1, v1, v3
	v_lshrrev_b32_e32 v3, 4, v1
	v_bitop3_b32 v1, v3, v1, 32 bitop3:0x6c
	v_ashrrev_i32_e32 v4, 31, v1
	v_lshrrev_b32_e32 v4, 26, v4
	v_lshlrev_b32_e32 v3, 3, v2
	v_add_u32_e32 v4, v1, v4
	v_readlane_b32 s1, v254, 46
	v_and_b32_e32 v3, -16, v3
	v_ashrrev_i32_e32 v5, 6, v4
	s_add_u32 s42, s2, s1
	v_add_u32_e32 v3, v5, v3
	v_and_b32_e32 v5, 3, v5
	s_addc_u32 s43, s19, 0
	v_and_or_b32 v5, v3, s4, v5
	s_ashr_i32 s4, s0, 6
	s_lshl_b32 s5, s4, 10
	s_ashr_i32 s1, s0, 8
	v_and_b32_e32 v4, 0xc0, v4
	s_add_i32 s56, s5, 0
	v_sub_u32_e32 v1, v1, v4
	s_add_u32 s14, s42, 0x20000
	v_lshlrev_b32_e32 v2, 5, v2
	v_ashrrev_i16_sdwa v1, v8, sext(v1) dst_sel:DWORD dst_unused:UNUSED_PAD src0_sel:DWORD src1_sel:BYTE_0
	v_lshlrev_b32_e32 v4, 1, v3
	v_lshrrev_b32_e32 v6, 2, v3
	s_addc_u32 s15, s43, 0
	v_and_b32_e32 v2, 32, v2
	v_bfe_i32 v1, v1, 0, 16
	v_and_b32_e32 v4, 24, v4
	v_and_b32_e32 v6, 4, v6
	s_add_u32 s16, s44, 0x80000
	v_or3_b32 v4, v5, v6, v4
	v_add_lshl_u32 v1, v2, v1, 1
	s_addc_u32 s17, s45, 0
	s_add_i32 s57, s56, 0x10000
	s_mov_b32 m0, s57
	s_nop 0
	global_load_lds_dwordx4 v129, s[44:45]
	v_lshl_add_u32 v131, v4, 12, v1
	s_add_i32 s60, s56, 0x12000
	s_mov_b32 m0, s60
	s_nop 0
	global_load_lds_dwordx4 v131, s[44:45]
	s_add_i32 s61, s56, 0x14000
	s_mov_b32 m0, s61
	s_nop 0
	global_load_lds_dwordx4 v129, s[16:17]
	s_add_i32 s62, s56, 0x16000
	s_mov_b32 m0, s62
	s_nop 0
	global_load_lds_dwordx4 v131, s[16:17]
	v_lshl_add_u32 v130, v3, 10, v1
	s_mov_b32 m0, s56
	s_nop 0
	global_load_lds_dwordx4 v128, s[42:43]
	s_add_i32 s63, s56, 0x2000
	s_mov_b32 m0, s63
	s_nop 0
	global_load_lds_dwordx4 v130, s[42:43]
	s_add_i32 s64, s56, 0x4000
	s_mov_b32 m0, s64
	s_nop 0
	global_load_lds_dwordx4 v128, s[14:15]
	s_add_i32 s68, s56, 0x6000
	s_mov_b32 m0, s68
	s_nop 0
	global_load_lds_dwordx4 v130, s[14:15]
	s_cmp_eq_u32 s1, 1
	s_cselect_b64 s[14:15], -1, 0
	s_setprio 1
	s_cmp_lg_u32 s1, 1
	s_cbranch_scc1 .LBB0_219
	s_barrier
	s_setprio 0
.LBB0_219:
	s_add_u32 s16, s44, 0x80
	s_addc_u32 s17, s45, 0
	s_add_u32 s22, s42, 0x80
	s_addc_u32 s23, s43, 0
	s_add_u32 s28, s44, 0x80080
	v_and_b32_e32 v1, 48, v0
	v_lshlrev_b32_e32 v2, 6, v0
	s_movk_i32 s5, 0x3c0
	v_lshlrev_b32_e32 v0, 2, v0
	s_addc_u32 s29, s45, 0
	s_lshl_b32 s69, s1, 6
	s_lshl_b32 s1, s1, 13
	v_and_or_b32 v1, v2, s5, v1
	v_and_b32_e32 v0, 32, v0
	v_bitop3_b32 v2, v1, s1, v0 bitop3:0xde
	s_lshl_b32 s1, s4, 5
	s_and_b32 s72, s1, 0x60
	s_lshl_b32 s1, s72, 7
	v_bitop3_b32 v0, s1, v1, v0 bitop3:0xf6
	s_waitcnt vmcnt(2)
	s_barrier
	s_add_i32 s73, s56, 0x18000
	s_mov_b32 m0, s73
	s_nop 0
	global_load_lds_dwordx4 v129, s[16:17]
	s_add_i32 s74, s56, 0x1a000
	s_mov_b32 m0, s74
	s_nop 0
	global_load_lds_dwordx4 v131, s[16:17]
	s_add_i32 s75, s56, 0x8000
	s_mov_b32 m0, s75
	s_nop 0
	global_load_lds_dwordx4 v128, s[22:23]
	s_add_i32 s76, s56, 0xa000
	s_mov_b32 m0, s76
	s_nop 0
	global_load_lds_dwordx4 v130, s[22:23]
	s_add_i32 s77, s56, 0x1c000
	s_mov_b32 m0, s77
	s_nop 0
	global_load_lds_dwordx4 v129, s[28:29]
	s_add_i32 s79, s56, 0x1e000
	s_mov_b32 m0, s79
	s_nop 0
	global_load_lds_dwordx4 v131, s[28:29]
	s_waitcnt vmcnt(6)
	s_add_i32 s80, s56, 0xc000
	s_cmpk_lt_u32 s0, 0x100
	v_add_u32_e32 v0, 0, v0
	v_readlane_b32 s0, v254, 49
	s_cselect_b64 s[16:17], -1, 0
	s_add_i32 s81, s56, 0xe000
	s_mov_b32 s82, 0
	v_add_u32_e32 v132, 0x10000, v0
	v_add_u32_e32 v133, 0x14000, v0
	v_add_u32_e32 v134, 0, v2
	v_add_u32_e32 v135, 0x18000, v0
	v_add_u32_e32 v136, 0x1c000, v0
	v_readlane_b32 s85, v254, 47
	s_mov_b32 s86, s0
	v_readlane_b32 s84, v254, 45
	s_barrier
	v_readlane_b32 s1, v254, 50
	s_branch .LBB0_222

; #define PG8_STAGE(bufoff, gbase, voff) do { _Pragma("unroll") for (int _i = 0; _i < 2; ++_i) glds16_s((gbase), (voff)[_i], ldsb + (unsigned)((bufoff) + _i * 8192)); } while (0)
; #define PG8_LDA(dst, b, h) do { _Pragma("unroll") for (int m = 0; m < 4; ++m) _Pragma("unroll") for (int k = 0; k < 2; ++k) dst[m][k] = *(const LAS h16x8*)(lds + PG8_SA(b, h) + aoff + m * 2048 + k * 1024); } while (0)
; #define PG8_LDB(dst, b, h) do { _Pragma("unroll") for (int n = 0; n < 2; ++n) _Pragma("unroll") for (int k = 0; k < 2; ++k) dst[n][k] = *(const LAS h16x8*)(lds + PG8_SB(b, h) + boff + n * 2048 + k * 1024); } while (0)
; #define PG8_MMA(ai, bj, At, Bt) do { __builtin_amdgcn_s_setprio(1); _Pragma("unroll") for (int m = 0; m < 4; ++m) _Pragma("unroll") for (int n = 0; n < 2; ++n) _Pragma("unroll") for (int k = 0; k < 2; ++k) \
;         acc[ai][bj][m][n] = mma_step<I8>(Bt[n][k], At[m][k], acc[ai][bj][m][n]); __builtin_amdgcn_s_setprio(0); } while (0)
; #define PG8_WAIT_V(n) asm volatile("s_waitcnt vmcnt(" #n ")" ::: "memory")
; #define PG8_WAIT_L(n) asm volatile("s_waitcnt lgkmcnt(" #n ")" ::: "memory")
; #define PG8_BAR __builtin_amdgcn_s_barrier()
; #define PG8_SCHED __builtin_amdgcn_sched_barrier(0)
; template <class Prob, class Epi, bool I8 = false, bool ALIGN_EPI = true, bool SP2 = true>
; __device__ __forceinline__ void gemm_phase(LAS unsigned char* lds, int wave, const Prob& P, const Epi& E) {
;     ...
;             PG8_LDB(B0, 0, 0); PG8_LDB(B1, 0, 1); PG8_SCHED; PG8_LDA(At, 0, 0); PG8_STAGE(PG8_SA(1, 1), a1 + hstepA, voffA);
;             PG8_WAIT_V(8); PG8_WAIT_L(0); PG8_BAR; PG8_MMA(0, 0, At, B0); PG8_MMA(0, 1, At, B1); PG8_BAR; PG8_SCHED;
;             PG8_LDA(At, 0, 1); PG8_STAGE(PG8_SB(0, 0), b2, voffB); PG8_STAGE(PG8_SB(0, 1), b2 + hstepB, voffB); PG8_STAGE(PG8_SA(0, 0), a2, voffA);
;             PG8_WAIT_V(8); PG8_WAIT_L(0); PG8_BAR; PG8_MMA(1, 0, At, B0); PG8_MMA(1, 1, At, B1); PG8_BAR; PG8_SCHED;
.Lpeel_225:
	ds_read_b128 v[138:141], v132
	ds_read_b128 v[142:145], v132 offset:1024
	ds_read_b128 v[146:149], v132 offset:2048
	ds_read_b128 v[150:153], v132 offset:3072
	ds_read_b128 v[154:157], v133
	ds_read_b128 v[158:161], v133 offset:1024
	ds_read_b128 v[162:165], v133 offset:2048
	ds_read_b128 v[166:169], v133 offset:3072
	s_add_u32 s44, s42, 0x100
	s_addc_u32 s45, s43, 0
	s_cmp_eq_u32 s29, 4
	s_cselect_b32 s50, s87, s44
	s_cselect_b32 s51, s23, s45
	s_cselect_b32 s48, s1, s4
	s_cselect_b32 s49, s0, s5
	s_add_u32 s46, s50, 0x80
	s_addc_u32 s47, s51, 0
	ds_read_b128 v[170:173], v134
	ds_read_b128 v[174:177], v134 offset:1024
	ds_read_b128 v[178:181], v134 offset:2048
	ds_read_b128 v[182:185], v134 offset:3072
	ds_read_b128 v[186:189], v134 offset:4096
	ds_read_b128 v[190:193], v134 offset:5120
	ds_read_b128 v[194:197], v134 offset:6144
	ds_read_b128 v[198:201], v134 offset:7168
	s_add_u32 s42, s42, 0x20080
	s_addc_u32 s43, s43, 0
	s_mov_b32 m0, s80
	s_nop 0
	global_load_lds_dwordx4 v128, s[42:43]
	s_mov_b32 m0, s81
	s_nop 0
	global_load_lds_dwordx4 v130, s[42:43]
	s_waitcnt vmcnt(8)
	s_waitcnt lgkmcnt(0)
	s_barrier
	s_waitcnt lgkmcnt(7)
	v_mfma_f32_16x16x32_f16 v[124:127], v[138:141], v[170:173], 0
	v_mfma_f32_16x16x32_f16 v[120:123], v[146:149], v[170:173], 0
	s_waitcnt lgkmcnt(5)
	v_mfma_f32_16x16x32_f16 v[116:119], v[138:141], v[178:181], 0
	v_mfma_f32_16x16x32_f16 v[112:115], v[146:149], v[178:181], 0
	s_waitcnt lgkmcnt(3)
	v_mfma_f32_16x16x32_f16 v[100:103], v[138:141], v[186:189], 0
	v_mfma_f32_16x16x32_f16 v[96:99], v[146:149], v[186:189], 0
	s_waitcnt lgkmcnt(1)
	v_mfma_f32_16x16x32_f16 v[84:87], v[138:141], v[194:197], 0
	v_mfma_f32_16x16x32_f16 v[80:83], v[146:149], v[194:197], 0
	v_mfma_f32_16x16x32_f16 v[124:127], v[142:145], v[174:177], v[124:127]
	v_mfma_f32_16x16x32_f16 v[120:123], v[150:153], v[174:177], v[120:123]
	v_mfma_f32_16x16x32_f16 v[116:119], v[142:145], v[182:185], v[116:119]
	v_mfma_f32_16x16x32_f16 v[112:115], v[150:153], v[182:185], v[112:115]
	v_mfma_f32_16x16x32_f16 v[100:103], v[142:145], v[190:193], v[100:103]
	v_mfma_f32_16x16x32_f16 v[96:99], v[150:153], v[190:193], v[96:99]
	s_waitcnt lgkmcnt(0)
	v_mfma_f32_16x16x32_f16 v[84:87], v[142:145], v[198:201], v[84:87]
	v_mfma_f32_16x16x32_f16 v[80:83], v[150:153], v[198:201], v[80:83]
	v_mfma_f32_16x16x32_f16 v[108:111], v[154:157], v[170:173], 0
	v_mfma_f32_16x16x32_f16 v[104:107], v[162:165], v[170:173], 0
	v_mfma_f32_16x16x32_f16 v[92:95], v[154:157], v[178:181], 0
	v_mfma_f32_16x16x32_f16 v[88:91], v[162:165], v[178:181], 0
	v_mfma_f32_16x16x32_f16 v[76:79], v[154:157], v[186:189], 0
	v_mfma_f32_16x16x32_f16 v[72:75], v[162:165], v[186:189], 0
	v_mfma_f32_16x16x32_f16 v[68:71], v[154:157], v[194:197], 0
	v_mfma_f32_16x16x32_f16 v[64:67], v[162:165], v[194:197], 0
	v_mfma_f32_16x16x32_f16 v[108:111], v[158:161], v[174:177], v[108:111]
	v_mfma_f32_16x16x32_f16 v[104:107], v[166:169], v[174:177], v[104:107]
	v_mfma_f32_16x16x32_f16 v[92:95], v[158:161], v[182:185], v[92:95]
	v_mfma_f32_16x16x32_f16 v[88:91], v[166:169], v[182:185], v[88:91]
	v_mfma_f32_16x16x32_f16 v[76:79], v[158:161], v[190:193], v[76:79]
	v_mfma_f32_16x16x32_f16 v[72:75], v[166:169], v[190:193], v[72:75]
	v_mfma_f32_16x16x32_f16 v[68:71], v[158:161], v[198:201], v[68:71]
	v_mfma_f32_16x16x32_f16 v[64:67], v[166:169], v[198:201], v[64:67]
	s_barrier
	ds_read_b128 v[170:173], v134 offset:16384
	ds_read_b128 v[174:177], v134 offset:17408
	ds_read_b128 v[178:181], v134 offset:18432
	ds_read_b128 v[182:185], v134 offset:19456
	ds_read_b128 v[186:189], v134 offset:20480
	ds_read_b128 v[190:193], v134 offset:21504
	ds_read_b128 v[194:197], v134 offset:22528
	ds_read_b128 v[198:201], v134 offset:23552
	s_mov_b32 m0, s57
	s_nop 0
	global_load_lds_dwordx4 v129, s[48:49]
	s_add_u32 s42, s48, 0x80000
	s_mov_b32 m0, s60
	s_nop 0
	global_load_lds_dwordx4 v131, s[48:49]
	s_addc_u32 s43, s49, 0
	s_mov_b32 m0, s61
	s_nop 0
	global_load_lds_dwordx4 v129, s[42:43]
	s_mov_b32 m0, s62
	s_nop 0
	global_load_lds_dwordx4 v131, s[42:43]
	s_mov_b32 m0, s56
	s_nop 0
	global_load_lds_dwordx4 v128, s[50:51]
	s_mov_b32 m0, s63
	s_nop 0
	global_load_lds_dwordx4 v130, s[50:51]
	s_waitcnt vmcnt(8)
	s_waitcnt lgkmcnt(0)
	s_barrier
	s_waitcnt lgkmcnt(7)
	v_mfma_f32_16x16x32_f16 v[60:63], v[138:141], v[170:173], 0
	v_mfma_f32_16x16x32_f16 v[56:59], v[146:149], v[170:173], 0
	s_waitcnt lgkmcnt(5)
	v_mfma_f32_16x16x32_f16 v[52:55], v[138:141], v[178:181], 0
	v_mfma_f32_16x16x32_f16 v[48:51], v[146:149], v[178:181], 0
	s_waitcnt lgkmcnt(3)
	v_mfma_f32_16x16x32_f16 v[36:39], v[138:141], v[186:189], 0
	v_mfma_f32_16x16x32_f16 v[32:35], v[146:149], v[186:189], 0
	s_waitcnt lgkmcnt(1)
	v_mfma_f32_16x16x32_f16 v[20:23], v[138:141], v[194:197], 0
	v_mfma_f32_16x16x32_f16 v[16:19], v[146:149], v[194:197], 0
	v_mfma_f32_16x16x32_f16 v[60:63], v[142:145], v[174:177], v[60:63]
	v_mfma_f32_16x16x32_f16 v[56:59], v[150:153], v[174:177], v[56:59]
	v_mfma_f32_16x16x32_f16 v[52:55], v[142:145], v[182:185], v[52:55]
	v_mfma_f32_16x16x32_f16 v[48:51], v[150:153], v[182:185], v[48:51]
	v_mfma_f32_16x16x32_f16 v[36:39], v[142:145], v[190:193], v[36:39]
	v_mfma_f32_16x16x32_f16 v[32:35], v[150:153], v[190:193], v[32:35]
	s_waitcnt lgkmcnt(0)
	v_mfma_f32_16x16x32_f16 v[20:23], v[142:145], v[198:201], v[20:23]
	v_mfma_f32_16x16x32_f16 v[16:19], v[150:153], v[198:201], v[16:19]
	v_mfma_f32_16x16x32_f16 v[44:47], v[154:157], v[170:173], 0
	v_mfma_f32_16x16x32_f16 v[40:43], v[162:165], v[170:173], 0
	v_mfma_f32_16x16x32_f16 v[28:31], v[154:157], v[178:181], 0
	v_mfma_f32_16x16x32_f16 v[24:27], v[162:165], v[178:181], 0
	v_mfma_f32_16x16x32_f16 v[12:15], v[154:157], v[186:189], 0
	v_mfma_f32_16x16x32_f16 v[8:11], v[162:165], v[186:189], 0
	v_mfma_f32_16x16x32_f16 v[4:7], v[154:157], v[194:197], 0
	v_mfma_f32_16x16x32_f16 v[0:3], v[162:165], v[194:197], 0
	v_mfma_f32_16x16x32_f16 v[44:47], v[158:161], v[174:177], v[44:47]
	v_mfma_f32_16x16x32_f16 v[40:43], v[166:169], v[174:177], v[40:43]
	v_mfma_f32_16x16x32_f16 v[28:31], v[158:161], v[182:185], v[28:31]
	v_mfma_f32_16x16x32_f16 v[24:27], v[166:169], v[182:185], v[24:27]
	v_mfma_f32_16x16x32_f16 v[12:15], v[158:161], v[190:193], v[12:15]
	v_mfma_f32_16x16x32_f16 v[8:11], v[166:169], v[190:193], v[8:11]
	v_mfma_f32_16x16x32_f16 v[4:7], v[158:161], v[198:201], v[4:7]
	v_mfma_f32_16x16x32_f16 v[0:3], v[166:169], v[198:201], v[0:3]
	s_barrier
; #define PG8_STAGE(bufoff, gbase, voff) do { _Pragma("unroll") for (int _i = 0; _i < 2; ++_i) glds16_s((gbase), (voff)[_i], ldsb + (unsigned)((bufoff) + _i * 8192)); } while (0)
; #define PG8_LDA(dst, b, h) do { _Pragma("unroll") for (int m = 0; m < 4; ++m) _Pragma("unroll") for (int k = 0; k < 2; ++k) dst[m][k] = *(const LAS h16x8*)(lds + PG8_SA(b, h) + aoff + m * 2048 + k * 1024); } while (0)
; #define PG8_LDB(dst, b, h) do { _Pragma("unroll") for (int n = 0; n < 2; ++n) _Pragma("unroll") for (int k = 0; k < 2; ++k) dst[n][k] = *(const LAS h16x8*)(lds + PG8_SB(b, h) + boff + n * 2048 + k * 1024); } while (0)
; #define PG8_MMA(ai, bj, At, Bt) do { __builtin_amdgcn_s_setprio(1); _Pragma("unroll") for (int m = 0; m < 4; ++m) _Pragma("unroll") for (int n = 0; n < 2; ++n) _Pragma("unroll") for (int k = 0; k < 2; ++k) \
;         acc[ai][bj][m][n] = mma_step<I8>(Bt[n][k], At[m][k], acc[ai][bj][m][n]); __builtin_amdgcn_s_setprio(0); } while (0)
; #define PG8_WAIT_V(n) asm volatile("s_waitcnt vmcnt(" #n ")" ::: "memory")
; #define PG8_WAIT_L(n) asm volatile("s_waitcnt lgkmcnt(" #n ")" ::: "memory")
; #define PG8_BAR __builtin_amdgcn_s_barrier()
; #define PG8_SCHED __builtin_amdgcn_sched_barrier(0)
; template <class Prob, class Epi, bool I8 = false, bool ALIGN_EPI = true, bool SP2 = true>
; __device__ __forceinline__ void gemm_phase(LAS unsigned char* lds, int wave, const Prob& P, const Epi& E) {
;     ...
;             PG8_LDB(B0, 1, 0); PG8_LDB(B1, 1, 1); PG8_SCHED; PG8_LDA(At, 1, 0); PG8_STAGE(PG8_SA(0, 1), a2 + hstepA, voffA);
;             PG8_WAIT_V(8); PG8_WAIT_L(0); PG8_BAR; PG8_MMA(0, 0, At, B0); PG8_MMA(0, 1, At, B1); PG8_BAR; PG8_SCHED;
;             PG8_LDA(At, 1, 1); PG8_STAGE(PG8_SB(1, 0), b3, voffB); PG8_STAGE(PG8_SB(1, 1), b3 + hstepB, voffB); PG8_STAGE(PG8_SA(1, 0), a3, voffA);
;             PG8_WAIT_V(8); PG8_WAIT_L(0); PG8_BAR; PG8_MMA(1, 0, At, B0); PG8_MMA(1, 1, At, B1); PG8_BAR; PG8_SCHED;
	ds_read_b128 v[138:141], v135
	ds_read_b128 v[142:145], v135 offset:1024
	ds_read_b128 v[146:149], v135 offset:2048
	ds_read_b128 v[150:153], v135 offset:3072
	ds_read_b128 v[154:157], v136
	ds_read_b128 v[158:161], v136 offset:1024
	ds_read_b128 v[162:165], v136 offset:2048
	ds_read_b128 v[166:169], v136 offset:3072
	ds_read_b128 v[170:173], v134 offset:32768
	ds_read_b128 v[174:177], v134 offset:33792
	ds_read_b128 v[178:181], v134 offset:34816
	ds_read_b128 v[182:185], v134 offset:35840
	ds_read_b128 v[186:189], v134 offset:36864
	ds_read_b128 v[190:193], v134 offset:37888
	ds_read_b128 v[194:197], v134 offset:38912
	ds_read_b128 v[198:201], v134 offset:39936
	s_add_u32 s42, s50, 0x20000
	s_addc_u32 s43, s51, 0
	s_mov_b32 m0, s64
	s_nop 0
	global_load_lds_dwordx4 v128, s[42:43]
	s_mov_b32 m0, s68
	s_nop 0
	global_load_lds_dwordx4 v130, s[42:43]
	s_waitcnt vmcnt(8)
	s_waitcnt lgkmcnt(0)
	s_barrier
	s_waitcnt lgkmcnt(7)
	v_mfma_f32_16x16x32_f16 v[124:127], v[138:141], v[170:173], v[124:127]
	v_mfma_f32_16x16x32_f16 v[120:123], v[146:149], v[170:173], v[120:123]
	s_waitcnt lgkmcnt(5)
	v_mfma_f32_16x16x32_f16 v[116:119], v[138:141], v[178:181], v[116:119]
	v_mfma_f32_16x16x32_f16 v[112:115], v[146:149], v[178:181], v[112:115]
	s_waitcnt lgkmcnt(3)
	v_mfma_f32_16x16x32_f16 v[100:103], v[138:141], v[186:189], v[100:103]
	v_mfma_f32_16x16x32_f16 v[96:99], v[146:149], v[186:189], v[96:99]
	s_waitcnt lgkmcnt(1)
	v_mfma_f32_16x16x32_f16 v[84:87], v[138:141], v[194:197], v[84:87]
	v_mfma_f32_16x16x32_f16 v[80:83], v[146:149], v[194:197], v[80:83]
	v_mfma_f32_16x16x32_f16 v[124:127], v[142:145], v[174:177], v[124:127]
	v_mfma_f32_16x16x32_f16 v[120:123], v[150:153], v[174:177], v[120:123]
	v_mfma_f32_16x16x32_f16 v[116:119], v[142:145], v[182:185], v[116:119]
	v_mfma_f32_16x16x32_f16 v[112:115], v[150:153], v[182:185], v[112:115]
	v_mfma_f32_16x16x32_f16 v[100:103], v[142:145], v[190:193], v[100:103]
	v_mfma_f32_16x16x32_f16 v[96:99], v[150:153], v[190:193], v[96:99]
	s_waitcnt lgkmcnt(0)
	v_mfma_f32_16x16x32_f16 v[84:87], v[142:145], v[198:201], v[84:87]
	v_mfma_f32_16x16x32_f16 v[80:83], v[150:153], v[198:201], v[80:83]
	v_mfma_f32_16x16x32_f16 v[108:111], v[154:157], v[170:173], v[108:111]
	v_mfma_f32_16x16x32_f16 v[104:107], v[162:165], v[170:173], v[104:107]
	v_mfma_f32_16x16x32_f16 v[92:95], v[154:157], v[178:181], v[92:95]
	v_mfma_f32_16x16x32_f16 v[88:91], v[162:165], v[178:181], v[88:91]
	v_mfma_f32_16x16x32_f16 v[76:79], v[154:157], v[186:189], v[76:79]
	v_mfma_f32_16x16x32_f16 v[72:75], v[162:165], v[186:189], v[72:75]
	v_mfma_f32_16x16x32_f16 v[68:71], v[154:157], v[194:197], v[68:71]
	v_mfma_f32_16x16x32_f16 v[64:67], v[162:165], v[194:197], v[64:67]
	v_mfma_f32_16x16x32_f16 v[108:111], v[158:161], v[174:177], v[108:111]
	v_mfma_f32_16x16x32_f16 v[104:107], v[166:169], v[174:177], v[104:107]
	v_mfma_f32_16x16x32_f16 v[92:95], v[158:161], v[182:185], v[92:95]
	v_mfma_f32_16x16x32_f16 v[88:91], v[166:169], v[182:185], v[88:91]
	v_mfma_f32_16x16x32_f16 v[76:79], v[158:161], v[190:193], v[76:79]
	v_mfma_f32_16x16x32_f16 v[72:75], v[166:169], v[190:193], v[72:75]
	v_mfma_f32_16x16x32_f16 v[68:71], v[158:161], v[198:201], v[68:71]
	v_mfma_f32_16x16x32_f16 v[64:67], v[166:169], v[198:201], v[64:67]
	s_barrier
	ds_read_b128 v[170:173], v134 offset:49152
	ds_read_b128 v[174:177], v134 offset:50176
	ds_read_b128 v[178:181], v134 offset:51200
	ds_read_b128 v[182:185], v134 offset:52224
	ds_read_b128 v[186:189], v134 offset:53248
	ds_read_b128 v[190:193], v134 offset:54272
	ds_read_b128 v[194:197], v134 offset:55296
	ds_read_b128 v[198:201], v134 offset:56320
	s_add_u32 s42, s48, 0x80
	s_addc_u32 s43, s49, 0
	s_mov_b32 m0, s73
	s_nop 0
	global_load_lds_dwordx4 v129, s[42:43]
	s_mov_b32 m0, s74
	s_nop 0
	global_load_lds_dwordx4 v131, s[42:43]
	s_add_u32 s42, s48, 0x80080
	s_addc_u32 s43, s49, 0
	s_mov_b32 m0, s77
	s_nop 0
	global_load_lds_dwordx4 v129, s[42:43]
	s_mov_b32 m0, s79
	s_nop 0
	global_load_lds_dwordx4 v131, s[42:43]
	s_mov_b32 m0, s75
	s_nop 0
	global_load_lds_dwordx4 v128, s[46:47]
	s_mov_b32 m0, s76
	s_nop 0
	global_load_lds_dwordx4 v130, s[46:47]
	s_waitcnt vmcnt(8)
	s_waitcnt lgkmcnt(0)
	s_barrier
	s_waitcnt lgkmcnt(7)
	v_mfma_f32_16x16x32_f16 v[60:63], v[138:141], v[170:173], v[60:63]
	v_mfma_f32_16x16x32_f16 v[56:59], v[146:149], v[170:173], v[56:59]
	s_waitcnt lgkmcnt(5)
	v_mfma_f32_16x16x32_f16 v[52:55], v[138:141], v[178:181], v[52:55]
	v_mfma_f32_16x16x32_f16 v[48:51], v[146:149], v[178:181], v[48:51]
	s_waitcnt lgkmcnt(3)
	v_mfma_f32_16x16x32_f16 v[36:39], v[138:141], v[186:189], v[36:39]
	v_mfma_f32_16x16x32_f16 v[32:35], v[146:149], v[186:189], v[32:35]
	s_waitcnt lgkmcnt(1)
	v_mfma_f32_16x16x32_f16 v[20:23], v[138:141], v[194:197], v[20:23]
	v_mfma_f32_16x16x32_f16 v[16:19], v[146:149], v[194:197], v[16:19]
	v_mfma_f32_16x16x32_f16 v[60:63], v[142:145], v[174:177], v[60:63]
	v_mfma_f32_16x16x32_f16 v[56:59], v[150:153], v[174:177], v[56:59]
	v_mfma_f32_16x16x32_f16 v[52:55], v[142:145], v[182:185], v[52:55]
	v_mfma_f32_16x16x32_f16 v[48:51], v[150:153], v[182:185], v[48:51]
	v_mfma_f32_16x16x32_f16 v[36:39], v[142:145], v[190:193], v[36:39]
	v_mfma_f32_16x16x32_f16 v[32:35], v[150:153], v[190:193], v[32:35]
	s_waitcnt lgkmcnt(0)
	v_mfma_f32_16x16x32_f16 v[20:23], v[142:145], v[198:201], v[20:23]
	v_mfma_f32_16x16x32_f16 v[16:19], v[150:153], v[198:201], v[16:19]
	v_mfma_f32_16x16x32_f16 v[44:47], v[154:157], v[170:173], v[44:47]
	v_mfma_f32_16x16x32_f16 v[40:43], v[162:165], v[170:173], v[40:43]
	v_mfma_f32_16x16x32_f16 v[28:31], v[154:157], v[178:181], v[28:31]
	v_mfma_f32_16x16x32_f16 v[24:27], v[162:165], v[178:181], v[24:27]
	v_mfma_f32_16x16x32_f16 v[12:15], v[154:157], v[186:189], v[12:15]
	v_mfma_f32_16x16x32_f16 v[8:11], v[162:165], v[186:189], v[8:11]
	v_mfma_f32_16x16x32_f16 v[4:7], v[154:157], v[194:197], v[4:7]
	v_mfma_f32_16x16x32_f16 v[0:3], v[162:165], v[194:197], v[0:3]
	v_mfma_f32_16x16x32_f16 v[44:47], v[158:161], v[174:177], v[44:47]
	v_mfma_f32_16x16x32_f16 v[40:43], v[166:169], v[174:177], v[40:43]
	v_mfma_f32_16x16x32_f16 v[28:31], v[158:161], v[182:185], v[28:31]
	v_mfma_f32_16x16x32_f16 v[24:27], v[166:169], v[182:185], v[24:27]
	v_mfma_f32_16x16x32_f16 v[12:15], v[158:161], v[190:193], v[12:15]
	v_mfma_f32_16x16x32_f16 v[8:11], v[166:169], v[190:193], v[8:11]
	v_mfma_f32_16x16x32_f16 v[4:7], v[158:161], v[198:201], v[4:7]
	v_mfma_f32_16x16x32_f16 v[0:3], v[166:169], v[198:201], v[0:3]
	s_barrier
	s_add_i32 s29, s29, 2
	s_add_u32 s4, s4, 0x100
	s_addc_u32 s5, s5, 0
	s_cmp_gt_u32 s29, 5
	s_mov_b64 s[42:43], s[44:45]
; #define PG8_STAGE(bufoff, gbase, voff) do { _Pragma("unroll") for (int _i = 0; _i < 2; ++_i) glds16_s((gbase), (voff)[_i], ldsb + (unsigned)((bufoff) + _i * 8192)); } while (0)
; #define PG8_LDA(dst, b, h) do { _Pragma("unroll") for (int m = 0; m < 4; ++m) _Pragma("unroll") for (int k = 0; k < 2; ++k) dst[m][k] = *(const LAS h16x8*)(lds + PG8_SA(b, h) + aoff + m * 2048 + k * 1024); } while (0)
; #define PG8_LDB(dst, b, h) do { _Pragma("unroll") for (int n = 0; n < 2; ++n) _Pragma("unroll") for (int k = 0; k < 2; ++k) dst[n][k] = *(const LAS h16x8*)(lds + PG8_SB(b, h) + boff + n * 2048 + k * 1024); } while (0)
; #define PG8_MMA(ai, bj, At, Bt) do { __builtin_amdgcn_s_setprio(1); _Pragma("unroll") for (int m = 0; m < 4; ++m) _Pragma("unroll") for (int n = 0; n < 2; ++n) _Pragma("unroll") for (int k = 0; k < 2; ++k) \
;         acc[ai][bj][m][n] = mma_step<I8>(Bt[n][k], At[m][k], acc[ai][bj][m][n]); __builtin_amdgcn_s_setprio(0); } while (0)
; #define PG8_WAIT_V(n) asm volatile("s_waitcnt vmcnt(" #n ")" ::: "memory")
; #define PG8_WAIT_L(n) asm volatile("s_waitcnt lgkmcnt(" #n ")" ::: "memory")
; #define PG8_BAR __builtin_amdgcn_s_barrier()
; #define PG8_SCHED __builtin_amdgcn_sched_barrier(0)
; template <class Prob, class Epi, bool I8 = false, bool ALIGN_EPI = true, bool SP2 = true>
; __device__ __forceinline__ void gemm_phase(LAS unsigned char* lds, int wave, const Prob& P, const Epi& E) {
;     ...
;             PG8_LDB(B0, 0, 0); PG8_LDB(B1, 0, 1); PG8_SCHED; PG8_LDA(At, 0, 0); PG8_STAGE(PG8_SA(1, 1), a1 + hstepA, voffA);
;             PG8_WAIT_V(8); PG8_WAIT_L(0); PG8_BAR; PG8_MMA(0, 0, At, B0); PG8_MMA(0, 1, At, B1); PG8_BAR; PG8_SCHED;
;             PG8_LDA(At, 0, 1); PG8_STAGE(PG8_SB(0, 0), b2, voffB); PG8_STAGE(PG8_SB(0, 1), b2 + hstepB, voffB); PG8_STAGE(PG8_SA(0, 0), a2, voffA);
;             PG8_WAIT_V(8); PG8_WAIT_L(0); PG8_BAR; PG8_MMA(1, 0, At, B0); PG8_MMA(1, 1, At, B1); PG8_BAR; PG8_SCHED;
.LBB0_225:
	ds_read_b128 v[138:141], v132
	ds_read_b128 v[142:145], v132 offset:1024
	ds_read_b128 v[146:149], v132 offset:2048
	ds_read_b128 v[150:153], v132 offset:3072
	ds_read_b128 v[154:157], v133
	ds_read_b128 v[158:161], v133 offset:1024
	ds_read_b128 v[162:165], v133 offset:2048
	ds_read_b128 v[166:169], v133 offset:3072
	s_add_u32 s44, s42, 0x100
	s_addc_u32 s45, s43, 0
	s_cmp_eq_u32 s29, 4
	s_cselect_b32 s50, s87, s44
	s_cselect_b32 s51, s23, s45
	s_cselect_b32 s48, s1, s4
	s_cselect_b32 s49, s0, s5
	s_add_u32 s46, s50, 0x80
	s_addc_u32 s47, s51, 0
	ds_read_b128 v[170:173], v134
	ds_read_b128 v[174:177], v134 offset:1024
	ds_read_b128 v[178:181], v134 offset:2048
	ds_read_b128 v[182:185], v134 offset:3072
	ds_read_b128 v[186:189], v134 offset:4096
	ds_read_b128 v[190:193], v134 offset:5120
	ds_read_b128 v[194:197], v134 offset:6144
	ds_read_b128 v[198:201], v134 offset:7168
	s_add_u32 s42, s42, 0x20080
	s_addc_u32 s43, s43, 0
	s_mov_b32 m0, s80
	s_nop 0
	global_load_lds_dwordx4 v128, s[42:43]
	s_mov_b32 m0, s81
	s_nop 0
	global_load_lds_dwordx4 v130, s[42:43]
	s_waitcnt vmcnt(8)
	s_waitcnt lgkmcnt(0)
	s_barrier
	s_waitcnt lgkmcnt(7)
	v_mfma_f32_16x16x32_f16 v[124:127], v[138:141], v[170:173], v[124:127]
	v_mfma_f32_16x16x32_f16 v[120:123], v[146:149], v[170:173], v[120:123]
	s_waitcnt lgkmcnt(5)
	v_mfma_f32_16x16x32_f16 v[116:119], v[138:141], v[178:181], v[116:119]
	v_mfma_f32_16x16x32_f16 v[112:115], v[146:149], v[178:181], v[112:115]
	s_waitcnt lgkmcnt(3)
	v_mfma_f32_16x16x32_f16 v[100:103], v[138:141], v[186:189], v[100:103]
	v_mfma_f32_16x16x32_f16 v[96:99], v[146:149], v[186:189], v[96:99]
	s_waitcnt lgkmcnt(1)
	v_mfma_f32_16x16x32_f16 v[84:87], v[138:141], v[194:197], v[84:87]
	v_mfma_f32_16x16x32_f16 v[80:83], v[146:149], v[194:197], v[80:83]
	v_mfma_f32_16x16x32_f16 v[124:127], v[142:145], v[174:177], v[124:127]
	v_mfma_f32_16x16x32_f16 v[120:123], v[150:153], v[174:177], v[120:123]
	v_mfma_f32_16x16x32_f16 v[116:119], v[142:145], v[182:185], v[116:119]
	v_mfma_f32_16x16x32_f16 v[112:115], v[150:153], v[182:185], v[112:115]
	v_mfma_f32_16x16x32_f16 v[100:103], v[142:145], v[190:193], v[100:103]
	v_mfma_f32_16x16x32_f16 v[96:99], v[150:153], v[190:193], v[96:99]
	s_waitcnt lgkmcnt(0)
	v_mfma_f32_16x16x32_f16 v[84:87], v[142:145], v[198:201], v[84:87]
	v_mfma_f32_16x16x32_f16 v[80:83], v[150:153], v[198:201], v[80:83]
	v_mfma_f32_16x16x32_f16 v[108:111], v[154:157], v[170:173], v[108:111]
	v_mfma_f32_16x16x32_f16 v[104:107], v[162:165], v[170:173], v[104:107]
	v_mfma_f32_16x16x32_f16 v[92:95], v[154:157], v[178:181], v[92:95]
	v_mfma_f32_16x16x32_f16 v[88:91], v[162:165], v[178:181], v[88:91]
	v_mfma_f32_16x16x32_f16 v[76:79], v[154:157], v[186:189], v[76:79]
	v_mfma_f32_16x16x32_f16 v[72:75], v[162:165], v[186:189], v[72:75]
	v_mfma_f32_16x16x32_f16 v[68:71], v[154:157], v[194:197], v[68:71]
	v_mfma_f32_16x16x32_f16 v[64:67], v[162:165], v[194:197], v[64:67]
	v_mfma_f32_16x16x32_f16 v[108:111], v[158:161], v[174:177], v[108:111]
	v_mfma_f32_16x16x32_f16 v[104:107], v[166:169], v[174:177], v[104:107]
	v_mfma_f32_16x16x32_f16 v[92:95], v[158:161], v[182:185], v[92:95]
	v_mfma_f32_16x16x32_f16 v[88:91], v[166:169], v[182:185], v[88:91]
	v_mfma_f32_16x16x32_f16 v[76:79], v[158:161], v[190:193], v[76:79]
	v_mfma_f32_16x16x32_f16 v[72:75], v[166:169], v[190:193], v[72:75]
	v_mfma_f32_16x16x32_f16 v[68:71], v[158:161], v[198:201], v[68:71]
	v_mfma_f32_16x16x32_f16 v[64:67], v[166:169], v[198:201], v[64:67]
	s_barrier
	ds_read_b128 v[170:173], v134 offset:16384
	ds_read_b128 v[174:177], v134 offset:17408
	ds_read_b128 v[178:181], v134 offset:18432
	ds_read_b128 v[182:185], v134 offset:19456
	ds_read_b128 v[186:189], v134 offset:20480
	ds_read_b128 v[190:193], v134 offset:21504
	ds_read_b128 v[194:197], v134 offset:22528
	ds_read_b128 v[198:201], v134 offset:23552
	s_mov_b32 m0, s57
	s_nop 0
	global_load_lds_dwordx4 v129, s[48:49]
	s_add_u32 s42, s48, 0x80000
	s_mov_b32 m0, s60
	s_nop 0
	global_load_lds_dwordx4 v131, s[48:49]
	s_addc_u32 s43, s49, 0
	s_mov_b32 m0, s61
	s_nop 0
	global_load_lds_dwordx4 v129, s[42:43]
	s_mov_b32 m0, s62
	s_nop 0
	global_load_lds_dwordx4 v131, s[42:43]
	s_mov_b32 m0, s56
	s_nop 0
	global_load_lds_dwordx4 v128, s[50:51]
	s_mov_b32 m0, s63
	s_nop 0
	global_load_lds_dwordx4 v130, s[50:51]
	s_waitcnt vmcnt(8)
	s_waitcnt lgkmcnt(0)
	s_barrier
	s_waitcnt lgkmcnt(7)
	v_mfma_f32_16x16x32_f16 v[60:63], v[138:141], v[170:173], v[60:63]
	v_mfma_f32_16x16x32_f16 v[56:59], v[146:149], v[170:173], v[56:59]
	s_waitcnt lgkmcnt(5)
	v_mfma_f32_16x16x32_f16 v[52:55], v[138:141], v[178:181], v[52:55]
	v_mfma_f32_16x16x32_f16 v[48:51], v[146:149], v[178:181], v[48:51]
	s_waitcnt lgkmcnt(3)
	v_mfma_f32_16x16x32_f16 v[36:39], v[138:141], v[186:189], v[36:39]
	v_mfma_f32_16x16x32_f16 v[32:35], v[146:149], v[186:189], v[32:35]
	s_waitcnt lgkmcnt(1)
	v_mfma_f32_16x16x32_f16 v[20:23], v[138:141], v[194:197], v[20:23]
	v_mfma_f32_16x16x32_f16 v[16:19], v[146:149], v[194:197], v[16:19]
	v_mfma_f32_16x16x32_f16 v[60:63], v[142:145], v[174:177], v[60:63]
	v_mfma_f32_16x16x32_f16 v[56:59], v[150:153], v[174:177], v[56:59]
	v_mfma_f32_16x16x32_f16 v[52:55], v[142:145], v[182:185], v[52:55]
	v_mfma_f32_16x16x32_f16 v[48:51], v[150:153], v[182:185], v[48:51]
	v_mfma_f32_16x16x32_f16 v[36:39], v[142:145], v[190:193], v[36:39]
	v_mfma_f32_16x16x32_f16 v[32:35], v[150:153], v[190:193], v[32:35]
	s_waitcnt lgkmcnt(0)
	v_mfma_f32_16x16x32_f16 v[20:23], v[142:145], v[198:201], v[20:23]
	v_mfma_f32_16x16x32_f16 v[16:19], v[150:153], v[198:201], v[16:19]
	v_mfma_f32_16x16x32_f16 v[44:47], v[154:157], v[170:173], v[44:47]
	v_mfma_f32_16x16x32_f16 v[40:43], v[162:165], v[170:173], v[40:43]
	v_mfma_f32_16x16x32_f16 v[28:31], v[154:157], v[178:181], v[28:31]
	v_mfma_f32_16x16x32_f16 v[24:27], v[162:165], v[178:181], v[24:27]
	v_mfma_f32_16x16x32_f16 v[12:15], v[154:157], v[186:189], v[12:15]
	v_mfma_f32_16x16x32_f16 v[8:11], v[162:165], v[186:189], v[8:11]
	v_mfma_f32_16x16x32_f16 v[4:7], v[154:157], v[194:197], v[4:7]
	v_mfma_f32_16x16x32_f16 v[0:3], v[162:165], v[194:197], v[0:3]
	v_mfma_f32_16x16x32_f16 v[44:47], v[158:161], v[174:177], v[44:47]
	v_mfma_f32_16x16x32_f16 v[40:43], v[166:169], v[174:177], v[40:43]
	v_mfma_f32_16x16x32_f16 v[28:31], v[158:161], v[182:185], v[28:31]
	v_mfma_f32_16x16x32_f16 v[24:27], v[166:169], v[182:185], v[24:27]
	v_mfma_f32_16x16x32_f16 v[12:15], v[158:161], v[190:193], v[12:15]
	v_mfma_f32_16x16x32_f16 v[8:11], v[166:169], v[190:193], v[8:11]
	v_mfma_f32_16x16x32_f16 v[4:7], v[158:161], v[198:201], v[4:7]
	v_mfma_f32_16x16x32_f16 v[0:3], v[166:169], v[198:201], v[0:3]
	s_barrier
; #define PG8_STAGE(bufoff, gbase, voff) do { _Pragma("unroll") for (int _i = 0; _i < 2; ++_i) glds16_s((gbase), (voff)[_i], ldsb + (unsigned)((bufoff) + _i * 8192)); } while (0)
; #define PG8_WAIT_V(n) asm volatile("s_waitcnt vmcnt(" #n ")" ::: "memory")
; #define PG8_BAR __builtin_amdgcn_s_barrier()
; template <class Prob, class Epi, bool I8 = false, bool ALIGN_EPI = true, bool SP2 = true>
; __device__ __forceinline__ void gemm_phase(LAS unsigned char* lds, int wave, const Prob& P, const Epi& E) {
;     ...
;             PG8_LDB(B0, 1, 0); PG8_LDB(B1, 1, 1); PG8_SCHED; PG8_LDA(At, 1, 0); PG8_STAGE(PG8_SA(0, 1), a2 + hstepA, voffA);
;             PG8_WAIT_V(8); PG8_WAIT_L(0); PG8_BAR; PG8_MMA(0, 0, At, B0); PG8_MMA(0, 1, At, B1); PG8_BAR; PG8_SCHED;
;             PG8_LDA(At, 1, 1); PG8_STAGE(PG8_SB(1, 0), b3, voffB); PG8_STAGE(PG8_SB(1, 1), b3 + hstepB, voffB); PG8_STAGE(PG8_SA(1, 0), a3, voffA);
;             PG8_WAIT_V(8); PG8_WAIT_L(0); PG8_BAR; PG8_MMA(1, 0, At, B0); PG8_MMA(1, 1, At, B1); PG8_BAR; PG8_SCHED;
;             } else {
;             PG8_LDB(B0, 0, 0); PG8_SCHED; PG8_LDA(At, 0, 0); PG8_STAGE(PG8_SA(1, 1), a1 + hstepA, voffA);
;             PG8_WAIT_L(8); PG8_BAR; PG8_WAIT_L(0); PG8_MMA(0, 0, At, B0); PG8_BAR; PG8_SCHED;
;             PG8_LDB(B1, 0, 1); PG8_STAGE(PG8_SB(0, 0), b2, voffB);
;             PG8_BAR; PG8_WAIT_L(0); PG8_MMA(0, 1, At, B1); PG8_BAR;
;             PG8_LDA(At, 0, 1); PG8_STAGE(PG8_SA(0, 0), a2, voffA);
;             PG8_BAR; PG8_WAIT_L(0); PG8_MMA(1, 0, At, B0); PG8_BAR; PG8_SCHED;
;             PG8_STAGE(PG8_SB(0, 1), b2 + hstepB, voffB);
;             PG8_WAIT_V(6); PG8_BAR; PG8_MMA(1, 1, At, B1); PG8_BAR;
;             PG8_LDB(B0, 1, 0); PG8_SCHED; PG8_LDA(At, 1, 0); PG8_STAGE(PG8_SA(0, 1), a2 + hstepA, voffA);
;             PG8_WAIT_L(8); PG8_BAR; PG8_WAIT_L(0); PG8_MMA(0, 0, At, B0); PG8_BAR; PG8_SCHED;
;             PG8_LDB(B1, 1, 1); PG8_STAGE(PG8_SB(1, 0), b3, voffB);
;             PG8_BAR; PG8_WAIT_L(0); PG8_MMA(0, 1, At, B1); PG8_BAR;
;             PG8_LDA(At, 1, 1); PG8_STAGE(PG8_SA(1, 0), a3, voffA);
;             PG8_BAR; PG8_WAIT_L(0); PG8_MMA(1, 0, At, B0); PG8_BAR; PG8_SCHED;
;             PG8_STAGE(PG8_SB(1, 1), b3 + hstepB, voffB);
;             PG8_WAIT_V(6); PG8_BAR; PG8_MMA(1, 1, At, B1); PG8_BAR;
;             }
;         }
;         if constexpr (ALIGN_EPI) { if (wr == 0) PG8_BAR; }
	ds_read_b128 v[138:141], v135
	ds_read_b128 v[142:145], v135 offset:1024
	ds_read_b128 v[146:149], v135 offset:2048
	ds_read_b128 v[150:153], v135 offset:3072
	ds_read_b128 v[154:157], v136
	ds_read_b128 v[158:161], v136 offset:1024
	ds_read_b128 v[162:165], v136 offset:2048
	ds_read_b128 v[166:169], v136 offset:3072
	ds_read_b128 v[170:173], v134 offset:32768
	ds_read_b128 v[174:177], v134 offset:33792
	ds_read_b128 v[178:181], v134 offset:34816
	ds_read_b128 v[182:185], v134 offset:35840
	ds_read_b128 v[186:189], v134 offset:36864
	ds_read_b128 v[190:193], v134 offset:37888
	ds_read_b128 v[194:197], v134 offset:38912
	ds_read_b128 v[198:201], v134 offset:39936
	s_add_u32 s42, s50, 0x20000
	s_addc_u32 s43, s51, 0
	s_mov_b32 m0, s64
	s_nop 0
	global_load_lds_dwordx4 v128, s[42:43]
	s_mov_b32 m0, s68
	s_nop 0
	global_load_lds_dwordx4 v130, s[42:43]
	s_waitcnt vmcnt(8)
	s_waitcnt lgkmcnt(0)
	s_barrier
	s_waitcnt lgkmcnt(7)
	v_mfma_f32_16x16x32_f16 v[124:127], v[138:141], v[170:173], v[124:127]
	v_mfma_f32_16x16x32_f16 v[120:123], v[146:149], v[170:173], v[120:123]
	s_waitcnt lgkmcnt(5)
	v_mfma_f32_16x16x32_f16 v[116:119], v[138:141], v[178:181], v[116:119]
	v_mfma_f32_16x16x32_f16 v[112:115], v[146:149], v[178:181], v[112:115]
	s_waitcnt lgkmcnt(3)
	v_mfma_f32_16x16x32_f16 v[100:103], v[138:141], v[186:189], v[100:103]
	v_mfma_f32_16x16x32_f16 v[96:99], v[146:149], v[186:189], v[96:99]
	s_waitcnt lgkmcnt(1)
	v_mfma_f32_16x16x32_f16 v[84:87], v[138:141], v[194:197], v[84:87]
	v_mfma_f32_16x16x32_f16 v[80:83], v[146:149], v[194:197], v[80:83]
	v_mfma_f32_16x16x32_f16 v[124:127], v[142:145], v[174:177], v[124:127]
	v_mfma_f32_16x16x32_f16 v[120:123], v[150:153], v[174:177], v[120:123]
	v_mfma_f32_16x16x32_f16 v[116:119], v[142:145], v[182:185], v[116:119]
	v_mfma_f32_16x16x32_f16 v[112:115], v[150:153], v[182:185], v[112:115]
	v_mfma_f32_16x16x32_f16 v[100:103], v[142:145], v[190:193], v[100:103]
	v_mfma_f32_16x16x32_f16 v[96:99], v[150:153], v[190:193], v[96:99]
	s_waitcnt lgkmcnt(0)
	v_mfma_f32_16x16x32_f16 v[84:87], v[142:145], v[198:201], v[84:87]
	v_mfma_f32_16x16x32_f16 v[80:83], v[150:153], v[198:201], v[80:83]
	v_mfma_f32_16x16x32_f16 v[108:111], v[154:157], v[170:173], v[108:111]
	v_mfma_f32_16x16x32_f16 v[104:107], v[162:165], v[170:173], v[104:107]
	v_mfma_f32_16x16x32_f16 v[92:95], v[154:157], v[178:181], v[92:95]
	v_mfma_f32_16x16x32_f16 v[88:91], v[162:165], v[178:181], v[88:91]
	v_mfma_f32_16x16x32_f16 v[76:79], v[154:157], v[186:189], v[76:79]
	v_mfma_f32_16x16x32_f16 v[72:75], v[162:165], v[186:189], v[72:75]
	v_mfma_f32_16x16x32_f16 v[68:71], v[154:157], v[194:197], v[68:71]
	v_mfma_f32_16x16x32_f16 v[64:67], v[162:165], v[194:197], v[64:67]
	v_mfma_f32_16x16x32_f16 v[108:111], v[158:161], v[174:177], v[108:111]
	v_mfma_f32_16x16x32_f16 v[104:107], v[166:169], v[174:177], v[104:107]
	v_mfma_f32_16x16x32_f16 v[92:95], v[158:161], v[182:185], v[92:95]
	v_mfma_f32_16x16x32_f16 v[88:91], v[166:169], v[182:185], v[88:91]
	v_mfma_f32_16x16x32_f16 v[76:79], v[158:161], v[190:193], v[76:79]
	v_mfma_f32_16x16x32_f16 v[72:75], v[166:169], v[190:193], v[72:75]
	v_mfma_f32_16x16x32_f16 v[68:71], v[158:161], v[198:201], v[68:71]
	v_mfma_f32_16x16x32_f16 v[64:67], v[166:169], v[198:201], v[64:67]
	s_barrier
	ds_read_b128 v[170:173], v134 offset:49152
	ds_read_b128 v[174:177], v134 offset:50176
	ds_read_b128 v[178:181], v134 offset:51200
	ds_read_b128 v[182:185], v134 offset:52224
	ds_read_b128 v[186:189], v134 offset:53248
	ds_read_b128 v[190:193], v134 offset:54272
	ds_read_b128 v[194:197], v134 offset:55296
	ds_read_b128 v[198:201], v134 offset:56320
	s_add_u32 s42, s48, 0x80
	s_addc_u32 s43, s49, 0
	s_mov_b32 m0, s73
	s_nop 0
	global_load_lds_dwordx4 v129, s[42:43]
	s_mov_b32 m0, s74
	s_nop 0
	global_load_lds_dwordx4 v131, s[42:43]
	s_add_u32 s42, s48, 0x80080
	s_addc_u32 s43, s49, 0
	s_mov_b32 m0, s77
	s_nop 0
	global_load_lds_dwordx4 v129, s[42:43]
	s_mov_b32 m0, s79
	s_nop 0
	global_load_lds_dwordx4 v131, s[42:43]
	s_mov_b32 m0, s75
	s_nop 0
	global_load_lds_dwordx4 v128, s[46:47]
	s_mov_b32 m0, s76
	s_nop 0
	global_load_lds_dwordx4 v130, s[46:47]
	s_waitcnt vmcnt(8)
	s_waitcnt lgkmcnt(0)
	s_barrier
	s_waitcnt lgkmcnt(7)
	v_mfma_f32_16x16x32_f16 v[60:63], v[138:141], v[170:173], v[60:63]
	v_mfma_f32_16x16x32_f16 v[56:59], v[146:149], v[170:173], v[56:59]
	s_waitcnt lgkmcnt(5)
	v_mfma_f32_16x16x32_f16 v[52:55], v[138:141], v[178:181], v[52:55]
	v_mfma_f32_16x16x32_f16 v[48:51], v[146:149], v[178:181], v[48:51]
	s_waitcnt lgkmcnt(3)
	v_mfma_f32_16x16x32_f16 v[36:39], v[138:141], v[186:189], v[36:39]
	v_mfma_f32_16x16x32_f16 v[32:35], v[146:149], v[186:189], v[32:35]
	s_waitcnt lgkmcnt(1)
	v_mfma_f32_16x16x32_f16 v[20:23], v[138:141], v[194:197], v[20:23]
	v_mfma_f32_16x16x32_f16 v[16:19], v[146:149], v[194:197], v[16:19]
	v_mfma_f32_16x16x32_f16 v[60:63], v[142:145], v[174:177], v[60:63]
	v_mfma_f32_16x16x32_f16 v[56:59], v[150:153], v[174:177], v[56:59]
	v_mfma_f32_16x16x32_f16 v[52:55], v[142:145], v[182:185], v[52:55]
	v_mfma_f32_16x16x32_f16 v[48:51], v[150:153], v[182:185], v[48:51]
	v_mfma_f32_16x16x32_f16 v[36:39], v[142:145], v[190:193], v[36:39]
	v_mfma_f32_16x16x32_f16 v[32:35], v[150:153], v[190:193], v[32:35]
	s_waitcnt lgkmcnt(0)
	v_mfma_f32_16x16x32_f16 v[20:23], v[142:145], v[198:201], v[20:23]
	v_mfma_f32_16x16x32_f16 v[16:19], v[150:153], v[198:201], v[16:19]
	v_mfma_f32_16x16x32_f16 v[44:47], v[154:157], v[170:173], v[44:47]
	v_mfma_f32_16x16x32_f16 v[40:43], v[162:165], v[170:173], v[40:43]
	v_mfma_f32_16x16x32_f16 v[28:31], v[154:157], v[178:181], v[28:31]
	v_mfma_f32_16x16x32_f16 v[24:27], v[162:165], v[178:181], v[24:27]
	v_mfma_f32_16x16x32_f16 v[12:15], v[154:157], v[186:189], v[12:15]
	v_mfma_f32_16x16x32_f16 v[8:11], v[162:165], v[186:189], v[8:11]
	v_mfma_f32_16x16x32_f16 v[4:7], v[154:157], v[194:197], v[4:7]
	v_mfma_f32_16x16x32_f16 v[0:3], v[162:165], v[194:197], v[0:3]
	v_mfma_f32_16x16x32_f16 v[44:47], v[158:161], v[174:177], v[44:47]
	v_mfma_f32_16x16x32_f16 v[40:43], v[166:169], v[174:177], v[40:43]
	v_mfma_f32_16x16x32_f16 v[28:31], v[158:161], v[182:185], v[28:31]
	v_mfma_f32_16x16x32_f16 v[24:27], v[166:169], v[182:185], v[24:27]
	v_mfma_f32_16x16x32_f16 v[12:15], v[158:161], v[190:193], v[12:15]
	v_mfma_f32_16x16x32_f16 v[8:11], v[166:169], v[190:193], v[8:11]
	v_mfma_f32_16x16x32_f16 v[4:7], v[158:161], v[198:201], v[4:7]
	v_mfma_f32_16x16x32_f16 v[0:3], v[166:169], v[198:201], v[0:3]
	s_barrier
	s_add_i32 s29, s29, 2
	s_add_u32 s4, s4, 0x100
	s_addc_u32 s5, s5, 0
	s_cmp_gt_u32 s29, 5
	s_mov_b64 s[42:43], s[44:45]
	s_cbranch_scc0 .LBB0_225
	s_and_b64 vcc, exec, s[16:17]
	s_cbranch_vccz .LBB0_228
	s_barrier

; __device__ __forceinline__ int mk_lane() { int l; asm volatile("v_mbcnt_lo_u32_b32 %0, -1, 0\n\tv_mbcnt_hi_u32_b32 %0, -1, %0" : "=v"(l)); return l; }
; template <class Prob, class Epi, bool I8 = false, bool ALIGN_EPI = true, bool SP2 = true>
; __device__ __forceinline__ void gemm_phase(LAS unsigned char* lds, int wave, const Prob& P, const Epi& E) {
;     const int tid_ = wave * 64 + mk_lane();
;     const int tid = tid_, wid = __builtin_amdgcn_readfirstlane(tid >> 6), lane = tid & 63, wr = wid >> 2, wc = wid & 3, fr = lane & 15, fq = lane >> 4;
;     const int K = P.K, nt = K / BK;
;     unsigned voffA[2], voffB[2];
; #pragma unroll
;     for (int i = 0; i < 2; ++i) { int R, C; stage_rc(tid * 16 + i * 8192, R, C); const int Rb = (R & ~31) + perm32(R & 31);
;         voffA[i] = P.a_rowoff(R) + (unsigned)C * 2u; voffB[i] = P.b_rowoff(Rb) + (unsigned)C * 2u; }
;     const size_t kstep = (size_t)(BK * 2);
;     const size_t hstepA = P.a_hstep(), hstepB = P.b_hstep();
;     const unsigned ldsw = (unsigned)wid * 1024u;
;     const unsigned ldsb = (unsigned)(size_t)lds + ldsw;
;     const int aoff = lds_byte(wr * 64 + fr, fq * 8), boff = lds_byte(wc * 32 + fr, fq * 8);
;     ...
;     Unit cur, nxt; int ui = 0;
;     if (!P.next(0, cur)) return;
;     Acc acc;
; #pragma unroll
;     for (int a = 0; a < 2; ++a)
; #pragma unroll
;         for (int b = 0; b < 2; ++b)
; #pragma unroll
;             for (int m = 0; m < 4; ++m)
; #pragma unroll
;                 for (int n = 0; n < 2; ++n) acc[a][b][m][n] = (f32x4){0.f, 0.f, 0.f, 0.f};
;     h16x8 At[4][2], B0[2][2], B1[2][2];
;     const char* cA = P.a_tile(cur); const char* cB = P.b_tile(cur);
;     if constexpr (SP2) {
;         PG8_STAGE(PG8_SB(0, 0), cB, voffB); PG8_STAGE(PG8_SB(0, 1), cB + hstepB, voffB); PG8_STAGE(PG8_SA(0, 0), cA, voffA); PG8_STAGE(PG8_SA(0, 1), cA + hstepA, voffA);
;         if (wr == 1) PG8_BAR;
;         PG8_WAIT_V(2); PG8_BAR;
;         PG8_STAGE(PG8_SB(1, 0), cB + kstep, voffB); PG8_STAGE(PG8_SA(1, 0), cA + kstep, voffA); PG8_STAGE(PG8_SB(1, 1), cB + hstepB + kstep, voffB);
;         PG8_WAIT_V(6); PG8_BAR;
;     } else {
;         PG8_STAGE(PG8_SB(0, 0), cB, voffB); PG8_STAGE(PG8_SA(0, 0), cA, voffA); PG8_STAGE(PG8_SB(0, 1), cB + hstepB, voffB); PG8_STAGE(PG8_SA(0, 1), cA + hstepA, voffA);
;         if (wr == 1) PG8_BAR;
;         PG8_WAIT_V(4); PG8_BAR;
.LBB0_286:
	s_add_u32 s46, s30, 0x4200000
	s_addc_u32 s47, s31, 0
	v_readlane_b32 s0, v254, 42
	v_readlane_b32 s4, v254, 55
	s_waitcnt lgkmcnt(0)
	s_barrier
	s_add_u32 s42, s30, 0x45200000
	v_mbcnt_lo_u32_b32 v0, -1, 0
	v_mbcnt_hi_u32_b32 v0, -1, v0
	v_readlane_b32 s5, v254, 56
	v_add_u32_e32 v1, s0, v0
	s_addc_u32 s43, s31, 0
	v_readfirstlane_b32 s0, v1
	s_and_b64 vcc, exec, s[4:5]
	s_cbranch_vccz .LBB0_380
	v_ashrrev_i32_e32 v2, 31, v1
	v_lshrrev_b32_e32 v2, 26, v2
	v_lshlrev_b32_e32 v3, 4, v1
	v_add_u32_e32 v2, v1, v2
	v_bfe_i32 v1, v1, 27, 1
	v_lshrrev_b32_e32 v1, 22, v1
	v_add_u32_e32 v1, v3, v1
	v_and_b32_e32 v1, 0xfffffc00, v1
	v_sub_u32_e32 v1, v3, v1
	v_lshrrev_b32_e32 v4, 4, v1
	v_bitop3_b32 v1, v4, v1, 32 bitop3:0x6c
	v_ashrrev_i32_e32 v5, 31, v1
	v_ashrrev_i32_e32 v2, 6, v2
	v_lshrrev_b32_e32 v5, 26, v5
	v_lshlrev_b32_e32 v4, 3, v2
	v_add_u32_e32 v5, v1, v5
	v_and_b32_e32 v4, -16, v4
	v_ashrrev_i32_e32 v6, 6, v5
	v_and_b32_e32 v5, 0xc0, v5
	v_add_u32_e32 v4, v6, v4
	v_sub_u32_e32 v1, v1, v5
	v_mov_b32_e32 v8, 1
	v_lshlrev_b32_e32 v2, 5, v2
	v_ashrrev_i16_sdwa v1, v8, sext(v1) dst_sel:DWORD dst_unused:UNUSED_PAD src0_sel:DWORD src1_sel:BYTE_0
	v_lshlrev_b32_e32 v5, 1, v4
	v_lshrrev_b32_e32 v7, 2, v4
	v_and_b32_e32 v6, 3, v6
	s_mov_b32 s2, 0x1ffffe0
	v_and_b32_e32 v2, 32, v2
	v_bfe_i32 v1, v1, 0, 16
	v_and_b32_e32 v5, 24, v5
	v_and_b32_e32 v7, 4, v7
	v_and_or_b32 v6, v4, s2, v6
	v_or3_b32 v5, v6, v7, v5
	v_add_lshl_u32 v2, v2, v1, 1
	v_add_u32_e32 v1, 0x2000, v3
	v_lshl_add_u32 v148, v4, 13, v2
	v_mad_u64_u32 v[136:137], s[4:5], v5, s21, v[2:3]
	v_ashrrev_i32_e32 v2, 31, v1
	v_lshrrev_b32_e32 v2, 22, v2
	v_add_u32_e32 v2, v1, v2
	v_ashrrev_i32_e32 v2, 10, v2
	v_mul_i32_i24_e32 v3, 0x400, v2
	v_sub_u32_e32 v1, v1, v3
	v_lshrrev_b32_e32 v3, 4, v1
	v_bitop3_b32 v1, v3, v1, 32 bitop3:0x6c
	v_ashrrev_i32_e32 v4, 31, v1
	v_lshrrev_b32_e32 v4, 26, v4
	v_lshlrev_b32_e32 v3, 3, v2
	v_add_u32_e32 v4, v1, v4
	v_and_b32_e32 v3, -16, v3
	v_ashrrev_i32_e32 v5, 6, v4
	v_and_b32_e32 v4, 0xc0, v4
	v_add_u32_e32 v3, v5, v3
	v_sub_u32_e32 v1, v1, v4
	v_lshlrev_b32_e32 v2, 5, v2
	v_ashrrev_i16_sdwa v1, v8, sext(v1) dst_sel:DWORD dst_unused:UNUSED_PAD src0_sel:DWORD src1_sel:BYTE_0
	v_lshlrev_b32_e32 v4, 1, v3
	v_lshrrev_b32_e32 v6, 2, v3
	v_and_b32_e32 v5, 3, v5
	v_and_b32_e32 v2, 32, v2
	v_bfe_i32 v1, v1, 0, 16
	v_and_b32_e32 v4, 24, v4
	v_and_b32_e32 v6, 4, v6
	v_and_or_b32 v5, v3, s2, v5
	v_or3_b32 v4, v5, v6, v4
	v_add_lshl_u32 v2, v2, v1, 1
	v_mad_u64_u32 v[138:139], s[4:5], v4, s21, v[2:3]
	s_ashr_i32 s4, s0, 6
	s_lshl_b32 s2, s4, 10
	v_readlane_b32 s6, v254, 58
	s_ashr_i32 s1, s0, 8
	s_add_i32 s2, s2, 0
	s_mul_i32 s5, s6, 0x820000
	s_add_u32 s5, s26, s5
	s_mul_hi_i32 s6, s6, 0x820000
	v_readlane_b32 s7, v254, 57
	s_addc_u32 s6, s27, s6
	s_mul_i32 s7, s7, 0x208000
	s_add_u32 s38, s5, s7
	s_addc_u32 s39, s6, 0
	s_add_i32 s19, s2, 0x10000
	s_mov_b32 m0, s19
	s_nop 0
	global_load_lds_dwordx4 v136, s[38:39]
	s_add_i32 s60, s2, 0x12000
	s_mov_b32 m0, s60
	s_nop 0
	global_load_lds_dwordx4 v138, s[38:39]
	s_add_u32 s14, s38, 0x104000
	s_addc_u32 s15, s39, 0
	s_add_i32 s61, s2, 0x14000
	s_mov_b32 m0, s61
	s_nop 0
	global_load_lds_dwordx4 v136, s[14:15]
	s_add_i32 s62, s2, 0x16000
	s_mov_b32 m0, s62
	s_nop 0
	global_load_lds_dwordx4 v138, s[14:15]
	v_lshl_add_u32 v137, v3, 13, v2
	v_readlane_b32 s5, v252, 30
	s_add_u32 s14, s46, s5
	s_addc_u32 s15, s47, 0
	s_mov_b32 m0, s2
	s_nop 0
	global_load_lds_dwordx4 v148, s[14:15]
	s_add_i32 s63, s2, 0x2000
	s_mov_b32 m0, s63
	s_nop 0
	global_load_lds_dwordx4 v137, s[14:15]
	s_add_u32 s16, s14, 0x100000
	s_addc_u32 s17, s15, 0
	s_add_i32 s68, s2, 0x4000
	s_mov_b32 m0, s68
	s_nop 0
	global_load_lds_dwordx4 v148, s[16:17]
	s_add_i32 s69, s2, 0x6000
	s_mov_b32 m0, s69
	s_nop 0
	global_load_lds_dwordx4 v137, s[16:17]
	s_cmp_eq_u32 s1, 1
	s_cselect_b64 s[76:77], -1, 0
	s_setprio 1
	s_cmp_lg_u32 s1, 1
	s_cbranch_scc1 .LBB0_289
	s_barrier
	s_setprio 0
; #define PG8_STAGE(bufoff, gbase, voff) do { _Pragma("unroll") for (int _i = 0; _i < 2; ++_i) glds16_s((gbase), (voff)[_i], ldsb + (unsigned)((bufoff) + _i * 8192)); } while (0)
; #define PG8_WAIT_V(n) asm volatile("s_waitcnt vmcnt(" #n ")" ::: "memory")
; #define PG8_BAR __builtin_amdgcn_s_barrier()
; template <class Prob, class Epi, bool I8 = false, bool ALIGN_EPI = true, bool SP2 = true>
; __device__ __forceinline__ void gemm_phase(LAS unsigned char* lds, int wave, const Prob& P, const Epi& E) {
;     ...
;     Acc acc;
; #pragma unroll
;     for (int a = 0; a < 2; ++a)
; #pragma unroll
;         for (int b = 0; b < 2; ++b)
; #pragma unroll
;             for (int m = 0; m < 4; ++m)
; #pragma unroll
;                 for (int n = 0; n < 2; ++n) acc[a][b][m][n] = (f32x4){0.f, 0.f, 0.f, 0.f};
;     h16x8 At[4][2], B0[2][2], B1[2][2];
;     const char* cA = P.a_tile(cur); const char* cB = P.b_tile(cur);
;     if constexpr (SP2) {
;         PG8_STAGE(PG8_SB(0, 0), cB, voffB); PG8_STAGE(PG8_SB(0, 1), cB + hstepB, voffB); PG8_STAGE(PG8_SA(0, 0), cA, voffA); PG8_STAGE(PG8_SA(0, 1), cA + hstepA, voffA);
;         if (wr == 1) PG8_BAR;
;         PG8_WAIT_V(2); PG8_BAR;
;         PG8_STAGE(PG8_SB(1, 0), cB + kstep, voffB); PG8_STAGE(PG8_SA(1, 0), cA + kstep, voffA); PG8_STAGE(PG8_SB(1, 1), cB + hstepB + kstep, voffB);
;         PG8_WAIT_V(6); PG8_BAR;
;     } else {
;         PG8_STAGE(PG8_SB(0, 0), cB, voffB); PG8_STAGE(PG8_SA(0, 0), cA, voffA); PG8_STAGE(PG8_SB(0, 1), cB + hstepB, voffB); PG8_STAGE(PG8_SA(0, 1), cA + hstepA, voffA);
;         if (wr == 1) PG8_BAR;
;         PG8_WAIT_V(4); PG8_BAR;
;         PG8_STAGE(PG8_SB(1, 0), cB + kstep, voffB); PG8_STAGE(PG8_SA(1, 0), cA + kstep, voffA); PG8_STAGE(PG8_SB(1, 1), cB + hstepB + kstep, voffB);
;         PG8_WAIT_V(6); PG8_BAR;
.LBB0_289:
	v_and_b32_e32 v1, 48, v0
	v_lshlrev_b32_e32 v2, 6, v0
	s_movk_i32 s5, 0x3c0
	v_lshlrev_b32_e32 v0, 2, v0
	s_lshl_b32 s79, s1, 6
	s_lshl_b32 s1, s1, 13
	v_and_or_b32 v1, v2, s5, v1
	v_and_b32_e32 v0, 32, v0
	v_bitop3_b32 v2, v1, s1, v0 bitop3:0xde
	s_lshl_b32 s1, s4, 5
	s_and_b32 s64, s1, 0x60
	s_lshl_b32 s1, s64, 7
	s_add_u32 s4, s38, 0x80
	v_bitop3_b32 v1, s1, v1, v0 bitop3:0xf6
	s_waitcnt vmcnt(2)
	s_barrier
	s_addc_u32 s5, s39, 0
	s_add_i32 s80, s2, 0x18000
	s_mov_b32 m0, s80
	s_nop 0
	global_load_lds_dwordx4 v136, s[4:5]
	s_add_i32 s81, s2, 0x1a000
	s_mov_b32 m0, s81
	s_nop 0
	global_load_lds_dwordx4 v138, s[4:5]
	s_add_u32 s4, s14, 0x80
	s_addc_u32 s5, s15, 0
	s_add_i32 s82, s2, 0x8000
	s_mov_b32 m0, s82
	s_nop 0
	global_load_lds_dwordx4 v148, s[4:5]
	s_add_i32 s83, s2, 0xa000
	s_mov_b32 m0, s83
	s_nop 0
	global_load_lds_dwordx4 v137, s[4:5]
	s_add_u32 s4, s38, 0x104080
	s_addc_u32 s5, s39, 0
	s_add_i32 s84, s2, 0x1c000
	s_mov_b32 m0, s84
	s_nop 0
	global_load_lds_dwordx4 v136, s[4:5]
	s_add_i32 s85, s2, 0x1e000
	s_mov_b32 m0, s85
	s_nop 0
	global_load_lds_dwordx4 v138, s[4:5]
	s_waitcnt vmcnt(6)
	s_add_i32 s86, s2, 0xc000
	s_cmpk_lt_u32 s0, 0x100
	v_mov_b32_e32 v0, 0
	s_cselect_b64 s[28:29], -1, 0
	s_add_i32 s87, s2, 0xe000
	s_mov_b32 s75, 0
	s_mov_b32 s90, 1
	v_add_u32_e32 v139, 0, v1
	v_add_u32_e32 v149, 0, v2
	v_readlane_b32 s72, v254, 58
	v_readlane_b32 s73, v254, 57
	v_readlane_b32 s74, v252, 29
	s_mov_b32 s88, 0
	v_mov_b32_e32 v1, v0
	v_mov_b32_e32 v2, v0
	v_mov_b32_e32 v3, v0
	v_mov_b32_e32 v4, v0
	v_mov_b32_e32 v5, v0
	v_mov_b32_e32 v6, v0
	v_mov_b32_e32 v7, v0
	v_mov_b32_e32 v8, v0
	v_mov_b32_e32 v9, v0
	v_mov_b32_e32 v10, v0
	v_mov_b32_e32 v11, v0
	v_mov_b32_e32 v12, v0
	v_mov_b32_e32 v13, v0
	v_mov_b32_e32 v14, v0
	v_mov_b32_e32 v15, v0
	v_mov_b32_e32 v16, v0
	v_mov_b32_e32 v17, v0
	v_mov_b32_e32 v18, v0
	v_mov_b32_e32 v19, v0
	v_mov_b32_e32 v20, v0
	v_mov_b32_e32 v21, v0
	v_mov_b32_e32 v22, v0
	v_mov_b32_e32 v23, v0
	v_mov_b32_e32 v24, v0
	v_mov_b32_e32 v25, v0
	v_mov_b32_e32 v26, v0
	v_mov_b32_e32 v27, v0
	v_mov_b32_e32 v28, v0
	v_mov_b32_e32 v29, v0
	v_mov_b32_e32 v30, v0
	v_mov_b32_e32 v31, v0
	v_mov_b32_e32 v32, v0
	v_mov_b32_e32 v33, v0
	v_mov_b32_e32 v34, v0
	v_mov_b32_e32 v35, v0
	v_mov_b32_e32 v36, v0
	v_mov_b32_e32 v37, v0
	v_mov_b32_e32 v38, v0
	v_mov_b32_e32 v39, v0
	v_mov_b32_e32 v40, v0
	v_mov_b32_e32 v41, v0
	v_mov_b32_e32 v42, v0
	v_mov_b32_e32 v43, v0
	v_mov_b32_e32 v44, v0
	v_mov_b32_e32 v45, v0
	v_mov_b32_e32 v46, v0
	v_mov_b32_e32 v47, v0
	v_mov_b32_e32 v48, v0
	v_mov_b32_e32 v49, v0
	v_mov_b32_e32 v50, v0
	v_mov_b32_e32 v51, v0
	v_mov_b32_e32 v52, v0
	v_mov_b32_e32 v53, v0
	v_mov_b32_e32 v54, v0
	v_mov_b32_e32 v55, v0
	v_mov_b32_e32 v56, v0
	v_mov_b32_e32 v57, v0
	v_mov_b32_e32 v58, v0
	v_mov_b32_e32 v59, v0
	v_mov_b32_e32 v60, v0
	v_mov_b32_e32 v61, v0
	v_mov_b32_e32 v62, v0
	v_mov_b32_e32 v63, v0
	v_mov_b32_e32 v64, v0
	v_mov_b32_e32 v65, v0
	v_mov_b32_e32 v66, v0
	v_mov_b32_e32 v67, v0
	v_mov_b32_e32 v68, v0
	v_mov_b32_e32 v69, v0
	v_mov_b32_e32 v70, v0
	v_mov_b32_e32 v71, v0
	v_mov_b32_e32 v72, v0
	v_mov_b32_e32 v73, v0
	v_mov_b32_e32 v74, v0
	v_mov_b32_e32 v75, v0
	v_mov_b32_e32 v76, v0
	v_mov_b32_e32 v77, v0
	v_mov_b32_e32 v78, v0
	v_mov_b32_e32 v79, v0
	v_mov_b32_e32 v80, v0
	v_mov_b32_e32 v81, v0
	v_mov_b32_e32 v82, v0
	v_mov_b32_e32 v83, v0
	v_mov_b32_e32 v84, v0
	v_mov_b32_e32 v85, v0
	v_mov_b32_e32 v86, v0
	v_mov_b32_e32 v87, v0
	v_mov_b32_e32 v88, v0
	v_mov_b32_e32 v89, v0
	v_mov_b32_e32 v90, v0
	v_mov_b32_e32 v91, v0
	v_mov_b32_e32 v92, v0
	v_mov_b32_e32 v93, v0
	v_mov_b32_e32 v94, v0
	v_mov_b32_e32 v95, v0
	v_mov_b32_e32 v96, v0
	v_mov_b32_e32 v97, v0
	v_mov_b32_e32 v98, v0
	v_mov_b32_e32 v99, v0
	v_mov_b32_e32 v100, v0
	v_mov_b32_e32 v101, v0
	v_mov_b32_e32 v102, v0
	v_mov_b32_e32 v103, v0
	v_mov_b32_e32 v104, v0
	v_mov_b32_e32 v105, v0
	v_mov_b32_e32 v106, v0
	v_mov_b32_e32 v107, v0
	v_mov_b32_e32 v108, v0
	v_mov_b32_e32 v109, v0
	v_mov_b32_e32 v110, v0
	v_mov_b32_e32 v111, v0
	v_mov_b32_e32 v112, v0
	v_mov_b32_e32 v113, v0
	v_mov_b32_e32 v114, v0
	v_mov_b32_e32 v115, v0
	v_mov_b32_e32 v116, v0
	v_mov_b32_e32 v117, v0
	v_mov_b32_e32 v118, v0
	v_mov_b32_e32 v119, v0
	v_mov_b32_e32 v120, v0
	v_mov_b32_e32 v121, v0
	v_mov_b32_e32 v122, v0
	v_mov_b32_e32 v123, v0
	v_mov_b32_e32 v124, v0
	v_mov_b32_e32 v125, v0
	v_mov_b32_e32 v126, v0
	v_mov_b32_e32 v127, v0
	s_barrier
	s_branch .LBB0_292

; #define PG8_STAGE(bufoff, gbase, voff) do { _Pragma("unroll") for (int _i = 0; _i < 2; ++_i) glds16_s((gbase), (voff)[_i], ldsb + (unsigned)((bufoff) + _i * 8192)); } while (0)
; #define PG8_LDA(dst, b, h) do { _Pragma("unroll") for (int m = 0; m < 4; ++m) _Pragma("unroll") for (int k = 0; k < 2; ++k) dst[m][k] = *(const LAS h16x8*)(lds + PG8_SA(b, h) + aoff + m * 2048 + k * 1024); } while (0)
; #define PG8_LDB(dst, b, h) do { _Pragma("unroll") for (int n = 0; n < 2; ++n) _Pragma("unroll") for (int k = 0; k < 2; ++k) dst[n][k] = *(const LAS h16x8*)(lds + PG8_SB(b, h) + boff + n * 2048 + k * 1024); } while (0)
; #define PG8_MMA(ai, bj, At, Bt) do { __builtin_amdgcn_s_setprio(1); _Pragma("unroll") for (int m = 0; m < 4; ++m) _Pragma("unroll") for (int n = 0; n < 2; ++n) _Pragma("unroll") for (int k = 0; k < 2; ++k) \
;         acc[ai][bj][m][n] = mma_step<I8>(Bt[n][k], At[m][k], acc[ai][bj][m][n]); __builtin_amdgcn_s_setprio(0); } while (0)
; #define PG8_WAIT_V(n) asm volatile("s_waitcnt vmcnt(" #n ")" ::: "memory")
; #define PG8_WAIT_L(n) asm volatile("s_waitcnt lgkmcnt(" #n ")" ::: "memory")
; #define PG8_BAR __builtin_amdgcn_s_barrier()
; #define PG8_SCHED __builtin_amdgcn_sched_barrier(0)
; template <class Prob, class Epi, bool I8 = false, bool ALIGN_EPI = true, bool SP2 = true>
; __device__ __forceinline__ void gemm_phase(LAS unsigned char* lds, int wave, const Prob& P, const Epi& E) {
;     ...
;             PG8_LDB(B0, 0, 0); PG8_LDB(B1, 0, 1); PG8_SCHED; PG8_LDA(At, 0, 0); PG8_STAGE(PG8_SA(1, 1), a1 + hstepA, voffA);
;             PG8_WAIT_V(8); PG8_WAIT_L(0); PG8_BAR; PG8_MMA(0, 0, At, B0); PG8_MMA(0, 1, At, B1); PG8_BAR; PG8_SCHED;
;             PG8_LDA(At, 0, 1); PG8_STAGE(PG8_SB(0, 0), b2, voffB); PG8_STAGE(PG8_SB(0, 1), b2 + hstepB, voffB); PG8_STAGE(PG8_SA(0, 0), a2, voffA);
;             PG8_WAIT_V(8); PG8_WAIT_L(0); PG8_BAR; PG8_MMA(1, 0, At, B0); PG8_MMA(1, 1, At, B1); PG8_BAR; PG8_SCHED;
.LBB0_297:
	v_add_u32_e32 v144, 0x10000, v139
	v_add_u32_e32 v162, 0x14000, v139
	ds_read_b128 v[128:131], v144
	ds_read_b128 v[132:135], v144 offset:1024
	ds_read_b128 v[140:143], v144 offset:2048
	ds_read_b128 v[144:147], v144 offset:3072
	ds_read_b128 v[150:153], v162
	ds_read_b128 v[154:157], v162 offset:1024
	ds_read_b128 v[158:161], v162 offset:2048
	ds_read_b128 v[162:165], v162 offset:3072
	s_add_u32 s38, s14, 0x100
	s_addc_u32 s39, s15, 0
	s_cmp_eq_u32 s5, 28
	s_cselect_b32 s56, s1, s38
	s_cselect_b32 s57, s0, s39
	s_cselect_b32 s44, s48, s17
	s_cselect_b32 s45, s49, s4
	s_add_u32 s40, s56, 0x80
	s_addc_u32 s41, s57, 0
	ds_read_b128 v[166:169], v149
	ds_read_b128 v[170:173], v149 offset:1024
	ds_read_b128 v[174:177], v149 offset:2048
	ds_read_b128 v[178:181], v149 offset:3072
	ds_read_b128 v[182:185], v149 offset:4096
	ds_read_b128 v[186:189], v149 offset:5120
	ds_read_b128 v[190:193], v149 offset:6144
	ds_read_b128 v[194:197], v149 offset:7168
	s_add_u32 s14, s14, 0x100080
	s_addc_u32 s15, s15, 0
	s_mov_b32 m0, s86
	s_nop 0
	global_load_lds_dwordx4 v148, s[14:15]
	s_mov_b32 m0, s87
	s_nop 0
	global_load_lds_dwordx4 v137, s[14:15]
	s_waitcnt vmcnt(8)
	s_waitcnt lgkmcnt(0)
	s_barrier
	s_waitcnt lgkmcnt(7)
	v_mfma_f32_16x16x32_f16 v[124:127], v[128:131], v[166:169], v[124:127]
	v_mfma_f32_16x16x32_f16 v[120:123], v[140:143], v[166:169], v[120:123]
	s_waitcnt lgkmcnt(5)
	v_mfma_f32_16x16x32_f16 v[116:119], v[128:131], v[174:177], v[116:119]
	v_mfma_f32_16x16x32_f16 v[112:115], v[140:143], v[174:177], v[112:115]
	s_waitcnt lgkmcnt(3)
	v_mfma_f32_16x16x32_f16 v[108:111], v[128:131], v[182:185], v[108:111]
	v_mfma_f32_16x16x32_f16 v[104:107], v[140:143], v[182:185], v[104:107]
	s_waitcnt lgkmcnt(1)
	v_mfma_f32_16x16x32_f16 v[100:103], v[128:131], v[190:193], v[100:103]
	v_mfma_f32_16x16x32_f16 v[96:99], v[140:143], v[190:193], v[96:99]
	v_mfma_f32_16x16x32_f16 v[124:127], v[132:135], v[170:173], v[124:127]
	v_mfma_f32_16x16x32_f16 v[120:123], v[144:147], v[170:173], v[120:123]
	v_mfma_f32_16x16x32_f16 v[116:119], v[132:135], v[178:181], v[116:119]
	v_mfma_f32_16x16x32_f16 v[112:115], v[144:147], v[178:181], v[112:115]
	v_mfma_f32_16x16x32_f16 v[108:111], v[132:135], v[186:189], v[108:111]
	v_mfma_f32_16x16x32_f16 v[104:107], v[144:147], v[186:189], v[104:107]
	s_waitcnt lgkmcnt(0)
	v_mfma_f32_16x16x32_f16 v[100:103], v[132:135], v[194:197], v[100:103]
	v_mfma_f32_16x16x32_f16 v[96:99], v[144:147], v[194:197], v[96:99]
	v_mfma_f32_16x16x32_f16 v[92:95], v[150:153], v[166:169], v[92:95]
	v_mfma_f32_16x16x32_f16 v[88:91], v[158:161], v[166:169], v[88:91]
	v_mfma_f32_16x16x32_f16 v[84:87], v[150:153], v[174:177], v[84:87]
	v_mfma_f32_16x16x32_f16 v[80:83], v[158:161], v[174:177], v[80:83]
	v_mfma_f32_16x16x32_f16 v[76:79], v[150:153], v[182:185], v[76:79]
	v_mfma_f32_16x16x32_f16 v[72:75], v[158:161], v[182:185], v[72:75]
	v_mfma_f32_16x16x32_f16 v[68:71], v[150:153], v[190:193], v[68:71]
	v_mfma_f32_16x16x32_f16 v[64:67], v[158:161], v[190:193], v[64:67]
	v_mfma_f32_16x16x32_f16 v[92:95], v[154:157], v[170:173], v[92:95]
	v_mfma_f32_16x16x32_f16 v[88:91], v[162:165], v[170:173], v[88:91]
	v_mfma_f32_16x16x32_f16 v[84:87], v[154:157], v[178:181], v[84:87]
	v_mfma_f32_16x16x32_f16 v[80:83], v[162:165], v[178:181], v[80:83]
	v_mfma_f32_16x16x32_f16 v[76:79], v[154:157], v[186:189], v[76:79]
	v_mfma_f32_16x16x32_f16 v[72:75], v[162:165], v[186:189], v[72:75]
	v_mfma_f32_16x16x32_f16 v[68:71], v[154:157], v[194:197], v[68:71]
	v_mfma_f32_16x16x32_f16 v[64:67], v[162:165], v[194:197], v[64:67]
	s_barrier
	ds_read_b128 v[166:169], v149 offset:16384
	ds_read_b128 v[170:173], v149 offset:17408
	ds_read_b128 v[174:177], v149 offset:18432
	ds_read_b128 v[178:181], v149 offset:19456
	ds_read_b128 v[182:185], v149 offset:20480
	ds_read_b128 v[186:189], v149 offset:21504
	ds_read_b128 v[190:193], v149 offset:22528
	ds_read_b128 v[194:197], v149 offset:23552
	s_mov_b32 m0, s19
	s_nop 0
	global_load_lds_dwordx4 v136, s[44:45]
	s_add_u32 s14, s44, 0x104000
	s_mov_b32 m0, s60
	s_nop 0
	global_load_lds_dwordx4 v138, s[44:45]
	s_addc_u32 s15, s45, 0
	s_mov_b32 m0, s61
	s_nop 0
	global_load_lds_dwordx4 v136, s[14:15]
	s_mov_b32 m0, s62
	s_nop 0
	global_load_lds_dwordx4 v138, s[14:15]
	s_mov_b32 m0, s2
	s_nop 0
	global_load_lds_dwordx4 v148, s[56:57]
	s_mov_b32 m0, s63
	s_nop 0
	global_load_lds_dwordx4 v137, s[56:57]
	s_waitcnt vmcnt(8)
	s_waitcnt lgkmcnt(0)
	s_barrier
	s_waitcnt lgkmcnt(7)
	v_mfma_f32_16x16x32_f16 v[60:63], v[128:131], v[166:169], v[60:63]
	v_mfma_f32_16x16x32_f16 v[56:59], v[140:143], v[166:169], v[56:59]
	s_waitcnt lgkmcnt(5)
	v_mfma_f32_16x16x32_f16 v[52:55], v[128:131], v[174:177], v[52:55]
	v_mfma_f32_16x16x32_f16 v[48:51], v[140:143], v[174:177], v[48:51]
	s_waitcnt lgkmcnt(3)
	v_mfma_f32_16x16x32_f16 v[44:47], v[128:131], v[182:185], v[44:47]
	v_mfma_f32_16x16x32_f16 v[40:43], v[140:143], v[182:185], v[40:43]
	s_waitcnt lgkmcnt(1)
	v_mfma_f32_16x16x32_f16 v[36:39], v[128:131], v[190:193], v[36:39]
	v_mfma_f32_16x16x32_f16 v[32:35], v[140:143], v[190:193], v[32:35]
	v_mfma_f32_16x16x32_f16 v[60:63], v[132:135], v[170:173], v[60:63]
	v_mfma_f32_16x16x32_f16 v[56:59], v[144:147], v[170:173], v[56:59]
	v_mfma_f32_16x16x32_f16 v[52:55], v[132:135], v[178:181], v[52:55]
	v_mfma_f32_16x16x32_f16 v[48:51], v[144:147], v[178:181], v[48:51]
	v_mfma_f32_16x16x32_f16 v[44:47], v[132:135], v[186:189], v[44:47]
	v_mfma_f32_16x16x32_f16 v[40:43], v[144:147], v[186:189], v[40:43]
	s_waitcnt lgkmcnt(0)
	v_mfma_f32_16x16x32_f16 v[36:39], v[132:135], v[194:197], v[36:39]
	v_mfma_f32_16x16x32_f16 v[32:35], v[144:147], v[194:197], v[32:35]
	v_mfma_f32_16x16x32_f16 v[28:31], v[150:153], v[166:169], v[28:31]
	v_mfma_f32_16x16x32_f16 v[24:27], v[158:161], v[166:169], v[24:27]
	v_mfma_f32_16x16x32_f16 v[20:23], v[150:153], v[174:177], v[20:23]
	v_mfma_f32_16x16x32_f16 v[16:19], v[158:161], v[174:177], v[16:19]
	v_mfma_f32_16x16x32_f16 v[12:15], v[150:153], v[182:185], v[12:15]
	v_mfma_f32_16x16x32_f16 v[8:11], v[158:161], v[182:185], v[8:11]
	v_mfma_f32_16x16x32_f16 v[4:7], v[150:153], v[190:193], v[4:7]
	v_mfma_f32_16x16x32_f16 v[0:3], v[158:161], v[190:193], v[0:3]
	v_mfma_f32_16x16x32_f16 v[28:31], v[154:157], v[170:173], v[28:31]
	v_mfma_f32_16x16x32_f16 v[24:27], v[162:165], v[170:173], v[24:27]
	v_mfma_f32_16x16x32_f16 v[20:23], v[154:157], v[178:181], v[20:23]
	v_mfma_f32_16x16x32_f16 v[16:19], v[162:165], v[178:181], v[16:19]
	v_mfma_f32_16x16x32_f16 v[12:15], v[154:157], v[186:189], v[12:15]
	v_mfma_f32_16x16x32_f16 v[8:11], v[162:165], v[186:189], v[8:11]
	v_mfma_f32_16x16x32_f16 v[4:7], v[154:157], v[194:197], v[4:7]
	v_mfma_f32_16x16x32_f16 v[0:3], v[162:165], v[194:197], v[0:3]
	s_barrier
; #define PG8_STAGE(bufoff, gbase, voff) do { _Pragma("unroll") for (int _i = 0; _i < 2; ++_i) glds16_s((gbase), (voff)[_i], ldsb + (unsigned)((bufoff) + _i * 8192)); } while (0)
; #define PG8_WAIT_V(n) asm volatile("s_waitcnt vmcnt(" #n ")" ::: "memory")
; #define PG8_BAR __builtin_amdgcn_s_barrier()
; template <class Prob, class Epi, bool I8 = false, bool ALIGN_EPI = true, bool SP2 = true>
; __device__ __forceinline__ void gemm_phase(LAS unsigned char* lds, int wave, const Prob& P, const Epi& E) {
;     ...
;             PG8_LDB(B0, 1, 0); PG8_LDB(B1, 1, 1); PG8_SCHED; PG8_LDA(At, 1, 0); PG8_STAGE(PG8_SA(0, 1), a2 + hstepA, voffA);
;             PG8_WAIT_V(8); PG8_WAIT_L(0); PG8_BAR; PG8_MMA(0, 0, At, B0); PG8_MMA(0, 1, At, B1); PG8_BAR; PG8_SCHED;
;             PG8_LDA(At, 1, 1); PG8_STAGE(PG8_SB(1, 0), b3, voffB); PG8_STAGE(PG8_SB(1, 1), b3 + hstepB, voffB); PG8_STAGE(PG8_SA(1, 0), a3, voffA);
;             PG8_WAIT_V(8); PG8_WAIT_L(0); PG8_BAR; PG8_MMA(1, 0, At, B0); PG8_MMA(1, 1, At, B1); PG8_BAR; PG8_SCHED;
;             } else {
;             PG8_LDB(B0, 0, 0); PG8_SCHED; PG8_LDA(At, 0, 0); PG8_STAGE(PG8_SA(1, 1), a1 + hstepA, voffA);
;             PG8_WAIT_L(8); PG8_BAR; PG8_WAIT_L(0); PG8_MMA(0, 0, At, B0); PG8_BAR; PG8_SCHED;
;             PG8_LDB(B1, 0, 1); PG8_STAGE(PG8_SB(0, 0), b2, voffB);
;             PG8_BAR; PG8_WAIT_L(0); PG8_MMA(0, 1, At, B1); PG8_BAR;
;             PG8_LDA(At, 0, 1); PG8_STAGE(PG8_SA(0, 0), a2, voffA);
;             PG8_BAR; PG8_WAIT_L(0); PG8_MMA(1, 0, At, B0); PG8_BAR; PG8_SCHED;
;             PG8_STAGE(PG8_SB(0, 1), b2 + hstepB, voffB);
;             PG8_WAIT_V(6); PG8_BAR; PG8_MMA(1, 1, At, B1); PG8_BAR;
;             PG8_LDB(B0, 1, 0); PG8_SCHED; PG8_LDA(At, 1, 0); PG8_STAGE(PG8_SA(0, 1), a2 + hstepA, voffA);
;             PG8_WAIT_L(8); PG8_BAR; PG8_WAIT_L(0); PG8_MMA(0, 0, At, B0); PG8_BAR; PG8_SCHED;
;             PG8_LDB(B1, 1, 1); PG8_STAGE(PG8_SB(1, 0), b3, voffB);
;             PG8_BAR; PG8_WAIT_L(0); PG8_MMA(0, 1, At, B1); PG8_BAR;
;             PG8_LDA(At, 1, 1); PG8_STAGE(PG8_SA(1, 0), a3, voffA);
;             PG8_BAR; PG8_WAIT_L(0); PG8_MMA(1, 0, At, B0); PG8_BAR; PG8_SCHED;
;             PG8_STAGE(PG8_SB(1, 1), b3 + hstepB, voffB);
;             PG8_WAIT_V(6); PG8_BAR; PG8_MMA(1, 1, At, B1); PG8_BAR;
;             }
;         }
;         if constexpr (ALIGN_EPI) { if (wr == 0) PG8_BAR; }
	v_add_u32_e32 v144, 0x18000, v139
	v_add_u32_e32 v162, 0x1c000, v139
	ds_read_b128 v[128:131], v144
	ds_read_b128 v[132:135], v144 offset:1024
	ds_read_b128 v[140:143], v144 offset:2048
	ds_read_b128 v[144:147], v144 offset:3072
	ds_read_b128 v[150:153], v162
	ds_read_b128 v[154:157], v162 offset:1024
	ds_read_b128 v[158:161], v162 offset:2048
	ds_read_b128 v[162:165], v162 offset:3072
	ds_read_b128 v[166:169], v149 offset:32768
	ds_read_b128 v[170:173], v149 offset:33792
	ds_read_b128 v[174:177], v149 offset:34816
	ds_read_b128 v[178:181], v149 offset:35840
	ds_read_b128 v[182:185], v149 offset:36864
	ds_read_b128 v[186:189], v149 offset:37888
	ds_read_b128 v[190:193], v149 offset:38912
	ds_read_b128 v[194:197], v149 offset:39936
	s_add_u32 s14, s56, 0x100000
	s_addc_u32 s15, s57, 0
	s_mov_b32 m0, s68
	s_nop 0
	global_load_lds_dwordx4 v148, s[14:15]
	s_mov_b32 m0, s69
	s_nop 0
	global_load_lds_dwordx4 v137, s[14:15]
	s_waitcnt vmcnt(8)
	s_waitcnt lgkmcnt(0)
	s_barrier
	s_waitcnt lgkmcnt(7)
	v_mfma_f32_16x16x32_f16 v[124:127], v[128:131], v[166:169], v[124:127]
	v_mfma_f32_16x16x32_f16 v[120:123], v[140:143], v[166:169], v[120:123]
	s_waitcnt lgkmcnt(5)
	v_mfma_f32_16x16x32_f16 v[116:119], v[128:131], v[174:177], v[116:119]
	v_mfma_f32_16x16x32_f16 v[112:115], v[140:143], v[174:177], v[112:115]
	s_waitcnt lgkmcnt(3)
	v_mfma_f32_16x16x32_f16 v[108:111], v[128:131], v[182:185], v[108:111]
	v_mfma_f32_16x16x32_f16 v[104:107], v[140:143], v[182:185], v[104:107]
	s_waitcnt lgkmcnt(1)
	v_mfma_f32_16x16x32_f16 v[100:103], v[128:131], v[190:193], v[100:103]
	v_mfma_f32_16x16x32_f16 v[96:99], v[140:143], v[190:193], v[96:99]
	v_mfma_f32_16x16x32_f16 v[124:127], v[132:135], v[170:173], v[124:127]
	v_mfma_f32_16x16x32_f16 v[120:123], v[144:147], v[170:173], v[120:123]
	v_mfma_f32_16x16x32_f16 v[116:119], v[132:135], v[178:181], v[116:119]
	v_mfma_f32_16x16x32_f16 v[112:115], v[144:147], v[178:181], v[112:115]
	v_mfma_f32_16x16x32_f16 v[108:111], v[132:135], v[186:189], v[108:111]
	v_mfma_f32_16x16x32_f16 v[104:107], v[144:147], v[186:189], v[104:107]
	s_waitcnt lgkmcnt(0)
	v_mfma_f32_16x16x32_f16 v[100:103], v[132:135], v[194:197], v[100:103]
	v_mfma_f32_16x16x32_f16 v[96:99], v[144:147], v[194:197], v[96:99]
	v_mfma_f32_16x16x32_f16 v[92:95], v[150:153], v[166:169], v[92:95]
	v_mfma_f32_16x16x32_f16 v[88:91], v[158:161], v[166:169], v[88:91]
	v_mfma_f32_16x16x32_f16 v[84:87], v[150:153], v[174:177], v[84:87]
	v_mfma_f32_16x16x32_f16 v[80:83], v[158:161], v[174:177], v[80:83]
	v_mfma_f32_16x16x32_f16 v[76:79], v[150:153], v[182:185], v[76:79]
	v_mfma_f32_16x16x32_f16 v[72:75], v[158:161], v[182:185], v[72:75]
	v_mfma_f32_16x16x32_f16 v[68:71], v[150:153], v[190:193], v[68:71]
	v_mfma_f32_16x16x32_f16 v[64:67], v[158:161], v[190:193], v[64:67]
	v_mfma_f32_16x16x32_f16 v[92:95], v[154:157], v[170:173], v[92:95]
	v_mfma_f32_16x16x32_f16 v[88:91], v[162:165], v[170:173], v[88:91]
	v_mfma_f32_16x16x32_f16 v[84:87], v[154:157], v[178:181], v[84:87]
	v_mfma_f32_16x16x32_f16 v[80:83], v[162:165], v[178:181], v[80:83]
	v_mfma_f32_16x16x32_f16 v[76:79], v[154:157], v[186:189], v[76:79]
	v_mfma_f32_16x16x32_f16 v[72:75], v[162:165], v[186:189], v[72:75]
	v_mfma_f32_16x16x32_f16 v[68:71], v[154:157], v[194:197], v[68:71]
	v_mfma_f32_16x16x32_f16 v[64:67], v[162:165], v[194:197], v[64:67]
	s_barrier
	ds_read_b128 v[166:169], v149 offset:49152
	ds_read_b128 v[170:173], v149 offset:50176
	ds_read_b128 v[174:177], v149 offset:51200
	ds_read_b128 v[178:181], v149 offset:52224
	ds_read_b128 v[182:185], v149 offset:53248
	ds_read_b128 v[186:189], v149 offset:54272
	ds_read_b128 v[190:193], v149 offset:55296
	ds_read_b128 v[194:197], v149 offset:56320
	s_add_u32 s14, s44, 0x80
	s_addc_u32 s15, s45, 0
	s_mov_b32 m0, s80
	s_nop 0
	global_load_lds_dwordx4 v136, s[14:15]
	s_mov_b32 m0, s81
	s_nop 0
	global_load_lds_dwordx4 v138, s[14:15]
	s_add_u32 s14, s44, 0x104080
	s_addc_u32 s15, s45, 0
	s_mov_b32 m0, s84
	s_nop 0
	global_load_lds_dwordx4 v136, s[14:15]
	s_mov_b32 m0, s85
	s_nop 0
	global_load_lds_dwordx4 v138, s[14:15]
	s_mov_b32 m0, s82
	s_nop 0
	global_load_lds_dwordx4 v148, s[40:41]
	s_mov_b32 m0, s83
	s_nop 0
	global_load_lds_dwordx4 v137, s[40:41]
	s_waitcnt vmcnt(8)
	s_waitcnt lgkmcnt(0)
	s_barrier
	s_waitcnt lgkmcnt(7)
	v_mfma_f32_16x16x32_f16 v[60:63], v[128:131], v[166:169], v[60:63]
	v_mfma_f32_16x16x32_f16 v[56:59], v[140:143], v[166:169], v[56:59]
	s_waitcnt lgkmcnt(5)
	v_mfma_f32_16x16x32_f16 v[52:55], v[128:131], v[174:177], v[52:55]
	v_mfma_f32_16x16x32_f16 v[48:51], v[140:143], v[174:177], v[48:51]
	s_waitcnt lgkmcnt(3)
	v_mfma_f32_16x16x32_f16 v[44:47], v[128:131], v[182:185], v[44:47]
	v_mfma_f32_16x16x32_f16 v[40:43], v[140:143], v[182:185], v[40:43]
	s_waitcnt lgkmcnt(1)
	v_mfma_f32_16x16x32_f16 v[36:39], v[128:131], v[190:193], v[36:39]
	v_mfma_f32_16x16x32_f16 v[32:35], v[140:143], v[190:193], v[32:35]
	v_mfma_f32_16x16x32_f16 v[60:63], v[132:135], v[170:173], v[60:63]
	v_mfma_f32_16x16x32_f16 v[56:59], v[144:147], v[170:173], v[56:59]
	v_mfma_f32_16x16x32_f16 v[52:55], v[132:135], v[178:181], v[52:55]
	v_mfma_f32_16x16x32_f16 v[48:51], v[144:147], v[178:181], v[48:51]
	v_mfma_f32_16x16x32_f16 v[44:47], v[132:135], v[186:189], v[44:47]
	v_mfma_f32_16x16x32_f16 v[40:43], v[144:147], v[186:189], v[40:43]
	s_waitcnt lgkmcnt(0)
	v_mfma_f32_16x16x32_f16 v[36:39], v[132:135], v[194:197], v[36:39]
	v_mfma_f32_16x16x32_f16 v[32:35], v[144:147], v[194:197], v[32:35]
	v_mfma_f32_16x16x32_f16 v[28:31], v[150:153], v[166:169], v[28:31]
	v_mfma_f32_16x16x32_f16 v[24:27], v[158:161], v[166:169], v[24:27]
	v_mfma_f32_16x16x32_f16 v[20:23], v[150:153], v[174:177], v[20:23]
	v_mfma_f32_16x16x32_f16 v[16:19], v[158:161], v[174:177], v[16:19]
	v_mfma_f32_16x16x32_f16 v[12:15], v[150:153], v[182:185], v[12:15]
	v_mfma_f32_16x16x32_f16 v[8:11], v[158:161], v[182:185], v[8:11]
	v_mfma_f32_16x16x32_f16 v[4:7], v[150:153], v[190:193], v[4:7]
	v_mfma_f32_16x16x32_f16 v[0:3], v[158:161], v[190:193], v[0:3]
	v_mfma_f32_16x16x32_f16 v[28:31], v[154:157], v[170:173], v[28:31]
	v_mfma_f32_16x16x32_f16 v[24:27], v[162:165], v[170:173], v[24:27]
	v_mfma_f32_16x16x32_f16 v[20:23], v[154:157], v[178:181], v[20:23]
	v_mfma_f32_16x16x32_f16 v[16:19], v[162:165], v[178:181], v[16:19]
	v_mfma_f32_16x16x32_f16 v[12:15], v[154:157], v[186:189], v[12:15]
	v_mfma_f32_16x16x32_f16 v[8:11], v[162:165], v[186:189], v[8:11]
	v_mfma_f32_16x16x32_f16 v[4:7], v[154:157], v[194:197], v[4:7]
	v_mfma_f32_16x16x32_f16 v[0:3], v[162:165], v[194:197], v[0:3]
	s_barrier
	s_add_i32 s5, s5, 2
	s_add_u32 s17, s17, 0x100
	s_addc_u32 s4, s4, 0
	s_cmp_gt_u32 s5, 29
	s_mov_b64 s[14:15], s[38:39]
	s_cbranch_scc0 .LBB0_297
	s_and_b64 vcc, exec, s[28:29]
	s_cbranch_vccz .LBB0_300
	s_barrier

; template <class Prob, class Epi, bool I8 = false, bool ALIGN_EPI = true, bool SP2 = true>
; __device__ __forceinline__ void gemm_phase(LAS unsigned char* lds, int wave, const Prob& P, const Epi& E) {
;     const int tid_ = wave * 64 + mk_lane();
;     const int tid = tid_, wid = __builtin_amdgcn_readfirstlane(tid >> 6), lane = tid & 63, wr = wid >> 2, wc = wid & 3, fr = lane & 15, fq = lane >> 4;
;     const int K = P.K, nt = K / BK;
;     unsigned voffA[2], voffB[2];
; #pragma unroll
;     for (int i = 0; i < 2; ++i) { int R, C; stage_rc(tid * 16 + i * 8192, R, C); const int Rb = (R & ~31) + perm32(R & 31);
;         voffA[i] = P.a_rowoff(R) + (unsigned)C * 2u; voffB[i] = P.b_rowoff(Rb) + (unsigned)C * 2u; }
;     const size_t kstep = (size_t)(BK * 2);
;     const size_t hstepA = P.a_hstep(), hstepB = P.b_hstep();
;     const unsigned ldsw = (unsigned)wid * 1024u;
;     const unsigned ldsb = (unsigned)(size_t)lds + ldsw;
;     const int aoff = lds_byte(wr * 64 + fr, fq * 8), boff = lds_byte(wc * 32 + fr, fq * 8);
;     ...
;     Unit cur, nxt; int ui = 0;
;     if (!P.next(0, cur)) return;
;     Acc acc;
; #pragma unroll
;     for (int a = 0; a < 2; ++a)
; #pragma unroll
;         for (int b = 0; b < 2; ++b)
; #pragma unroll
;             for (int m = 0; m < 4; ++m)
; #pragma unroll
;                 for (int n = 0; n < 2; ++n) acc[a][b][m][n] = (f32x4){0.f, 0.f, 0.f, 0.f};
;     h16x8 At[4][2], B0[2][2], B1[2][2];
;     const char* cA = P.a_tile(cur); const char* cB = P.b_tile(cur);
;     if constexpr (SP2) {
;         PG8_STAGE(PG8_SB(0, 0), cB, voffB); PG8_STAGE(PG8_SB(0, 1), cB + hstepB, voffB); PG8_STAGE(PG8_SA(0, 0), cA, voffA); PG8_STAGE(PG8_SA(0, 1), cA + hstepA, voffA);
;         if (wr == 1) PG8_BAR;
;         PG8_WAIT_V(2); PG8_BAR;
;         PG8_STAGE(PG8_SB(1, 0), cB + kstep, voffB); PG8_STAGE(PG8_SA(1, 0), cA + kstep, voffA); PG8_STAGE(PG8_SB(1, 1), cB + hstepB + kstep, voffB);
;         PG8_WAIT_V(6); PG8_BAR;
;     } else {
;         PG8_STAGE(PG8_SB(0, 0), cB, voffB); PG8_STAGE(PG8_SA(0, 0), cA, voffA); PG8_STAGE(PG8_SB(0, 1), cB + hstepB, voffB); PG8_STAGE(PG8_SA(0, 1), cA + hstepA, voffA);
;         if (wr == 1) PG8_BAR;
;         PG8_WAIT_V(4); PG8_BAR;
;         PG8_STAGE(PG8_SB(1, 0), cB + kstep, voffB); PG8_STAGE(PG8_SA(1, 0), cA + kstep, voffA); PG8_STAGE(PG8_SB(1, 1), cB + hstepB + kstep, voffB);
;         PG8_WAIT_V(6); PG8_BAR;
.LBB0_455:
	v_readlane_b32 s0, v254, 42
	v_readlane_b32 s4, v254, 43
	s_waitcnt lgkmcnt(0)
	s_barrier
	v_mbcnt_lo_u32_b32 v0, -1, 0
	v_mbcnt_hi_u32_b32 v0, -1, v0
	v_readlane_b32 s5, v254, 44
	v_add_u32_e32 v1, s0, v0
	s_and_b64 vcc, exec, s[4:5]
	v_readfirstlane_b32 s0, v1
	s_cbranch_vccz .LBB0_471
	v_ashrrev_i32_e32 v3, 31, v1
	v_lshrrev_b32_e32 v3, 26, v3
	v_lshlrev_b32_e32 v2, 4, v1
	v_add_u32_e32 v3, v1, v3
	v_bfe_i32 v1, v1, 27, 1
	v_lshrrev_b32_e32 v1, 22, v1
	v_add_u32_e32 v1, v2, v1
	v_and_b32_e32 v1, 0xfffffc00, v1
	v_sub_u32_e32 v1, v2, v1
	v_lshrrev_b32_e32 v4, 4, v1
	v_bitop3_b32 v1, v4, v1, 32 bitop3:0x6c
	v_ashrrev_i32_e32 v5, 31, v1
	v_readlane_b32 s1, v253, 52
	v_ashrrev_i32_e32 v3, 6, v3
	v_lshrrev_b32_e32 v5, 26, v5
	s_add_u32 s1, s30, s1
	v_lshlrev_b32_e32 v4, 3, v3
	v_add_u32_e32 v5, v1, v5
	s_addc_u32 s4, s31, 0
	v_and_b32_e32 v4, -16, v4
	v_ashrrev_i32_e32 v6, 6, v5
	v_and_b32_e32 v5, 0xc0, v5
	s_add_u32 s2, s1, 0x9a00000
	v_add_u32_e32 v4, v6, v4
	v_sub_u32_e32 v1, v1, v5
	v_mov_b32_e32 v8, 1
	s_addc_u32 s19, s4, 0
	v_lshlrev_b32_e32 v3, 5, v3
	v_ashrrev_i16_sdwa v1, v8, sext(v1) dst_sel:DWORD dst_unused:UNUSED_PAD src0_sel:DWORD src1_sel:BYTE_0
	v_lshlrev_b32_e32 v5, 1, v4
	v_lshrrev_b32_e32 v7, 2, v4
	v_and_b32_e32 v6, 3, v6
	s_mov_b32 s4, 0xfffe0
	v_and_b32_e32 v3, 32, v3
	v_bfe_i32 v1, v1, 0, 16
	v_and_b32_e32 v5, 24, v5
	v_and_b32_e32 v7, 4, v7
	v_and_or_b32 v6, v4, s4, v6
	v_or3_b32 v5, v6, v7, v5
	v_add_lshl_u32 v1, v3, v1, 1
	v_lshl_add_u32 v142, v4, 12, v1
	v_lshl_add_u32 v143, v5, 12, v1
	v_add_u32_e32 v1, 0x2000, v2
	v_ashrrev_i32_e32 v2, 31, v1
	v_lshrrev_b32_e32 v2, 22, v2
	v_add_u32_e32 v2, v1, v2
	v_ashrrev_i32_e32 v2, 10, v2
	v_mul_i32_i24_e32 v3, 0x400, v2
	v_sub_u32_e32 v1, v1, v3
	v_lshrrev_b32_e32 v3, 4, v1
	v_bitop3_b32 v1, v3, v1, 32 bitop3:0x6c
	v_ashrrev_i32_e32 v4, 31, v1
	v_lshrrev_b32_e32 v4, 26, v4
	v_lshlrev_b32_e32 v3, 3, v2
	v_add_u32_e32 v4, v1, v4
	v_and_b32_e32 v3, -16, v3
	v_ashrrev_i32_e32 v5, 6, v4
	v_add_u32_e32 v3, v5, v3
	v_and_b32_e32 v5, 3, v5
	v_and_b32_e32 v4, 0xc0, v4
	v_and_or_b32 v5, v3, s4, v5
	s_ashr_i32 s4, s0, 6
	v_sub_u32_e32 v1, v1, v4
	s_lshl_b32 s5, s4, 10
	s_ashr_i32 s1, s0, 8
	v_lshlrev_b32_e32 v2, 5, v2
	v_ashrrev_i16_sdwa v1, v8, sext(v1) dst_sel:DWORD dst_unused:UNUSED_PAD src0_sel:DWORD src1_sel:BYTE_0
	v_lshlrev_b32_e32 v4, 1, v3
	v_lshrrev_b32_e32 v6, 2, v3
	s_add_i32 s50, s5, 0
	v_readlane_b32 s6, v252, 32
	v_and_b32_e32 v2, 32, v2
	v_bfe_i32 v1, v1, 0, 16
	v_and_b32_e32 v4, 24, v4
	v_and_b32_e32 v6, 4, v6
	v_readlane_b32 s7, v252, 33
	s_add_u32 s40, s2, s6
	v_or3_b32 v4, v5, v6, v4
	v_add_lshl_u32 v1, v2, v1, 1
	s_addc_u32 s41, s19, s7
	s_add_i32 s51, s50, 0x10000
	s_mov_b32 m0, s51
	s_nop 0
	global_load_lds_dwordx4 v143, s[40:41]
	s_add_i32 s56, s50, 0x12000
	v_lshl_add_u32 v145, v4, 12, v1
	s_mov_b32 m0, s56
	s_nop 0
	global_load_lds_dwordx4 v145, s[40:41]
	s_add_u32 s14, s40, 0x80000
	s_addc_u32 s15, s41, 0
	s_add_i32 s57, s50, 0x14000
	s_mov_b32 m0, s57
	s_nop 0
	global_load_lds_dwordx4 v143, s[14:15]
	s_add_i32 s60, s50, 0x16000
	v_readlane_b32 s6, v252, 38
	s_mov_b32 m0, s60
	s_nop 0
	global_load_lds_dwordx4 v145, s[14:15]
	v_readlane_b32 s7, v252, 39
	s_add_u32 s44, s42, s6
	s_addc_u32 s45, s43, s7
	s_mov_b32 m0, s50
	s_nop 0
	global_load_lds_dwordx4 v142, s[44:45]
	s_add_i32 s61, s50, 0x2000
	v_lshl_add_u32 v144, v3, 12, v1
	s_mov_b32 m0, s61
	s_nop 0
	global_load_lds_dwordx4 v144, s[44:45]
	s_add_u32 s14, s44, 0x80000
	s_addc_u32 s15, s45, 0
	s_add_i32 s62, s50, 0x4000
	s_mov_b32 m0, s62
	s_nop 0
	global_load_lds_dwordx4 v142, s[14:15]
	s_add_i32 s63, s50, 0x6000
	s_mov_b32 m0, s63
	s_nop 0
	global_load_lds_dwordx4 v144, s[14:15]
	s_cmp_eq_u32 s1, 1
	s_cselect_b64 s[14:15], -1, 0
	s_setprio 1
	s_cmp_lg_u32 s1, 1
	s_cbranch_scc1 .LBB0_458
	s_barrier
	s_setprio 0
.LBB0_458:
	v_and_b32_e32 v1, 48, v0
	v_lshlrev_b32_e32 v2, 6, v0
	s_movk_i32 s5, 0x3c0
	v_lshlrev_b32_e32 v0, 2, v0
	s_lshl_b32 s64, s1, 6
	s_lshl_b32 s1, s1, 13
	v_and_or_b32 v1, v2, s5, v1
	v_and_b32_e32 v0, 32, v0
	v_bitop3_b32 v2, v1, s1, v0 bitop3:0xde
	s_lshl_b32 s1, s4, 5
	s_and_b32 s68, s1, 0x60
	s_lshl_b32 s1, s68, 7
	s_add_u32 s4, s40, 0x80
	v_bitop3_b32 v0, s1, v1, v0 bitop3:0xf6
	s_waitcnt vmcnt(2)
	s_barrier
	s_addc_u32 s5, s41, 0
	s_add_i32 s69, s50, 0x18000
	s_mov_b32 m0, s69
	s_nop 0
	global_load_lds_dwordx4 v143, s[4:5]
	s_add_i32 s72, s50, 0x1a000
	s_mov_b32 m0, s72
	s_nop 0
	global_load_lds_dwordx4 v145, s[4:5]
	s_add_u32 s4, s44, 0x80
	s_addc_u32 s5, s45, 0
	s_add_i32 s73, s50, 0x8000
	s_mov_b32 m0, s73
	s_nop 0
	global_load_lds_dwordx4 v142, s[4:5]
	s_add_i32 s74, s50, 0xa000
	s_mov_b32 m0, s74
	s_nop 0
	global_load_lds_dwordx4 v144, s[4:5]
	s_add_u32 s4, s40, 0x80080
	s_addc_u32 s5, s41, 0
	s_add_i32 s75, s50, 0x1c000
	s_mov_b32 m0, s75
	s_nop 0
	global_load_lds_dwordx4 v143, s[4:5]
	s_add_i32 s76, s50, 0x1e000
	s_mov_b32 m0, s76
	s_nop 0
	global_load_lds_dwordx4 v145, s[4:5]
	s_waitcnt vmcnt(6)
	s_add_i32 s77, s50, 0xc000
	s_cmpk_lt_u32 s0, 0x100
	v_readlane_b32 s0, v252, 36
	s_cselect_b64 s[16:17], -1, 0
	s_add_i32 s79, s50, 0xe000
	s_mov_b32 s80, 0
	v_add_u32_e32 v146, 0, v0
	v_add_u32_e32 v147, 0, v2
	v_readlane_b32 s82, v252, 31
	s_mov_b32 s81, s0
	s_barrier
	v_readlane_b32 s1, v252, 37
	s_branch .LBB0_461

; #define PG8_STAGE(bufoff, gbase, voff) do { _Pragma("unroll") for (int _i = 0; _i < 2; ++_i) glds16_s((gbase), (voff)[_i], ldsb + (unsigned)((bufoff) + _i * 8192)); } while (0)
; #define PG8_LDA(dst, b, h) do { _Pragma("unroll") for (int m = 0; m < 4; ++m) _Pragma("unroll") for (int k = 0; k < 2; ++k) dst[m][k] = *(const LAS h16x8*)(lds + PG8_SA(b, h) + aoff + m * 2048 + k * 1024); } while (0)
; #define PG8_LDB(dst, b, h) do { _Pragma("unroll") for (int n = 0; n < 2; ++n) _Pragma("unroll") for (int k = 0; k < 2; ++k) dst[n][k] = *(const LAS h16x8*)(lds + PG8_SB(b, h) + boff + n * 2048 + k * 1024); } while (0)
; #define PG8_MMA(ai, bj, At, Bt) do { __builtin_amdgcn_s_setprio(1); _Pragma("unroll") for (int m = 0; m < 4; ++m) _Pragma("unroll") for (int n = 0; n < 2; ++n) _Pragma("unroll") for (int k = 0; k < 2; ++k) \
;         acc[ai][bj][m][n] = mma_step<I8>(Bt[n][k], At[m][k], acc[ai][bj][m][n]); __builtin_amdgcn_s_setprio(0); } while (0)
; #define PG8_WAIT_V(n) asm volatile("s_waitcnt vmcnt(" #n ")" ::: "memory")
; #define PG8_WAIT_L(n) asm volatile("s_waitcnt lgkmcnt(" #n ")" ::: "memory")
; #define PG8_BAR __builtin_amdgcn_s_barrier()
; #define PG8_SCHED __builtin_amdgcn_sched_barrier(0)
; template <class Prob, class Epi, bool I8 = false, bool ALIGN_EPI = true, bool SP2 = true>
; __device__ __forceinline__ void gemm_phase(LAS unsigned char* lds, int wave, const Prob& P, const Epi& E) {
;     ...
;             PG8_LDB(B0, 0, 0); PG8_LDB(B1, 0, 1); PG8_SCHED; PG8_LDA(At, 0, 0); PG8_STAGE(PG8_SA(1, 1), a1 + hstepA, voffA);
;             PG8_WAIT_V(8); PG8_WAIT_L(0); PG8_BAR; PG8_MMA(0, 0, At, B0); PG8_MMA(0, 1, At, B1); PG8_BAR; PG8_SCHED;
;             PG8_LDA(At, 0, 1); PG8_STAGE(PG8_SB(0, 0), b2, voffB); PG8_STAGE(PG8_SB(0, 1), b2 + hstepB, voffB); PG8_STAGE(PG8_SA(0, 0), a2, voffA);
;             PG8_WAIT_V(8); PG8_WAIT_L(0); PG8_BAR; PG8_MMA(1, 0, At, B0); PG8_MMA(1, 1, At, B1); PG8_BAR; PG8_SCHED;
.Lpeel_464:
	v_add_u32_e32 v140, 0x10000, v146
	ds_read_b128 v[128:131], v140
	ds_read_b128 v[132:135], v140 offset:1024
	ds_read_b128 v[136:139], v140 offset:2048
	ds_read_b128 v[148:151], v140 offset:3072
	v_add_u32_e32 v140, 0x14000, v146
	ds_read_b128 v[152:155], v140
	ds_read_b128 v[156:159], v140 offset:1024
	ds_read_b128 v[160:163], v140 offset:2048
	ds_read_b128 v[164:167], v140 offset:3072
	s_cmp_eq_u32 s1, 28
	s_cselect_b32 s48, s83, s85
	s_cselect_b32 s49, s27, s86
	s_cselect_b32 s46, s84, s87
	s_cselect_b32 s47, s23, s0
	s_add_u32 s44, s48, 0x80
	s_addc_u32 s45, s49, 0
	ds_read_b128 v[168:171], v147
	ds_read_b128 v[172:175], v147 offset:1024
	ds_read_b128 v[176:179], v147 offset:2048
	ds_read_b128 v[180:183], v147 offset:3072
	ds_read_b128 v[184:187], v147 offset:4096
	ds_read_b128 v[188:191], v147 offset:5120
	ds_read_b128 v[192:195], v147 offset:6144
	ds_read_b128 v[196:199], v147 offset:7168
	s_mov_b32 m0, s77
	s_nop 0
	global_load_lds_dwordx4 v142, s[40:41]
	s_mov_b32 m0, s79
	s_nop 0
	global_load_lds_dwordx4 v144, s[40:41]
	s_waitcnt vmcnt(8)
	s_waitcnt lgkmcnt(0)
	s_barrier
	s_waitcnt lgkmcnt(7)
	v_mfma_f32_16x16x32_f16 v[124:127], v[128:131], v[168:171], 0
	v_mfma_f32_16x16x32_f16 v[120:123], v[136:139], v[168:171], 0
	s_waitcnt lgkmcnt(5)
	v_mfma_f32_16x16x32_f16 v[116:119], v[128:131], v[176:179], 0
	v_mfma_f32_16x16x32_f16 v[112:115], v[136:139], v[176:179], 0
	s_waitcnt lgkmcnt(3)
	v_mfma_f32_16x16x32_f16 v[108:111], v[128:131], v[184:187], 0
	v_mfma_f32_16x16x32_f16 v[104:107], v[136:139], v[184:187], 0
	s_waitcnt lgkmcnt(1)
	v_mfma_f32_16x16x32_f16 v[100:103], v[128:131], v[192:195], 0
	v_mfma_f32_16x16x32_f16 v[96:99], v[136:139], v[192:195], 0
	v_mfma_f32_16x16x32_f16 v[124:127], v[132:135], v[172:175], v[124:127]
	v_mfma_f32_16x16x32_f16 v[120:123], v[148:151], v[172:175], v[120:123]
	v_mfma_f32_16x16x32_f16 v[116:119], v[132:135], v[180:183], v[116:119]
	v_mfma_f32_16x16x32_f16 v[112:115], v[148:151], v[180:183], v[112:115]
	v_mfma_f32_16x16x32_f16 v[108:111], v[132:135], v[188:191], v[108:111]
	v_mfma_f32_16x16x32_f16 v[104:107], v[148:151], v[188:191], v[104:107]
	s_waitcnt lgkmcnt(0)
	v_mfma_f32_16x16x32_f16 v[100:103], v[132:135], v[196:199], v[100:103]
	v_mfma_f32_16x16x32_f16 v[96:99], v[148:151], v[196:199], v[96:99]
	v_mfma_f32_16x16x32_f16 v[64:67], v[152:155], v[168:171], 0
	v_mfma_f32_16x16x32_f16 v[56:59], v[160:163], v[168:171], 0
	v_mfma_f32_16x16x32_f16 v[52:55], v[152:155], v[176:179], 0
	v_mfma_f32_16x16x32_f16 v[48:51], v[160:163], v[176:179], 0
	v_mfma_f32_16x16x32_f16 v[44:47], v[152:155], v[184:187], 0
	v_mfma_f32_16x16x32_f16 v[40:43], v[160:163], v[184:187], 0
	v_mfma_f32_16x16x32_f16 v[36:39], v[152:155], v[192:195], 0
	v_mfma_f32_16x16x32_f16 v[32:35], v[160:163], v[192:195], 0
	v_mfma_f32_16x16x32_f16 v[64:67], v[156:159], v[172:175], v[64:67]
	v_mfma_f32_16x16x32_f16 v[56:59], v[164:167], v[172:175], v[56:59]
	v_mfma_f32_16x16x32_f16 v[52:55], v[156:159], v[180:183], v[52:55]
	v_mfma_f32_16x16x32_f16 v[48:51], v[164:167], v[180:183], v[48:51]
	v_mfma_f32_16x16x32_f16 v[44:47], v[156:159], v[188:191], v[44:47]
	v_mfma_f32_16x16x32_f16 v[40:43], v[164:167], v[188:191], v[40:43]
	v_mfma_f32_16x16x32_f16 v[36:39], v[156:159], v[196:199], v[36:39]
	v_mfma_f32_16x16x32_f16 v[32:35], v[164:167], v[196:199], v[32:35]
	s_barrier
	ds_read_b128 v[168:171], v147 offset:16384
	ds_read_b128 v[172:175], v147 offset:17408
	ds_read_b128 v[176:179], v147 offset:18432
	ds_read_b128 v[180:183], v147 offset:19456
	ds_read_b128 v[184:187], v147 offset:20480
	ds_read_b128 v[188:191], v147 offset:21504
	ds_read_b128 v[192:195], v147 offset:22528
	ds_read_b128 v[196:199], v147 offset:23552
	s_mov_b32 m0, s51
	s_nop 0
	global_load_lds_dwordx4 v143, s[46:47]
	s_mov_b32 m0, s56
	s_nop 0
	global_load_lds_dwordx4 v145, s[46:47]
	s_add_u32 s4, s46, 0x80000
	s_addc_u32 s5, s47, 0
	s_mov_b32 m0, s57
	s_nop 0
	global_load_lds_dwordx4 v143, s[4:5]
	s_mov_b32 m0, s60
	s_nop 0
	global_load_lds_dwordx4 v145, s[4:5]
	s_mov_b32 m0, s50
	s_nop 0
	global_load_lds_dwordx4 v142, s[48:49]
	s_mov_b32 m0, s61
	s_nop 0
	global_load_lds_dwordx4 v144, s[48:49]
	s_waitcnt vmcnt(8)
	s_waitcnt lgkmcnt(0)
	s_barrier
	s_waitcnt lgkmcnt(7)
	v_mfma_f32_16x16x32_f16 v[92:95], v[128:131], v[168:171], 0
	v_mfma_f32_16x16x32_f16 v[88:91], v[136:139], v[168:171], 0
	s_waitcnt lgkmcnt(5)
	v_mfma_f32_16x16x32_f16 v[84:87], v[128:131], v[176:179], 0
	v_mfma_f32_16x16x32_f16 v[80:83], v[136:139], v[176:179], 0
	s_waitcnt lgkmcnt(3)
	v_mfma_f32_16x16x32_f16 v[76:79], v[128:131], v[184:187], 0
	v_mfma_f32_16x16x32_f16 v[72:75], v[136:139], v[184:187], 0
	s_waitcnt lgkmcnt(1)
	v_mfma_f32_16x16x32_f16 v[68:71], v[128:131], v[192:195], 0
	v_mfma_f32_16x16x32_f16 v[60:63], v[136:139], v[192:195], 0
	v_mfma_f32_16x16x32_f16 v[92:95], v[132:135], v[172:175], v[92:95]
	v_mfma_f32_16x16x32_f16 v[88:91], v[148:151], v[172:175], v[88:91]
	v_mfma_f32_16x16x32_f16 v[84:87], v[132:135], v[180:183], v[84:87]
	v_mfma_f32_16x16x32_f16 v[80:83], v[148:151], v[180:183], v[80:83]
	v_mfma_f32_16x16x32_f16 v[76:79], v[132:135], v[188:191], v[76:79]
	v_mfma_f32_16x16x32_f16 v[72:75], v[148:151], v[188:191], v[72:75]
	s_waitcnt lgkmcnt(0)
	v_mfma_f32_16x16x32_f16 v[68:71], v[132:135], v[196:199], v[68:71]
	v_mfma_f32_16x16x32_f16 v[60:63], v[148:151], v[196:199], v[60:63]
	v_mfma_f32_16x16x32_f16 v[28:31], v[152:155], v[168:171], 0
	v_mfma_f32_16x16x32_f16 v[24:27], v[160:163], v[168:171], 0
	v_mfma_f32_16x16x32_f16 v[20:23], v[152:155], v[176:179], 0
	v_mfma_f32_16x16x32_f16 v[16:19], v[160:163], v[176:179], 0
	v_mfma_f32_16x16x32_f16 v[12:15], v[152:155], v[184:187], 0
	v_mfma_f32_16x16x32_f16 v[8:11], v[160:163], v[184:187], 0
	v_mfma_f32_16x16x32_f16 v[4:7], v[152:155], v[192:195], 0
	v_mfma_f32_16x16x32_f16 v[0:3], v[160:163], v[192:195], 0
	v_mfma_f32_16x16x32_f16 v[28:31], v[156:159], v[172:175], v[28:31]
	v_mfma_f32_16x16x32_f16 v[24:27], v[164:167], v[172:175], v[24:27]
	v_mfma_f32_16x16x32_f16 v[20:23], v[156:159], v[180:183], v[20:23]
	v_mfma_f32_16x16x32_f16 v[16:19], v[164:167], v[180:183], v[16:19]
	v_mfma_f32_16x16x32_f16 v[12:15], v[156:159], v[188:191], v[12:15]
	v_mfma_f32_16x16x32_f16 v[8:11], v[164:167], v[188:191], v[8:11]
	v_mfma_f32_16x16x32_f16 v[4:7], v[156:159], v[196:199], v[4:7]
	v_mfma_f32_16x16x32_f16 v[0:3], v[164:167], v[196:199], v[0:3]
	s_barrier
; #define PG8_STAGE(bufoff, gbase, voff) do { _Pragma("unroll") for (int _i = 0; _i < 2; ++_i) glds16_s((gbase), (voff)[_i], ldsb + (unsigned)((bufoff) + _i * 8192)); } while (0)
; #define PG8_LDA(dst, b, h) do { _Pragma("unroll") for (int m = 0; m < 4; ++m) _Pragma("unroll") for (int k = 0; k < 2; ++k) dst[m][k] = *(const LAS h16x8*)(lds + PG8_SA(b, h) + aoff + m * 2048 + k * 1024); } while (0)
; #define PG8_LDB(dst, b, h) do { _Pragma("unroll") for (int n = 0; n < 2; ++n) _Pragma("unroll") for (int k = 0; k < 2; ++k) dst[n][k] = *(const LAS h16x8*)(lds + PG8_SB(b, h) + boff + n * 2048 + k * 1024); } while (0)
; #define PG8_MMA(ai, bj, At, Bt) do { __builtin_amdgcn_s_setprio(1); _Pragma("unroll") for (int m = 0; m < 4; ++m) _Pragma("unroll") for (int n = 0; n < 2; ++n) _Pragma("unroll") for (int k = 0; k < 2; ++k) \
;         acc[ai][bj][m][n] = mma_step<I8>(Bt[n][k], At[m][k], acc[ai][bj][m][n]); __builtin_amdgcn_s_setprio(0); } while (0)
; #define PG8_WAIT_V(n) asm volatile("s_waitcnt vmcnt(" #n ")" ::: "memory")
; #define PG8_WAIT_L(n) asm volatile("s_waitcnt lgkmcnt(" #n ")" ::: "memory")
; #define PG8_BAR __builtin_amdgcn_s_barrier()
; #define PG8_SCHED __builtin_amdgcn_sched_barrier(0)
; __device__ __forceinline__ void glds16_s(const void* sbase, unsigned voff, unsigned lds_dst) {
;     unsigned keep;
;     asm volatile("s_mov_b32 %0, m0\n\ts_mov_b32 m0, %3\n\ts_nop 0\n\tglobal_load_lds_dwordx4 %1, %2\n\ts_mov_b32 m0, %0" : "=&s"(keep) : "v"(voff), "s"(sbase), "s"(lds_dst) : "memory");
; }
; template <class Prob, class Epi, bool I8 = false, bool ALIGN_EPI = true, bool SP2 = true>
; __device__ __forceinline__ void gemm_phase(LAS unsigned char* lds, int wave, const Prob& P, const Epi& E) {
;     ...
;             PG8_LDB(B0, 1, 0); PG8_LDB(B1, 1, 1); PG8_SCHED; PG8_LDA(At, 1, 0); PG8_STAGE(PG8_SA(0, 1), a2 + hstepA, voffA);
;             PG8_WAIT_V(8); PG8_WAIT_L(0); PG8_BAR; PG8_MMA(0, 0, At, B0); PG8_MMA(0, 1, At, B1); PG8_BAR; PG8_SCHED;
;             PG8_LDA(At, 1, 1); PG8_STAGE(PG8_SB(1, 0), b3, voffB); PG8_STAGE(PG8_SB(1, 1), b3 + hstepB, voffB); PG8_STAGE(PG8_SA(1, 0), a3, voffA);
;             PG8_WAIT_V(8); PG8_WAIT_L(0); PG8_BAR; PG8_MMA(1, 0, At, B0); PG8_MMA(1, 1, At, B1); PG8_BAR; PG8_SCHED;
	v_add_u32_e32 v140, 0x18000, v146
	ds_read_b128 v[128:131], v140
	ds_read_b128 v[132:135], v140 offset:1024
	ds_read_b128 v[136:139], v140 offset:2048
	ds_read_b128 v[148:151], v140 offset:3072
	v_add_u32_e32 v140, 0x1c000, v146
	ds_read_b128 v[152:155], v140
	ds_read_b128 v[156:159], v140 offset:1024
	ds_read_b128 v[160:163], v140 offset:2048
	ds_read_b128 v[164:167], v140 offset:3072
	ds_read_b128 v[168:171], v147 offset:32768
	ds_read_b128 v[172:175], v147 offset:33792
	ds_read_b128 v[176:179], v147 offset:34816
	ds_read_b128 v[180:183], v147 offset:35840
	ds_read_b128 v[184:187], v147 offset:36864
	ds_read_b128 v[188:191], v147 offset:37888
	ds_read_b128 v[192:195], v147 offset:38912
	ds_read_b128 v[196:199], v147 offset:39936
	s_add_u32 s4, s48, 0x80000
	s_addc_u32 s5, s49, 0
	s_mov_b32 m0, s62
	s_nop 0
	global_load_lds_dwordx4 v142, s[4:5]
	s_mov_b32 m0, s63
	s_nop 0
	global_load_lds_dwordx4 v144, s[4:5]
	s_waitcnt vmcnt(8)
	s_waitcnt lgkmcnt(0)
	s_barrier
	s_waitcnt lgkmcnt(7)
	v_mfma_f32_16x16x32_f16 v[124:127], v[128:131], v[168:171], v[124:127]
	v_mfma_f32_16x16x32_f16 v[120:123], v[136:139], v[168:171], v[120:123]
	s_waitcnt lgkmcnt(5)
	v_mfma_f32_16x16x32_f16 v[116:119], v[128:131], v[176:179], v[116:119]
	v_mfma_f32_16x16x32_f16 v[112:115], v[136:139], v[176:179], v[112:115]
	s_waitcnt lgkmcnt(3)
	v_mfma_f32_16x16x32_f16 v[108:111], v[128:131], v[184:187], v[108:111]
	v_mfma_f32_16x16x32_f16 v[104:107], v[136:139], v[184:187], v[104:107]
	s_waitcnt lgkmcnt(1)
	v_mfma_f32_16x16x32_f16 v[100:103], v[128:131], v[192:195], v[100:103]
	v_mfma_f32_16x16x32_f16 v[96:99], v[136:139], v[192:195], v[96:99]
	v_mfma_f32_16x16x32_f16 v[124:127], v[132:135], v[172:175], v[124:127]
	v_mfma_f32_16x16x32_f16 v[120:123], v[148:151], v[172:175], v[120:123]
	v_mfma_f32_16x16x32_f16 v[116:119], v[132:135], v[180:183], v[116:119]
	v_mfma_f32_16x16x32_f16 v[112:115], v[148:151], v[180:183], v[112:115]
	v_mfma_f32_16x16x32_f16 v[108:111], v[132:135], v[188:191], v[108:111]
	v_mfma_f32_16x16x32_f16 v[104:107], v[148:151], v[188:191], v[104:107]
	s_waitcnt lgkmcnt(0)
	v_mfma_f32_16x16x32_f16 v[100:103], v[132:135], v[196:199], v[100:103]
	v_mfma_f32_16x16x32_f16 v[96:99], v[148:151], v[196:199], v[96:99]
	v_mfma_f32_16x16x32_f16 v[64:67], v[152:155], v[168:171], v[64:67]
	v_mfma_f32_16x16x32_f16 v[56:59], v[160:163], v[168:171], v[56:59]
	v_mfma_f32_16x16x32_f16 v[52:55], v[152:155], v[176:179], v[52:55]
	v_mfma_f32_16x16x32_f16 v[48:51], v[160:163], v[176:179], v[48:51]
	v_mfma_f32_16x16x32_f16 v[44:47], v[152:155], v[184:187], v[44:47]
	v_mfma_f32_16x16x32_f16 v[40:43], v[160:163], v[184:187], v[40:43]
	v_mfma_f32_16x16x32_f16 v[36:39], v[152:155], v[192:195], v[36:39]
	v_mfma_f32_16x16x32_f16 v[32:35], v[160:163], v[192:195], v[32:35]
	v_mfma_f32_16x16x32_f16 v[64:67], v[156:159], v[172:175], v[64:67]
	v_mfma_f32_16x16x32_f16 v[56:59], v[164:167], v[172:175], v[56:59]
	v_mfma_f32_16x16x32_f16 v[52:55], v[156:159], v[180:183], v[52:55]
	v_mfma_f32_16x16x32_f16 v[48:51], v[164:167], v[180:183], v[48:51]
	v_mfma_f32_16x16x32_f16 v[44:47], v[156:159], v[188:191], v[44:47]
	v_mfma_f32_16x16x32_f16 v[40:43], v[164:167], v[188:191], v[40:43]
	v_mfma_f32_16x16x32_f16 v[36:39], v[156:159], v[196:199], v[36:39]
	v_mfma_f32_16x16x32_f16 v[32:35], v[164:167], v[196:199], v[32:35]
	s_barrier
	ds_read_b128 v[168:171], v147 offset:49152
	ds_read_b128 v[172:175], v147 offset:50176
	ds_read_b128 v[176:179], v147 offset:51200
	ds_read_b128 v[180:183], v147 offset:52224
	ds_read_b128 v[184:187], v147 offset:53248
	ds_read_b128 v[188:191], v147 offset:54272
	ds_read_b128 v[192:195], v147 offset:55296
	ds_read_b128 v[196:199], v147 offset:56320
	s_add_u32 s4, s46, 0x80
	s_addc_u32 s5, s47, 0
	s_mov_b32 m0, s69
	s_nop 0
	global_load_lds_dwordx4 v143, s[4:5]
	s_mov_b32 m0, s72
	s_nop 0
	global_load_lds_dwordx4 v145, s[4:5]
	s_add_u32 s4, s46, 0x80080
	s_addc_u32 s5, s47, 0
	s_mov_b32 m0, s75
	s_nop 0
	global_load_lds_dwordx4 v143, s[4:5]
	s_mov_b32 m0, s76
	s_nop 0
	global_load_lds_dwordx4 v145, s[4:5]
	s_mov_b32 m0, s73
	s_nop 0
	global_load_lds_dwordx4 v142, s[44:45]
	s_mov_b32 m0, s74
	s_nop 0
	global_load_lds_dwordx4 v144, s[44:45]
	s_waitcnt vmcnt(8)
	s_waitcnt lgkmcnt(0)
	s_barrier
	s_waitcnt lgkmcnt(7)
	v_mfma_f32_16x16x32_f16 v[92:95], v[128:131], v[168:171], v[92:95]
	v_mfma_f32_16x16x32_f16 v[88:91], v[136:139], v[168:171], v[88:91]
	s_waitcnt lgkmcnt(5)
	v_mfma_f32_16x16x32_f16 v[84:87], v[128:131], v[176:179], v[84:87]
	v_mfma_f32_16x16x32_f16 v[80:83], v[136:139], v[176:179], v[80:83]
	s_waitcnt lgkmcnt(3)
	v_mfma_f32_16x16x32_f16 v[76:79], v[128:131], v[184:187], v[76:79]
	v_mfma_f32_16x16x32_f16 v[72:75], v[136:139], v[184:187], v[72:75]
	s_waitcnt lgkmcnt(1)
	v_mfma_f32_16x16x32_f16 v[68:71], v[128:131], v[192:195], v[68:71]
	v_mfma_f32_16x16x32_f16 v[60:63], v[136:139], v[192:195], v[60:63]
	v_mfma_f32_16x16x32_f16 v[92:95], v[132:135], v[172:175], v[92:95]
	v_mfma_f32_16x16x32_f16 v[88:91], v[148:151], v[172:175], v[88:91]
	v_mfma_f32_16x16x32_f16 v[84:87], v[132:135], v[180:183], v[84:87]
	v_mfma_f32_16x16x32_f16 v[80:83], v[148:151], v[180:183], v[80:83]
	v_mfma_f32_16x16x32_f16 v[76:79], v[132:135], v[188:191], v[76:79]
	v_mfma_f32_16x16x32_f16 v[72:75], v[148:151], v[188:191], v[72:75]
	s_waitcnt lgkmcnt(0)
	v_mfma_f32_16x16x32_f16 v[68:71], v[132:135], v[196:199], v[68:71]
	v_mfma_f32_16x16x32_f16 v[60:63], v[148:151], v[196:199], v[60:63]
	v_mfma_f32_16x16x32_f16 v[28:31], v[152:155], v[168:171], v[28:31]
	v_mfma_f32_16x16x32_f16 v[24:27], v[160:163], v[168:171], v[24:27]
	v_mfma_f32_16x16x32_f16 v[20:23], v[152:155], v[176:179], v[20:23]
	v_mfma_f32_16x16x32_f16 v[16:19], v[160:163], v[176:179], v[16:19]
	v_mfma_f32_16x16x32_f16 v[12:15], v[152:155], v[184:187], v[12:15]
	v_mfma_f32_16x16x32_f16 v[8:11], v[160:163], v[184:187], v[8:11]
	v_mfma_f32_16x16x32_f16 v[4:7], v[152:155], v[192:195], v[4:7]
	v_mfma_f32_16x16x32_f16 v[0:3], v[160:163], v[192:195], v[0:3]
	v_mfma_f32_16x16x32_f16 v[28:31], v[156:159], v[172:175], v[28:31]
	v_mfma_f32_16x16x32_f16 v[24:27], v[164:167], v[172:175], v[24:27]
	v_mfma_f32_16x16x32_f16 v[20:23], v[156:159], v[180:183], v[20:23]
	v_mfma_f32_16x16x32_f16 v[16:19], v[164:167], v[180:183], v[16:19]
	v_mfma_f32_16x16x32_f16 v[12:15], v[156:159], v[188:191], v[12:15]
	v_mfma_f32_16x16x32_f16 v[8:11], v[164:167], v[188:191], v[8:11]
	v_mfma_f32_16x16x32_f16 v[4:7], v[156:159], v[196:199], v[4:7]
	v_mfma_f32_16x16x32_f16 v[0:3], v[164:167], v[196:199], v[0:3]
	s_barrier
	s_add_i32 s1, s1, 2
	s_add_u32 s85, s85, 0x100
	s_addc_u32 s86, s86, 0
	s_add_u32 s87, s87, 0x100
	s_addc_u32 s0, s0, 0
	s_add_u32 s40, s40, 0x100
	s_addc_u32 s41, s41, 0
	s_cmp_gt_u32 s1, 29
; #define PG8_STAGE(bufoff, gbase, voff) do { _Pragma("unroll") for (int _i = 0; _i < 2; ++_i) glds16_s((gbase), (voff)[_i], ldsb + (unsigned)((bufoff) + _i * 8192)); } while (0)
; #define PG8_LDA(dst, b, h) do { _Pragma("unroll") for (int m = 0; m < 4; ++m) _Pragma("unroll") for (int k = 0; k < 2; ++k) dst[m][k] = *(const LAS h16x8*)(lds + PG8_SA(b, h) + aoff + m * 2048 + k * 1024); } while (0)
; #define PG8_LDB(dst, b, h) do { _Pragma("unroll") for (int n = 0; n < 2; ++n) _Pragma("unroll") for (int k = 0; k < 2; ++k) dst[n][k] = *(const LAS h16x8*)(lds + PG8_SB(b, h) + boff + n * 2048 + k * 1024); } while (0)
; #define PG8_WAIT_V(n) asm volatile("s_waitcnt vmcnt(" #n ")" ::: "memory")
; #define PG8_WAIT_L(n) asm volatile("s_waitcnt lgkmcnt(" #n ")" ::: "memory")
; #define PG8_BAR __builtin_amdgcn_s_barrier()
; __device__ __forceinline__ void glds16_s(const void* sbase, unsigned voff, unsigned lds_dst) {
;     unsigned keep;
;     asm volatile("s_mov_b32 %0, m0\n\ts_mov_b32 m0, %3\n\ts_nop 0\n\tglobal_load_lds_dwordx4 %1, %2\n\ts_mov_b32 m0, %0" : "=&s"(keep) : "v"(voff), "s"(sbase), "s"(lds_dst) : "memory");
; }
; template <class Prob, class Epi, bool I8 = false, bool ALIGN_EPI = true, bool SP2 = true>
; __device__ __forceinline__ void gemm_phase(LAS unsigned char* lds, int wave, const Prob& P, const Epi& E) {
;     ...
;         const bool has_next = P.next(ui + 1, nxt);
;         const char* nA = has_next ? P.a_tile(nxt) : cA; const char* nB = has_next ? P.b_tile(nxt) : cB;
;         for (int t = 0; t < nt; t += 2) {
;             const bool last = (t == nt - 2);
;             const char* a1 = cA + (size_t)(t + 1) * kstep;
;             const char* a2 = last ? nA : cA + (size_t)(t + 2) * kstep; const char* b2 = last ? nB : cB + (size_t)(t + 2) * kstep;
;             const char* a3 = a2 + kstep; const char* b3 = b2 + kstep;
;             if constexpr (SP2) {
;             PG8_LDB(B0, 0, 0); PG8_LDB(B1, 0, 1); PG8_SCHED; PG8_LDA(At, 0, 0); PG8_STAGE(PG8_SA(1, 1), a1 + hstepA, voffA);
;             PG8_WAIT_V(8); PG8_WAIT_L(0); PG8_BAR; PG8_MMA(0, 0, At, B0); PG8_MMA(0, 1, At, B1); PG8_BAR; PG8_SCHED;
;             PG8_LDA(At, 0, 1); PG8_STAGE(PG8_SB(0, 0), b2, voffB); PG8_STAGE(PG8_SB(0, 1), b2 + hstepB, voffB); PG8_STAGE(PG8_SA(0, 0), a2, voffA);
;             PG8_WAIT_V(8); PG8_WAIT_L(0); PG8_BAR; PG8_MMA(1, 0, At, B0); PG8_MMA(1, 1, At, B1); PG8_BAR; PG8_SCHED;
.LBB0_464:
	v_add_u32_e32 v140, 0x10000, v146
	ds_read_b128 v[128:131], v140
	ds_read_b128 v[132:135], v140 offset:1024
	ds_read_b128 v[136:139], v140 offset:2048
	ds_read_b128 v[148:151], v140 offset:3072
	v_add_u32_e32 v140, 0x14000, v146
	ds_read_b128 v[152:155], v140
	ds_read_b128 v[156:159], v140 offset:1024
	ds_read_b128 v[160:163], v140 offset:2048
	ds_read_b128 v[164:167], v140 offset:3072
	s_cmp_eq_u32 s1, 28
	s_cselect_b32 s48, s83, s85
	s_cselect_b32 s49, s27, s86
	s_cselect_b32 s46, s84, s87
	s_cselect_b32 s47, s23, s0
	s_add_u32 s44, s48, 0x80
	s_addc_u32 s45, s49, 0
	ds_read_b128 v[168:171], v147
	ds_read_b128 v[172:175], v147 offset:1024
	ds_read_b128 v[176:179], v147 offset:2048
	ds_read_b128 v[180:183], v147 offset:3072
	ds_read_b128 v[184:187], v147 offset:4096
	ds_read_b128 v[188:191], v147 offset:5120
	ds_read_b128 v[192:195], v147 offset:6144
	ds_read_b128 v[196:199], v147 offset:7168
	s_mov_b32 m0, s77
	s_nop 0
	global_load_lds_dwordx4 v142, s[40:41]
	s_mov_b32 m0, s79
	s_nop 0
	global_load_lds_dwordx4 v144, s[40:41]
	s_waitcnt vmcnt(8)
	s_waitcnt lgkmcnt(0)
	s_barrier
	s_waitcnt lgkmcnt(7)
	v_mfma_f32_16x16x32_f16 v[124:127], v[128:131], v[168:171], v[124:127]
	v_mfma_f32_16x16x32_f16 v[120:123], v[136:139], v[168:171], v[120:123]
	s_waitcnt lgkmcnt(5)
	v_mfma_f32_16x16x32_f16 v[116:119], v[128:131], v[176:179], v[116:119]
	v_mfma_f32_16x16x32_f16 v[112:115], v[136:139], v[176:179], v[112:115]
	s_waitcnt lgkmcnt(3)
	v_mfma_f32_16x16x32_f16 v[108:111], v[128:131], v[184:187], v[108:111]
	v_mfma_f32_16x16x32_f16 v[104:107], v[136:139], v[184:187], v[104:107]
	s_waitcnt lgkmcnt(1)
	v_mfma_f32_16x16x32_f16 v[100:103], v[128:131], v[192:195], v[100:103]
	v_mfma_f32_16x16x32_f16 v[96:99], v[136:139], v[192:195], v[96:99]
	v_mfma_f32_16x16x32_f16 v[124:127], v[132:135], v[172:175], v[124:127]
	v_mfma_f32_16x16x32_f16 v[120:123], v[148:151], v[172:175], v[120:123]
	v_mfma_f32_16x16x32_f16 v[116:119], v[132:135], v[180:183], v[116:119]
	v_mfma_f32_16x16x32_f16 v[112:115], v[148:151], v[180:183], v[112:115]
	v_mfma_f32_16x16x32_f16 v[108:111], v[132:135], v[188:191], v[108:111]
	v_mfma_f32_16x16x32_f16 v[104:107], v[148:151], v[188:191], v[104:107]
	s_waitcnt lgkmcnt(0)
	v_mfma_f32_16x16x32_f16 v[100:103], v[132:135], v[196:199], v[100:103]
	v_mfma_f32_16x16x32_f16 v[96:99], v[148:151], v[196:199], v[96:99]
	v_mfma_f32_16x16x32_f16 v[64:67], v[152:155], v[168:171], v[64:67]
	v_mfma_f32_16x16x32_f16 v[56:59], v[160:163], v[168:171], v[56:59]
	v_mfma_f32_16x16x32_f16 v[52:55], v[152:155], v[176:179], v[52:55]
	v_mfma_f32_16x16x32_f16 v[48:51], v[160:163], v[176:179], v[48:51]
	v_mfma_f32_16x16x32_f16 v[44:47], v[152:155], v[184:187], v[44:47]
	v_mfma_f32_16x16x32_f16 v[40:43], v[160:163], v[184:187], v[40:43]
	v_mfma_f32_16x16x32_f16 v[36:39], v[152:155], v[192:195], v[36:39]
	v_mfma_f32_16x16x32_f16 v[32:35], v[160:163], v[192:195], v[32:35]
	v_mfma_f32_16x16x32_f16 v[64:67], v[156:159], v[172:175], v[64:67]
	v_mfma_f32_16x16x32_f16 v[56:59], v[164:167], v[172:175], v[56:59]
	v_mfma_f32_16x16x32_f16 v[52:55], v[156:159], v[180:183], v[52:55]
	v_mfma_f32_16x16x32_f16 v[48:51], v[164:167], v[180:183], v[48:51]
	v_mfma_f32_16x16x32_f16 v[44:47], v[156:159], v[188:191], v[44:47]
	v_mfma_f32_16x16x32_f16 v[40:43], v[164:167], v[188:191], v[40:43]
	v_mfma_f32_16x16x32_f16 v[36:39], v[156:159], v[196:199], v[36:39]
	v_mfma_f32_16x16x32_f16 v[32:35], v[164:167], v[196:199], v[32:35]
	s_barrier
	ds_read_b128 v[168:171], v147 offset:16384
	ds_read_b128 v[172:175], v147 offset:17408
	ds_read_b128 v[176:179], v147 offset:18432
	ds_read_b128 v[180:183], v147 offset:19456
	ds_read_b128 v[184:187], v147 offset:20480
	ds_read_b128 v[188:191], v147 offset:21504
	ds_read_b128 v[192:195], v147 offset:22528
	ds_read_b128 v[196:199], v147 offset:23552
	s_mov_b32 m0, s51
	s_nop 0
	global_load_lds_dwordx4 v143, s[46:47]
	s_mov_b32 m0, s56
	s_nop 0
	global_load_lds_dwordx4 v145, s[46:47]
	s_add_u32 s4, s46, 0x80000
	s_addc_u32 s5, s47, 0
	s_mov_b32 m0, s57
	s_nop 0
	global_load_lds_dwordx4 v143, s[4:5]
	s_mov_b32 m0, s60
	s_nop 0
	global_load_lds_dwordx4 v145, s[4:5]
	s_mov_b32 m0, s50
	s_nop 0
	global_load_lds_dwordx4 v142, s[48:49]
	s_mov_b32 m0, s61
	s_nop 0
	global_load_lds_dwordx4 v144, s[48:49]
	s_waitcnt vmcnt(8)
	s_waitcnt lgkmcnt(0)
	s_barrier
	s_waitcnt lgkmcnt(7)
	v_mfma_f32_16x16x32_f16 v[92:95], v[128:131], v[168:171], v[92:95]
	v_mfma_f32_16x16x32_f16 v[88:91], v[136:139], v[168:171], v[88:91]
	s_waitcnt lgkmcnt(5)
	v_mfma_f32_16x16x32_f16 v[84:87], v[128:131], v[176:179], v[84:87]
	v_mfma_f32_16x16x32_f16 v[80:83], v[136:139], v[176:179], v[80:83]
	s_waitcnt lgkmcnt(3)
	v_mfma_f32_16x16x32_f16 v[76:79], v[128:131], v[184:187], v[76:79]
	v_mfma_f32_16x16x32_f16 v[72:75], v[136:139], v[184:187], v[72:75]
	s_waitcnt lgkmcnt(1)
	v_mfma_f32_16x16x32_f16 v[68:71], v[128:131], v[192:195], v[68:71]
	v_mfma_f32_16x16x32_f16 v[60:63], v[136:139], v[192:195], v[60:63]
	v_mfma_f32_16x16x32_f16 v[92:95], v[132:135], v[172:175], v[92:95]
	v_mfma_f32_16x16x32_f16 v[88:91], v[148:151], v[172:175], v[88:91]
	v_mfma_f32_16x16x32_f16 v[84:87], v[132:135], v[180:183], v[84:87]
	v_mfma_f32_16x16x32_f16 v[80:83], v[148:151], v[180:183], v[80:83]
	v_mfma_f32_16x16x32_f16 v[76:79], v[132:135], v[188:191], v[76:79]
	v_mfma_f32_16x16x32_f16 v[72:75], v[148:151], v[188:191], v[72:75]
	s_waitcnt lgkmcnt(0)
	v_mfma_f32_16x16x32_f16 v[68:71], v[132:135], v[196:199], v[68:71]
	v_mfma_f32_16x16x32_f16 v[60:63], v[148:151], v[196:199], v[60:63]
	v_mfma_f32_16x16x32_f16 v[28:31], v[152:155], v[168:171], v[28:31]
	v_mfma_f32_16x16x32_f16 v[24:27], v[160:163], v[168:171], v[24:27]
	v_mfma_f32_16x16x32_f16 v[20:23], v[152:155], v[176:179], v[20:23]
	v_mfma_f32_16x16x32_f16 v[16:19], v[160:163], v[176:179], v[16:19]
	v_mfma_f32_16x16x32_f16 v[12:15], v[152:155], v[184:187], v[12:15]
	v_mfma_f32_16x16x32_f16 v[8:11], v[160:163], v[184:187], v[8:11]
	v_mfma_f32_16x16x32_f16 v[4:7], v[152:155], v[192:195], v[4:7]
	v_mfma_f32_16x16x32_f16 v[0:3], v[160:163], v[192:195], v[0:3]
	v_mfma_f32_16x16x32_f16 v[28:31], v[156:159], v[172:175], v[28:31]
	v_mfma_f32_16x16x32_f16 v[24:27], v[164:167], v[172:175], v[24:27]
	v_mfma_f32_16x16x32_f16 v[20:23], v[156:159], v[180:183], v[20:23]
	v_mfma_f32_16x16x32_f16 v[16:19], v[164:167], v[180:183], v[16:19]
	v_mfma_f32_16x16x32_f16 v[12:15], v[156:159], v[188:191], v[12:15]
	v_mfma_f32_16x16x32_f16 v[8:11], v[164:167], v[188:191], v[8:11]
	v_mfma_f32_16x16x32_f16 v[4:7], v[156:159], v[196:199], v[4:7]
	v_mfma_f32_16x16x32_f16 v[0:3], v[164:167], v[196:199], v[0:3]
	s_barrier
; #define PG8_STAGE(bufoff, gbase, voff) do { _Pragma("unroll") for (int _i = 0; _i < 2; ++_i) glds16_s((gbase), (voff)[_i], ldsb + (unsigned)((bufoff) + _i * 8192)); } while (0)
; #define PG8_LDA(dst, b, h) do { _Pragma("unroll") for (int m = 0; m < 4; ++m) _Pragma("unroll") for (int k = 0; k < 2; ++k) dst[m][k] = *(const LAS h16x8*)(lds + PG8_SA(b, h) + aoff + m * 2048 + k * 1024); } while (0)
; #define PG8_LDB(dst, b, h) do { _Pragma("unroll") for (int n = 0; n < 2; ++n) _Pragma("unroll") for (int k = 0; k < 2; ++k) dst[n][k] = *(const LAS h16x8*)(lds + PG8_SB(b, h) + boff + n * 2048 + k * 1024); } while (0)
; #define PG8_MMA(ai, bj, At, Bt) do { __builtin_amdgcn_s_setprio(1); _Pragma("unroll") for (int m = 0; m < 4; ++m) _Pragma("unroll") for (int n = 0; n < 2; ++n) _Pragma("unroll") for (int k = 0; k < 2; ++k) \
;         acc[ai][bj][m][n] = mma_step<I8>(Bt[n][k], At[m][k], acc[ai][bj][m][n]); __builtin_amdgcn_s_setprio(0); } while (0)
; #define PG8_WAIT_V(n) asm volatile("s_waitcnt vmcnt(" #n ")" ::: "memory")
; #define PG8_WAIT_L(n) asm volatile("s_waitcnt lgkmcnt(" #n ")" ::: "memory")
; #define PG8_BAR __builtin_amdgcn_s_barrier()
; #define PG8_SCHED __builtin_amdgcn_sched_barrier(0)
; __device__ __forceinline__ void glds16_s(const void* sbase, unsigned voff, unsigned lds_dst) {
;     unsigned keep;
;     asm volatile("s_mov_b32 %0, m0\n\ts_mov_b32 m0, %3\n\ts_nop 0\n\tglobal_load_lds_dwordx4 %1, %2\n\ts_mov_b32 m0, %0" : "=&s"(keep) : "v"(voff), "s"(sbase), "s"(lds_dst) : "memory");
; }
; template <class Prob, class Epi, bool I8 = false, bool ALIGN_EPI = true, bool SP2 = true>
; __device__ __forceinline__ void gemm_phase(LAS unsigned char* lds, int wave, const Prob& P, const Epi& E) {
;     ...
;             PG8_LDB(B0, 1, 0); PG8_LDB(B1, 1, 1); PG8_SCHED; PG8_LDA(At, 1, 0); PG8_STAGE(PG8_SA(0, 1), a2 + hstepA, voffA);
;             PG8_WAIT_V(8); PG8_WAIT_L(0); PG8_BAR; PG8_MMA(0, 0, At, B0); PG8_MMA(0, 1, At, B1); PG8_BAR; PG8_SCHED;
;             PG8_LDA(At, 1, 1); PG8_STAGE(PG8_SB(1, 0), b3, voffB); PG8_STAGE(PG8_SB(1, 1), b3 + hstepB, voffB); PG8_STAGE(PG8_SA(1, 0), a3, voffA);
;             PG8_WAIT_V(8); PG8_WAIT_L(0); PG8_BAR; PG8_MMA(1, 0, At, B0); PG8_MMA(1, 1, At, B1); PG8_BAR; PG8_SCHED;
	v_add_u32_e32 v140, 0x18000, v146
	ds_read_b128 v[128:131], v140
	ds_read_b128 v[132:135], v140 offset:1024
	ds_read_b128 v[136:139], v140 offset:2048
	ds_read_b128 v[148:151], v140 offset:3072
	v_add_u32_e32 v140, 0x1c000, v146
	ds_read_b128 v[152:155], v140
	ds_read_b128 v[156:159], v140 offset:1024
	ds_read_b128 v[160:163], v140 offset:2048
	ds_read_b128 v[164:167], v140 offset:3072
	ds_read_b128 v[168:171], v147 offset:32768
	ds_read_b128 v[172:175], v147 offset:33792
	ds_read_b128 v[176:179], v147 offset:34816
	ds_read_b128 v[180:183], v147 offset:35840
	ds_read_b128 v[184:187], v147 offset:36864
	ds_read_b128 v[188:191], v147 offset:37888
	ds_read_b128 v[192:195], v147 offset:38912
	ds_read_b128 v[196:199], v147 offset:39936
	s_add_u32 s4, s48, 0x80000
	s_addc_u32 s5, s49, 0
	s_mov_b32 m0, s62
	s_nop 0
	global_load_lds_dwordx4 v142, s[4:5]
	s_mov_b32 m0, s63
	s_nop 0
	global_load_lds_dwordx4 v144, s[4:5]
	s_waitcnt vmcnt(8)
	s_waitcnt lgkmcnt(0)
	s_barrier
	s_waitcnt lgkmcnt(7)
	v_mfma_f32_16x16x32_f16 v[124:127], v[128:131], v[168:171], v[124:127]
	v_mfma_f32_16x16x32_f16 v[120:123], v[136:139], v[168:171], v[120:123]
	s_waitcnt lgkmcnt(5)
	v_mfma_f32_16x16x32_f16 v[116:119], v[128:131], v[176:179], v[116:119]
	v_mfma_f32_16x16x32_f16 v[112:115], v[136:139], v[176:179], v[112:115]
	s_waitcnt lgkmcnt(3)
	v_mfma_f32_16x16x32_f16 v[108:111], v[128:131], v[184:187], v[108:111]
	v_mfma_f32_16x16x32_f16 v[104:107], v[136:139], v[184:187], v[104:107]
	s_waitcnt lgkmcnt(1)
	v_mfma_f32_16x16x32_f16 v[100:103], v[128:131], v[192:195], v[100:103]
	v_mfma_f32_16x16x32_f16 v[96:99], v[136:139], v[192:195], v[96:99]
	v_mfma_f32_16x16x32_f16 v[124:127], v[132:135], v[172:175], v[124:127]
	v_mfma_f32_16x16x32_f16 v[120:123], v[148:151], v[172:175], v[120:123]
	v_mfma_f32_16x16x32_f16 v[116:119], v[132:135], v[180:183], v[116:119]
	v_mfma_f32_16x16x32_f16 v[112:115], v[148:151], v[180:183], v[112:115]
	v_mfma_f32_16x16x32_f16 v[108:111], v[132:135], v[188:191], v[108:111]
	v_mfma_f32_16x16x32_f16 v[104:107], v[148:151], v[188:191], v[104:107]
	s_waitcnt lgkmcnt(0)
	v_mfma_f32_16x16x32_f16 v[100:103], v[132:135], v[196:199], v[100:103]
	v_mfma_f32_16x16x32_f16 v[96:99], v[148:151], v[196:199], v[96:99]
	v_mfma_f32_16x16x32_f16 v[64:67], v[152:155], v[168:171], v[64:67]
	v_mfma_f32_16x16x32_f16 v[56:59], v[160:163], v[168:171], v[56:59]
	v_mfma_f32_16x16x32_f16 v[52:55], v[152:155], v[176:179], v[52:55]
	v_mfma_f32_16x16x32_f16 v[48:51], v[160:163], v[176:179], v[48:51]
	v_mfma_f32_16x16x32_f16 v[44:47], v[152:155], v[184:187], v[44:47]
	v_mfma_f32_16x16x32_f16 v[40:43], v[160:163], v[184:187], v[40:43]
	v_mfma_f32_16x16x32_f16 v[36:39], v[152:155], v[192:195], v[36:39]
	v_mfma_f32_16x16x32_f16 v[32:35], v[160:163], v[192:195], v[32:35]
	v_mfma_f32_16x16x32_f16 v[64:67], v[156:159], v[172:175], v[64:67]
	v_mfma_f32_16x16x32_f16 v[56:59], v[164:167], v[172:175], v[56:59]
	v_mfma_f32_16x16x32_f16 v[52:55], v[156:159], v[180:183], v[52:55]
	v_mfma_f32_16x16x32_f16 v[48:51], v[164:167], v[180:183], v[48:51]
	v_mfma_f32_16x16x32_f16 v[44:47], v[156:159], v[188:191], v[44:47]
	v_mfma_f32_16x16x32_f16 v[40:43], v[164:167], v[188:191], v[40:43]
	v_mfma_f32_16x16x32_f16 v[36:39], v[156:159], v[196:199], v[36:39]
	v_mfma_f32_16x16x32_f16 v[32:35], v[164:167], v[196:199], v[32:35]
	s_barrier
	ds_read_b128 v[168:171], v147 offset:49152
	ds_read_b128 v[172:175], v147 offset:50176
	ds_read_b128 v[176:179], v147 offset:51200
	ds_read_b128 v[180:183], v147 offset:52224
	ds_read_b128 v[184:187], v147 offset:53248
	ds_read_b128 v[188:191], v147 offset:54272
	ds_read_b128 v[192:195], v147 offset:55296
	ds_read_b128 v[196:199], v147 offset:56320
	s_add_u32 s4, s46, 0x80
	s_addc_u32 s5, s47, 0
	s_mov_b32 m0, s69
	s_nop 0
	global_load_lds_dwordx4 v143, s[4:5]
	s_mov_b32 m0, s72
	s_nop 0
	global_load_lds_dwordx4 v145, s[4:5]
	s_add_u32 s4, s46, 0x80080
	s_addc_u32 s5, s47, 0
	s_mov_b32 m0, s75
	s_nop 0
	global_load_lds_dwordx4 v143, s[4:5]
	s_mov_b32 m0, s76
	s_nop 0
	global_load_lds_dwordx4 v145, s[4:5]
	s_mov_b32 m0, s73
	s_nop 0
	global_load_lds_dwordx4 v142, s[44:45]
	s_mov_b32 m0, s74
	s_nop 0
	global_load_lds_dwordx4 v144, s[44:45]
	s_waitcnt vmcnt(8)
	s_waitcnt lgkmcnt(0)
	s_barrier
; #define PG8_BAR __builtin_amdgcn_s_barrier()
; template <class Prob, class Epi, bool I8 = false, bool ALIGN_EPI = true, bool SP2 = true>
; __device__ __forceinline__ void gemm_phase(LAS unsigned char* lds, int wave, const Prob& P, const Epi& E) {
;     ...
;             PG8_WAIT_V(8); PG8_WAIT_L(0); PG8_BAR; PG8_MMA(1, 0, At, B0); PG8_MMA(1, 1, At, B1); PG8_BAR; PG8_SCHED;
;             } else {
;             PG8_LDB(B0, 0, 0); PG8_SCHED; PG8_LDA(At, 0, 0); PG8_STAGE(PG8_SA(1, 1), a1 + hstepA, voffA);
;             PG8_WAIT_L(8); PG8_BAR; PG8_WAIT_L(0); PG8_MMA(0, 0, At, B0); PG8_BAR; PG8_SCHED;
;             PG8_LDB(B1, 0, 1); PG8_STAGE(PG8_SB(0, 0), b2, voffB);
;             PG8_BAR; PG8_WAIT_L(0); PG8_MMA(0, 1, At, B1); PG8_BAR;
;             PG8_LDA(At, 0, 1); PG8_STAGE(PG8_SA(0, 0), a2, voffA);
;             PG8_BAR; PG8_WAIT_L(0); PG8_MMA(1, 0, At, B0); PG8_BAR; PG8_SCHED;
;             PG8_STAGE(PG8_SB(0, 1), b2 + hstepB, voffB);
;             PG8_WAIT_V(6); PG8_BAR; PG8_MMA(1, 1, At, B1); PG8_BAR;
;             PG8_LDB(B0, 1, 0); PG8_SCHED; PG8_LDA(At, 1, 0); PG8_STAGE(PG8_SA(0, 1), a2 + hstepA, voffA);
;             PG8_WAIT_L(8); PG8_BAR; PG8_WAIT_L(0); PG8_MMA(0, 0, At, B0); PG8_BAR; PG8_SCHED;
;             PG8_LDB(B1, 1, 1); PG8_STAGE(PG8_SB(1, 0), b3, voffB);
;             PG8_BAR; PG8_WAIT_L(0); PG8_MMA(0, 1, At, B1); PG8_BAR;
;             PG8_LDA(At, 1, 1); PG8_STAGE(PG8_SA(1, 0), a3, voffA);
;             PG8_BAR; PG8_WAIT_L(0); PG8_MMA(1, 0, At, B0); PG8_BAR; PG8_SCHED;
;             PG8_STAGE(PG8_SB(1, 1), b3 + hstepB, voffB);
;             PG8_WAIT_V(6); PG8_BAR; PG8_MMA(1, 1, At, B1); PG8_BAR;
;             }
;         }
;         if constexpr (ALIGN_EPI) { if (wr == 0) PG8_BAR; }
;     __device__ __forceinline__ void operator()(Acc& acc, const Unit& u, int wr, int wc, int fr, int fq, LAS unsigned char* lds, int tid) const {
;     ...
;             for (int ai = 0; ai < 2; ++ai) {
;                 h16x8 xv[4];
;                 f32x2 st[4]; float rs[4];
; #pragma unroll
;                 for (int m = 0; m < 4; ++m) { const unsigned row = u.pm * 256 + ai * 128 + wr * 64 + m * 16 + fr; xv[m] = *(const h16x8*)(X + (size_t)row * D + colt);
;                     if constexpr (LNX) st[m] = *(const f32x2*)((const char*)stats + (row << 3));
;                     if constexpr (I8) rs[m] = *(const float*)((const char*)sa + (row << 2)); }
	s_waitcnt lgkmcnt(7)
	v_mfma_f32_16x16x32_f16 v[92:95], v[128:131], v[168:171], v[92:95]
	v_mfma_f32_16x16x32_f16 v[88:91], v[136:139], v[168:171], v[88:91]
	s_waitcnt lgkmcnt(5)
	v_mfma_f32_16x16x32_f16 v[84:87], v[128:131], v[176:179], v[84:87]
	v_mfma_f32_16x16x32_f16 v[80:83], v[136:139], v[176:179], v[80:83]
	s_waitcnt lgkmcnt(3)
	v_mfma_f32_16x16x32_f16 v[76:79], v[128:131], v[184:187], v[76:79]
	v_mfma_f32_16x16x32_f16 v[72:75], v[136:139], v[184:187], v[72:75]
	s_waitcnt lgkmcnt(1)
	v_mfma_f32_16x16x32_f16 v[68:71], v[128:131], v[192:195], v[68:71]
	v_mfma_f32_16x16x32_f16 v[60:63], v[136:139], v[192:195], v[60:63]
	v_mfma_f32_16x16x32_f16 v[92:95], v[132:135], v[172:175], v[92:95]
	v_mfma_f32_16x16x32_f16 v[88:91], v[148:151], v[172:175], v[88:91]
	v_mfma_f32_16x16x32_f16 v[84:87], v[132:135], v[180:183], v[84:87]
	v_mfma_f32_16x16x32_f16 v[80:83], v[148:151], v[180:183], v[80:83]
	v_mfma_f32_16x16x32_f16 v[76:79], v[132:135], v[188:191], v[76:79]
	v_mfma_f32_16x16x32_f16 v[72:75], v[148:151], v[188:191], v[72:75]
	s_waitcnt lgkmcnt(0)
	v_mfma_f32_16x16x32_f16 v[68:71], v[132:135], v[196:199], v[68:71]
	v_mfma_f32_16x16x32_f16 v[60:63], v[148:151], v[196:199], v[60:63]
	v_mfma_f32_16x16x32_f16 v[28:31], v[152:155], v[168:171], v[28:31]
	v_mfma_f32_16x16x32_f16 v[24:27], v[160:163], v[168:171], v[24:27]
	v_mfma_f32_16x16x32_f16 v[20:23], v[152:155], v[176:179], v[20:23]
	v_mfma_f32_16x16x32_f16 v[16:19], v[160:163], v[176:179], v[16:19]
	v_mfma_f32_16x16x32_f16 v[12:15], v[152:155], v[184:187], v[12:15]
	v_mfma_f32_16x16x32_f16 v[8:11], v[160:163], v[184:187], v[8:11]
	v_mfma_f32_16x16x32_f16 v[4:7], v[152:155], v[192:195], v[4:7]
	v_mfma_f32_16x16x32_f16 v[0:3], v[160:163], v[192:195], v[0:3]
	v_mfma_f32_16x16x32_f16 v[28:31], v[156:159], v[172:175], v[28:31]
	v_mfma_f32_16x16x32_f16 v[24:27], v[164:167], v[172:175], v[24:27]
	v_mfma_f32_16x16x32_f16 v[20:23], v[156:159], v[180:183], v[20:23]
	v_mfma_f32_16x16x32_f16 v[16:19], v[164:167], v[180:183], v[16:19]
	v_mfma_f32_16x16x32_f16 v[12:15], v[156:159], v[188:191], v[12:15]
	v_mfma_f32_16x16x32_f16 v[8:11], v[164:167], v[188:191], v[8:11]
	v_mfma_f32_16x16x32_f16 v[4:7], v[156:159], v[196:199], v[4:7]
	v_mfma_f32_16x16x32_f16 v[0:3], v[164:167], v[196:199], v[0:3]
	s_barrier
	s_add_i32 s1, s1, 2
	s_add_u32 s85, s85, 0x100
	s_addc_u32 s86, s86, 0
	s_add_u32 s87, s87, 0x100
	s_addc_u32 s0, s0, 0
	s_add_u32 s40, s40, 0x100
	s_addc_u32 s41, s41, 0
	s_cmp_gt_u32 s1, 29
	s_cbranch_scc0 .LBB0_464
	v_mbcnt_lo_u32_b32 v128, -1, 0
	v_mbcnt_hi_u32_b32 v128, -1, v128
	s_lshl_b32 s0, s82, 8
	s_lshl_b32 s1, s81, 8
	v_lshrrev_b32_e32 v129, 1, v128
	s_add_i32 s1, s1, s64
	v_and_or_b32 v129, v129, 24, s0
	v_and_or_b32 v130, v128, 15, s1
	v_or_b32_e32 v129, s68, v129
	v_lshlrev_b32_e32 v130, 12, v130
	v_lshl_add_u32 v128, v129, 1, v130
	v_add_u32_e32 v129, 0x10000, v128
	v_add_u32_e32 v130, 0x20000, v128
	v_add_u32_e32 v131, 0x30000, v128
	v_add_u32_e32 v132, 0x80000, v128
	v_add_u32_e32 v133, 0x90000, v128
	v_add_u32_e32 v134, 0xa0000, v128
	v_add_u32_e32 v135, 0xb0000, v128
	global_load_dwordx4 v[148:151], v128, s[54:55]
	global_load_dwordx4 v[152:155], v129, s[54:55]
	global_load_dwordx4 v[156:159], v130, s[54:55]
	global_load_dwordx4 v[160:163], v131, s[54:55]
	global_load_dwordx4 v[164:167], v132, s[54:55]
	global_load_dwordx4 v[168:171], v133, s[54:55]
	global_load_dwordx4 v[172:175], v134, s[54:55]
	global_load_dwordx4 v[176:179], v135, s[54:55]
	global_load_dwordx4 v[180:183], v128, s[54:55] offset:256
	global_load_dwordx4 v[184:187], v129, s[54:55] offset:256
	global_load_dwordx4 v[188:191], v130, s[54:55] offset:256
	global_load_dwordx4 v[192:195], v131, s[54:55] offset:256
	global_load_dwordx4 v[196:199], v132, s[54:55] offset:256
	global_load_dwordx4 v[200:203], v133, s[54:55] offset:256
	global_load_dwordx4 v[204:207], v134, s[54:55] offset:256
	global_load_dwordx4 v[212:215], v135, s[54:55] offset:256
	s_and_b64 vcc, exec, s[16:17]
	s_cbranch_vccz .LBB0_467
	s_barrier

; __device__ __forceinline__ int mk_lane() { int l; asm volatile("v_mbcnt_lo_u32_b32 %0, -1, 0\n\tv_mbcnt_hi_u32_b32 %0, -1, %0" : "=v"(l)); return l; }
; #define PG8_STAGE(bufoff, gbase, voff) do { _Pragma("unroll") for (int _i = 0; _i < 2; ++_i) glds16_s((gbase), (voff)[_i], ldsb + (unsigned)((bufoff) + _i * 8192)); } while (0)
; #define PG8_WAIT_V(n) asm volatile("s_waitcnt vmcnt(" #n ")" ::: "memory")
; template <class Prob, class Epi, bool I8 = false, bool ALIGN_EPI = true, bool SP2 = true>
; __device__ __forceinline__ void gemm_phase(LAS unsigned char* lds, int wave, const Prob& P, const Epi& E) {
;     const int tid_ = wave * 64 + mk_lane();
;     const int tid = tid_, wid = __builtin_amdgcn_readfirstlane(tid >> 6), lane = tid & 63, wr = wid >> 2, wc = wid & 3, fr = lane & 15, fq = lane >> 4;
;     const int K = P.K, nt = K / BK;
;     unsigned voffA[2], voffB[2];
; #pragma unroll
;     for (int i = 0; i < 2; ++i) { int R, C; stage_rc(tid * 16 + i * 8192, R, C); const int Rb = (R & ~31) + perm32(R & 31);
;         voffA[i] = P.a_rowoff(R) + (unsigned)C * 2u; voffB[i] = P.b_rowoff(Rb) + (unsigned)C * 2u; }
;     const size_t kstep = (size_t)(BK * 2);
;     const size_t hstepA = P.a_hstep(), hstepB = P.b_hstep();
;     const unsigned ldsw = (unsigned)wid * 1024u;
;     const unsigned ldsb = (unsigned)(size_t)lds + ldsw;
;     const int aoff = lds_byte(wr * 64 + fr, fq * 8), boff = lds_byte(wc * 32 + fr, fq * 8);
;     ...
;     Unit cur, nxt; int ui = 0;
;     if (!P.next(0, cur)) return;
;     Acc acc;
; #pragma unroll
;     for (int a = 0; a < 2; ++a)
; #pragma unroll
;         for (int b = 0; b < 2; ++b)
; #pragma unroll
;             for (int m = 0; m < 4; ++m)
; #pragma unroll
;                 for (int n = 0; n < 2; ++n) acc[a][b][m][n] = (f32x4){0.f, 0.f, 0.f, 0.f};
;     h16x8 At[4][2], B0[2][2], B1[2][2];
;     const char* cA = P.a_tile(cur); const char* cB = P.b_tile(cur);
;     if constexpr (SP2) {
;         PG8_STAGE(PG8_SB(0, 0), cB, voffB); PG8_STAGE(PG8_SB(0, 1), cB + hstepB, voffB); PG8_STAGE(PG8_SA(0, 0), cA, voffA); PG8_STAGE(PG8_SA(0, 1), cA + hstepA, voffA);
;         if (wr == 1) PG8_BAR;
;         PG8_WAIT_V(2); PG8_BAR;
;         PG8_STAGE(PG8_SB(1, 0), cB + kstep, voffB); PG8_STAGE(PG8_SA(1, 0), cA + kstep, voffA); PG8_STAGE(PG8_SB(1, 1), cB + hstepB + kstep, voffB);
;         PG8_WAIT_V(6); PG8_BAR;
.LBB0_526:
	s_and_b64 vcc, exec, s[14:15]
	s_cbranch_vccz .LBB0_925
	s_add_u32 s76, s30, 0x3f200000
	s_addc_u32 s77, s31, 0
	s_add_u32 s46, s30, 0x100000
	s_addc_u32 s47, s31, 0
	v_readlane_b32 s0, v254, 42
	v_readlane_b32 s4, v252, 1
	s_add_u32 s26, s30, 0x180000
	v_mbcnt_lo_u32_b32 v0, -1, 0
	v_mbcnt_hi_u32_b32 v0, -1, v0
	v_readlane_b32 s5, v252, 2
	v_add_u32_e32 v1, s0, v0
	s_addc_u32 s27, s31, 0
	v_readfirstlane_b32 s0, v1
	s_and_b64 vcc, exec, s[4:5]
	v_writelane_b32 v255, s93, 1
	s_cbranch_vccz .LBB0_607
	v_ashrrev_i32_e32 v3, 31, v1
	v_lshrrev_b32_e32 v3, 26, v3
	v_lshlrev_b32_e32 v2, 4, v1
	v_add_u32_e32 v3, v1, v3
	v_bfe_i32 v1, v1, 27, 1
	v_lshrrev_b32_e32 v1, 22, v1
	v_add_u32_e32 v1, v2, v1
	v_and_b32_e32 v1, 0xfffffc00, v1
	v_sub_u32_e32 v1, v2, v1
	v_lshrrev_b32_e32 v4, 4, v1
	v_bitop3_b32 v1, v4, v1, 32 bitop3:0x6c
	v_ashrrev_i32_e32 v5, 31, v1
	v_readlane_b32 s1, v253, 53
	v_ashrrev_i32_e32 v3, 6, v3
	v_lshrrev_b32_e32 v5, 26, v5
	s_add_u32 s1, s30, s1
	v_lshlrev_b32_e32 v4, 3, v3
	v_add_u32_e32 v5, v1, v5
	s_addc_u32 s2, s31, 0
	v_and_b32_e32 v4, -16, v4
	v_ashrrev_i32_e32 v6, 6, v5
	v_and_b32_e32 v5, 0xc0, v5
	s_add_u32 s19, s1, 0x5a00000
	v_add_u32_e32 v4, v6, v4
	v_sub_u32_e32 v1, v1, v5
	v_mov_b32_e32 v8, 1
	s_addc_u32 s62, s2, 0
	v_lshlrev_b32_e32 v3, 5, v3
	v_ashrrev_i16_sdwa v1, v8, sext(v1) dst_sel:DWORD dst_unused:UNUSED_PAD src0_sel:DWORD src1_sel:BYTE_0
	v_lshlrev_b32_e32 v5, 1, v4
	v_lshrrev_b32_e32 v7, 2, v4
	v_and_b32_e32 v6, 3, v6
	s_mov_b32 s2, 0xfffe0
	v_and_b32_e32 v3, 32, v3
	v_bfe_i32 v1, v1, 0, 16
	v_and_b32_e32 v5, 24, v5
	v_and_b32_e32 v7, 4, v7
	v_and_or_b32 v6, v4, s2, v6
	v_or3_b32 v5, v6, v7, v5
	v_add_lshl_u32 v1, v3, v1, 1
	v_lshl_add_u32 v132, v4, 12, v1
	v_lshl_add_u32 v133, v5, 12, v1
	v_add_u32_e32 v1, 0x2000, v2
	v_ashrrev_i32_e32 v2, 31, v1
	v_lshrrev_b32_e32 v2, 22, v2
	v_add_u32_e32 v2, v1, v2
	v_ashrrev_i32_e32 v2, 10, v2
	v_mul_i32_i24_e32 v3, 0x400, v2
	v_sub_u32_e32 v1, v1, v3
	v_lshrrev_b32_e32 v3, 4, v1
	v_bitop3_b32 v1, v3, v1, 32 bitop3:0x6c
	v_ashrrev_i32_e32 v4, 31, v1
	v_lshrrev_b32_e32 v4, 26, v4
	v_lshlrev_b32_e32 v3, 3, v2
	v_add_u32_e32 v4, v1, v4
	s_ashr_i32 s1, s0, 6
	v_and_b32_e32 v3, -16, v3
	v_ashrrev_i32_e32 v5, 6, v4
	v_and_b32_e32 v4, 0xc0, v4
	v_add_u32_e32 v3, v5, v3
	v_sub_u32_e32 v1, v1, v4
	v_and_b32_e32 v5, 3, v5
	s_lshl_b32 s63, s1, 10
	v_lshlrev_b32_e32 v2, 5, v2
	v_ashrrev_i16_sdwa v1, v8, sext(v1) dst_sel:DWORD dst_unused:UNUSED_PAD src0_sel:DWORD src1_sel:BYTE_0
	v_lshlrev_b32_e32 v4, 1, v3
	v_lshrrev_b32_e32 v6, 2, v3
	v_and_or_b32 v5, v3, s2, v5
	s_ashr_i32 s2, s0, 8
	s_add_i32 s63, s63, 0
	v_readlane_b32 s4, v252, 46
	v_and_b32_e32 v2, 32, v2
	v_bfe_i32 v1, v1, 0, 16
	v_and_b32_e32 v4, 24, v4
	v_and_b32_e32 v6, 4, v6
	v_readlane_b32 s5, v252, 47
	s_add_u32 s38, s19, s4
	v_or3_b32 v4, v5, v6, v4
	v_add_lshl_u32 v1, v2, v1, 1
	s_addc_u32 s39, s62, s5
	s_add_i32 s64, s63, 0x10000
	s_mov_b32 m0, s64
	s_nop 0
	global_load_lds_dwordx4 v133, s[38:39]
	v_lshl_add_u32 v135, v4, 12, v1
	s_add_i32 s68, s63, 0x12000
	s_mov_b32 m0, s68
	s_nop 0
	global_load_lds_dwordx4 v135, s[38:39]
	s_add_u32 s4, s38, 0x80000
	s_addc_u32 s5, s39, 0
	s_add_i32 s69, s63, 0x14000
	s_mov_b32 m0, s69
	s_nop 0
	global_load_lds_dwordx4 v133, s[4:5]
	s_add_i32 s79, s63, 0x16000
	s_mov_b32 m0, s79
	s_nop 0
	global_load_lds_dwordx4 v135, s[4:5]
	v_readlane_b32 s4, v252, 52
	v_readlane_b32 s5, v252, 53
	s_add_u32 s40, s54, s4
	s_addc_u32 s41, s55, s5
	s_mov_b32 m0, s63
	s_nop 0
	global_load_lds_dwordx4 v132, s[40:41]
	v_lshl_add_u32 v134, v3, 12, v1
	s_add_i32 s80, s63, 0x2000
	s_mov_b32 m0, s80
	s_nop 0
	global_load_lds_dwordx4 v134, s[40:41]
	s_add_u32 s4, s40, 0x80000
	s_addc_u32 s5, s41, 0
	s_add_i32 s81, s63, 0x4000
	s_mov_b32 m0, s81
	s_nop 0
	global_load_lds_dwordx4 v132, s[4:5]
	s_add_i32 s82, s63, 0x6000
	s_mov_b32 m0, s82
	s_nop 0
	global_load_lds_dwordx4 v134, s[4:5]
	s_cmp_eq_u32 s2, 1
	s_cselect_b64 s[16:17], -1, 0
	s_setprio 1
	s_cmp_lg_u32 s2, 1
	s_cbranch_scc1 .LBB0_530
	s_barrier
	s_setprio 0
.LBB0_530:
	s_add_u32 s22, s30, 0x2d200000
	v_and_b32_e32 v1, 48, v0
	v_lshlrev_b32_e32 v2, 6, v0
	s_movk_i32 s5, 0x3c0
	v_lshlrev_b32_e32 v0, 2, v0
	s_addc_u32 s23, s31, 0
	s_and_b32 s4, s1, 3
	s_lshl_b32 s83, s2, 6
	s_lshl_b32 s2, s2, 13
	v_and_or_b32 v1, v2, s5, v1
	v_and_b32_e32 v0, 32, v0
	v_bitop3_b32 v2, v1, s2, v0 bitop3:0xde
	s_lshl_b32 s84, s4, 5
	s_lshl_b32 s2, s4, 12
	s_add_u32 s4, s38, 0x80
	v_bitop3_b32 v0, v1, s2, v0 bitop3:0xde
	s_waitcnt vmcnt(2)
	s_barrier
	s_addc_u32 s5, s39, 0
	s_add_i32 s85, s63, 0x18000
	s_mov_b32 m0, s85
	s_nop 0
	global_load_lds_dwordx4 v133, s[4:5]
	s_add_i32 s86, s63, 0x1a000
	s_mov_b32 m0, s86
	s_nop 0
	global_load_lds_dwordx4 v135, s[4:5]
	s_add_u32 s4, s40, 0x80
	s_addc_u32 s5, s41, 0
	s_add_i32 s87, s63, 0x8000
	s_mov_b32 m0, s87
	s_nop 0
	global_load_lds_dwordx4 v132, s[4:5]
	s_add_i32 s88, s63, 0xa000
	s_mov_b32 m0, s88
	s_nop 0
	global_load_lds_dwordx4 v134, s[4:5]
	s_add_u32 s4, s38, 0x80080
	s_addc_u32 s5, s39, 0
	s_add_i32 s89, s63, 0x1c000
	s_add_i32 s90, s63, 0x1e000
	s_add_i32 s91, s63, 0xc000
	s_mov_b32 m0, s89
	s_nop 0
	global_load_lds_dwordx4 v133, s[4:5]
	s_cmpk_lt_u32 s0, 0x100
	s_mov_b32 m0, s90
	s_nop 0
	global_load_lds_dwordx4 v135, s[4:5]
	s_cselect_b64 s[28:29], -1, 0
	s_lshl_b32 s0, s1, 6
	s_waitcnt vmcnt(6)
	s_and_b32 s0, s0, 0x80
	s_or_b32 s93, s0, 0xfffff400
	v_readlane_b32 s0, v252, 50
	s_and_b32 s92, s84, 32
	s_add_i32 s94, s63, 0xe000
	s_mov_b32 s95, 0
	v_add_u32_e32 v136, 0, v0
	v_add_u32_e32 v137, 0, v2
	v_readlane_b32 s2, v252, 34
	s_mov_b32 s56, s0
	s_barrier
	v_readlane_b32 s1, v252, 51
	s_branch .LBB0_533

; #define PG8_STAGE(bufoff, gbase, voff) do { _Pragma("unroll") for (int _i = 0; _i < 2; ++_i) glds16_s((gbase), (voff)[_i], ldsb + (unsigned)((bufoff) + _i * 8192)); } while (0)
; #define PG8_LDA(dst, b, h) do { _Pragma("unroll") for (int m = 0; m < 4; ++m) _Pragma("unroll") for (int k = 0; k < 2; ++k) dst[m][k] = *(const LAS h16x8*)(lds + PG8_SA(b, h) + aoff + m * 2048 + k * 1024); } while (0)
; #define PG8_LDB(dst, b, h) do { _Pragma("unroll") for (int n = 0; n < 2; ++n) _Pragma("unroll") for (int k = 0; k < 2; ++k) dst[n][k] = *(const LAS h16x8*)(lds + PG8_SB(b, h) + boff + n * 2048 + k * 1024); } while (0)
; #define PG8_MMA(ai, bj, At, Bt) do { __builtin_amdgcn_s_setprio(1); _Pragma("unroll") for (int m = 0; m < 4; ++m) _Pragma("unroll") for (int n = 0; n < 2; ++n) _Pragma("unroll") for (int k = 0; k < 2; ++k) \
;         acc[ai][bj][m][n] = mma_step<I8>(Bt[n][k], At[m][k], acc[ai][bj][m][n]); __builtin_amdgcn_s_setprio(0); } while (0)
; #define PG8_WAIT_V(n) asm volatile("s_waitcnt vmcnt(" #n ")" ::: "memory")
; #define PG8_WAIT_L(n) asm volatile("s_waitcnt lgkmcnt(" #n ")" ::: "memory")
; #define PG8_BAR __builtin_amdgcn_s_barrier()
; #define PG8_SCHED __builtin_amdgcn_sched_barrier(0)
; __device__ __forceinline__ void glds16_s(const void* sbase, unsigned voff, unsigned lds_dst) {
;     unsigned keep;
;     asm volatile("s_mov_b32 %0, m0\n\ts_mov_b32 m0, %3\n\ts_nop 0\n\tglobal_load_lds_dwordx4 %1, %2\n\ts_mov_b32 m0, %0" : "=&s"(keep) : "v"(voff), "s"(sbase), "s"(lds_dst) : "memory");
; }
; template <class Prob, class Epi, bool I8 = false, bool ALIGN_EPI = true, bool SP2 = true>
; __device__ __forceinline__ void gemm_phase(LAS unsigned char* lds, int wave, const Prob& P, const Epi& E) {
;     ...
;             PG8_LDB(B0, 0, 0); PG8_LDB(B1, 0, 1); PG8_SCHED; PG8_LDA(At, 0, 0); PG8_STAGE(PG8_SA(1, 1), a1 + hstepA, voffA);
;             PG8_WAIT_V(8); PG8_WAIT_L(0); PG8_BAR; PG8_MMA(0, 0, At, B0); PG8_MMA(0, 1, At, B1); PG8_BAR; PG8_SCHED;
;             PG8_LDA(At, 0, 1); PG8_STAGE(PG8_SB(0, 0), b2, voffB); PG8_STAGE(PG8_SB(0, 1), b2 + hstepB, voffB); PG8_STAGE(PG8_SA(0, 0), a2, voffA);
;             PG8_WAIT_V(8); PG8_WAIT_L(0); PG8_BAR; PG8_MMA(1, 0, At, B0); PG8_MMA(1, 1, At, B1); PG8_BAR; PG8_SCHED;
.Lpeel_536:
	v_add_u32_e32 v146, 0x10000, v136
	v_add_u32_e32 v162, 0x14000, v136
	ds_read_b128 v[128:131], v146
	ds_read_b128 v[138:141], v146 offset:1024
	ds_read_b128 v[142:145], v146 offset:2048
	ds_read_b128 v[146:149], v146 offset:3072
	ds_read_b128 v[150:153], v162
	ds_read_b128 v[154:157], v162 offset:1024
	ds_read_b128 v[158:161], v162 offset:2048
	ds_read_b128 v[162:165], v162 offset:3072
	s_cmp_eq_u32 s1, 28
	s_cselect_b32 s44, s57, s73
	s_cselect_b32 s45, s51, s74
	s_cselect_b32 s42, s72, s75
	s_cselect_b32 s43, s49, s0
	s_add_u32 s40, s44, 0x80
	s_addc_u32 s41, s45, 0
	ds_read_b128 v[166:169], v137
	ds_read_b128 v[170:173], v137 offset:1024
	ds_read_b128 v[174:177], v137 offset:2048
	ds_read_b128 v[178:181], v137 offset:3072
	ds_read_b128 v[182:185], v137 offset:4096
	ds_read_b128 v[186:189], v137 offset:5120
	ds_read_b128 v[190:193], v137 offset:6144
	ds_read_b128 v[194:197], v137 offset:7168
	s_mov_b32 m0, s91
	s_nop 0
	global_load_lds_dwordx4 v132, s[38:39]
	s_mov_b32 m0, s94
	s_nop 0
	global_load_lds_dwordx4 v134, s[38:39]
	s_waitcnt vmcnt(8)
	s_waitcnt lgkmcnt(0)
	s_barrier
	s_waitcnt lgkmcnt(7)
	v_mfma_f32_16x16x32_f16 v[124:127], v[128:131], v[166:169], 0
	v_mfma_f32_16x16x32_f16 v[120:123], v[142:145], v[166:169], 0
	s_waitcnt lgkmcnt(5)
	v_mfma_f32_16x16x32_f16 v[108:111], v[128:131], v[174:177], 0
	v_mfma_f32_16x16x32_f16 v[104:107], v[142:145], v[174:177], 0
	s_waitcnt lgkmcnt(3)
	v_mfma_f32_16x16x32_f16 v[92:95], v[128:131], v[182:185], 0
	v_mfma_f32_16x16x32_f16 v[88:91], v[142:145], v[182:185], 0
	s_waitcnt lgkmcnt(1)
	v_mfma_f32_16x16x32_f16 v[76:79], v[128:131], v[190:193], 0
	v_mfma_f32_16x16x32_f16 v[72:75], v[142:145], v[190:193], 0
	v_mfma_f32_16x16x32_f16 v[124:127], v[138:141], v[170:173], v[124:127]
	v_mfma_f32_16x16x32_f16 v[120:123], v[146:149], v[170:173], v[120:123]
	v_mfma_f32_16x16x32_f16 v[108:111], v[138:141], v[178:181], v[108:111]
	v_mfma_f32_16x16x32_f16 v[104:107], v[146:149], v[178:181], v[104:107]
	v_mfma_f32_16x16x32_f16 v[92:95], v[138:141], v[186:189], v[92:95]
	v_mfma_f32_16x16x32_f16 v[88:91], v[146:149], v[186:189], v[88:91]
	s_waitcnt lgkmcnt(0)
	v_mfma_f32_16x16x32_f16 v[76:79], v[138:141], v[194:197], v[76:79]
	v_mfma_f32_16x16x32_f16 v[72:75], v[146:149], v[194:197], v[72:75]
	v_mfma_f32_16x16x32_f16 v[116:119], v[150:153], v[166:169], 0
	v_mfma_f32_16x16x32_f16 v[112:115], v[158:161], v[166:169], 0
	v_mfma_f32_16x16x32_f16 v[100:103], v[150:153], v[174:177], 0
	v_mfma_f32_16x16x32_f16 v[96:99], v[158:161], v[174:177], 0
	v_mfma_f32_16x16x32_f16 v[84:87], v[150:153], v[182:185], 0
	v_mfma_f32_16x16x32_f16 v[80:83], v[158:161], v[182:185], 0
	v_mfma_f32_16x16x32_f16 v[68:71], v[150:153], v[190:193], 0
	v_mfma_f32_16x16x32_f16 v[64:67], v[158:161], v[190:193], 0
	v_mfma_f32_16x16x32_f16 v[116:119], v[154:157], v[170:173], v[116:119]
	v_mfma_f32_16x16x32_f16 v[112:115], v[162:165], v[170:173], v[112:115]
	v_mfma_f32_16x16x32_f16 v[100:103], v[154:157], v[178:181], v[100:103]
	v_mfma_f32_16x16x32_f16 v[96:99], v[162:165], v[178:181], v[96:99]
	v_mfma_f32_16x16x32_f16 v[84:87], v[154:157], v[186:189], v[84:87]
	v_mfma_f32_16x16x32_f16 v[80:83], v[162:165], v[186:189], v[80:83]
	v_mfma_f32_16x16x32_f16 v[68:71], v[154:157], v[194:197], v[68:71]
	v_mfma_f32_16x16x32_f16 v[64:67], v[162:165], v[194:197], v[64:67]
	s_barrier
	ds_read_b128 v[166:169], v137 offset:16384
	ds_read_b128 v[170:173], v137 offset:17408
	ds_read_b128 v[174:177], v137 offset:18432
	ds_read_b128 v[178:181], v137 offset:19456
	ds_read_b128 v[182:185], v137 offset:20480
	ds_read_b128 v[186:189], v137 offset:21504
	ds_read_b128 v[190:193], v137 offset:22528
	ds_read_b128 v[194:197], v137 offset:23552
	s_mov_b32 m0, s64
	s_nop 0
	global_load_lds_dwordx4 v133, s[42:43]
	s_mov_b32 m0, s68
	s_nop 0
	global_load_lds_dwordx4 v135, s[42:43]
	s_add_u32 s4, s42, 0x80000
	s_addc_u32 s5, s43, 0
	s_mov_b32 m0, s69
	s_nop 0
	global_load_lds_dwordx4 v133, s[4:5]
	s_mov_b32 m0, s79
	s_nop 0
	global_load_lds_dwordx4 v135, s[4:5]
	s_mov_b32 m0, s63
	s_nop 0
	global_load_lds_dwordx4 v132, s[44:45]
	s_mov_b32 m0, s80
	s_nop 0
	global_load_lds_dwordx4 v134, s[44:45]
	s_waitcnt vmcnt(8)
	s_waitcnt lgkmcnt(0)
	s_barrier
	s_waitcnt lgkmcnt(7)
	v_mfma_f32_16x16x32_f16 v[60:63], v[128:131], v[166:169], 0
	v_mfma_f32_16x16x32_f16 v[56:59], v[142:145], v[166:169], 0
	s_waitcnt lgkmcnt(5)
	v_mfma_f32_16x16x32_f16 v[44:47], v[128:131], v[174:177], 0
	v_mfma_f32_16x16x32_f16 v[40:43], v[142:145], v[174:177], 0
	s_waitcnt lgkmcnt(3)
	v_mfma_f32_16x16x32_f16 v[28:31], v[128:131], v[182:185], 0
	v_mfma_f32_16x16x32_f16 v[24:27], v[142:145], v[182:185], 0
	s_waitcnt lgkmcnt(1)
	v_mfma_f32_16x16x32_f16 v[12:15], v[128:131], v[190:193], 0
	v_mfma_f32_16x16x32_f16 v[8:11], v[142:145], v[190:193], 0
	v_mfma_f32_16x16x32_f16 v[60:63], v[138:141], v[170:173], v[60:63]
	v_mfma_f32_16x16x32_f16 v[56:59], v[146:149], v[170:173], v[56:59]
	v_mfma_f32_16x16x32_f16 v[44:47], v[138:141], v[178:181], v[44:47]
	v_mfma_f32_16x16x32_f16 v[40:43], v[146:149], v[178:181], v[40:43]
	v_mfma_f32_16x16x32_f16 v[28:31], v[138:141], v[186:189], v[28:31]
	v_mfma_f32_16x16x32_f16 v[24:27], v[146:149], v[186:189], v[24:27]
	s_waitcnt lgkmcnt(0)
	v_mfma_f32_16x16x32_f16 v[12:15], v[138:141], v[194:197], v[12:15]
	v_mfma_f32_16x16x32_f16 v[8:11], v[146:149], v[194:197], v[8:11]
	v_mfma_f32_16x16x32_f16 v[52:55], v[150:153], v[166:169], 0
	v_mfma_f32_16x16x32_f16 v[48:51], v[158:161], v[166:169], 0
	v_mfma_f32_16x16x32_f16 v[36:39], v[150:153], v[174:177], 0
	v_mfma_f32_16x16x32_f16 v[32:35], v[158:161], v[174:177], 0
	v_mfma_f32_16x16x32_f16 v[20:23], v[150:153], v[182:185], 0
	v_mfma_f32_16x16x32_f16 v[16:19], v[158:161], v[182:185], 0
	v_mfma_f32_16x16x32_f16 v[4:7], v[150:153], v[190:193], 0
	v_mfma_f32_16x16x32_f16 v[0:3], v[158:161], v[190:193], 0
	v_mfma_f32_16x16x32_f16 v[52:55], v[154:157], v[170:173], v[52:55]
	v_mfma_f32_16x16x32_f16 v[48:51], v[162:165], v[170:173], v[48:51]
	v_mfma_f32_16x16x32_f16 v[36:39], v[154:157], v[178:181], v[36:39]
	v_mfma_f32_16x16x32_f16 v[32:35], v[162:165], v[178:181], v[32:35]
	v_mfma_f32_16x16x32_f16 v[20:23], v[154:157], v[186:189], v[20:23]
	v_mfma_f32_16x16x32_f16 v[16:19], v[162:165], v[186:189], v[16:19]
	v_mfma_f32_16x16x32_f16 v[4:7], v[154:157], v[194:197], v[4:7]
	v_mfma_f32_16x16x32_f16 v[0:3], v[162:165], v[194:197], v[0:3]
	s_barrier
; #define PG8_STAGE(bufoff, gbase, voff) do { _Pragma("unroll") for (int _i = 0; _i < 2; ++_i) glds16_s((gbase), (voff)[_i], ldsb + (unsigned)((bufoff) + _i * 8192)); } while (0)
; #define PG8_LDA(dst, b, h) do { _Pragma("unroll") for (int m = 0; m < 4; ++m) _Pragma("unroll") for (int k = 0; k < 2; ++k) dst[m][k] = *(const LAS h16x8*)(lds + PG8_SA(b, h) + aoff + m * 2048 + k * 1024); } while (0)
; #define PG8_LDB(dst, b, h) do { _Pragma("unroll") for (int n = 0; n < 2; ++n) _Pragma("unroll") for (int k = 0; k < 2; ++k) dst[n][k] = *(const LAS h16x8*)(lds + PG8_SB(b, h) + boff + n * 2048 + k * 1024); } while (0)
; #define PG8_MMA(ai, bj, At, Bt) do { __builtin_amdgcn_s_setprio(1); _Pragma("unroll") for (int m = 0; m < 4; ++m) _Pragma("unroll") for (int n = 0; n < 2; ++n) _Pragma("unroll") for (int k = 0; k < 2; ++k) \
;         acc[ai][bj][m][n] = mma_step<I8>(Bt[n][k], At[m][k], acc[ai][bj][m][n]); __builtin_amdgcn_s_setprio(0); } while (0)
; #define PG8_WAIT_V(n) asm volatile("s_waitcnt vmcnt(" #n ")" ::: "memory")
; #define PG8_WAIT_L(n) asm volatile("s_waitcnt lgkmcnt(" #n ")" ::: "memory")
; #define PG8_BAR __builtin_amdgcn_s_barrier()
; #define PG8_SCHED __builtin_amdgcn_sched_barrier(0)
; __device__ __forceinline__ void glds16_s(const void* sbase, unsigned voff, unsigned lds_dst) {
;     unsigned keep;
;     asm volatile("s_mov_b32 %0, m0\n\ts_mov_b32 m0, %3\n\ts_nop 0\n\tglobal_load_lds_dwordx4 %1, %2\n\ts_mov_b32 m0, %0" : "=&s"(keep) : "v"(voff), "s"(sbase), "s"(lds_dst) : "memory");
; }
; template <class Prob, class Epi, bool I8 = false, bool ALIGN_EPI = true, bool SP2 = true>
; __device__ __forceinline__ void gemm_phase(LAS unsigned char* lds, int wave, const Prob& P, const Epi& E) {
;     ...
;             PG8_LDB(B0, 1, 0); PG8_LDB(B1, 1, 1); PG8_SCHED; PG8_LDA(At, 1, 0); PG8_STAGE(PG8_SA(0, 1), a2 + hstepA, voffA);
;             PG8_WAIT_V(8); PG8_WAIT_L(0); PG8_BAR; PG8_MMA(0, 0, At, B0); PG8_MMA(0, 1, At, B1); PG8_BAR; PG8_SCHED;
;             PG8_LDA(At, 1, 1); PG8_STAGE(PG8_SB(1, 0), b3, voffB); PG8_STAGE(PG8_SB(1, 1), b3 + hstepB, voffB); PG8_STAGE(PG8_SA(1, 0), a3, voffA);
;             PG8_WAIT_V(8); PG8_WAIT_L(0); PG8_BAR; PG8_MMA(1, 0, At, B0); PG8_MMA(1, 1, At, B1); PG8_BAR; PG8_SCHED;
	v_add_u32_e32 v146, 0x18000, v136
	v_add_u32_e32 v162, 0x1c000, v136
	ds_read_b128 v[128:131], v146
	ds_read_b128 v[138:141], v146 offset:1024
	ds_read_b128 v[142:145], v146 offset:2048
	ds_read_b128 v[146:149], v146 offset:3072
	ds_read_b128 v[150:153], v162
	ds_read_b128 v[154:157], v162 offset:1024
	ds_read_b128 v[158:161], v162 offset:2048
	ds_read_b128 v[162:165], v162 offset:3072
	ds_read_b128 v[166:169], v137 offset:32768
	ds_read_b128 v[170:173], v137 offset:33792
	ds_read_b128 v[174:177], v137 offset:34816
	ds_read_b128 v[178:181], v137 offset:35840
	ds_read_b128 v[182:185], v137 offset:36864
	ds_read_b128 v[186:189], v137 offset:37888
	ds_read_b128 v[190:193], v137 offset:38912
	ds_read_b128 v[194:197], v137 offset:39936
	s_add_u32 s4, s44, 0x80000
	s_addc_u32 s5, s45, 0
	s_mov_b32 m0, s81
	s_nop 0
	global_load_lds_dwordx4 v132, s[4:5]
	s_mov_b32 m0, s82
	s_nop 0
	global_load_lds_dwordx4 v134, s[4:5]
	s_waitcnt vmcnt(8)
	s_waitcnt lgkmcnt(0)
	s_barrier
	s_waitcnt lgkmcnt(7)
	v_mfma_f32_16x16x32_f16 v[124:127], v[128:131], v[166:169], v[124:127]
	v_mfma_f32_16x16x32_f16 v[120:123], v[142:145], v[166:169], v[120:123]
	s_waitcnt lgkmcnt(5)
	v_mfma_f32_16x16x32_f16 v[108:111], v[128:131], v[174:177], v[108:111]
	v_mfma_f32_16x16x32_f16 v[104:107], v[142:145], v[174:177], v[104:107]
	s_waitcnt lgkmcnt(3)
	v_mfma_f32_16x16x32_f16 v[92:95], v[128:131], v[182:185], v[92:95]
	v_mfma_f32_16x16x32_f16 v[88:91], v[142:145], v[182:185], v[88:91]
	s_waitcnt lgkmcnt(1)
	v_mfma_f32_16x16x32_f16 v[76:79], v[128:131], v[190:193], v[76:79]
	v_mfma_f32_16x16x32_f16 v[72:75], v[142:145], v[190:193], v[72:75]
	v_mfma_f32_16x16x32_f16 v[124:127], v[138:141], v[170:173], v[124:127]
	v_mfma_f32_16x16x32_f16 v[120:123], v[146:149], v[170:173], v[120:123]
	v_mfma_f32_16x16x32_f16 v[108:111], v[138:141], v[178:181], v[108:111]
	v_mfma_f32_16x16x32_f16 v[104:107], v[146:149], v[178:181], v[104:107]
	v_mfma_f32_16x16x32_f16 v[92:95], v[138:141], v[186:189], v[92:95]
	v_mfma_f32_16x16x32_f16 v[88:91], v[146:149], v[186:189], v[88:91]
	s_waitcnt lgkmcnt(0)
	v_mfma_f32_16x16x32_f16 v[76:79], v[138:141], v[194:197], v[76:79]
	v_mfma_f32_16x16x32_f16 v[72:75], v[146:149], v[194:197], v[72:75]
	v_mfma_f32_16x16x32_f16 v[116:119], v[150:153], v[166:169], v[116:119]
	v_mfma_f32_16x16x32_f16 v[112:115], v[158:161], v[166:169], v[112:115]
	v_mfma_f32_16x16x32_f16 v[100:103], v[150:153], v[174:177], v[100:103]
	v_mfma_f32_16x16x32_f16 v[96:99], v[158:161], v[174:177], v[96:99]
	v_mfma_f32_16x16x32_f16 v[84:87], v[150:153], v[182:185], v[84:87]
	v_mfma_f32_16x16x32_f16 v[80:83], v[158:161], v[182:185], v[80:83]
	v_mfma_f32_16x16x32_f16 v[68:71], v[150:153], v[190:193], v[68:71]
	v_mfma_f32_16x16x32_f16 v[64:67], v[158:161], v[190:193], v[64:67]
	v_mfma_f32_16x16x32_f16 v[116:119], v[154:157], v[170:173], v[116:119]
	v_mfma_f32_16x16x32_f16 v[112:115], v[162:165], v[170:173], v[112:115]
	v_mfma_f32_16x16x32_f16 v[100:103], v[154:157], v[178:181], v[100:103]
	v_mfma_f32_16x16x32_f16 v[96:99], v[162:165], v[178:181], v[96:99]
	v_mfma_f32_16x16x32_f16 v[84:87], v[154:157], v[186:189], v[84:87]
	v_mfma_f32_16x16x32_f16 v[80:83], v[162:165], v[186:189], v[80:83]
	v_mfma_f32_16x16x32_f16 v[68:71], v[154:157], v[194:197], v[68:71]
	v_mfma_f32_16x16x32_f16 v[64:67], v[162:165], v[194:197], v[64:67]
	s_barrier
	ds_read_b128 v[166:169], v137 offset:49152
	ds_read_b128 v[170:173], v137 offset:50176
	ds_read_b128 v[174:177], v137 offset:51200
	ds_read_b128 v[178:181], v137 offset:52224
	ds_read_b128 v[182:185], v137 offset:53248
	ds_read_b128 v[186:189], v137 offset:54272
	ds_read_b128 v[190:193], v137 offset:55296
	ds_read_b128 v[194:197], v137 offset:56320
	s_add_u32 s4, s42, 0x80
	s_addc_u32 s5, s43, 0
	s_mov_b32 m0, s85
	s_nop 0
	global_load_lds_dwordx4 v133, s[4:5]
	s_mov_b32 m0, s86
	s_nop 0
	global_load_lds_dwordx4 v135, s[4:5]
	s_add_u32 s4, s42, 0x80080
	s_addc_u32 s5, s43, 0
	s_mov_b32 m0, s89
	s_nop 0
	global_load_lds_dwordx4 v133, s[4:5]
	s_mov_b32 m0, s90
	s_nop 0
	global_load_lds_dwordx4 v135, s[4:5]
	s_mov_b32 m0, s87
	s_nop 0
	global_load_lds_dwordx4 v132, s[40:41]
	s_mov_b32 m0, s88
	s_nop 0
	global_load_lds_dwordx4 v134, s[40:41]
	s_waitcnt vmcnt(8)
	s_waitcnt lgkmcnt(0)
	s_barrier
	s_waitcnt lgkmcnt(7)
	v_mfma_f32_16x16x32_f16 v[60:63], v[128:131], v[166:169], v[60:63]
	v_mfma_f32_16x16x32_f16 v[56:59], v[142:145], v[166:169], v[56:59]
	s_waitcnt lgkmcnt(5)
	v_mfma_f32_16x16x32_f16 v[44:47], v[128:131], v[174:177], v[44:47]
	v_mfma_f32_16x16x32_f16 v[40:43], v[142:145], v[174:177], v[40:43]
	s_waitcnt lgkmcnt(3)
	v_mfma_f32_16x16x32_f16 v[28:31], v[128:131], v[182:185], v[28:31]
	v_mfma_f32_16x16x32_f16 v[24:27], v[142:145], v[182:185], v[24:27]
	s_waitcnt lgkmcnt(1)
	v_mfma_f32_16x16x32_f16 v[12:15], v[128:131], v[190:193], v[12:15]
	v_mfma_f32_16x16x32_f16 v[8:11], v[142:145], v[190:193], v[8:11]
	v_mfma_f32_16x16x32_f16 v[60:63], v[138:141], v[170:173], v[60:63]
	v_mfma_f32_16x16x32_f16 v[56:59], v[146:149], v[170:173], v[56:59]
	v_mfma_f32_16x16x32_f16 v[44:47], v[138:141], v[178:181], v[44:47]
	v_mfma_f32_16x16x32_f16 v[40:43], v[146:149], v[178:181], v[40:43]
	v_mfma_f32_16x16x32_f16 v[28:31], v[138:141], v[186:189], v[28:31]
	v_mfma_f32_16x16x32_f16 v[24:27], v[146:149], v[186:189], v[24:27]
	s_waitcnt lgkmcnt(0)
	v_mfma_f32_16x16x32_f16 v[12:15], v[138:141], v[194:197], v[12:15]
	v_mfma_f32_16x16x32_f16 v[8:11], v[146:149], v[194:197], v[8:11]
	v_mfma_f32_16x16x32_f16 v[52:55], v[150:153], v[166:169], v[52:55]
	v_mfma_f32_16x16x32_f16 v[48:51], v[158:161], v[166:169], v[48:51]
	v_mfma_f32_16x16x32_f16 v[36:39], v[150:153], v[174:177], v[36:39]
	v_mfma_f32_16x16x32_f16 v[32:35], v[158:161], v[174:177], v[32:35]
	v_mfma_f32_16x16x32_f16 v[20:23], v[150:153], v[182:185], v[20:23]
	v_mfma_f32_16x16x32_f16 v[16:19], v[158:161], v[182:185], v[16:19]
	v_mfma_f32_16x16x32_f16 v[4:7], v[150:153], v[190:193], v[4:7]
	v_mfma_f32_16x16x32_f16 v[0:3], v[158:161], v[190:193], v[0:3]
	v_mfma_f32_16x16x32_f16 v[52:55], v[154:157], v[170:173], v[52:55]
	v_mfma_f32_16x16x32_f16 v[48:51], v[162:165], v[170:173], v[48:51]
	v_mfma_f32_16x16x32_f16 v[36:39], v[154:157], v[178:181], v[36:39]
	v_mfma_f32_16x16x32_f16 v[32:35], v[162:165], v[178:181], v[32:35]
	v_mfma_f32_16x16x32_f16 v[20:23], v[154:157], v[186:189], v[20:23]
	v_mfma_f32_16x16x32_f16 v[16:19], v[162:165], v[186:189], v[16:19]
	v_mfma_f32_16x16x32_f16 v[4:7], v[154:157], v[194:197], v[4:7]
	v_mfma_f32_16x16x32_f16 v[0:3], v[162:165], v[194:197], v[0:3]
	s_barrier
	s_add_i32 s1, s1, 2
	s_add_u32 s73, s73, 0x100
	s_addc_u32 s74, s74, 0
	s_add_u32 s75, s75, 0x100
	s_addc_u32 s0, s0, 0
	s_add_u32 s38, s38, 0x100
	s_addc_u32 s39, s39, 0
	s_cmp_gt_u32 s1, 29
; #define PG8_STAGE(bufoff, gbase, voff) do { _Pragma("unroll") for (int _i = 0; _i < 2; ++_i) glds16_s((gbase), (voff)[_i], ldsb + (unsigned)((bufoff) + _i * 8192)); } while (0)
; #define PG8_LDA(dst, b, h) do { _Pragma("unroll") for (int m = 0; m < 4; ++m) _Pragma("unroll") for (int k = 0; k < 2; ++k) dst[m][k] = *(const LAS h16x8*)(lds + PG8_SA(b, h) + aoff + m * 2048 + k * 1024); } while (0)
; #define PG8_LDB(dst, b, h) do { _Pragma("unroll") for (int n = 0; n < 2; ++n) _Pragma("unroll") for (int k = 0; k < 2; ++k) dst[n][k] = *(const LAS h16x8*)(lds + PG8_SB(b, h) + boff + n * 2048 + k * 1024); } while (0)
; #define PG8_MMA(ai, bj, At, Bt) do { __builtin_amdgcn_s_setprio(1); _Pragma("unroll") for (int m = 0; m < 4; ++m) _Pragma("unroll") for (int n = 0; n < 2; ++n) _Pragma("unroll") for (int k = 0; k < 2; ++k) \
;         acc[ai][bj][m][n] = mma_step<I8>(Bt[n][k], At[m][k], acc[ai][bj][m][n]); __builtin_amdgcn_s_setprio(0); } while (0)
; #define PG8_WAIT_V(n) asm volatile("s_waitcnt vmcnt(" #n ")" ::: "memory")
; #define PG8_WAIT_L(n) asm volatile("s_waitcnt lgkmcnt(" #n ")" ::: "memory")
; #define PG8_BAR __builtin_amdgcn_s_barrier()
; #define PG8_SCHED __builtin_amdgcn_sched_barrier(0)
; __device__ __forceinline__ void glds16_s(const void* sbase, unsigned voff, unsigned lds_dst) {
;     unsigned keep;
;     asm volatile("s_mov_b32 %0, m0\n\ts_mov_b32 m0, %3\n\ts_nop 0\n\tglobal_load_lds_dwordx4 %1, %2\n\ts_mov_b32 m0, %0" : "=&s"(keep) : "v"(voff), "s"(sbase), "s"(lds_dst) : "memory");
; }
; template <class Prob, class Epi, bool I8 = false, bool ALIGN_EPI = true, bool SP2 = true>
; __device__ __forceinline__ void gemm_phase(LAS unsigned char* lds, int wave, const Prob& P, const Epi& E) {
;     ...
;             PG8_LDB(B0, 0, 0); PG8_LDB(B1, 0, 1); PG8_SCHED; PG8_LDA(At, 0, 0); PG8_STAGE(PG8_SA(1, 1), a1 + hstepA, voffA);
;             PG8_WAIT_V(8); PG8_WAIT_L(0); PG8_BAR; PG8_MMA(0, 0, At, B0); PG8_MMA(0, 1, At, B1); PG8_BAR; PG8_SCHED;
;             PG8_LDA(At, 0, 1); PG8_STAGE(PG8_SB(0, 0), b2, voffB); PG8_STAGE(PG8_SB(0, 1), b2 + hstepB, voffB); PG8_STAGE(PG8_SA(0, 0), a2, voffA);
;             PG8_WAIT_V(8); PG8_WAIT_L(0); PG8_BAR; PG8_MMA(1, 0, At, B0); PG8_MMA(1, 1, At, B1); PG8_BAR; PG8_SCHED;
.LBB0_536:
	v_add_u32_e32 v146, 0x10000, v136
	v_add_u32_e32 v162, 0x14000, v136
	ds_read_b128 v[128:131], v146
	ds_read_b128 v[138:141], v146 offset:1024
	ds_read_b128 v[142:145], v146 offset:2048
	ds_read_b128 v[146:149], v146 offset:3072
	ds_read_b128 v[150:153], v162
	ds_read_b128 v[154:157], v162 offset:1024
	ds_read_b128 v[158:161], v162 offset:2048
	ds_read_b128 v[162:165], v162 offset:3072
	s_cmp_eq_u32 s1, 28
	s_cselect_b32 s44, s57, s73
	s_cselect_b32 s45, s51, s74
	s_cselect_b32 s42, s72, s75
	s_cselect_b32 s43, s49, s0
	s_add_u32 s40, s44, 0x80
	s_addc_u32 s41, s45, 0
	ds_read_b128 v[166:169], v137
	ds_read_b128 v[170:173], v137 offset:1024
	ds_read_b128 v[174:177], v137 offset:2048
	ds_read_b128 v[178:181], v137 offset:3072
	ds_read_b128 v[182:185], v137 offset:4096
	ds_read_b128 v[186:189], v137 offset:5120
	ds_read_b128 v[190:193], v137 offset:6144
	ds_read_b128 v[194:197], v137 offset:7168
	s_mov_b32 m0, s91
	s_nop 0
	global_load_lds_dwordx4 v132, s[38:39]
	s_mov_b32 m0, s94
	s_nop 0
	global_load_lds_dwordx4 v134, s[38:39]
	s_waitcnt vmcnt(8)
	s_waitcnt lgkmcnt(0)
	s_barrier
	s_waitcnt lgkmcnt(7)
	v_mfma_f32_16x16x32_f16 v[124:127], v[128:131], v[166:169], v[124:127]
	v_mfma_f32_16x16x32_f16 v[120:123], v[142:145], v[166:169], v[120:123]
	s_waitcnt lgkmcnt(5)
	v_mfma_f32_16x16x32_f16 v[108:111], v[128:131], v[174:177], v[108:111]
	v_mfma_f32_16x16x32_f16 v[104:107], v[142:145], v[174:177], v[104:107]
	s_waitcnt lgkmcnt(3)
	v_mfma_f32_16x16x32_f16 v[92:95], v[128:131], v[182:185], v[92:95]
	v_mfma_f32_16x16x32_f16 v[88:91], v[142:145], v[182:185], v[88:91]
	s_waitcnt lgkmcnt(1)
	v_mfma_f32_16x16x32_f16 v[76:79], v[128:131], v[190:193], v[76:79]
	v_mfma_f32_16x16x32_f16 v[72:75], v[142:145], v[190:193], v[72:75]
	v_mfma_f32_16x16x32_f16 v[124:127], v[138:141], v[170:173], v[124:127]
	v_mfma_f32_16x16x32_f16 v[120:123], v[146:149], v[170:173], v[120:123]
	v_mfma_f32_16x16x32_f16 v[108:111], v[138:141], v[178:181], v[108:111]
	v_mfma_f32_16x16x32_f16 v[104:107], v[146:149], v[178:181], v[104:107]
	v_mfma_f32_16x16x32_f16 v[92:95], v[138:141], v[186:189], v[92:95]
	v_mfma_f32_16x16x32_f16 v[88:91], v[146:149], v[186:189], v[88:91]
	s_waitcnt lgkmcnt(0)
	v_mfma_f32_16x16x32_f16 v[76:79], v[138:141], v[194:197], v[76:79]
	v_mfma_f32_16x16x32_f16 v[72:75], v[146:149], v[194:197], v[72:75]
	v_mfma_f32_16x16x32_f16 v[116:119], v[150:153], v[166:169], v[116:119]
	v_mfma_f32_16x16x32_f16 v[112:115], v[158:161], v[166:169], v[112:115]
	v_mfma_f32_16x16x32_f16 v[100:103], v[150:153], v[174:177], v[100:103]
	v_mfma_f32_16x16x32_f16 v[96:99], v[158:161], v[174:177], v[96:99]
	v_mfma_f32_16x16x32_f16 v[84:87], v[150:153], v[182:185], v[84:87]
	v_mfma_f32_16x16x32_f16 v[80:83], v[158:161], v[182:185], v[80:83]
	v_mfma_f32_16x16x32_f16 v[68:71], v[150:153], v[190:193], v[68:71]
	v_mfma_f32_16x16x32_f16 v[64:67], v[158:161], v[190:193], v[64:67]
	v_mfma_f32_16x16x32_f16 v[116:119], v[154:157], v[170:173], v[116:119]
	v_mfma_f32_16x16x32_f16 v[112:115], v[162:165], v[170:173], v[112:115]
	v_mfma_f32_16x16x32_f16 v[100:103], v[154:157], v[178:181], v[100:103]
	v_mfma_f32_16x16x32_f16 v[96:99], v[162:165], v[178:181], v[96:99]
	v_mfma_f32_16x16x32_f16 v[84:87], v[154:157], v[186:189], v[84:87]
	v_mfma_f32_16x16x32_f16 v[80:83], v[162:165], v[186:189], v[80:83]
	v_mfma_f32_16x16x32_f16 v[68:71], v[154:157], v[194:197], v[68:71]
	v_mfma_f32_16x16x32_f16 v[64:67], v[162:165], v[194:197], v[64:67]
	s_barrier
	ds_read_b128 v[166:169], v137 offset:16384
	ds_read_b128 v[170:173], v137 offset:17408
	ds_read_b128 v[174:177], v137 offset:18432
	ds_read_b128 v[178:181], v137 offset:19456
	ds_read_b128 v[182:185], v137 offset:20480
	ds_read_b128 v[186:189], v137 offset:21504
	ds_read_b128 v[190:193], v137 offset:22528
	ds_read_b128 v[194:197], v137 offset:23552
	s_mov_b32 m0, s64
	s_nop 0
	global_load_lds_dwordx4 v133, s[42:43]
	s_mov_b32 m0, s68
	s_nop 0
	global_load_lds_dwordx4 v135, s[42:43]
	s_add_u32 s4, s42, 0x80000
	s_addc_u32 s5, s43, 0
	s_mov_b32 m0, s69
	s_nop 0
	global_load_lds_dwordx4 v133, s[4:5]
	s_mov_b32 m0, s79
	s_nop 0
	global_load_lds_dwordx4 v135, s[4:5]
	s_mov_b32 m0, s63
	s_nop 0
	global_load_lds_dwordx4 v132, s[44:45]
	s_mov_b32 m0, s80
	s_nop 0
	global_load_lds_dwordx4 v134, s[44:45]
	s_waitcnt vmcnt(8)
	s_waitcnt lgkmcnt(0)
	s_barrier
	s_waitcnt lgkmcnt(7)
	v_mfma_f32_16x16x32_f16 v[60:63], v[128:131], v[166:169], v[60:63]
	v_mfma_f32_16x16x32_f16 v[56:59], v[142:145], v[166:169], v[56:59]
	s_waitcnt lgkmcnt(5)
	v_mfma_f32_16x16x32_f16 v[44:47], v[128:131], v[174:177], v[44:47]
	v_mfma_f32_16x16x32_f16 v[40:43], v[142:145], v[174:177], v[40:43]
	s_waitcnt lgkmcnt(3)
	v_mfma_f32_16x16x32_f16 v[28:31], v[128:131], v[182:185], v[28:31]
	v_mfma_f32_16x16x32_f16 v[24:27], v[142:145], v[182:185], v[24:27]
	s_waitcnt lgkmcnt(1)
	v_mfma_f32_16x16x32_f16 v[12:15], v[128:131], v[190:193], v[12:15]
	v_mfma_f32_16x16x32_f16 v[8:11], v[142:145], v[190:193], v[8:11]
	v_mfma_f32_16x16x32_f16 v[60:63], v[138:141], v[170:173], v[60:63]
	v_mfma_f32_16x16x32_f16 v[56:59], v[146:149], v[170:173], v[56:59]
	v_mfma_f32_16x16x32_f16 v[44:47], v[138:141], v[178:181], v[44:47]
	v_mfma_f32_16x16x32_f16 v[40:43], v[146:149], v[178:181], v[40:43]
	v_mfma_f32_16x16x32_f16 v[28:31], v[138:141], v[186:189], v[28:31]
	v_mfma_f32_16x16x32_f16 v[24:27], v[146:149], v[186:189], v[24:27]
	s_waitcnt lgkmcnt(0)
	v_mfma_f32_16x16x32_f16 v[12:15], v[138:141], v[194:197], v[12:15]
	v_mfma_f32_16x16x32_f16 v[8:11], v[146:149], v[194:197], v[8:11]
	v_mfma_f32_16x16x32_f16 v[52:55], v[150:153], v[166:169], v[52:55]
	v_mfma_f32_16x16x32_f16 v[48:51], v[158:161], v[166:169], v[48:51]
	v_mfma_f32_16x16x32_f16 v[36:39], v[150:153], v[174:177], v[36:39]
	v_mfma_f32_16x16x32_f16 v[32:35], v[158:161], v[174:177], v[32:35]
	v_mfma_f32_16x16x32_f16 v[20:23], v[150:153], v[182:185], v[20:23]
	v_mfma_f32_16x16x32_f16 v[16:19], v[158:161], v[182:185], v[16:19]
	v_mfma_f32_16x16x32_f16 v[4:7], v[150:153], v[190:193], v[4:7]
	v_mfma_f32_16x16x32_f16 v[0:3], v[158:161], v[190:193], v[0:3]
	v_mfma_f32_16x16x32_f16 v[52:55], v[154:157], v[170:173], v[52:55]
	v_mfma_f32_16x16x32_f16 v[48:51], v[162:165], v[170:173], v[48:51]
	v_mfma_f32_16x16x32_f16 v[36:39], v[154:157], v[178:181], v[36:39]
	v_mfma_f32_16x16x32_f16 v[32:35], v[162:165], v[178:181], v[32:35]
	v_mfma_f32_16x16x32_f16 v[20:23], v[154:157], v[186:189], v[20:23]
	v_mfma_f32_16x16x32_f16 v[16:19], v[162:165], v[186:189], v[16:19]
	v_mfma_f32_16x16x32_f16 v[4:7], v[154:157], v[194:197], v[4:7]
	v_mfma_f32_16x16x32_f16 v[0:3], v[162:165], v[194:197], v[0:3]
	s_barrier
; #define PG8_STAGE(bufoff, gbase, voff) do { _Pragma("unroll") for (int _i = 0; _i < 2; ++_i) glds16_s((gbase), (voff)[_i], ldsb + (unsigned)((bufoff) + _i * 8192)); } while (0)
; #define PG8_LDA(dst, b, h) do { _Pragma("unroll") for (int m = 0; m < 4; ++m) _Pragma("unroll") for (int k = 0; k < 2; ++k) dst[m][k] = *(const LAS h16x8*)(lds + PG8_SA(b, h) + aoff + m * 2048 + k * 1024); } while (0)
; #define PG8_LDB(dst, b, h) do { _Pragma("unroll") for (int n = 0; n < 2; ++n) _Pragma("unroll") for (int k = 0; k < 2; ++k) dst[n][k] = *(const LAS h16x8*)(lds + PG8_SB(b, h) + boff + n * 2048 + k * 1024); } while (0)
; #define PG8_MMA(ai, bj, At, Bt) do { __builtin_amdgcn_s_setprio(1); _Pragma("unroll") for (int m = 0; m < 4; ++m) _Pragma("unroll") for (int n = 0; n < 2; ++n) _Pragma("unroll") for (int k = 0; k < 2; ++k) \
;         acc[ai][bj][m][n] = mma_step<I8>(Bt[n][k], At[m][k], acc[ai][bj][m][n]); __builtin_amdgcn_s_setprio(0); } while (0)
; #define PG8_WAIT_V(n) asm volatile("s_waitcnt vmcnt(" #n ")" ::: "memory")
; #define PG8_WAIT_L(n) asm volatile("s_waitcnt lgkmcnt(" #n ")" ::: "memory")
; #define PG8_BAR __builtin_amdgcn_s_barrier()
; #define PG8_SCHED __builtin_amdgcn_sched_barrier(0)
; template <class Prob, class Epi, bool I8 = false, bool ALIGN_EPI = true, bool SP2 = true>
; __device__ __forceinline__ void gemm_phase(LAS unsigned char* lds, int wave, const Prob& P, const Epi& E) {
;     ...
;             PG8_LDB(B0, 1, 0); PG8_LDB(B1, 1, 1); PG8_SCHED; PG8_LDA(At, 1, 0); PG8_STAGE(PG8_SA(0, 1), a2 + hstepA, voffA);
;             PG8_WAIT_V(8); PG8_WAIT_L(0); PG8_BAR; PG8_MMA(0, 0, At, B0); PG8_MMA(0, 1, At, B1); PG8_BAR; PG8_SCHED;
;             PG8_LDA(At, 1, 1); PG8_STAGE(PG8_SB(1, 0), b3, voffB); PG8_STAGE(PG8_SB(1, 1), b3 + hstepB, voffB); PG8_STAGE(PG8_SA(1, 0), a3, voffA);
;             PG8_WAIT_V(8); PG8_WAIT_L(0); PG8_BAR; PG8_MMA(1, 0, At, B0); PG8_MMA(1, 1, At, B1); PG8_BAR; PG8_SCHED;
;     ...
;         if constexpr (ALIGN_EPI) { if (wr == 0) PG8_BAR; }
	v_add_u32_e32 v146, 0x18000, v136
	v_add_u32_e32 v162, 0x1c000, v136
	ds_read_b128 v[128:131], v146
	ds_read_b128 v[138:141], v146 offset:1024
	ds_read_b128 v[142:145], v146 offset:2048
	ds_read_b128 v[146:149], v146 offset:3072
	ds_read_b128 v[150:153], v162
	ds_read_b128 v[154:157], v162 offset:1024
	ds_read_b128 v[158:161], v162 offset:2048
	ds_read_b128 v[162:165], v162 offset:3072
	ds_read_b128 v[166:169], v137 offset:32768
	ds_read_b128 v[170:173], v137 offset:33792
	ds_read_b128 v[174:177], v137 offset:34816
	ds_read_b128 v[178:181], v137 offset:35840
	ds_read_b128 v[182:185], v137 offset:36864
	ds_read_b128 v[186:189], v137 offset:37888
	ds_read_b128 v[190:193], v137 offset:38912
	ds_read_b128 v[194:197], v137 offset:39936
	s_add_u32 s4, s44, 0x80000
	s_addc_u32 s5, s45, 0
	s_mov_b32 m0, s81
	s_nop 0
	global_load_lds_dwordx4 v132, s[4:5]
	s_mov_b32 m0, s82
	s_nop 0
	global_load_lds_dwordx4 v134, s[4:5]
	s_waitcnt vmcnt(8)
	s_waitcnt lgkmcnt(0)
	s_barrier
	s_waitcnt lgkmcnt(7)
	v_mfma_f32_16x16x32_f16 v[124:127], v[128:131], v[166:169], v[124:127]
	v_mfma_f32_16x16x32_f16 v[120:123], v[142:145], v[166:169], v[120:123]
	s_waitcnt lgkmcnt(5)
	v_mfma_f32_16x16x32_f16 v[108:111], v[128:131], v[174:177], v[108:111]
	v_mfma_f32_16x16x32_f16 v[104:107], v[142:145], v[174:177], v[104:107]
	s_waitcnt lgkmcnt(3)
	v_mfma_f32_16x16x32_f16 v[92:95], v[128:131], v[182:185], v[92:95]
	v_mfma_f32_16x16x32_f16 v[88:91], v[142:145], v[182:185], v[88:91]
	s_waitcnt lgkmcnt(1)
	v_mfma_f32_16x16x32_f16 v[76:79], v[128:131], v[190:193], v[76:79]
	v_mfma_f32_16x16x32_f16 v[72:75], v[142:145], v[190:193], v[72:75]
	v_mfma_f32_16x16x32_f16 v[124:127], v[138:141], v[170:173], v[124:127]
	v_mfma_f32_16x16x32_f16 v[120:123], v[146:149], v[170:173], v[120:123]
	v_mfma_f32_16x16x32_f16 v[108:111], v[138:141], v[178:181], v[108:111]
	v_mfma_f32_16x16x32_f16 v[104:107], v[146:149], v[178:181], v[104:107]
	v_mfma_f32_16x16x32_f16 v[92:95], v[138:141], v[186:189], v[92:95]
	v_mfma_f32_16x16x32_f16 v[88:91], v[146:149], v[186:189], v[88:91]
	s_waitcnt lgkmcnt(0)
	v_mfma_f32_16x16x32_f16 v[76:79], v[138:141], v[194:197], v[76:79]
	v_mfma_f32_16x16x32_f16 v[72:75], v[146:149], v[194:197], v[72:75]
	v_mfma_f32_16x16x32_f16 v[116:119], v[150:153], v[166:169], v[116:119]
	v_mfma_f32_16x16x32_f16 v[112:115], v[158:161], v[166:169], v[112:115]
	v_mfma_f32_16x16x32_f16 v[100:103], v[150:153], v[174:177], v[100:103]
	v_mfma_f32_16x16x32_f16 v[96:99], v[158:161], v[174:177], v[96:99]
	v_mfma_f32_16x16x32_f16 v[84:87], v[150:153], v[182:185], v[84:87]
	v_mfma_f32_16x16x32_f16 v[80:83], v[158:161], v[182:185], v[80:83]
	v_mfma_f32_16x16x32_f16 v[68:71], v[150:153], v[190:193], v[68:71]
	v_mfma_f32_16x16x32_f16 v[64:67], v[158:161], v[190:193], v[64:67]
	v_mfma_f32_16x16x32_f16 v[116:119], v[154:157], v[170:173], v[116:119]
	v_mfma_f32_16x16x32_f16 v[112:115], v[162:165], v[170:173], v[112:115]
	v_mfma_f32_16x16x32_f16 v[100:103], v[154:157], v[178:181], v[100:103]
	v_mfma_f32_16x16x32_f16 v[96:99], v[162:165], v[178:181], v[96:99]
	v_mfma_f32_16x16x32_f16 v[84:87], v[154:157], v[186:189], v[84:87]
	v_mfma_f32_16x16x32_f16 v[80:83], v[162:165], v[186:189], v[80:83]
	v_mfma_f32_16x16x32_f16 v[68:71], v[154:157], v[194:197], v[68:71]
	v_mfma_f32_16x16x32_f16 v[64:67], v[162:165], v[194:197], v[64:67]
	s_barrier
	ds_read_b128 v[166:169], v137 offset:49152
	ds_read_b128 v[170:173], v137 offset:50176
	ds_read_b128 v[174:177], v137 offset:51200
	ds_read_b128 v[178:181], v137 offset:52224
	ds_read_b128 v[182:185], v137 offset:53248
	ds_read_b128 v[186:189], v137 offset:54272
	ds_read_b128 v[190:193], v137 offset:55296
	ds_read_b128 v[194:197], v137 offset:56320
	s_add_u32 s4, s42, 0x80
	s_addc_u32 s5, s43, 0
	s_mov_b32 m0, s85
	s_nop 0
	global_load_lds_dwordx4 v133, s[4:5]
	s_mov_b32 m0, s86
	s_nop 0
	global_load_lds_dwordx4 v135, s[4:5]
	s_add_u32 s4, s42, 0x80080
	s_addc_u32 s5, s43, 0
	s_mov_b32 m0, s89
	s_nop 0
	global_load_lds_dwordx4 v133, s[4:5]
	s_mov_b32 m0, s90
	s_nop 0
	global_load_lds_dwordx4 v135, s[4:5]
	s_mov_b32 m0, s87
	s_nop 0
	global_load_lds_dwordx4 v132, s[40:41]
	s_mov_b32 m0, s88
	s_nop 0
	global_load_lds_dwordx4 v134, s[40:41]
	s_waitcnt vmcnt(8)
	s_waitcnt lgkmcnt(0)
	s_barrier
	s_waitcnt lgkmcnt(7)
	v_mfma_f32_16x16x32_f16 v[60:63], v[128:131], v[166:169], v[60:63]
	v_mfma_f32_16x16x32_f16 v[56:59], v[142:145], v[166:169], v[56:59]
	s_waitcnt lgkmcnt(5)
	v_mfma_f32_16x16x32_f16 v[44:47], v[128:131], v[174:177], v[44:47]
	v_mfma_f32_16x16x32_f16 v[40:43], v[142:145], v[174:177], v[40:43]
	s_waitcnt lgkmcnt(3)
	v_mfma_f32_16x16x32_f16 v[28:31], v[128:131], v[182:185], v[28:31]
	v_mfma_f32_16x16x32_f16 v[24:27], v[142:145], v[182:185], v[24:27]
	s_waitcnt lgkmcnt(1)
	v_mfma_f32_16x16x32_f16 v[12:15], v[128:131], v[190:193], v[12:15]
	v_mfma_f32_16x16x32_f16 v[8:11], v[142:145], v[190:193], v[8:11]
	v_mfma_f32_16x16x32_f16 v[60:63], v[138:141], v[170:173], v[60:63]
	v_mfma_f32_16x16x32_f16 v[56:59], v[146:149], v[170:173], v[56:59]
	v_mfma_f32_16x16x32_f16 v[44:47], v[138:141], v[178:181], v[44:47]
	v_mfma_f32_16x16x32_f16 v[40:43], v[146:149], v[178:181], v[40:43]
	v_mfma_f32_16x16x32_f16 v[28:31], v[138:141], v[186:189], v[28:31]
	v_mfma_f32_16x16x32_f16 v[24:27], v[146:149], v[186:189], v[24:27]
	s_waitcnt lgkmcnt(0)
	v_mfma_f32_16x16x32_f16 v[12:15], v[138:141], v[194:197], v[12:15]
	v_mfma_f32_16x16x32_f16 v[8:11], v[146:149], v[194:197], v[8:11]
	v_mfma_f32_16x16x32_f16 v[52:55], v[150:153], v[166:169], v[52:55]
	v_mfma_f32_16x16x32_f16 v[48:51], v[158:161], v[166:169], v[48:51]
	v_mfma_f32_16x16x32_f16 v[36:39], v[150:153], v[174:177], v[36:39]
	v_mfma_f32_16x16x32_f16 v[32:35], v[158:161], v[174:177], v[32:35]
	v_mfma_f32_16x16x32_f16 v[20:23], v[150:153], v[182:185], v[20:23]
	v_mfma_f32_16x16x32_f16 v[16:19], v[158:161], v[182:185], v[16:19]
	v_mfma_f32_16x16x32_f16 v[4:7], v[150:153], v[190:193], v[4:7]
	v_mfma_f32_16x16x32_f16 v[0:3], v[158:161], v[190:193], v[0:3]
	v_mfma_f32_16x16x32_f16 v[52:55], v[154:157], v[170:173], v[52:55]
	v_mfma_f32_16x16x32_f16 v[48:51], v[162:165], v[170:173], v[48:51]
	v_mfma_f32_16x16x32_f16 v[36:39], v[154:157], v[178:181], v[36:39]
	v_mfma_f32_16x16x32_f16 v[32:35], v[162:165], v[178:181], v[32:35]
	v_mfma_f32_16x16x32_f16 v[20:23], v[154:157], v[186:189], v[20:23]
	v_mfma_f32_16x16x32_f16 v[16:19], v[162:165], v[186:189], v[16:19]
	v_mfma_f32_16x16x32_f16 v[4:7], v[154:157], v[194:197], v[4:7]
	v_mfma_f32_16x16x32_f16 v[0:3], v[162:165], v[194:197], v[0:3]
	s_barrier
	s_add_i32 s1, s1, 2
	s_add_u32 s73, s73, 0x100
	s_addc_u32 s74, s74, 0
	s_add_u32 s75, s75, 0x100
	s_addc_u32 s0, s0, 0
	s_add_u32 s38, s38, 0x100
	s_addc_u32 s39, s39, 0
	s_cmp_gt_u32 s1, 29
	s_cbranch_scc0 .LBB0_536
	s_and_b64 vcc, exec, s[28:29]
	s_cbranch_vccz .LBB0_539
	s_barrier

; __device__ __forceinline__ int mk_lane() { int l; asm volatile("v_mbcnt_lo_u32_b32 %0, -1, 0\n\tv_mbcnt_hi_u32_b32 %0, -1, %0" : "=v"(l)); return l; }
; #define PG8_STAGE(bufoff, gbase, voff) do { _Pragma("unroll") for (int _i = 0; _i < 2; ++_i) glds16_s((gbase), (voff)[_i], ldsb + (unsigned)((bufoff) + _i * 8192)); } while (0)
; #define PG8_WAIT_V(n) asm volatile("s_waitcnt vmcnt(" #n ")" ::: "memory")
; template <class Prob, class Epi, bool I8 = false, bool ALIGN_EPI = true, bool SP2 = true>
; __device__ __forceinline__ void gemm_phase(LAS unsigned char* lds, int wave, const Prob& P, const Epi& E) {
;     const int tid_ = wave * 64 + mk_lane();
;     const int tid = tid_, wid = __builtin_amdgcn_readfirstlane(tid >> 6), lane = tid & 63, wr = wid >> 2, wc = wid & 3, fr = lane & 15, fq = lane >> 4;
;     const int K = P.K, nt = K / BK;
;     unsigned voffA[2], voffB[2];
; #pragma unroll
;     for (int i = 0; i < 2; ++i) { int R, C; stage_rc(tid * 16 + i * 8192, R, C); const int Rb = (R & ~31) + perm32(R & 31);
;         voffA[i] = P.a_rowoff(R) + (unsigned)C * 2u; voffB[i] = P.b_rowoff(Rb) + (unsigned)C * 2u; }
;     const size_t kstep = (size_t)(BK * 2);
;     const size_t hstepA = P.a_hstep(), hstepB = P.b_hstep();
;     const unsigned ldsw = (unsigned)wid * 1024u;
;     const unsigned ldsb = (unsigned)(size_t)lds + ldsw;
;     const int aoff = lds_byte(wr * 64 + fr, fq * 8), boff = lds_byte(wc * 32 + fr, fq * 8);
;     ...
;     Unit cur, nxt; int ui = 0;
;     if (!P.next(0, cur)) return;
;     Acc acc;
; #pragma unroll
;     for (int a = 0; a < 2; ++a)
; #pragma unroll
;         for (int b = 0; b < 2; ++b)
; #pragma unroll
;             for (int m = 0; m < 4; ++m)
; #pragma unroll
;                 for (int n = 0; n < 2; ++n) acc[a][b][m][n] = (f32x4){0.f, 0.f, 0.f, 0.f};
;     h16x8 At[4][2], B0[2][2], B1[2][2];
;     const char* cA = P.a_tile(cur); const char* cB = P.b_tile(cur);
;     if constexpr (SP2) {
;         PG8_STAGE(PG8_SB(0, 0), cB, voffB); PG8_STAGE(PG8_SB(0, 1), cB + hstepB, voffB); PG8_STAGE(PG8_SA(0, 0), cA, voffA); PG8_STAGE(PG8_SA(0, 1), cA + hstepA, voffA);
;         if (wr == 1) PG8_BAR;
;         PG8_WAIT_V(2); PG8_BAR;
;         PG8_STAGE(PG8_SB(1, 0), cB + kstep, voffB); PG8_STAGE(PG8_SA(1, 0), cA + kstep, voffA); PG8_STAGE(PG8_SB(1, 1), cB + hstepB + kstep, voffB);
;         PG8_WAIT_V(6); PG8_BAR;
.LBB0_607:
	v_readlane_b32 s0, v254, 42
	s_waitcnt vmcnt(63) expcnt(7) lgkmcnt(15)
	s_barrier
	v_mbcnt_lo_u32_b32 v0, -1, 0
	v_mbcnt_hi_u32_b32 v0, -1, v0
	s_nop 0
	v_add_u32_e32 v1, s0, v0
	v_readlane_b32 s0, v252, 1
	v_readlane_b32 s1, v252, 2
	s_andn2_b64 vcc, exec, s[0:1]
	v_readfirstlane_b32 s1, v1
	s_cbranch_vccnz .LBB0_647
	v_ashrrev_i32_e32 v3, 31, v1
	v_lshrrev_b32_e32 v3, 26, v3
	v_lshlrev_b32_e32 v2, 4, v1
	v_add_u32_e32 v3, v1, v3
	v_bfe_i32 v1, v1, 27, 1
	v_lshrrev_b32_e32 v1, 22, v1
	v_add_u32_e32 v1, v2, v1
	v_and_b32_e32 v1, 0xfffffc00, v1
	v_sub_u32_e32 v1, v2, v1
	v_lshrrev_b32_e32 v4, 4, v1
	v_bitop3_b32 v1, v4, v1, 32 bitop3:0x6c
	v_ashrrev_i32_e32 v5, 31, v1
	v_ashrrev_i32_e32 v3, 6, v3
	v_lshrrev_b32_e32 v5, 26, v5
	v_lshlrev_b32_e32 v4, 3, v3
	v_add_u32_e32 v5, v1, v5
	v_and_b32_e32 v4, -16, v4
	v_ashrrev_i32_e32 v6, 6, v5
	v_and_b32_e32 v5, 0xc0, v5
	v_add_u32_e32 v4, v6, v4
	v_sub_u32_e32 v1, v1, v5
	v_mov_b32_e32 v8, 1
	v_lshlrev_b32_e32 v3, 5, v3
	v_ashrrev_i16_sdwa v1, v8, sext(v1) dst_sel:DWORD dst_unused:UNUSED_PAD src0_sel:DWORD src1_sel:BYTE_0
	v_lshlrev_b32_e32 v5, 1, v4
	v_lshrrev_b32_e32 v7, 2, v4
	v_and_b32_e32 v6, 3, v6
	s_mov_b32 s2, 0x1fffe0
	v_and_b32_e32 v3, 32, v3
	v_bfe_i32 v1, v1, 0, 16
	v_and_b32_e32 v5, 24, v5
	v_and_b32_e32 v7, 4, v7
	v_and_or_b32 v6, v4, s2, v6
	v_or3_b32 v5, v6, v7, v5
	v_add_lshl_u32 v1, v3, v1, 1
	v_lshl_add_u32 v148, v4, 11, v1
	v_lshl_add_u32 v149, v5, 11, v1
	v_add_u32_e32 v1, 0x2000, v2
	v_ashrrev_i32_e32 v2, 31, v1
	v_lshrrev_b32_e32 v2, 22, v2
	v_add_u32_e32 v2, v1, v2
	v_ashrrev_i32_e32 v2, 10, v2
	v_mul_i32_i24_e32 v3, 0x400, v2
	v_sub_u32_e32 v1, v1, v3
	v_lshrrev_b32_e32 v3, 4, v1
	v_bitop3_b32 v1, v3, v1, 32 bitop3:0x6c
	v_ashrrev_i32_e32 v4, 31, v1
	v_lshrrev_b32_e32 v4, 26, v4
	v_lshlrev_b32_e32 v3, 3, v2
	v_add_u32_e32 v4, v1, v4
	v_and_b32_e32 v3, -16, v3
	v_ashrrev_i32_e32 v5, 6, v4
	s_ashr_i32 s0, s1, 6
	v_add_u32_e32 v3, v5, v3
	v_and_b32_e32 v5, 3, v5
	v_and_or_b32 v5, v3, s2, v5
	s_lshl_b32 s2, s0, 10
	s_ashr_i32 s4, s1, 8
	s_add_i32 s2, s2, 0
	s_add_u32 s19, s30, 0x51200000
	s_addc_u32 s64, s31, 0
	v_readlane_b32 s5, v253, 54
	s_add_u32 s5, s30, s5
	s_addc_u32 s6, s31, 0
	v_and_b32_e32 v4, 0xc0, v4
	s_add_u32 s79, s5, 0xaa00000
	v_sub_u32_e32 v1, v1, v4
	s_addc_u32 s80, s6, 0
	s_ashr_i32 s61, s60, 31
	s_ashr_i32 s39, s38, 31
	v_lshlrev_b32_e32 v2, 5, v2
	v_ashrrev_i16_sdwa v1, v8, sext(v1) dst_sel:DWORD dst_unused:UNUSED_PAD src0_sel:DWORD src1_sel:BYTE_0
	v_lshlrev_b32_e32 v4, 1, v3
	v_lshrrev_b32_e32 v6, 2, v3
	s_lshl_b64 s[14:15], s[60:61], 19
	s_lshl_b64 s[16:17], s[38:39], 19
	v_and_b32_e32 v2, 32, v2
	v_bfe_i32 v1, v1, 0, 16
	v_and_b32_e32 v4, 24, v4
	v_and_b32_e32 v6, 4, v6
	s_add_u32 s44, s79, s16
	v_or3_b32 v4, v5, v6, v4
	v_add_lshl_u32 v1, v2, v1, 1
	s_addc_u32 s45, s80, s17
	s_add_i32 s81, s2, 0x10000
	s_mov_b32 m0, s81
	s_nop 0
	global_load_lds_dwordx4 v149, s[44:45]
	s_add_i32 s82, s2, 0x12000
	v_lshl_add_u32 v151, v4, 11, v1
	s_mov_b32 m0, s82
	s_nop 0
	global_load_lds_dwordx4 v151, s[44:45]
	s_add_u32 s16, s44, 0x40000
	s_addc_u32 s17, s45, 0
	s_add_i32 s83, s2, 0x14000
	s_mov_b32 m0, s83
	s_nop 0
	global_load_lds_dwordx4 v149, s[16:17]
	s_add_i32 s84, s2, 0x16000
	s_mov_b32 m0, s84
	s_nop 0
	global_load_lds_dwordx4 v151, s[16:17]
	s_add_u32 s56, s19, s14
	s_addc_u32 s57, s64, s15
	s_mov_b32 m0, s2
	s_nop 0
	global_load_lds_dwordx4 v148, s[56:57]
	s_add_i32 s85, s2, 0x2000
	v_lshl_add_u32 v150, v3, 11, v1
	s_mov_b32 m0, s85
	s_nop 0
	global_load_lds_dwordx4 v150, s[56:57]
	s_add_u32 s14, s56, 0x40000
	s_addc_u32 s15, s57, 0
	s_add_i32 s86, s2, 0x4000
	s_mov_b32 m0, s86
	s_nop 0
	global_load_lds_dwordx4 v148, s[14:15]
	s_add_i32 s87, s2, 0x6000
	s_mov_b32 m0, s87
	s_nop 0
	global_load_lds_dwordx4 v150, s[14:15]
	s_cmp_eq_u32 s4, 1
	s_cselect_b64 s[14:15], -1, 0
	s_setprio 1
	s_cmp_lg_u32 s4, 1
	s_cbranch_scc1 .LBB0_610
	s_barrier
	s_setprio 0
.LBB0_610:
	v_and_b32_e32 v1, 48, v0
	v_lshlrev_b32_e32 v2, 6, v0
	s_movk_i32 s6, 0x3c0
	v_lshlrev_b32_e32 v0, 2, v0
	s_and_b32 s5, s0, 3
	s_lshl_b32 s88, s4, 6
	s_lshl_b32 s4, s4, 13
	v_and_or_b32 v1, v2, s6, v1
	v_and_b32_e32 v0, 32, v0
	v_bitop3_b32 v2, v1, s4, v0 bitop3:0xde
	s_lshl_b32 s89, s5, 5
	s_lshl_b32 s4, s5, 12
	s_add_u32 s16, s30, 0x240000
	v_bitop3_b32 v0, v1, s4, v0 bitop3:0xde
	s_addc_u32 s17, s31, 0
	v_readlane_b32 s4, v253, 55
	v_readlane_b32 s5, v253, 56
	s_add_u32 s4, s30, s4
	s_addc_u32 s5, s31, s5
	s_add_u32 s22, s4, 0x22c000
	s_addc_u32 s23, s5, 0
	s_add_u32 s4, s44, 0x80
	s_waitcnt vmcnt(2)
	s_barrier
	s_addc_u32 s5, s45, 0
	s_add_i32 s90, s2, 0x18000
	s_mov_b32 m0, s90
	s_nop 0
	global_load_lds_dwordx4 v149, s[4:5]
	s_add_i32 s91, s2, 0x1a000
	s_mov_b32 m0, s91
	s_nop 0
	global_load_lds_dwordx4 v151, s[4:5]
	s_add_u32 s4, s56, 0x80
	s_addc_u32 s5, s57, 0
	s_add_i32 s92, s2, 0x8000
	s_mov_b32 m0, s92
	s_nop 0
	global_load_lds_dwordx4 v148, s[4:5]
	s_add_i32 s93, s2, 0xa000
	s_mov_b32 m0, s93
	s_nop 0
	global_load_lds_dwordx4 v150, s[4:5]
	s_add_u32 s4, s44, 0x40080
	s_addc_u32 s5, s45, 0
	s_add_i32 s94, s2, 0x1c000
	s_mov_b32 m0, s94
	s_nop 0
	global_load_lds_dwordx4 v149, s[4:5]
	s_add_i32 s95, s2, 0x1e000
	s_mov_b32 m0, s95
	s_nop 0
	global_load_lds_dwordx4 v151, s[4:5]
	s_add_i32 s96, s2, 0xc000
	s_waitcnt vmcnt(6)
	s_cmpk_lt_u32 s1, 0x100
	s_cselect_b64 s[28:29], -1, 0
	s_lshl_b32 s0, s0, 6
	s_and_b32 s97, s89, 32
	s_and_b32 s74, s0, 0x80
	s_add_i32 s75, s2, 0xe000
	s_mov_b32 s72, 0
	v_add_u32_e32 v152, 0, v0
	v_add_u32_e32 v153, 0, v2
	s_barrier
	s_branch .LBB0_613

; #define PG8_STAGE(bufoff, gbase, voff) do { _Pragma("unroll") for (int _i = 0; _i < 2; ++_i) glds16_s((gbase), (voff)[_i], ldsb + (unsigned)((bufoff) + _i * 8192)); } while (0)
; #define PG8_LDA(dst, b, h) do { _Pragma("unroll") for (int m = 0; m < 4; ++m) _Pragma("unroll") for (int k = 0; k < 2; ++k) dst[m][k] = *(const LAS h16x8*)(lds + PG8_SA(b, h) + aoff + m * 2048 + k * 1024); } while (0)
; #define PG8_LDB(dst, b, h) do { _Pragma("unroll") for (int n = 0; n < 2; ++n) _Pragma("unroll") for (int k = 0; k < 2; ++k) dst[n][k] = *(const LAS h16x8*)(lds + PG8_SB(b, h) + boff + n * 2048 + k * 1024); } while (0)
; #define PG8_MMA(ai, bj, At, Bt) do { __builtin_amdgcn_s_setprio(1); _Pragma("unroll") for (int m = 0; m < 4; ++m) _Pragma("unroll") for (int n = 0; n < 2; ++n) _Pragma("unroll") for (int k = 0; k < 2; ++k) \
;         acc[ai][bj][m][n] = mma_step<I8>(Bt[n][k], At[m][k], acc[ai][bj][m][n]); __builtin_amdgcn_s_setprio(0); } while (0)
; #define PG8_WAIT_V(n) asm volatile("s_waitcnt vmcnt(" #n ")" ::: "memory")
; #define PG8_WAIT_L(n) asm volatile("s_waitcnt lgkmcnt(" #n ")" ::: "memory")
; #define PG8_BAR __builtin_amdgcn_s_barrier()
; #define PG8_SCHED __builtin_amdgcn_sched_barrier(0)
; template <bool I8> __device__ __forceinline__ f32x4 mma_step(const h16x8& b, const h16x8& a, const f32x4& c) {
;     if constexpr (I8) return __builtin_bit_cast(f32x4, __builtin_amdgcn_mfma_i32_16x16x64_i8(__builtin_bit_cast(i32x4, b), __builtin_bit_cast(i32x4, a), __builtin_bit_cast(i32x4, c), 0, 0, 0));
;     else return __builtin_amdgcn_mfma_f32_16x16x32_f16(b, a, c, 0, 0, 0);
; template <class Prob, class Epi, bool I8 = false, bool ALIGN_EPI = true, bool SP2 = true>
; __device__ __forceinline__ void gemm_phase(LAS unsigned char* lds, int wave, const Prob& P, const Epi& E) {
;     ...
;             PG8_LDB(B0, 0, 0); PG8_LDB(B1, 0, 1); PG8_SCHED; PG8_LDA(At, 0, 0); PG8_STAGE(PG8_SA(1, 1), a1 + hstepA, voffA);
;             PG8_WAIT_V(8); PG8_WAIT_L(0); PG8_BAR; PG8_MMA(0, 0, At, B0); PG8_MMA(0, 1, At, B1); PG8_BAR; PG8_SCHED;
;             PG8_LDA(At, 0, 1); PG8_STAGE(PG8_SB(0, 0), b2, voffB); PG8_STAGE(PG8_SB(0, 1), b2 + hstepB, voffB); PG8_STAGE(PG8_SA(0, 0), a2, voffA);
;             PG8_WAIT_V(8); PG8_WAIT_L(0); PG8_BAR; PG8_MMA(1, 0, At, B0); PG8_MMA(1, 1, At, B1); PG8_BAR; PG8_SCHED;
.Lpeel_616:
	v_add_u32_e32 v140, 0x10000, v152
	v_add_u32_e32 v162, 0x14000, v152
	ds_read_b128 v[128:131], v140
	ds_read_b128 v[132:135], v140 offset:1024
	ds_read_b128 v[136:139], v140 offset:2048
	ds_read_b128 v[140:143], v140 offset:3072
	ds_read_b128 v[144:147], v162
	ds_read_b128 v[154:157], v162 offset:1024
	ds_read_b128 v[158:161], v162 offset:2048
	ds_read_b128 v[162:165], v162 offset:3072
	s_cmp_eq_u32 s1, 12
	s_cselect_b32 s62, s43, s73
	s_cselect_b32 s63, s39, vcc_lo
	s_cselect_b32 s68, s61, vcc_hi
	s_cselect_b32 s69, s41, s0
	s_add_u32 s56, s62, 0x80
	s_addc_u32 s57, s63, 0
	ds_read_b128 v[166:169], v153
	ds_read_b128 v[170:173], v153 offset:1024
	ds_read_b128 v[174:177], v153 offset:2048
	ds_read_b128 v[178:181], v153 offset:3072
	ds_read_b128 v[182:185], v153 offset:4096
	ds_read_b128 v[186:189], v153 offset:5120
	ds_read_b128 v[190:193], v153 offset:6144
	ds_read_b128 v[194:197], v153 offset:7168
	s_mov_b32 m0, s96
	s_nop 0
	global_load_lds_dwordx4 v148, s[44:45]
	s_mov_b32 m0, s75
	s_nop 0
	global_load_lds_dwordx4 v150, s[44:45]
	s_waitcnt vmcnt(8)
	s_waitcnt lgkmcnt(0)
	s_barrier
	s_waitcnt lgkmcnt(7)
	v_mfma_i32_16x16x64_i8 v[124:127], v[128:131], v[166:169], 0
	v_mfma_i32_16x16x64_i8 v[120:123], v[136:139], v[166:169], 0
	s_waitcnt lgkmcnt(5)
	v_mfma_i32_16x16x64_i8 v[108:111], v[128:131], v[174:177], 0
	v_mfma_i32_16x16x64_i8 v[104:107], v[136:139], v[174:177], 0
	s_waitcnt lgkmcnt(3)
	v_mfma_i32_16x16x64_i8 v[92:95], v[128:131], v[182:185], 0
	v_mfma_i32_16x16x64_i8 v[88:91], v[136:139], v[182:185], 0
	s_waitcnt lgkmcnt(1)
	v_mfma_i32_16x16x64_i8 v[76:79], v[128:131], v[190:193], 0
	v_mfma_i32_16x16x64_i8 v[72:75], v[136:139], v[190:193], 0
	v_mfma_i32_16x16x64_i8 v[124:127], v[132:135], v[170:173], v[124:127]
	v_mfma_i32_16x16x64_i8 v[120:123], v[140:143], v[170:173], v[120:123]
	v_mfma_i32_16x16x64_i8 v[108:111], v[132:135], v[178:181], v[108:111]
	v_mfma_i32_16x16x64_i8 v[104:107], v[140:143], v[178:181], v[104:107]
	v_mfma_i32_16x16x64_i8 v[92:95], v[132:135], v[186:189], v[92:95]
	v_mfma_i32_16x16x64_i8 v[88:91], v[140:143], v[186:189], v[88:91]
	s_waitcnt lgkmcnt(0)
	v_mfma_i32_16x16x64_i8 v[76:79], v[132:135], v[194:197], v[76:79]
	v_mfma_i32_16x16x64_i8 v[72:75], v[140:143], v[194:197], v[72:75]
	v_mfma_i32_16x16x64_i8 v[116:119], v[144:147], v[166:169], 0
	v_mfma_i32_16x16x64_i8 v[112:115], v[158:161], v[166:169], 0
	v_mfma_i32_16x16x64_i8 v[100:103], v[144:147], v[174:177], 0
	v_mfma_i32_16x16x64_i8 v[96:99], v[158:161], v[174:177], 0
	v_mfma_i32_16x16x64_i8 v[84:87], v[144:147], v[182:185], 0
	v_mfma_i32_16x16x64_i8 v[80:83], v[158:161], v[182:185], 0
	v_mfma_i32_16x16x64_i8 v[68:71], v[144:147], v[190:193], 0
	v_mfma_i32_16x16x64_i8 v[64:67], v[158:161], v[190:193], 0
	v_mfma_i32_16x16x64_i8 v[116:119], v[154:157], v[170:173], v[116:119]
	v_mfma_i32_16x16x64_i8 v[112:115], v[162:165], v[170:173], v[112:115]
	v_mfma_i32_16x16x64_i8 v[100:103], v[154:157], v[178:181], v[100:103]
	v_mfma_i32_16x16x64_i8 v[96:99], v[162:165], v[178:181], v[96:99]
	v_mfma_i32_16x16x64_i8 v[84:87], v[154:157], v[186:189], v[84:87]
	v_mfma_i32_16x16x64_i8 v[80:83], v[162:165], v[186:189], v[80:83]
	v_mfma_i32_16x16x64_i8 v[68:71], v[154:157], v[194:197], v[68:71]
	v_mfma_i32_16x16x64_i8 v[64:67], v[162:165], v[194:197], v[64:67]
	s_barrier
	ds_read_b128 v[166:169], v153 offset:16384
	ds_read_b128 v[170:173], v153 offset:17408
	ds_read_b128 v[174:177], v153 offset:18432
	ds_read_b128 v[178:181], v153 offset:19456
	ds_read_b128 v[182:185], v153 offset:20480
	ds_read_b128 v[186:189], v153 offset:21504
	ds_read_b128 v[190:193], v153 offset:22528
	ds_read_b128 v[194:197], v153 offset:23552
	s_mov_b32 m0, s81
	s_nop 0
	global_load_lds_dwordx4 v149, s[68:69]
	s_mov_b32 m0, s82
	s_nop 0
	global_load_lds_dwordx4 v151, s[68:69]
	s_add_u32 s4, s68, 0x40000
	s_addc_u32 s5, s69, 0
	s_mov_b32 m0, s83
	s_nop 0
	global_load_lds_dwordx4 v149, s[4:5]
	s_mov_b32 m0, s84
	s_nop 0
	global_load_lds_dwordx4 v151, s[4:5]
	s_mov_b32 m0, s2
	s_nop 0
	global_load_lds_dwordx4 v148, s[62:63]
	s_mov_b32 m0, s85
	s_nop 0
	global_load_lds_dwordx4 v150, s[62:63]
	s_waitcnt vmcnt(8)
	s_waitcnt lgkmcnt(0)
	s_barrier
	s_waitcnt lgkmcnt(7)
	v_mfma_i32_16x16x64_i8 v[60:63], v[128:131], v[166:169], 0
	v_mfma_i32_16x16x64_i8 v[56:59], v[136:139], v[166:169], 0
	s_waitcnt lgkmcnt(5)
	v_mfma_i32_16x16x64_i8 v[44:47], v[128:131], v[174:177], 0
	v_mfma_i32_16x16x64_i8 v[40:43], v[136:139], v[174:177], 0
	s_waitcnt lgkmcnt(3)
	v_mfma_i32_16x16x64_i8 v[28:31], v[128:131], v[182:185], 0
	v_mfma_i32_16x16x64_i8 v[24:27], v[136:139], v[182:185], 0
	s_waitcnt lgkmcnt(1)
	v_mfma_i32_16x16x64_i8 v[12:15], v[128:131], v[190:193], 0
	v_mfma_i32_16x16x64_i8 v[8:11], v[136:139], v[190:193], 0
	v_mfma_i32_16x16x64_i8 v[60:63], v[132:135], v[170:173], v[60:63]
	v_mfma_i32_16x16x64_i8 v[56:59], v[140:143], v[170:173], v[56:59]
	v_mfma_i32_16x16x64_i8 v[44:47], v[132:135], v[178:181], v[44:47]
	v_mfma_i32_16x16x64_i8 v[40:43], v[140:143], v[178:181], v[40:43]
	v_mfma_i32_16x16x64_i8 v[28:31], v[132:135], v[186:189], v[28:31]
	v_mfma_i32_16x16x64_i8 v[24:27], v[140:143], v[186:189], v[24:27]
	s_waitcnt lgkmcnt(0)
	v_mfma_i32_16x16x64_i8 v[12:15], v[132:135], v[194:197], v[12:15]
	v_mfma_i32_16x16x64_i8 v[8:11], v[140:143], v[194:197], v[8:11]
	v_mfma_i32_16x16x64_i8 v[52:55], v[144:147], v[166:169], 0
	v_mfma_i32_16x16x64_i8 v[48:51], v[158:161], v[166:169], 0
	v_mfma_i32_16x16x64_i8 v[36:39], v[144:147], v[174:177], 0
	v_mfma_i32_16x16x64_i8 v[32:35], v[158:161], v[174:177], 0
	v_mfma_i32_16x16x64_i8 v[20:23], v[144:147], v[182:185], 0
	v_mfma_i32_16x16x64_i8 v[16:19], v[158:161], v[182:185], 0
	v_mfma_i32_16x16x64_i8 v[4:7], v[144:147], v[190:193], 0
	v_mfma_i32_16x16x64_i8 v[0:3], v[158:161], v[190:193], 0
	v_mfma_i32_16x16x64_i8 v[52:55], v[154:157], v[170:173], v[52:55]
	v_mfma_i32_16x16x64_i8 v[48:51], v[162:165], v[170:173], v[48:51]
	v_mfma_i32_16x16x64_i8 v[36:39], v[154:157], v[178:181], v[36:39]
	v_mfma_i32_16x16x64_i8 v[32:35], v[162:165], v[178:181], v[32:35]
	v_mfma_i32_16x16x64_i8 v[20:23], v[154:157], v[186:189], v[20:23]
	v_mfma_i32_16x16x64_i8 v[16:19], v[162:165], v[186:189], v[16:19]
	v_mfma_i32_16x16x64_i8 v[4:7], v[154:157], v[194:197], v[4:7]
	v_mfma_i32_16x16x64_i8 v[0:3], v[162:165], v[194:197], v[0:3]
	s_barrier
; #define PG8_STAGE(bufoff, gbase, voff) do { _Pragma("unroll") for (int _i = 0; _i < 2; ++_i) glds16_s((gbase), (voff)[_i], ldsb + (unsigned)((bufoff) + _i * 8192)); } while (0)
; #define PG8_LDA(dst, b, h) do { _Pragma("unroll") for (int m = 0; m < 4; ++m) _Pragma("unroll") for (int k = 0; k < 2; ++k) dst[m][k] = *(const LAS h16x8*)(lds + PG8_SA(b, h) + aoff + m * 2048 + k * 1024); } while (0)
; #define PG8_LDB(dst, b, h) do { _Pragma("unroll") for (int n = 0; n < 2; ++n) _Pragma("unroll") for (int k = 0; k < 2; ++k) dst[n][k] = *(const LAS h16x8*)(lds + PG8_SB(b, h) + boff + n * 2048 + k * 1024); } while (0)
; #define PG8_MMA(ai, bj, At, Bt) do { __builtin_amdgcn_s_setprio(1); _Pragma("unroll") for (int m = 0; m < 4; ++m) _Pragma("unroll") for (int n = 0; n < 2; ++n) _Pragma("unroll") for (int k = 0; k < 2; ++k) \
;         acc[ai][bj][m][n] = mma_step<I8>(Bt[n][k], At[m][k], acc[ai][bj][m][n]); __builtin_amdgcn_s_setprio(0); } while (0)
; #define PG8_WAIT_V(n) asm volatile("s_waitcnt vmcnt(" #n ")" ::: "memory")
; #define PG8_WAIT_L(n) asm volatile("s_waitcnt lgkmcnt(" #n ")" ::: "memory")
; #define PG8_BAR __builtin_amdgcn_s_barrier()
; #define PG8_SCHED __builtin_amdgcn_sched_barrier(0)
; template <bool I8> __device__ __forceinline__ f32x4 mma_step(const h16x8& b, const h16x8& a, const f32x4& c) {
;     if constexpr (I8) return __builtin_bit_cast(f32x4, __builtin_amdgcn_mfma_i32_16x16x64_i8(__builtin_bit_cast(i32x4, b), __builtin_bit_cast(i32x4, a), __builtin_bit_cast(i32x4, c), 0, 0, 0));
;     else return __builtin_amdgcn_mfma_f32_16x16x32_f16(b, a, c, 0, 0, 0);
; template <class Prob, class Epi, bool I8 = false, bool ALIGN_EPI = true, bool SP2 = true>
; __device__ __forceinline__ void gemm_phase(LAS unsigned char* lds, int wave, const Prob& P, const Epi& E) {
;     ...
;             PG8_LDB(B0, 1, 0); PG8_LDB(B1, 1, 1); PG8_SCHED; PG8_LDA(At, 1, 0); PG8_STAGE(PG8_SA(0, 1), a2 + hstepA, voffA);
;             PG8_WAIT_V(8); PG8_WAIT_L(0); PG8_BAR; PG8_MMA(0, 0, At, B0); PG8_MMA(0, 1, At, B1); PG8_BAR; PG8_SCHED;
;             PG8_LDA(At, 1, 1); PG8_STAGE(PG8_SB(1, 0), b3, voffB); PG8_STAGE(PG8_SB(1, 1), b3 + hstepB, voffB); PG8_STAGE(PG8_SA(1, 0), a3, voffA);
;             PG8_WAIT_V(8); PG8_WAIT_L(0); PG8_BAR; PG8_MMA(1, 0, At, B0); PG8_MMA(1, 1, At, B1); PG8_BAR; PG8_SCHED;
	v_add_u32_e32 v140, 0x18000, v152
	v_add_u32_e32 v162, 0x1c000, v152
	ds_read_b128 v[128:131], v140
	ds_read_b128 v[132:135], v140 offset:1024
	ds_read_b128 v[136:139], v140 offset:2048
	ds_read_b128 v[140:143], v140 offset:3072
	ds_read_b128 v[144:147], v162
	ds_read_b128 v[154:157], v162 offset:1024
	ds_read_b128 v[158:161], v162 offset:2048
	ds_read_b128 v[162:165], v162 offset:3072
	ds_read_b128 v[166:169], v153 offset:32768
	ds_read_b128 v[170:173], v153 offset:33792
	ds_read_b128 v[174:177], v153 offset:34816
	ds_read_b128 v[178:181], v153 offset:35840
	ds_read_b128 v[182:185], v153 offset:36864
	ds_read_b128 v[186:189], v153 offset:37888
	ds_read_b128 v[190:193], v153 offset:38912
	ds_read_b128 v[194:197], v153 offset:39936
	s_add_u32 s4, s62, 0x40000
	s_addc_u32 s5, s63, 0
	s_mov_b32 m0, s86
	s_nop 0
	global_load_lds_dwordx4 v148, s[4:5]
	s_mov_b32 m0, s87
	s_nop 0
	global_load_lds_dwordx4 v150, s[4:5]
	s_waitcnt vmcnt(8)
	s_waitcnt lgkmcnt(0)
	s_barrier
	s_waitcnt lgkmcnt(7)
	v_mfma_i32_16x16x64_i8 v[124:127], v[128:131], v[166:169], v[124:127]
	v_mfma_i32_16x16x64_i8 v[120:123], v[136:139], v[166:169], v[120:123]
	s_waitcnt lgkmcnt(5)
	v_mfma_i32_16x16x64_i8 v[108:111], v[128:131], v[174:177], v[108:111]
	v_mfma_i32_16x16x64_i8 v[104:107], v[136:139], v[174:177], v[104:107]
	s_waitcnt lgkmcnt(3)
	v_mfma_i32_16x16x64_i8 v[92:95], v[128:131], v[182:185], v[92:95]
	v_mfma_i32_16x16x64_i8 v[88:91], v[136:139], v[182:185], v[88:91]
	s_waitcnt lgkmcnt(1)
	v_mfma_i32_16x16x64_i8 v[76:79], v[128:131], v[190:193], v[76:79]
	v_mfma_i32_16x16x64_i8 v[72:75], v[136:139], v[190:193], v[72:75]
	v_mfma_i32_16x16x64_i8 v[124:127], v[132:135], v[170:173], v[124:127]
	v_mfma_i32_16x16x64_i8 v[120:123], v[140:143], v[170:173], v[120:123]
	v_mfma_i32_16x16x64_i8 v[108:111], v[132:135], v[178:181], v[108:111]
	v_mfma_i32_16x16x64_i8 v[104:107], v[140:143], v[178:181], v[104:107]
	v_mfma_i32_16x16x64_i8 v[92:95], v[132:135], v[186:189], v[92:95]
	v_mfma_i32_16x16x64_i8 v[88:91], v[140:143], v[186:189], v[88:91]
	s_waitcnt lgkmcnt(0)
	v_mfma_i32_16x16x64_i8 v[76:79], v[132:135], v[194:197], v[76:79]
	v_mfma_i32_16x16x64_i8 v[72:75], v[140:143], v[194:197], v[72:75]
	v_mfma_i32_16x16x64_i8 v[116:119], v[144:147], v[166:169], v[116:119]
	v_mfma_i32_16x16x64_i8 v[112:115], v[158:161], v[166:169], v[112:115]
	v_mfma_i32_16x16x64_i8 v[100:103], v[144:147], v[174:177], v[100:103]
	v_mfma_i32_16x16x64_i8 v[96:99], v[158:161], v[174:177], v[96:99]
	v_mfma_i32_16x16x64_i8 v[84:87], v[144:147], v[182:185], v[84:87]
	v_mfma_i32_16x16x64_i8 v[80:83], v[158:161], v[182:185], v[80:83]
	v_mfma_i32_16x16x64_i8 v[68:71], v[144:147], v[190:193], v[68:71]
	v_mfma_i32_16x16x64_i8 v[64:67], v[158:161], v[190:193], v[64:67]
	v_mfma_i32_16x16x64_i8 v[116:119], v[154:157], v[170:173], v[116:119]
	v_mfma_i32_16x16x64_i8 v[112:115], v[162:165], v[170:173], v[112:115]
	v_mfma_i32_16x16x64_i8 v[100:103], v[154:157], v[178:181], v[100:103]
	v_mfma_i32_16x16x64_i8 v[96:99], v[162:165], v[178:181], v[96:99]
	v_mfma_i32_16x16x64_i8 v[84:87], v[154:157], v[186:189], v[84:87]
	v_mfma_i32_16x16x64_i8 v[80:83], v[162:165], v[186:189], v[80:83]
	v_mfma_i32_16x16x64_i8 v[68:71], v[154:157], v[194:197], v[68:71]
	v_mfma_i32_16x16x64_i8 v[64:67], v[162:165], v[194:197], v[64:67]
	s_barrier
	ds_read_b128 v[166:169], v153 offset:49152
	ds_read_b128 v[170:173], v153 offset:50176
	ds_read_b128 v[174:177], v153 offset:51200
	ds_read_b128 v[178:181], v153 offset:52224
	ds_read_b128 v[182:185], v153 offset:53248
	ds_read_b128 v[186:189], v153 offset:54272
	ds_read_b128 v[190:193], v153 offset:55296
	ds_read_b128 v[194:197], v153 offset:56320
	s_add_u32 s4, s68, 0x80
	s_addc_u32 s5, s69, 0
	s_mov_b32 m0, s90
	s_nop 0
	global_load_lds_dwordx4 v149, s[4:5]
	s_mov_b32 m0, s91
	s_nop 0
	global_load_lds_dwordx4 v151, s[4:5]
	s_add_u32 s4, s68, 0x40080
	s_addc_u32 s5, s69, 0
	s_mov_b32 m0, s94
	s_nop 0
	global_load_lds_dwordx4 v149, s[4:5]
	s_mov_b32 m0, s95
	s_nop 0
	global_load_lds_dwordx4 v151, s[4:5]
	s_mov_b32 m0, s92
	s_nop 0
	global_load_lds_dwordx4 v148, s[56:57]
	s_mov_b32 m0, s93
	s_nop 0
	global_load_lds_dwordx4 v150, s[56:57]
	s_waitcnt vmcnt(8)
	s_waitcnt lgkmcnt(0)
	s_barrier
	s_waitcnt lgkmcnt(7)
	v_mfma_i32_16x16x64_i8 v[60:63], v[128:131], v[166:169], v[60:63]
	v_mfma_i32_16x16x64_i8 v[56:59], v[136:139], v[166:169], v[56:59]
	s_waitcnt lgkmcnt(5)
	v_mfma_i32_16x16x64_i8 v[44:47], v[128:131], v[174:177], v[44:47]
	v_mfma_i32_16x16x64_i8 v[40:43], v[136:139], v[174:177], v[40:43]
	s_waitcnt lgkmcnt(3)
	v_mfma_i32_16x16x64_i8 v[28:31], v[128:131], v[182:185], v[28:31]
	v_mfma_i32_16x16x64_i8 v[24:27], v[136:139], v[182:185], v[24:27]
	s_waitcnt lgkmcnt(1)
	v_mfma_i32_16x16x64_i8 v[12:15], v[128:131], v[190:193], v[12:15]
	v_mfma_i32_16x16x64_i8 v[8:11], v[136:139], v[190:193], v[8:11]
	v_mfma_i32_16x16x64_i8 v[60:63], v[132:135], v[170:173], v[60:63]
	v_mfma_i32_16x16x64_i8 v[56:59], v[140:143], v[170:173], v[56:59]
	v_mfma_i32_16x16x64_i8 v[44:47], v[132:135], v[178:181], v[44:47]
	v_mfma_i32_16x16x64_i8 v[40:43], v[140:143], v[178:181], v[40:43]
	v_mfma_i32_16x16x64_i8 v[28:31], v[132:135], v[186:189], v[28:31]
	v_mfma_i32_16x16x64_i8 v[24:27], v[140:143], v[186:189], v[24:27]
	s_waitcnt lgkmcnt(0)
	v_mfma_i32_16x16x64_i8 v[12:15], v[132:135], v[194:197], v[12:15]
	v_mfma_i32_16x16x64_i8 v[8:11], v[140:143], v[194:197], v[8:11]
	v_mfma_i32_16x16x64_i8 v[52:55], v[144:147], v[166:169], v[52:55]
	v_mfma_i32_16x16x64_i8 v[48:51], v[158:161], v[166:169], v[48:51]
	v_mfma_i32_16x16x64_i8 v[36:39], v[144:147], v[174:177], v[36:39]
	v_mfma_i32_16x16x64_i8 v[32:35], v[158:161], v[174:177], v[32:35]
	v_mfma_i32_16x16x64_i8 v[20:23], v[144:147], v[182:185], v[20:23]
	v_mfma_i32_16x16x64_i8 v[16:19], v[158:161], v[182:185], v[16:19]
	v_mfma_i32_16x16x64_i8 v[4:7], v[144:147], v[190:193], v[4:7]
	v_mfma_i32_16x16x64_i8 v[0:3], v[158:161], v[190:193], v[0:3]
	v_mfma_i32_16x16x64_i8 v[52:55], v[154:157], v[170:173], v[52:55]
	v_mfma_i32_16x16x64_i8 v[48:51], v[162:165], v[170:173], v[48:51]
	v_mfma_i32_16x16x64_i8 v[36:39], v[154:157], v[178:181], v[36:39]
	v_mfma_i32_16x16x64_i8 v[32:35], v[162:165], v[178:181], v[32:35]
	v_mfma_i32_16x16x64_i8 v[20:23], v[154:157], v[186:189], v[20:23]
	v_mfma_i32_16x16x64_i8 v[16:19], v[162:165], v[186:189], v[16:19]
	v_mfma_i32_16x16x64_i8 v[4:7], v[154:157], v[194:197], v[4:7]
	v_mfma_i32_16x16x64_i8 v[0:3], v[162:165], v[194:197], v[0:3]
	s_barrier
	s_add_i32 s1, s1, 2
	s_add_u32 s73, s73, 0x100
	s_addc_u32 vcc_lo, vcc_lo, 0
	s_add_u32 vcc_hi, vcc_hi, 0x100
	s_addc_u32 s0, s0, 0
	s_add_u32 s44, s44, 0x100
	s_addc_u32 s45, s45, 0
	s_cmp_gt_u32 s1, 13
; #define PG8_STAGE(bufoff, gbase, voff) do { _Pragma("unroll") for (int _i = 0; _i < 2; ++_i) glds16_s((gbase), (voff)[_i], ldsb + (unsigned)((bufoff) + _i * 8192)); } while (0)
; #define PG8_LDA(dst, b, h) do { _Pragma("unroll") for (int m = 0; m < 4; ++m) _Pragma("unroll") for (int k = 0; k < 2; ++k) dst[m][k] = *(const LAS h16x8*)(lds + PG8_SA(b, h) + aoff + m * 2048 + k * 1024); } while (0)
; #define PG8_LDB(dst, b, h) do { _Pragma("unroll") for (int n = 0; n < 2; ++n) _Pragma("unroll") for (int k = 0; k < 2; ++k) dst[n][k] = *(const LAS h16x8*)(lds + PG8_SB(b, h) + boff + n * 2048 + k * 1024); } while (0)
; #define PG8_MMA(ai, bj, At, Bt) do { __builtin_amdgcn_s_setprio(1); _Pragma("unroll") for (int m = 0; m < 4; ++m) _Pragma("unroll") for (int n = 0; n < 2; ++n) _Pragma("unroll") for (int k = 0; k < 2; ++k) \
;         acc[ai][bj][m][n] = mma_step<I8>(Bt[n][k], At[m][k], acc[ai][bj][m][n]); __builtin_amdgcn_s_setprio(0); } while (0)
; #define PG8_WAIT_V(n) asm volatile("s_waitcnt vmcnt(" #n ")" ::: "memory")
; #define PG8_WAIT_L(n) asm volatile("s_waitcnt lgkmcnt(" #n ")" ::: "memory")
; #define PG8_BAR __builtin_amdgcn_s_barrier()
; #define PG8_SCHED __builtin_amdgcn_sched_barrier(0)
; template <bool I8> __device__ __forceinline__ f32x4 mma_step(const h16x8& b, const h16x8& a, const f32x4& c) {
;     if constexpr (I8) return __builtin_bit_cast(f32x4, __builtin_amdgcn_mfma_i32_16x16x64_i8(__builtin_bit_cast(i32x4, b), __builtin_bit_cast(i32x4, a), __builtin_bit_cast(i32x4, c), 0, 0, 0));
;     else return __builtin_amdgcn_mfma_f32_16x16x32_f16(b, a, c, 0, 0, 0);
; template <class Prob, class Epi, bool I8 = false, bool ALIGN_EPI = true, bool SP2 = true>
; __device__ __forceinline__ void gemm_phase(LAS unsigned char* lds, int wave, const Prob& P, const Epi& E) {
;     ...
;             PG8_LDB(B0, 0, 0); PG8_LDB(B1, 0, 1); PG8_SCHED; PG8_LDA(At, 0, 0); PG8_STAGE(PG8_SA(1, 1), a1 + hstepA, voffA);
;             PG8_WAIT_V(8); PG8_WAIT_L(0); PG8_BAR; PG8_MMA(0, 0, At, B0); PG8_MMA(0, 1, At, B1); PG8_BAR; PG8_SCHED;
;             PG8_LDA(At, 0, 1); PG8_STAGE(PG8_SB(0, 0), b2, voffB); PG8_STAGE(PG8_SB(0, 1), b2 + hstepB, voffB); PG8_STAGE(PG8_SA(0, 0), a2, voffA);
;             PG8_WAIT_V(8); PG8_WAIT_L(0); PG8_BAR; PG8_MMA(1, 0, At, B0); PG8_MMA(1, 1, At, B1); PG8_BAR; PG8_SCHED;
.LBB0_616:
	v_add_u32_e32 v140, 0x10000, v152
	v_add_u32_e32 v162, 0x14000, v152
	ds_read_b128 v[128:131], v140
	ds_read_b128 v[132:135], v140 offset:1024
	ds_read_b128 v[136:139], v140 offset:2048
	ds_read_b128 v[140:143], v140 offset:3072
	ds_read_b128 v[144:147], v162
	ds_read_b128 v[154:157], v162 offset:1024
	ds_read_b128 v[158:161], v162 offset:2048
	ds_read_b128 v[162:165], v162 offset:3072
	s_cmp_eq_u32 s1, 12
	s_cselect_b32 s62, s43, s73
	s_cselect_b32 s63, s39, vcc_lo
	s_cselect_b32 s68, s61, vcc_hi
	s_cselect_b32 s69, s41, s0
	s_add_u32 s56, s62, 0x80
	s_addc_u32 s57, s63, 0
	ds_read_b128 v[166:169], v153
	ds_read_b128 v[170:173], v153 offset:1024
	ds_read_b128 v[174:177], v153 offset:2048
	ds_read_b128 v[178:181], v153 offset:3072
	ds_read_b128 v[182:185], v153 offset:4096
	ds_read_b128 v[186:189], v153 offset:5120
	ds_read_b128 v[190:193], v153 offset:6144
	ds_read_b128 v[194:197], v153 offset:7168
	s_mov_b32 m0, s96
	s_nop 0
	global_load_lds_dwordx4 v148, s[44:45]
	s_mov_b32 m0, s75
	s_nop 0
	global_load_lds_dwordx4 v150, s[44:45]
	s_waitcnt vmcnt(8)
	s_waitcnt lgkmcnt(0)
	s_barrier
	s_waitcnt lgkmcnt(7)
	v_mfma_i32_16x16x64_i8 v[124:127], v[128:131], v[166:169], v[124:127]
	v_mfma_i32_16x16x64_i8 v[120:123], v[136:139], v[166:169], v[120:123]
	s_waitcnt lgkmcnt(5)
	v_mfma_i32_16x16x64_i8 v[108:111], v[128:131], v[174:177], v[108:111]
	v_mfma_i32_16x16x64_i8 v[104:107], v[136:139], v[174:177], v[104:107]
	s_waitcnt lgkmcnt(3)
	v_mfma_i32_16x16x64_i8 v[92:95], v[128:131], v[182:185], v[92:95]
	v_mfma_i32_16x16x64_i8 v[88:91], v[136:139], v[182:185], v[88:91]
	s_waitcnt lgkmcnt(1)
	v_mfma_i32_16x16x64_i8 v[76:79], v[128:131], v[190:193], v[76:79]
	v_mfma_i32_16x16x64_i8 v[72:75], v[136:139], v[190:193], v[72:75]
	v_mfma_i32_16x16x64_i8 v[124:127], v[132:135], v[170:173], v[124:127]
	v_mfma_i32_16x16x64_i8 v[120:123], v[140:143], v[170:173], v[120:123]
	v_mfma_i32_16x16x64_i8 v[108:111], v[132:135], v[178:181], v[108:111]
	v_mfma_i32_16x16x64_i8 v[104:107], v[140:143], v[178:181], v[104:107]
	v_mfma_i32_16x16x64_i8 v[92:95], v[132:135], v[186:189], v[92:95]
	v_mfma_i32_16x16x64_i8 v[88:91], v[140:143], v[186:189], v[88:91]
	s_waitcnt lgkmcnt(0)
	v_mfma_i32_16x16x64_i8 v[76:79], v[132:135], v[194:197], v[76:79]
	v_mfma_i32_16x16x64_i8 v[72:75], v[140:143], v[194:197], v[72:75]
	v_mfma_i32_16x16x64_i8 v[116:119], v[144:147], v[166:169], v[116:119]
	v_mfma_i32_16x16x64_i8 v[112:115], v[158:161], v[166:169], v[112:115]
	v_mfma_i32_16x16x64_i8 v[100:103], v[144:147], v[174:177], v[100:103]
	v_mfma_i32_16x16x64_i8 v[96:99], v[158:161], v[174:177], v[96:99]
	v_mfma_i32_16x16x64_i8 v[84:87], v[144:147], v[182:185], v[84:87]
	v_mfma_i32_16x16x64_i8 v[80:83], v[158:161], v[182:185], v[80:83]
	v_mfma_i32_16x16x64_i8 v[68:71], v[144:147], v[190:193], v[68:71]
	v_mfma_i32_16x16x64_i8 v[64:67], v[158:161], v[190:193], v[64:67]
	v_mfma_i32_16x16x64_i8 v[116:119], v[154:157], v[170:173], v[116:119]
	v_mfma_i32_16x16x64_i8 v[112:115], v[162:165], v[170:173], v[112:115]
	v_mfma_i32_16x16x64_i8 v[100:103], v[154:157], v[178:181], v[100:103]
	v_mfma_i32_16x16x64_i8 v[96:99], v[162:165], v[178:181], v[96:99]
	v_mfma_i32_16x16x64_i8 v[84:87], v[154:157], v[186:189], v[84:87]
	v_mfma_i32_16x16x64_i8 v[80:83], v[162:165], v[186:189], v[80:83]
	v_mfma_i32_16x16x64_i8 v[68:71], v[154:157], v[194:197], v[68:71]
	v_mfma_i32_16x16x64_i8 v[64:67], v[162:165], v[194:197], v[64:67]
	s_barrier
	ds_read_b128 v[166:169], v153 offset:16384
	ds_read_b128 v[170:173], v153 offset:17408
	ds_read_b128 v[174:177], v153 offset:18432
	ds_read_b128 v[178:181], v153 offset:19456
	ds_read_b128 v[182:185], v153 offset:20480
	ds_read_b128 v[186:189], v153 offset:21504
	ds_read_b128 v[190:193], v153 offset:22528
	ds_read_b128 v[194:197], v153 offset:23552
	s_mov_b32 m0, s81
	s_nop 0
	global_load_lds_dwordx4 v149, s[68:69]
	s_mov_b32 m0, s82
	s_nop 0
	global_load_lds_dwordx4 v151, s[68:69]
	s_add_u32 s4, s68, 0x40000
	s_addc_u32 s5, s69, 0
	s_mov_b32 m0, s83
	s_nop 0
	global_load_lds_dwordx4 v149, s[4:5]
	s_mov_b32 m0, s84
	s_nop 0
	global_load_lds_dwordx4 v151, s[4:5]
	s_mov_b32 m0, s2
	s_nop 0
	global_load_lds_dwordx4 v148, s[62:63]
	s_mov_b32 m0, s85
	s_nop 0
	global_load_lds_dwordx4 v150, s[62:63]
	s_waitcnt vmcnt(8)
	s_waitcnt lgkmcnt(0)
	s_barrier
	s_waitcnt lgkmcnt(7)
	v_mfma_i32_16x16x64_i8 v[60:63], v[128:131], v[166:169], v[60:63]
	v_mfma_i32_16x16x64_i8 v[56:59], v[136:139], v[166:169], v[56:59]
	s_waitcnt lgkmcnt(5)
	v_mfma_i32_16x16x64_i8 v[44:47], v[128:131], v[174:177], v[44:47]
	v_mfma_i32_16x16x64_i8 v[40:43], v[136:139], v[174:177], v[40:43]
	s_waitcnt lgkmcnt(3)
	v_mfma_i32_16x16x64_i8 v[28:31], v[128:131], v[182:185], v[28:31]
	v_mfma_i32_16x16x64_i8 v[24:27], v[136:139], v[182:185], v[24:27]
	s_waitcnt lgkmcnt(1)
	v_mfma_i32_16x16x64_i8 v[12:15], v[128:131], v[190:193], v[12:15]
	v_mfma_i32_16x16x64_i8 v[8:11], v[136:139], v[190:193], v[8:11]
	v_mfma_i32_16x16x64_i8 v[60:63], v[132:135], v[170:173], v[60:63]
	v_mfma_i32_16x16x64_i8 v[56:59], v[140:143], v[170:173], v[56:59]
	v_mfma_i32_16x16x64_i8 v[44:47], v[132:135], v[178:181], v[44:47]
	v_mfma_i32_16x16x64_i8 v[40:43], v[140:143], v[178:181], v[40:43]
	v_mfma_i32_16x16x64_i8 v[28:31], v[132:135], v[186:189], v[28:31]
	v_mfma_i32_16x16x64_i8 v[24:27], v[140:143], v[186:189], v[24:27]
	s_waitcnt lgkmcnt(0)
	v_mfma_i32_16x16x64_i8 v[12:15], v[132:135], v[194:197], v[12:15]
	v_mfma_i32_16x16x64_i8 v[8:11], v[140:143], v[194:197], v[8:11]
	v_mfma_i32_16x16x64_i8 v[52:55], v[144:147], v[166:169], v[52:55]
	v_mfma_i32_16x16x64_i8 v[48:51], v[158:161], v[166:169], v[48:51]
	v_mfma_i32_16x16x64_i8 v[36:39], v[144:147], v[174:177], v[36:39]
	v_mfma_i32_16x16x64_i8 v[32:35], v[158:161], v[174:177], v[32:35]
	v_mfma_i32_16x16x64_i8 v[20:23], v[144:147], v[182:185], v[20:23]
	v_mfma_i32_16x16x64_i8 v[16:19], v[158:161], v[182:185], v[16:19]
	v_mfma_i32_16x16x64_i8 v[4:7], v[144:147], v[190:193], v[4:7]
	v_mfma_i32_16x16x64_i8 v[0:3], v[158:161], v[190:193], v[0:3]
	v_mfma_i32_16x16x64_i8 v[52:55], v[154:157], v[170:173], v[52:55]
	v_mfma_i32_16x16x64_i8 v[48:51], v[162:165], v[170:173], v[48:51]
	v_mfma_i32_16x16x64_i8 v[36:39], v[154:157], v[178:181], v[36:39]
	v_mfma_i32_16x16x64_i8 v[32:35], v[162:165], v[178:181], v[32:35]
	v_mfma_i32_16x16x64_i8 v[20:23], v[154:157], v[186:189], v[20:23]
	v_mfma_i32_16x16x64_i8 v[16:19], v[162:165], v[186:189], v[16:19]
	v_mfma_i32_16x16x64_i8 v[4:7], v[154:157], v[194:197], v[4:7]
	v_mfma_i32_16x16x64_i8 v[0:3], v[162:165], v[194:197], v[0:3]
	s_barrier
; #define PG8_STAGE(bufoff, gbase, voff) do { _Pragma("unroll") for (int _i = 0; _i < 2; ++_i) glds16_s((gbase), (voff)[_i], ldsb + (unsigned)((bufoff) + _i * 8192)); } while (0)
; #define PG8_LDA(dst, b, h) do { _Pragma("unroll") for (int m = 0; m < 4; ++m) _Pragma("unroll") for (int k = 0; k < 2; ++k) dst[m][k] = *(const LAS h16x8*)(lds + PG8_SA(b, h) + aoff + m * 2048 + k * 1024); } while (0)
; #define PG8_LDB(dst, b, h) do { _Pragma("unroll") for (int n = 0; n < 2; ++n) _Pragma("unroll") for (int k = 0; k < 2; ++k) dst[n][k] = *(const LAS h16x8*)(lds + PG8_SB(b, h) + boff + n * 2048 + k * 1024); } while (0)
; #define PG8_MMA(ai, bj, At, Bt) do { __builtin_amdgcn_s_setprio(1); _Pragma("unroll") for (int m = 0; m < 4; ++m) _Pragma("unroll") for (int n = 0; n < 2; ++n) _Pragma("unroll") for (int k = 0; k < 2; ++k) \
;         acc[ai][bj][m][n] = mma_step<I8>(Bt[n][k], At[m][k], acc[ai][bj][m][n]); __builtin_amdgcn_s_setprio(0); } while (0)
; #define PG8_WAIT_V(n) asm volatile("s_waitcnt vmcnt(" #n ")" ::: "memory")
; #define PG8_WAIT_L(n) asm volatile("s_waitcnt lgkmcnt(" #n ")" ::: "memory")
; #define PG8_BAR __builtin_amdgcn_s_barrier()
; #define PG8_SCHED __builtin_amdgcn_sched_barrier(0)
; template <class Prob, class Epi, bool I8 = false, bool ALIGN_EPI = true, bool SP2 = true>
; __device__ __forceinline__ void gemm_phase(LAS unsigned char* lds, int wave, const Prob& P, const Epi& E) {
;     ...
;             PG8_LDB(B0, 1, 0); PG8_LDB(B1, 1, 1); PG8_SCHED; PG8_LDA(At, 1, 0); PG8_STAGE(PG8_SA(0, 1), a2 + hstepA, voffA);
;             PG8_WAIT_V(8); PG8_WAIT_L(0); PG8_BAR; PG8_MMA(0, 0, At, B0); PG8_MMA(0, 1, At, B1); PG8_BAR; PG8_SCHED;
;             PG8_LDA(At, 1, 1); PG8_STAGE(PG8_SB(1, 0), b3, voffB); PG8_STAGE(PG8_SB(1, 1), b3 + hstepB, voffB); PG8_STAGE(PG8_SA(1, 0), a3, voffA);
;             PG8_WAIT_V(8); PG8_WAIT_L(0); PG8_BAR; PG8_MMA(1, 0, At, B0); PG8_MMA(1, 1, At, B1); PG8_BAR; PG8_SCHED;
;     ...
;         if constexpr (ALIGN_EPI) { if (wr == 0) PG8_BAR; }
	v_add_u32_e32 v140, 0x18000, v152
	v_add_u32_e32 v162, 0x1c000, v152
	ds_read_b128 v[128:131], v140
	ds_read_b128 v[132:135], v140 offset:1024
	ds_read_b128 v[136:139], v140 offset:2048
	ds_read_b128 v[140:143], v140 offset:3072
	ds_read_b128 v[144:147], v162
	ds_read_b128 v[154:157], v162 offset:1024
	ds_read_b128 v[158:161], v162 offset:2048
	ds_read_b128 v[162:165], v162 offset:3072
	ds_read_b128 v[166:169], v153 offset:32768
	ds_read_b128 v[170:173], v153 offset:33792
	ds_read_b128 v[174:177], v153 offset:34816
	ds_read_b128 v[178:181], v153 offset:35840
	ds_read_b128 v[182:185], v153 offset:36864
	ds_read_b128 v[186:189], v153 offset:37888
	ds_read_b128 v[190:193], v153 offset:38912
	ds_read_b128 v[194:197], v153 offset:39936
	s_add_u32 s4, s62, 0x40000
	s_addc_u32 s5, s63, 0
	s_mov_b32 m0, s86
	s_nop 0
	global_load_lds_dwordx4 v148, s[4:5]
	s_mov_b32 m0, s87
	s_nop 0
	global_load_lds_dwordx4 v150, s[4:5]
	s_waitcnt vmcnt(8)
	s_waitcnt lgkmcnt(0)
	s_barrier
	s_waitcnt lgkmcnt(7)
	v_mfma_i32_16x16x64_i8 v[124:127], v[128:131], v[166:169], v[124:127]
	v_mfma_i32_16x16x64_i8 v[120:123], v[136:139], v[166:169], v[120:123]
	s_waitcnt lgkmcnt(5)
	v_mfma_i32_16x16x64_i8 v[108:111], v[128:131], v[174:177], v[108:111]
	v_mfma_i32_16x16x64_i8 v[104:107], v[136:139], v[174:177], v[104:107]
	s_waitcnt lgkmcnt(3)
	v_mfma_i32_16x16x64_i8 v[92:95], v[128:131], v[182:185], v[92:95]
	v_mfma_i32_16x16x64_i8 v[88:91], v[136:139], v[182:185], v[88:91]
	s_waitcnt lgkmcnt(1)
	v_mfma_i32_16x16x64_i8 v[76:79], v[128:131], v[190:193], v[76:79]
	v_mfma_i32_16x16x64_i8 v[72:75], v[136:139], v[190:193], v[72:75]
	v_mfma_i32_16x16x64_i8 v[124:127], v[132:135], v[170:173], v[124:127]
	v_mfma_i32_16x16x64_i8 v[120:123], v[140:143], v[170:173], v[120:123]
	v_mfma_i32_16x16x64_i8 v[108:111], v[132:135], v[178:181], v[108:111]
	v_mfma_i32_16x16x64_i8 v[104:107], v[140:143], v[178:181], v[104:107]
	v_mfma_i32_16x16x64_i8 v[92:95], v[132:135], v[186:189], v[92:95]
	v_mfma_i32_16x16x64_i8 v[88:91], v[140:143], v[186:189], v[88:91]
	s_waitcnt lgkmcnt(0)
	v_mfma_i32_16x16x64_i8 v[76:79], v[132:135], v[194:197], v[76:79]
	v_mfma_i32_16x16x64_i8 v[72:75], v[140:143], v[194:197], v[72:75]
	v_mfma_i32_16x16x64_i8 v[116:119], v[144:147], v[166:169], v[116:119]
	v_mfma_i32_16x16x64_i8 v[112:115], v[158:161], v[166:169], v[112:115]
	v_mfma_i32_16x16x64_i8 v[100:103], v[144:147], v[174:177], v[100:103]
	v_mfma_i32_16x16x64_i8 v[96:99], v[158:161], v[174:177], v[96:99]
	v_mfma_i32_16x16x64_i8 v[84:87], v[144:147], v[182:185], v[84:87]
	v_mfma_i32_16x16x64_i8 v[80:83], v[158:161], v[182:185], v[80:83]
	v_mfma_i32_16x16x64_i8 v[68:71], v[144:147], v[190:193], v[68:71]
	v_mfma_i32_16x16x64_i8 v[64:67], v[158:161], v[190:193], v[64:67]
	v_mfma_i32_16x16x64_i8 v[116:119], v[154:157], v[170:173], v[116:119]
	v_mfma_i32_16x16x64_i8 v[112:115], v[162:165], v[170:173], v[112:115]
	v_mfma_i32_16x16x64_i8 v[100:103], v[154:157], v[178:181], v[100:103]
	v_mfma_i32_16x16x64_i8 v[96:99], v[162:165], v[178:181], v[96:99]
	v_mfma_i32_16x16x64_i8 v[84:87], v[154:157], v[186:189], v[84:87]
	v_mfma_i32_16x16x64_i8 v[80:83], v[162:165], v[186:189], v[80:83]
	v_mfma_i32_16x16x64_i8 v[68:71], v[154:157], v[194:197], v[68:71]
	v_mfma_i32_16x16x64_i8 v[64:67], v[162:165], v[194:197], v[64:67]
	s_barrier
	ds_read_b128 v[166:169], v153 offset:49152
	ds_read_b128 v[170:173], v153 offset:50176
	ds_read_b128 v[174:177], v153 offset:51200
	ds_read_b128 v[178:181], v153 offset:52224
	ds_read_b128 v[182:185], v153 offset:53248
	ds_read_b128 v[186:189], v153 offset:54272
	ds_read_b128 v[190:193], v153 offset:55296
	ds_read_b128 v[194:197], v153 offset:56320
	s_add_u32 s4, s68, 0x80
	s_addc_u32 s5, s69, 0
	s_mov_b32 m0, s90
	s_nop 0
	global_load_lds_dwordx4 v149, s[4:5]
	s_mov_b32 m0, s91
	s_nop 0
	global_load_lds_dwordx4 v151, s[4:5]
	s_add_u32 s4, s68, 0x40080
	s_addc_u32 s5, s69, 0
	s_mov_b32 m0, s94
	s_nop 0
	global_load_lds_dwordx4 v149, s[4:5]
	s_mov_b32 m0, s95
	s_nop 0
	global_load_lds_dwordx4 v151, s[4:5]
	s_mov_b32 m0, s92
	s_nop 0
	global_load_lds_dwordx4 v148, s[56:57]
	s_mov_b32 m0, s93
	s_nop 0
	global_load_lds_dwordx4 v150, s[56:57]
	s_waitcnt vmcnt(8)
	s_waitcnt lgkmcnt(0)
	s_barrier
	s_waitcnt lgkmcnt(7)
	v_mfma_i32_16x16x64_i8 v[60:63], v[128:131], v[166:169], v[60:63]
	v_mfma_i32_16x16x64_i8 v[56:59], v[136:139], v[166:169], v[56:59]
	s_waitcnt lgkmcnt(5)
	v_mfma_i32_16x16x64_i8 v[44:47], v[128:131], v[174:177], v[44:47]
	v_mfma_i32_16x16x64_i8 v[40:43], v[136:139], v[174:177], v[40:43]
	s_waitcnt lgkmcnt(3)
	v_mfma_i32_16x16x64_i8 v[28:31], v[128:131], v[182:185], v[28:31]
	v_mfma_i32_16x16x64_i8 v[24:27], v[136:139], v[182:185], v[24:27]
	s_waitcnt lgkmcnt(1)
	v_mfma_i32_16x16x64_i8 v[12:15], v[128:131], v[190:193], v[12:15]
	v_mfma_i32_16x16x64_i8 v[8:11], v[136:139], v[190:193], v[8:11]
	v_mfma_i32_16x16x64_i8 v[60:63], v[132:135], v[170:173], v[60:63]
	v_mfma_i32_16x16x64_i8 v[56:59], v[140:143], v[170:173], v[56:59]
	v_mfma_i32_16x16x64_i8 v[44:47], v[132:135], v[178:181], v[44:47]
	v_mfma_i32_16x16x64_i8 v[40:43], v[140:143], v[178:181], v[40:43]
	v_mfma_i32_16x16x64_i8 v[28:31], v[132:135], v[186:189], v[28:31]
	v_mfma_i32_16x16x64_i8 v[24:27], v[140:143], v[186:189], v[24:27]
	s_waitcnt lgkmcnt(0)
	v_mfma_i32_16x16x64_i8 v[12:15], v[132:135], v[194:197], v[12:15]
	v_mfma_i32_16x16x64_i8 v[8:11], v[140:143], v[194:197], v[8:11]
	v_mfma_i32_16x16x64_i8 v[52:55], v[144:147], v[166:169], v[52:55]
	v_mfma_i32_16x16x64_i8 v[48:51], v[158:161], v[166:169], v[48:51]
	v_mfma_i32_16x16x64_i8 v[36:39], v[144:147], v[174:177], v[36:39]
	v_mfma_i32_16x16x64_i8 v[32:35], v[158:161], v[174:177], v[32:35]
	v_mfma_i32_16x16x64_i8 v[20:23], v[144:147], v[182:185], v[20:23]
	v_mfma_i32_16x16x64_i8 v[16:19], v[158:161], v[182:185], v[16:19]
	v_mfma_i32_16x16x64_i8 v[4:7], v[144:147], v[190:193], v[4:7]
	v_mfma_i32_16x16x64_i8 v[0:3], v[158:161], v[190:193], v[0:3]
	v_mfma_i32_16x16x64_i8 v[52:55], v[154:157], v[170:173], v[52:55]
	v_mfma_i32_16x16x64_i8 v[48:51], v[162:165], v[170:173], v[48:51]
	v_mfma_i32_16x16x64_i8 v[36:39], v[154:157], v[178:181], v[36:39]
	v_mfma_i32_16x16x64_i8 v[32:35], v[162:165], v[178:181], v[32:35]
	v_mfma_i32_16x16x64_i8 v[20:23], v[154:157], v[186:189], v[20:23]
	v_mfma_i32_16x16x64_i8 v[16:19], v[162:165], v[186:189], v[16:19]
	v_mfma_i32_16x16x64_i8 v[4:7], v[154:157], v[194:197], v[4:7]
	v_mfma_i32_16x16x64_i8 v[0:3], v[162:165], v[194:197], v[0:3]
	s_barrier
	s_add_i32 s1, s1, 2
	s_add_u32 s73, s73, 0x100
	s_addc_u32 vcc_lo, vcc_lo, 0
	s_add_u32 vcc_hi, vcc_hi, 0x100
	s_addc_u32 s0, s0, 0
	s_add_u32 s44, s44, 0x100
	s_addc_u32 s45, s45, 0
	s_cmp_gt_u32 s1, 13
	s_cbranch_scc0 .LBB0_616
	s_and_b64 vcc, exec, s[28:29]
	s_cbranch_vccz .LBB0_619
	s_barrier

; __device__ __forceinline__ int mk_lane() { int l; asm volatile("v_mbcnt_lo_u32_b32 %0, -1, 0\n\tv_mbcnt_hi_u32_b32 %0, -1, %0" : "=v"(l)); return l; }
; #define PG8_STAGE(bufoff, gbase, voff) do { _Pragma("unroll") for (int _i = 0; _i < 2; ++_i) glds16_s((gbase), (voff)[_i], ldsb + (unsigned)((bufoff) + _i * 8192)); } while (0)
; #define PG8_WAIT_V(n) asm volatile("s_waitcnt vmcnt(" #n ")" ::: "memory")
; template <class Prob, class Epi, bool I8 = false, bool ALIGN_EPI = true, bool SP2 = true>
; __device__ __forceinline__ void gemm_phase(LAS unsigned char* lds, int wave, const Prob& P, const Epi& E) {
;     const int tid_ = wave * 64 + mk_lane();
;     const int tid = tid_, wid = __builtin_amdgcn_readfirstlane(tid >> 6), lane = tid & 63, wr = wid >> 2, wc = wid & 3, fr = lane & 15, fq = lane >> 4;
;     const int K = P.K, nt = K / BK;
;     unsigned voffA[2], voffB[2];
; #pragma unroll
;     for (int i = 0; i < 2; ++i) { int R, C; stage_rc(tid * 16 + i * 8192, R, C); const int Rb = (R & ~31) + perm32(R & 31);
;         voffA[i] = P.a_rowoff(R) + (unsigned)C * 2u; voffB[i] = P.b_rowoff(Rb) + (unsigned)C * 2u; }
;     const size_t kstep = (size_t)(BK * 2);
;     const size_t hstepA = P.a_hstep(), hstepB = P.b_hstep();
;     const unsigned ldsw = (unsigned)wid * 1024u;
;     const unsigned ldsb = (unsigned)(size_t)lds + ldsw;
;     const int aoff = lds_byte(wr * 64 + fr, fq * 8), boff = lds_byte(wc * 32 + fr, fq * 8);
;     ...
;     Unit cur, nxt; int ui = 0;
;     if (!P.next(0, cur)) return;
;     Acc acc;
; #pragma unroll
;     for (int a = 0; a < 2; ++a)
; #pragma unroll
;         for (int b = 0; b < 2; ++b)
; #pragma unroll
;             for (int m = 0; m < 4; ++m)
; #pragma unroll
;                 for (int n = 0; n < 2; ++n) acc[a][b][m][n] = (f32x4){0.f, 0.f, 0.f, 0.f};
;     h16x8 At[4][2], B0[2][2], B1[2][2];
;     const char* cA = P.a_tile(cur); const char* cB = P.b_tile(cur);
;     if constexpr (SP2) {
;         PG8_STAGE(PG8_SB(0, 0), cB, voffB); PG8_STAGE(PG8_SB(0, 1), cB + hstepB, voffB); PG8_STAGE(PG8_SA(0, 0), cA, voffA); PG8_STAGE(PG8_SA(0, 1), cA + hstepA, voffA);
;         if (wr == 1) PG8_BAR;
;         PG8_WAIT_V(2); PG8_BAR;
;         PG8_STAGE(PG8_SB(1, 0), cB + kstep, voffB); PG8_STAGE(PG8_SA(1, 0), cA + kstep, voffA); PG8_STAGE(PG8_SB(1, 1), cB + hstepB + kstep, voffB);
;         PG8_WAIT_V(6); PG8_BAR;
.LBB0_854:
	v_readlane_b32 s0, v254, 42
	v_readlane_b32 s4, v254, 43
	s_waitcnt lgkmcnt(0)
	s_barrier
	v_mbcnt_lo_u32_b32 v0, -1, 0
	v_mbcnt_hi_u32_b32 v0, -1, v0
	v_readlane_b32 s5, v254, 44
	v_add_u32_e32 v1, s0, v0
	s_and_b64 vcc, exec, s[4:5]
	v_readfirstlane_b32 s0, v1
	s_cbranch_vccz .LBB0_870
	v_ashrrev_i32_e32 v3, 31, v1
	v_lshrrev_b32_e32 v3, 26, v3
	v_lshlrev_b32_e32 v2, 4, v1
	v_add_u32_e32 v3, v1, v3
	v_bfe_i32 v1, v1, 27, 1
	v_lshrrev_b32_e32 v1, 22, v1
	v_add_u32_e32 v1, v2, v1
	v_and_b32_e32 v1, 0xfffffc00, v1
	v_sub_u32_e32 v1, v2, v1
	v_lshrrev_b32_e32 v4, 4, v1
	v_bitop3_b32 v1, v4, v1, 32 bitop3:0x6c
	v_ashrrev_i32_e32 v5, 31, v1
	v_readlane_b32 s1, v253, 52
	v_ashrrev_i32_e32 v3, 6, v3
	v_lshrrev_b32_e32 v5, 26, v5
	s_add_u32 s1, s30, s1
	v_lshlrev_b32_e32 v4, 3, v3
	v_add_u32_e32 v5, v1, v5
	s_addc_u32 s4, s31, 0
	v_and_b32_e32 v4, -16, v4
	v_ashrrev_i32_e32 v6, 6, v5
	v_and_b32_e32 v5, 0xc0, v5
	s_add_u32 s2, s1, 0x8a00000
	v_add_u32_e32 v4, v6, v4
	v_sub_u32_e32 v1, v1, v5
	v_mov_b32_e32 v8, 1
	s_addc_u32 s19, s4, 0
	v_lshlrev_b32_e32 v3, 5, v3
	v_ashrrev_i16_sdwa v1, v8, sext(v1) dst_sel:DWORD dst_unused:UNUSED_PAD src0_sel:DWORD src1_sel:BYTE_0
	v_lshlrev_b32_e32 v5, 1, v4
	v_lshrrev_b32_e32 v7, 2, v4
	v_and_b32_e32 v6, 3, v6
	s_mov_b32 s4, 0xfffe0
	v_and_b32_e32 v3, 32, v3
	v_bfe_i32 v1, v1, 0, 16
	v_and_b32_e32 v5, 24, v5
	v_and_b32_e32 v7, 4, v7
	v_and_or_b32 v6, v4, s4, v6
	v_or3_b32 v5, v6, v7, v5
	v_add_lshl_u32 v1, v3, v1, 1
	v_lshl_add_u32 v142, v4, 12, v1
	v_lshl_add_u32 v143, v5, 12, v1
	v_add_u32_e32 v1, 0x2000, v2
	v_ashrrev_i32_e32 v2, 31, v1
	v_lshrrev_b32_e32 v2, 22, v2
	v_add_u32_e32 v2, v1, v2
	v_ashrrev_i32_e32 v2, 10, v2
	v_mul_i32_i24_e32 v3, 0x400, v2
	v_sub_u32_e32 v1, v1, v3
	v_lshrrev_b32_e32 v3, 4, v1
	v_bitop3_b32 v1, v3, v1, 32 bitop3:0x6c
	v_ashrrev_i32_e32 v4, 31, v1
	v_lshrrev_b32_e32 v4, 26, v4
	v_lshlrev_b32_e32 v3, 3, v2
	v_add_u32_e32 v4, v1, v4
	v_and_b32_e32 v3, -16, v3
	v_ashrrev_i32_e32 v5, 6, v4
	v_add_u32_e32 v3, v5, v3
	v_and_b32_e32 v5, 3, v5
	v_and_b32_e32 v4, 0xc0, v4
	v_and_or_b32 v5, v3, s4, v5
	s_ashr_i32 s4, s0, 6
	v_sub_u32_e32 v1, v1, v4
	s_lshl_b32 s5, s4, 10
	s_ashr_i32 s1, s0, 8
	v_lshlrev_b32_e32 v2, 5, v2
	v_ashrrev_i16_sdwa v1, v8, sext(v1) dst_sel:DWORD dst_unused:UNUSED_PAD src0_sel:DWORD src1_sel:BYTE_0
	v_lshlrev_b32_e32 v4, 1, v3
	v_lshrrev_b32_e32 v6, 2, v3
	s_add_i32 s48, s5, 0
	v_readlane_b32 s6, v252, 32
	v_and_b32_e32 v2, 32, v2
	v_bfe_i32 v1, v1, 0, 16
	v_and_b32_e32 v4, 24, v4
	v_and_b32_e32 v6, 4, v6
	v_readlane_b32 s7, v252, 33
	s_add_u32 s40, s2, s6
	v_or3_b32 v4, v5, v6, v4
	v_add_lshl_u32 v1, v2, v1, 1
	s_addc_u32 s41, s19, s7
	s_add_i32 s49, s48, 0x10000
	s_mov_b32 m0, s49
	s_nop 0
	global_load_lds_dwordx4 v143, s[40:41]
	s_add_i32 s50, s48, 0x12000
	v_lshl_add_u32 v145, v4, 12, v1
	s_mov_b32 m0, s50
	s_nop 0
	global_load_lds_dwordx4 v145, s[40:41]
	s_add_u32 s14, s40, 0x80000
	s_addc_u32 s15, s41, 0
	s_add_i32 s51, s48, 0x14000
	s_mov_b32 m0, s51
	s_nop 0
	global_load_lds_dwordx4 v143, s[14:15]
	s_add_i32 s56, s48, 0x16000
	v_readlane_b32 s6, v252, 38
	s_mov_b32 m0, s56
	s_nop 0
	global_load_lds_dwordx4 v145, s[14:15]
	v_readlane_b32 s7, v252, 39
	s_add_u32 s42, s76, s6
	s_addc_u32 s43, s77, s7
	s_mov_b32 m0, s48
	s_nop 0
	global_load_lds_dwordx4 v142, s[42:43]
	s_add_i32 s57, s48, 0x2000
	v_lshl_add_u32 v144, v3, 12, v1
	s_mov_b32 m0, s57
	s_nop 0
	global_load_lds_dwordx4 v144, s[42:43]
	s_add_u32 s14, s42, 0x80000
	s_addc_u32 s15, s43, 0
	s_add_i32 s60, s48, 0x4000
	s_mov_b32 m0, s60
	s_nop 0
	global_load_lds_dwordx4 v142, s[14:15]
	s_add_i32 s61, s48, 0x6000
	s_mov_b32 m0, s61
	s_nop 0
	global_load_lds_dwordx4 v144, s[14:15]
	s_cmp_eq_u32 s1, 1
	s_cselect_b64 s[14:15], -1, 0
	s_setprio 1
	s_cmp_lg_u32 s1, 1
	s_cbranch_scc1 .LBB0_857
	s_barrier
	s_setprio 0
.LBB0_857:
	v_and_b32_e32 v1, 48, v0
	v_lshlrev_b32_e32 v2, 6, v0
	s_movk_i32 s5, 0x3c0
	v_lshlrev_b32_e32 v0, 2, v0
	s_lshl_b32 s62, s1, 6
	s_lshl_b32 s1, s1, 13
	v_and_or_b32 v1, v2, s5, v1
	v_and_b32_e32 v0, 32, v0
	v_bitop3_b32 v2, v1, s1, v0 bitop3:0xde
	s_lshl_b32 s1, s4, 5
	s_and_b32 s63, s1, 0x60
	s_lshl_b32 s1, s63, 7
	s_add_u32 s4, s40, 0x80
	v_bitop3_b32 v0, s1, v1, v0 bitop3:0xf6
	s_waitcnt vmcnt(2)
	s_barrier
	s_addc_u32 s5, s41, 0
	s_add_i32 s64, s48, 0x18000
	s_mov_b32 m0, s64
	s_nop 0
	global_load_lds_dwordx4 v143, s[4:5]
	s_add_i32 s68, s48, 0x1a000
	s_mov_b32 m0, s68
	s_nop 0
	global_load_lds_dwordx4 v145, s[4:5]
	s_add_u32 s4, s42, 0x80
	s_addc_u32 s5, s43, 0
	s_add_i32 s69, s48, 0x8000
	s_mov_b32 m0, s69
	s_nop 0
	global_load_lds_dwordx4 v142, s[4:5]
	s_add_i32 s72, s48, 0xa000
	s_mov_b32 m0, s72
	s_nop 0
	global_load_lds_dwordx4 v144, s[4:5]
	s_add_u32 s4, s40, 0x80080
	s_addc_u32 s5, s41, 0
	s_add_i32 s73, s48, 0x1c000
	s_mov_b32 m0, s73
	s_nop 0
	global_load_lds_dwordx4 v143, s[4:5]
	s_add_i32 s74, s48, 0x1e000
	s_mov_b32 m0, s74
	s_nop 0
	global_load_lds_dwordx4 v145, s[4:5]
	s_waitcnt vmcnt(6)
	s_add_i32 s75, s48, 0xc000
	s_cmpk_lt_u32 s0, 0x100
	v_readlane_b32 s0, v252, 36
	s_cselect_b64 s[16:17], -1, 0
	s_add_i32 s79, s48, 0xe000
	s_mov_b32 s80, 0
	v_add_u32_e32 v146, 0, v0
	v_add_u32_e32 v147, 0, v2
	v_readlane_b32 s82, v252, 31
	s_mov_b32 s81, s0
	s_barrier
	v_readlane_b32 s1, v252, 37
	s_branch .LBB0_860

; #define PG8_STAGE(bufoff, gbase, voff) do { _Pragma("unroll") for (int _i = 0; _i < 2; ++_i) glds16_s((gbase), (voff)[_i], ldsb + (unsigned)((bufoff) + _i * 8192)); } while (0)
; #define PG8_LDA(dst, b, h) do { _Pragma("unroll") for (int m = 0; m < 4; ++m) _Pragma("unroll") for (int k = 0; k < 2; ++k) dst[m][k] = *(const LAS h16x8*)(lds + PG8_SA(b, h) + aoff + m * 2048 + k * 1024); } while (0)
; #define PG8_LDB(dst, b, h) do { _Pragma("unroll") for (int n = 0; n < 2; ++n) _Pragma("unroll") for (int k = 0; k < 2; ++k) dst[n][k] = *(const LAS h16x8*)(lds + PG8_SB(b, h) + boff + n * 2048 + k * 1024); } while (0)
; #define PG8_MMA(ai, bj, At, Bt) do { __builtin_amdgcn_s_setprio(1); _Pragma("unroll") for (int m = 0; m < 4; ++m) _Pragma("unroll") for (int n = 0; n < 2; ++n) _Pragma("unroll") for (int k = 0; k < 2; ++k) \
;         acc[ai][bj][m][n] = mma_step<I8>(Bt[n][k], At[m][k], acc[ai][bj][m][n]); __builtin_amdgcn_s_setprio(0); } while (0)
; #define PG8_WAIT_V(n) asm volatile("s_waitcnt vmcnt(" #n ")" ::: "memory")
; #define PG8_WAIT_L(n) asm volatile("s_waitcnt lgkmcnt(" #n ")" ::: "memory")
; #define PG8_BAR __builtin_amdgcn_s_barrier()
; #define PG8_SCHED __builtin_amdgcn_sched_barrier(0)
; __device__ __forceinline__ void glds16_s(const void* sbase, unsigned voff, unsigned lds_dst) {
;     unsigned keep;
;     asm volatile("s_mov_b32 %0, m0\n\ts_mov_b32 m0, %3\n\ts_nop 0\n\tglobal_load_lds_dwordx4 %1, %2\n\ts_mov_b32 m0, %0" : "=&s"(keep) : "v"(voff), "s"(sbase), "s"(lds_dst) : "memory");
; }
; template <class Prob, class Epi, bool I8 = false, bool ALIGN_EPI = true, bool SP2 = true>
; __device__ __forceinline__ void gemm_phase(LAS unsigned char* lds, int wave, const Prob& P, const Epi& E) {
;     ...
;             PG8_LDB(B0, 0, 0); PG8_LDB(B1, 0, 1); PG8_SCHED; PG8_LDA(At, 0, 0); PG8_STAGE(PG8_SA(1, 1), a1 + hstepA, voffA);
;             PG8_WAIT_V(8); PG8_WAIT_L(0); PG8_BAR; PG8_MMA(0, 0, At, B0); PG8_MMA(0, 1, At, B1); PG8_BAR; PG8_SCHED;
;             PG8_LDA(At, 0, 1); PG8_STAGE(PG8_SB(0, 0), b2, voffB); PG8_STAGE(PG8_SB(0, 1), b2 + hstepB, voffB); PG8_STAGE(PG8_SA(0, 0), a2, voffA);
;             PG8_WAIT_V(8); PG8_WAIT_L(0); PG8_BAR; PG8_MMA(1, 0, At, B0); PG8_MMA(1, 1, At, B1); PG8_BAR; PG8_SCHED;
.Lpeel_863:
	v_add_u32_e32 v140, 0x10000, v146
	ds_read_b128 v[128:131], v140
	ds_read_b128 v[132:135], v140 offset:1024
	ds_read_b128 v[136:139], v140 offset:2048
	ds_read_b128 v[148:151], v140 offset:3072
	v_add_u32_e32 v140, 0x14000, v146
	ds_read_b128 v[152:155], v140
	ds_read_b128 v[156:159], v140 offset:1024
	ds_read_b128 v[160:163], v140 offset:2048
	ds_read_b128 v[164:167], v140 offset:3072
	s_cmp_eq_u32 s1, 28
	s_cselect_b32 s46, s83, s85
	s_cselect_b32 s47, s27, s86
	s_cselect_b32 s44, s84, s87
	s_cselect_b32 s45, s23, s0
	s_add_u32 s42, s46, 0x80
	s_addc_u32 s43, s47, 0
	ds_read_b128 v[168:171], v147
	ds_read_b128 v[172:175], v147 offset:1024
	ds_read_b128 v[176:179], v147 offset:2048
	ds_read_b128 v[180:183], v147 offset:3072
	ds_read_b128 v[184:187], v147 offset:4096
	ds_read_b128 v[188:191], v147 offset:5120
	ds_read_b128 v[192:195], v147 offset:6144
	ds_read_b128 v[196:199], v147 offset:7168
	s_mov_b32 m0, s75
	s_nop 0
	global_load_lds_dwordx4 v142, s[40:41]
	s_mov_b32 m0, s79
	s_nop 0
	global_load_lds_dwordx4 v144, s[40:41]
	s_waitcnt vmcnt(8)
	s_waitcnt lgkmcnt(0)
	s_barrier
	s_waitcnt lgkmcnt(7)
	v_mfma_f32_16x16x32_f16 v[124:127], v[128:131], v[168:171], 0
	v_mfma_f32_16x16x32_f16 v[120:123], v[136:139], v[168:171], 0
	s_waitcnt lgkmcnt(5)
	v_mfma_f32_16x16x32_f16 v[116:119], v[128:131], v[176:179], 0
	v_mfma_f32_16x16x32_f16 v[112:115], v[136:139], v[176:179], 0
	s_waitcnt lgkmcnt(3)
	v_mfma_f32_16x16x32_f16 v[108:111], v[128:131], v[184:187], 0
	v_mfma_f32_16x16x32_f16 v[104:107], v[136:139], v[184:187], 0
	s_waitcnt lgkmcnt(1)
	v_mfma_f32_16x16x32_f16 v[100:103], v[128:131], v[192:195], 0
	v_mfma_f32_16x16x32_f16 v[96:99], v[136:139], v[192:195], 0
	v_mfma_f32_16x16x32_f16 v[124:127], v[132:135], v[172:175], v[124:127]
	v_mfma_f32_16x16x32_f16 v[120:123], v[148:151], v[172:175], v[120:123]
	v_mfma_f32_16x16x32_f16 v[116:119], v[132:135], v[180:183], v[116:119]
	v_mfma_f32_16x16x32_f16 v[112:115], v[148:151], v[180:183], v[112:115]
	v_mfma_f32_16x16x32_f16 v[108:111], v[132:135], v[188:191], v[108:111]
	v_mfma_f32_16x16x32_f16 v[104:107], v[148:151], v[188:191], v[104:107]
	s_waitcnt lgkmcnt(0)
	v_mfma_f32_16x16x32_f16 v[100:103], v[132:135], v[196:199], v[100:103]
	v_mfma_f32_16x16x32_f16 v[96:99], v[148:151], v[196:199], v[96:99]
	v_mfma_f32_16x16x32_f16 v[64:67], v[152:155], v[168:171], 0
	v_mfma_f32_16x16x32_f16 v[56:59], v[160:163], v[168:171], 0
	v_mfma_f32_16x16x32_f16 v[52:55], v[152:155], v[176:179], 0
	v_mfma_f32_16x16x32_f16 v[48:51], v[160:163], v[176:179], 0
	v_mfma_f32_16x16x32_f16 v[44:47], v[152:155], v[184:187], 0
	v_mfma_f32_16x16x32_f16 v[40:43], v[160:163], v[184:187], 0
	v_mfma_f32_16x16x32_f16 v[36:39], v[152:155], v[192:195], 0
	v_mfma_f32_16x16x32_f16 v[32:35], v[160:163], v[192:195], 0
	v_mfma_f32_16x16x32_f16 v[64:67], v[156:159], v[172:175], v[64:67]
	v_mfma_f32_16x16x32_f16 v[56:59], v[164:167], v[172:175], v[56:59]
	v_mfma_f32_16x16x32_f16 v[52:55], v[156:159], v[180:183], v[52:55]
	v_mfma_f32_16x16x32_f16 v[48:51], v[164:167], v[180:183], v[48:51]
	v_mfma_f32_16x16x32_f16 v[44:47], v[156:159], v[188:191], v[44:47]
	v_mfma_f32_16x16x32_f16 v[40:43], v[164:167], v[188:191], v[40:43]
	v_mfma_f32_16x16x32_f16 v[36:39], v[156:159], v[196:199], v[36:39]
	v_mfma_f32_16x16x32_f16 v[32:35], v[164:167], v[196:199], v[32:35]
	s_barrier
	ds_read_b128 v[168:171], v147 offset:16384
	ds_read_b128 v[172:175], v147 offset:17408
	ds_read_b128 v[176:179], v147 offset:18432
	ds_read_b128 v[180:183], v147 offset:19456
	ds_read_b128 v[184:187], v147 offset:20480
	ds_read_b128 v[188:191], v147 offset:21504
	ds_read_b128 v[192:195], v147 offset:22528
	ds_read_b128 v[196:199], v147 offset:23552
	s_mov_b32 m0, s49
	s_nop 0
	global_load_lds_dwordx4 v143, s[44:45]
	s_mov_b32 m0, s50
	s_nop 0
	global_load_lds_dwordx4 v145, s[44:45]
	s_add_u32 s4, s44, 0x80000
	s_addc_u32 s5, s45, 0
	s_mov_b32 m0, s51
	s_nop 0
	global_load_lds_dwordx4 v143, s[4:5]
	s_mov_b32 m0, s56
	s_nop 0
	global_load_lds_dwordx4 v145, s[4:5]
	s_mov_b32 m0, s48
	s_nop 0
	global_load_lds_dwordx4 v142, s[46:47]
	s_mov_b32 m0, s57
	s_nop 0
	global_load_lds_dwordx4 v144, s[46:47]
	s_waitcnt vmcnt(8)
	s_waitcnt lgkmcnt(0)
	s_barrier
	s_waitcnt lgkmcnt(7)
	v_mfma_f32_16x16x32_f16 v[92:95], v[128:131], v[168:171], 0
	v_mfma_f32_16x16x32_f16 v[88:91], v[136:139], v[168:171], 0
	s_waitcnt lgkmcnt(5)
	v_mfma_f32_16x16x32_f16 v[84:87], v[128:131], v[176:179], 0
	v_mfma_f32_16x16x32_f16 v[80:83], v[136:139], v[176:179], 0
	s_waitcnt lgkmcnt(3)
	v_mfma_f32_16x16x32_f16 v[76:79], v[128:131], v[184:187], 0
	v_mfma_f32_16x16x32_f16 v[72:75], v[136:139], v[184:187], 0
	s_waitcnt lgkmcnt(1)
	v_mfma_f32_16x16x32_f16 v[68:71], v[128:131], v[192:195], 0
	v_mfma_f32_16x16x32_f16 v[60:63], v[136:139], v[192:195], 0
	v_mfma_f32_16x16x32_f16 v[92:95], v[132:135], v[172:175], v[92:95]
	v_mfma_f32_16x16x32_f16 v[88:91], v[148:151], v[172:175], v[88:91]
	v_mfma_f32_16x16x32_f16 v[84:87], v[132:135], v[180:183], v[84:87]
	v_mfma_f32_16x16x32_f16 v[80:83], v[148:151], v[180:183], v[80:83]
	v_mfma_f32_16x16x32_f16 v[76:79], v[132:135], v[188:191], v[76:79]
	v_mfma_f32_16x16x32_f16 v[72:75], v[148:151], v[188:191], v[72:75]
	s_waitcnt lgkmcnt(0)
	v_mfma_f32_16x16x32_f16 v[68:71], v[132:135], v[196:199], v[68:71]
	v_mfma_f32_16x16x32_f16 v[60:63], v[148:151], v[196:199], v[60:63]
	v_mfma_f32_16x16x32_f16 v[28:31], v[152:155], v[168:171], 0
	v_mfma_f32_16x16x32_f16 v[24:27], v[160:163], v[168:171], 0
	v_mfma_f32_16x16x32_f16 v[20:23], v[152:155], v[176:179], 0
	v_mfma_f32_16x16x32_f16 v[16:19], v[160:163], v[176:179], 0
	v_mfma_f32_16x16x32_f16 v[12:15], v[152:155], v[184:187], 0
	v_mfma_f32_16x16x32_f16 v[8:11], v[160:163], v[184:187], 0
	v_mfma_f32_16x16x32_f16 v[4:7], v[152:155], v[192:195], 0
	v_mfma_f32_16x16x32_f16 v[0:3], v[160:163], v[192:195], 0
	v_mfma_f32_16x16x32_f16 v[28:31], v[156:159], v[172:175], v[28:31]
	v_mfma_f32_16x16x32_f16 v[24:27], v[164:167], v[172:175], v[24:27]
	v_mfma_f32_16x16x32_f16 v[20:23], v[156:159], v[180:183], v[20:23]
	v_mfma_f32_16x16x32_f16 v[16:19], v[164:167], v[180:183], v[16:19]
	v_mfma_f32_16x16x32_f16 v[12:15], v[156:159], v[188:191], v[12:15]
	v_mfma_f32_16x16x32_f16 v[8:11], v[164:167], v[188:191], v[8:11]
	v_mfma_f32_16x16x32_f16 v[4:7], v[156:159], v[196:199], v[4:7]
	v_mfma_f32_16x16x32_f16 v[0:3], v[164:167], v[196:199], v[0:3]
	s_barrier
; #define PG8_STAGE(bufoff, gbase, voff) do { _Pragma("unroll") for (int _i = 0; _i < 2; ++_i) glds16_s((gbase), (voff)[_i], ldsb + (unsigned)((bufoff) + _i * 8192)); } while (0)
; #define PG8_LDA(dst, b, h) do { _Pragma("unroll") for (int m = 0; m < 4; ++m) _Pragma("unroll") for (int k = 0; k < 2; ++k) dst[m][k] = *(const LAS h16x8*)(lds + PG8_SA(b, h) + aoff + m * 2048 + k * 1024); } while (0)
; #define PG8_LDB(dst, b, h) do { _Pragma("unroll") for (int n = 0; n < 2; ++n) _Pragma("unroll") for (int k = 0; k < 2; ++k) dst[n][k] = *(const LAS h16x8*)(lds + PG8_SB(b, h) + boff + n * 2048 + k * 1024); } while (0)
; #define PG8_MMA(ai, bj, At, Bt) do { __builtin_amdgcn_s_setprio(1); _Pragma("unroll") for (int m = 0; m < 4; ++m) _Pragma("unroll") for (int n = 0; n < 2; ++n) _Pragma("unroll") for (int k = 0; k < 2; ++k) \
;         acc[ai][bj][m][n] = mma_step<I8>(Bt[n][k], At[m][k], acc[ai][bj][m][n]); __builtin_amdgcn_s_setprio(0); } while (0)
; #define PG8_WAIT_V(n) asm volatile("s_waitcnt vmcnt(" #n ")" ::: "memory")
; #define PG8_WAIT_L(n) asm volatile("s_waitcnt lgkmcnt(" #n ")" ::: "memory")
; #define PG8_BAR __builtin_amdgcn_s_barrier()
; #define PG8_SCHED __builtin_amdgcn_sched_barrier(0)
; __device__ __forceinline__ void glds16_s(const void* sbase, unsigned voff, unsigned lds_dst) {
;     unsigned keep;
;     asm volatile("s_mov_b32 %0, m0\n\ts_mov_b32 m0, %3\n\ts_nop 0\n\tglobal_load_lds_dwordx4 %1, %2\n\ts_mov_b32 m0, %0" : "=&s"(keep) : "v"(voff), "s"(sbase), "s"(lds_dst) : "memory");
; }
; template <class Prob, class Epi, bool I8 = false, bool ALIGN_EPI = true, bool SP2 = true>
; __device__ __forceinline__ void gemm_phase(LAS unsigned char* lds, int wave, const Prob& P, const Epi& E) {
;     ...
;             PG8_LDB(B0, 1, 0); PG8_LDB(B1, 1, 1); PG8_SCHED; PG8_LDA(At, 1, 0); PG8_STAGE(PG8_SA(0, 1), a2 + hstepA, voffA);
;             PG8_WAIT_V(8); PG8_WAIT_L(0); PG8_BAR; PG8_MMA(0, 0, At, B0); PG8_MMA(0, 1, At, B1); PG8_BAR; PG8_SCHED;
;             PG8_LDA(At, 1, 1); PG8_STAGE(PG8_SB(1, 0), b3, voffB); PG8_STAGE(PG8_SB(1, 1), b3 + hstepB, voffB); PG8_STAGE(PG8_SA(1, 0), a3, voffA);
;             PG8_WAIT_V(8); PG8_WAIT_L(0); PG8_BAR; PG8_MMA(1, 0, At, B0); PG8_MMA(1, 1, At, B1); PG8_BAR; PG8_SCHED;
	v_add_u32_e32 v140, 0x18000, v146
	ds_read_b128 v[128:131], v140
	ds_read_b128 v[132:135], v140 offset:1024
	ds_read_b128 v[136:139], v140 offset:2048
	ds_read_b128 v[148:151], v140 offset:3072
	v_add_u32_e32 v140, 0x1c000, v146
	ds_read_b128 v[152:155], v140
	ds_read_b128 v[156:159], v140 offset:1024
	ds_read_b128 v[160:163], v140 offset:2048
	ds_read_b128 v[164:167], v140 offset:3072
	ds_read_b128 v[168:171], v147 offset:32768
	ds_read_b128 v[172:175], v147 offset:33792
	ds_read_b128 v[176:179], v147 offset:34816
	ds_read_b128 v[180:183], v147 offset:35840
	ds_read_b128 v[184:187], v147 offset:36864
	ds_read_b128 v[188:191], v147 offset:37888
	ds_read_b128 v[192:195], v147 offset:38912
	ds_read_b128 v[196:199], v147 offset:39936
	s_add_u32 s4, s46, 0x80000
	s_addc_u32 s5, s47, 0
	s_mov_b32 m0, s60
	s_nop 0
	global_load_lds_dwordx4 v142, s[4:5]
	s_mov_b32 m0, s61
	s_nop 0
	global_load_lds_dwordx4 v144, s[4:5]
	s_waitcnt vmcnt(8)
	s_waitcnt lgkmcnt(0)
	s_barrier
	s_waitcnt lgkmcnt(7)
	v_mfma_f32_16x16x32_f16 v[124:127], v[128:131], v[168:171], v[124:127]
	v_mfma_f32_16x16x32_f16 v[120:123], v[136:139], v[168:171], v[120:123]
	s_waitcnt lgkmcnt(5)
	v_mfma_f32_16x16x32_f16 v[116:119], v[128:131], v[176:179], v[116:119]
	v_mfma_f32_16x16x32_f16 v[112:115], v[136:139], v[176:179], v[112:115]
	s_waitcnt lgkmcnt(3)
	v_mfma_f32_16x16x32_f16 v[108:111], v[128:131], v[184:187], v[108:111]
	v_mfma_f32_16x16x32_f16 v[104:107], v[136:139], v[184:187], v[104:107]
	s_waitcnt lgkmcnt(1)
	v_mfma_f32_16x16x32_f16 v[100:103], v[128:131], v[192:195], v[100:103]
	v_mfma_f32_16x16x32_f16 v[96:99], v[136:139], v[192:195], v[96:99]
	v_mfma_f32_16x16x32_f16 v[124:127], v[132:135], v[172:175], v[124:127]
	v_mfma_f32_16x16x32_f16 v[120:123], v[148:151], v[172:175], v[120:123]
	v_mfma_f32_16x16x32_f16 v[116:119], v[132:135], v[180:183], v[116:119]
	v_mfma_f32_16x16x32_f16 v[112:115], v[148:151], v[180:183], v[112:115]
	v_mfma_f32_16x16x32_f16 v[108:111], v[132:135], v[188:191], v[108:111]
	v_mfma_f32_16x16x32_f16 v[104:107], v[148:151], v[188:191], v[104:107]
	s_waitcnt lgkmcnt(0)
	v_mfma_f32_16x16x32_f16 v[100:103], v[132:135], v[196:199], v[100:103]
	v_mfma_f32_16x16x32_f16 v[96:99], v[148:151], v[196:199], v[96:99]
	v_mfma_f32_16x16x32_f16 v[64:67], v[152:155], v[168:171], v[64:67]
	v_mfma_f32_16x16x32_f16 v[56:59], v[160:163], v[168:171], v[56:59]
	v_mfma_f32_16x16x32_f16 v[52:55], v[152:155], v[176:179], v[52:55]
	v_mfma_f32_16x16x32_f16 v[48:51], v[160:163], v[176:179], v[48:51]
	v_mfma_f32_16x16x32_f16 v[44:47], v[152:155], v[184:187], v[44:47]
	v_mfma_f32_16x16x32_f16 v[40:43], v[160:163], v[184:187], v[40:43]
	v_mfma_f32_16x16x32_f16 v[36:39], v[152:155], v[192:195], v[36:39]
	v_mfma_f32_16x16x32_f16 v[32:35], v[160:163], v[192:195], v[32:35]
	v_mfma_f32_16x16x32_f16 v[64:67], v[156:159], v[172:175], v[64:67]
	v_mfma_f32_16x16x32_f16 v[56:59], v[164:167], v[172:175], v[56:59]
	v_mfma_f32_16x16x32_f16 v[52:55], v[156:159], v[180:183], v[52:55]
	v_mfma_f32_16x16x32_f16 v[48:51], v[164:167], v[180:183], v[48:51]
	v_mfma_f32_16x16x32_f16 v[44:47], v[156:159], v[188:191], v[44:47]
	v_mfma_f32_16x16x32_f16 v[40:43], v[164:167], v[188:191], v[40:43]
	v_mfma_f32_16x16x32_f16 v[36:39], v[156:159], v[196:199], v[36:39]
	v_mfma_f32_16x16x32_f16 v[32:35], v[164:167], v[196:199], v[32:35]
	s_barrier
	ds_read_b128 v[168:171], v147 offset:49152
	ds_read_b128 v[172:175], v147 offset:50176
	ds_read_b128 v[176:179], v147 offset:51200
	ds_read_b128 v[180:183], v147 offset:52224
	ds_read_b128 v[184:187], v147 offset:53248
	ds_read_b128 v[188:191], v147 offset:54272
	ds_read_b128 v[192:195], v147 offset:55296
	ds_read_b128 v[196:199], v147 offset:56320
	s_add_u32 s4, s44, 0x80
	s_addc_u32 s5, s45, 0
	s_mov_b32 m0, s64
	s_nop 0
	global_load_lds_dwordx4 v143, s[4:5]
	s_mov_b32 m0, s68
	s_nop 0
	global_load_lds_dwordx4 v145, s[4:5]
	s_add_u32 s4, s44, 0x80080
	s_addc_u32 s5, s45, 0
	s_mov_b32 m0, s73
	s_nop 0
	global_load_lds_dwordx4 v143, s[4:5]
	s_mov_b32 m0, s74
	s_nop 0
	global_load_lds_dwordx4 v145, s[4:5]
	s_mov_b32 m0, s69
	s_nop 0
	global_load_lds_dwordx4 v142, s[42:43]
	s_mov_b32 m0, s72
	s_nop 0
	global_load_lds_dwordx4 v144, s[42:43]
	s_waitcnt vmcnt(8)
	s_waitcnt lgkmcnt(0)
	s_barrier
	s_waitcnt lgkmcnt(7)
	v_mfma_f32_16x16x32_f16 v[92:95], v[128:131], v[168:171], v[92:95]
	v_mfma_f32_16x16x32_f16 v[88:91], v[136:139], v[168:171], v[88:91]
	s_waitcnt lgkmcnt(5)
	v_mfma_f32_16x16x32_f16 v[84:87], v[128:131], v[176:179], v[84:87]
	v_mfma_f32_16x16x32_f16 v[80:83], v[136:139], v[176:179], v[80:83]
	s_waitcnt lgkmcnt(3)
	v_mfma_f32_16x16x32_f16 v[76:79], v[128:131], v[184:187], v[76:79]
	v_mfma_f32_16x16x32_f16 v[72:75], v[136:139], v[184:187], v[72:75]
	s_waitcnt lgkmcnt(1)
	v_mfma_f32_16x16x32_f16 v[68:71], v[128:131], v[192:195], v[68:71]
	v_mfma_f32_16x16x32_f16 v[60:63], v[136:139], v[192:195], v[60:63]
	v_mfma_f32_16x16x32_f16 v[92:95], v[132:135], v[172:175], v[92:95]
	v_mfma_f32_16x16x32_f16 v[88:91], v[148:151], v[172:175], v[88:91]
	v_mfma_f32_16x16x32_f16 v[84:87], v[132:135], v[180:183], v[84:87]
	v_mfma_f32_16x16x32_f16 v[80:83], v[148:151], v[180:183], v[80:83]
	v_mfma_f32_16x16x32_f16 v[76:79], v[132:135], v[188:191], v[76:79]
	v_mfma_f32_16x16x32_f16 v[72:75], v[148:151], v[188:191], v[72:75]
	s_waitcnt lgkmcnt(0)
	v_mfma_f32_16x16x32_f16 v[68:71], v[132:135], v[196:199], v[68:71]
	v_mfma_f32_16x16x32_f16 v[60:63], v[148:151], v[196:199], v[60:63]
	v_mfma_f32_16x16x32_f16 v[28:31], v[152:155], v[168:171], v[28:31]
	v_mfma_f32_16x16x32_f16 v[24:27], v[160:163], v[168:171], v[24:27]
	v_mfma_f32_16x16x32_f16 v[20:23], v[152:155], v[176:179], v[20:23]
	v_mfma_f32_16x16x32_f16 v[16:19], v[160:163], v[176:179], v[16:19]
	v_mfma_f32_16x16x32_f16 v[12:15], v[152:155], v[184:187], v[12:15]
	v_mfma_f32_16x16x32_f16 v[8:11], v[160:163], v[184:187], v[8:11]
	v_mfma_f32_16x16x32_f16 v[4:7], v[152:155], v[192:195], v[4:7]
	v_mfma_f32_16x16x32_f16 v[0:3], v[160:163], v[192:195], v[0:3]
	v_mfma_f32_16x16x32_f16 v[28:31], v[156:159], v[172:175], v[28:31]
	v_mfma_f32_16x16x32_f16 v[24:27], v[164:167], v[172:175], v[24:27]
	v_mfma_f32_16x16x32_f16 v[20:23], v[156:159], v[180:183], v[20:23]
	v_mfma_f32_16x16x32_f16 v[16:19], v[164:167], v[180:183], v[16:19]
	v_mfma_f32_16x16x32_f16 v[12:15], v[156:159], v[188:191], v[12:15]
	v_mfma_f32_16x16x32_f16 v[8:11], v[164:167], v[188:191], v[8:11]
	v_mfma_f32_16x16x32_f16 v[4:7], v[156:159], v[196:199], v[4:7]
	v_mfma_f32_16x16x32_f16 v[0:3], v[164:167], v[196:199], v[0:3]
	s_barrier
	s_add_i32 s1, s1, 2
	s_add_u32 s85, s85, 0x100
	s_addc_u32 s86, s86, 0
	s_add_u32 s87, s87, 0x100
	s_addc_u32 s0, s0, 0
	s_add_u32 s40, s40, 0x100
	s_addc_u32 s41, s41, 0
	s_cmp_gt_u32 s1, 29
; #define PG8_STAGE(bufoff, gbase, voff) do { _Pragma("unroll") for (int _i = 0; _i < 2; ++_i) glds16_s((gbase), (voff)[_i], ldsb + (unsigned)((bufoff) + _i * 8192)); } while (0)
; #define PG8_LDA(dst, b, h) do { _Pragma("unroll") for (int m = 0; m < 4; ++m) _Pragma("unroll") for (int k = 0; k < 2; ++k) dst[m][k] = *(const LAS h16x8*)(lds + PG8_SA(b, h) + aoff + m * 2048 + k * 1024); } while (0)
; #define PG8_LDB(dst, b, h) do { _Pragma("unroll") for (int n = 0; n < 2; ++n) _Pragma("unroll") for (int k = 0; k < 2; ++k) dst[n][k] = *(const LAS h16x8*)(lds + PG8_SB(b, h) + boff + n * 2048 + k * 1024); } while (0)
; #define PG8_MMA(ai, bj, At, Bt) do { __builtin_amdgcn_s_setprio(1); _Pragma("unroll") for (int m = 0; m < 4; ++m) _Pragma("unroll") for (int n = 0; n < 2; ++n) _Pragma("unroll") for (int k = 0; k < 2; ++k) \
;         acc[ai][bj][m][n] = mma_step<I8>(Bt[n][k], At[m][k], acc[ai][bj][m][n]); __builtin_amdgcn_s_setprio(0); } while (0)
; #define PG8_WAIT_V(n) asm volatile("s_waitcnt vmcnt(" #n ")" ::: "memory")
; #define PG8_WAIT_L(n) asm volatile("s_waitcnt lgkmcnt(" #n ")" ::: "memory")
; #define PG8_BAR __builtin_amdgcn_s_barrier()
; #define PG8_SCHED __builtin_amdgcn_sched_barrier(0)
; __device__ __forceinline__ void glds16_s(const void* sbase, unsigned voff, unsigned lds_dst) {
;     unsigned keep;
;     asm volatile("s_mov_b32 %0, m0\n\ts_mov_b32 m0, %3\n\ts_nop 0\n\tglobal_load_lds_dwordx4 %1, %2\n\ts_mov_b32 m0, %0" : "=&s"(keep) : "v"(voff), "s"(sbase), "s"(lds_dst) : "memory");
; }
; template <class Prob, class Epi, bool I8 = false, bool ALIGN_EPI = true, bool SP2 = true>
; __device__ __forceinline__ void gemm_phase(LAS unsigned char* lds, int wave, const Prob& P, const Epi& E) {
;     ...
;             PG8_LDB(B0, 0, 0); PG8_LDB(B1, 0, 1); PG8_SCHED; PG8_LDA(At, 0, 0); PG8_STAGE(PG8_SA(1, 1), a1 + hstepA, voffA);
;             PG8_WAIT_V(8); PG8_WAIT_L(0); PG8_BAR; PG8_MMA(0, 0, At, B0); PG8_MMA(0, 1, At, B1); PG8_BAR; PG8_SCHED;
;             PG8_LDA(At, 0, 1); PG8_STAGE(PG8_SB(0, 0), b2, voffB); PG8_STAGE(PG8_SB(0, 1), b2 + hstepB, voffB); PG8_STAGE(PG8_SA(0, 0), a2, voffA);
;             PG8_WAIT_V(8); PG8_WAIT_L(0); PG8_BAR; PG8_MMA(1, 0, At, B0); PG8_MMA(1, 1, At, B1); PG8_BAR; PG8_SCHED;
.LBB0_863:
	v_add_u32_e32 v140, 0x10000, v146
	ds_read_b128 v[128:131], v140
	ds_read_b128 v[132:135], v140 offset:1024
	ds_read_b128 v[136:139], v140 offset:2048
	ds_read_b128 v[148:151], v140 offset:3072
	v_add_u32_e32 v140, 0x14000, v146
	ds_read_b128 v[152:155], v140
	ds_read_b128 v[156:159], v140 offset:1024
	ds_read_b128 v[160:163], v140 offset:2048
	ds_read_b128 v[164:167], v140 offset:3072
	s_cmp_eq_u32 s1, 28
	s_cselect_b32 s46, s83, s85
	s_cselect_b32 s47, s27, s86
	s_cselect_b32 s44, s84, s87
	s_cselect_b32 s45, s23, s0
	s_add_u32 s42, s46, 0x80
	s_addc_u32 s43, s47, 0
	ds_read_b128 v[168:171], v147
	ds_read_b128 v[172:175], v147 offset:1024
	ds_read_b128 v[176:179], v147 offset:2048
	ds_read_b128 v[180:183], v147 offset:3072
	ds_read_b128 v[184:187], v147 offset:4096
	ds_read_b128 v[188:191], v147 offset:5120
	ds_read_b128 v[192:195], v147 offset:6144
	ds_read_b128 v[196:199], v147 offset:7168
	s_mov_b32 m0, s75
	s_nop 0
	global_load_lds_dwordx4 v142, s[40:41]
	s_mov_b32 m0, s79
	s_nop 0
	global_load_lds_dwordx4 v144, s[40:41]
	s_waitcnt vmcnt(8)
	s_waitcnt lgkmcnt(0)
	s_barrier
	s_waitcnt lgkmcnt(7)
	v_mfma_f32_16x16x32_f16 v[124:127], v[128:131], v[168:171], v[124:127]
	v_mfma_f32_16x16x32_f16 v[120:123], v[136:139], v[168:171], v[120:123]
	s_waitcnt lgkmcnt(5)
	v_mfma_f32_16x16x32_f16 v[116:119], v[128:131], v[176:179], v[116:119]
	v_mfma_f32_16x16x32_f16 v[112:115], v[136:139], v[176:179], v[112:115]
	s_waitcnt lgkmcnt(3)
	v_mfma_f32_16x16x32_f16 v[108:111], v[128:131], v[184:187], v[108:111]
	v_mfma_f32_16x16x32_f16 v[104:107], v[136:139], v[184:187], v[104:107]
	s_waitcnt lgkmcnt(1)
	v_mfma_f32_16x16x32_f16 v[100:103], v[128:131], v[192:195], v[100:103]
	v_mfma_f32_16x16x32_f16 v[96:99], v[136:139], v[192:195], v[96:99]
	v_mfma_f32_16x16x32_f16 v[124:127], v[132:135], v[172:175], v[124:127]
	v_mfma_f32_16x16x32_f16 v[120:123], v[148:151], v[172:175], v[120:123]
	v_mfma_f32_16x16x32_f16 v[116:119], v[132:135], v[180:183], v[116:119]
	v_mfma_f32_16x16x32_f16 v[112:115], v[148:151], v[180:183], v[112:115]
	v_mfma_f32_16x16x32_f16 v[108:111], v[132:135], v[188:191], v[108:111]
	v_mfma_f32_16x16x32_f16 v[104:107], v[148:151], v[188:191], v[104:107]
	s_waitcnt lgkmcnt(0)
	v_mfma_f32_16x16x32_f16 v[100:103], v[132:135], v[196:199], v[100:103]
	v_mfma_f32_16x16x32_f16 v[96:99], v[148:151], v[196:199], v[96:99]
	v_mfma_f32_16x16x32_f16 v[64:67], v[152:155], v[168:171], v[64:67]
	v_mfma_f32_16x16x32_f16 v[56:59], v[160:163], v[168:171], v[56:59]
	v_mfma_f32_16x16x32_f16 v[52:55], v[152:155], v[176:179], v[52:55]
	v_mfma_f32_16x16x32_f16 v[48:51], v[160:163], v[176:179], v[48:51]
	v_mfma_f32_16x16x32_f16 v[44:47], v[152:155], v[184:187], v[44:47]
	v_mfma_f32_16x16x32_f16 v[40:43], v[160:163], v[184:187], v[40:43]
	v_mfma_f32_16x16x32_f16 v[36:39], v[152:155], v[192:195], v[36:39]
	v_mfma_f32_16x16x32_f16 v[32:35], v[160:163], v[192:195], v[32:35]
	v_mfma_f32_16x16x32_f16 v[64:67], v[156:159], v[172:175], v[64:67]
	v_mfma_f32_16x16x32_f16 v[56:59], v[164:167], v[172:175], v[56:59]
	v_mfma_f32_16x16x32_f16 v[52:55], v[156:159], v[180:183], v[52:55]
	v_mfma_f32_16x16x32_f16 v[48:51], v[164:167], v[180:183], v[48:51]
	v_mfma_f32_16x16x32_f16 v[44:47], v[156:159], v[188:191], v[44:47]
	v_mfma_f32_16x16x32_f16 v[40:43], v[164:167], v[188:191], v[40:43]
	v_mfma_f32_16x16x32_f16 v[36:39], v[156:159], v[196:199], v[36:39]
	v_mfma_f32_16x16x32_f16 v[32:35], v[164:167], v[196:199], v[32:35]
	s_barrier
	ds_read_b128 v[168:171], v147 offset:16384
	ds_read_b128 v[172:175], v147 offset:17408
	ds_read_b128 v[176:179], v147 offset:18432
	ds_read_b128 v[180:183], v147 offset:19456
	ds_read_b128 v[184:187], v147 offset:20480
	ds_read_b128 v[188:191], v147 offset:21504
	ds_read_b128 v[192:195], v147 offset:22528
	ds_read_b128 v[196:199], v147 offset:23552
	s_mov_b32 m0, s49
	s_nop 0
	global_load_lds_dwordx4 v143, s[44:45]
	s_mov_b32 m0, s50
	s_nop 0
	global_load_lds_dwordx4 v145, s[44:45]
	s_add_u32 s4, s44, 0x80000
	s_addc_u32 s5, s45, 0
	s_mov_b32 m0, s51
	s_nop 0
	global_load_lds_dwordx4 v143, s[4:5]
	s_mov_b32 m0, s56
	s_nop 0
	global_load_lds_dwordx4 v145, s[4:5]
	s_mov_b32 m0, s48
	s_nop 0
	global_load_lds_dwordx4 v142, s[46:47]
	s_mov_b32 m0, s57
	s_nop 0
	global_load_lds_dwordx4 v144, s[46:47]
	s_waitcnt vmcnt(8)
	s_waitcnt lgkmcnt(0)
	s_barrier
	s_waitcnt lgkmcnt(7)
	v_mfma_f32_16x16x32_f16 v[92:95], v[128:131], v[168:171], v[92:95]
	v_mfma_f32_16x16x32_f16 v[88:91], v[136:139], v[168:171], v[88:91]
	s_waitcnt lgkmcnt(5)
	v_mfma_f32_16x16x32_f16 v[84:87], v[128:131], v[176:179], v[84:87]
	v_mfma_f32_16x16x32_f16 v[80:83], v[136:139], v[176:179], v[80:83]
	s_waitcnt lgkmcnt(3)
	v_mfma_f32_16x16x32_f16 v[76:79], v[128:131], v[184:187], v[76:79]
	v_mfma_f32_16x16x32_f16 v[72:75], v[136:139], v[184:187], v[72:75]
	s_waitcnt lgkmcnt(1)
	v_mfma_f32_16x16x32_f16 v[68:71], v[128:131], v[192:195], v[68:71]
	v_mfma_f32_16x16x32_f16 v[60:63], v[136:139], v[192:195], v[60:63]
	v_mfma_f32_16x16x32_f16 v[92:95], v[132:135], v[172:175], v[92:95]
	v_mfma_f32_16x16x32_f16 v[88:91], v[148:151], v[172:175], v[88:91]
	v_mfma_f32_16x16x32_f16 v[84:87], v[132:135], v[180:183], v[84:87]
	v_mfma_f32_16x16x32_f16 v[80:83], v[148:151], v[180:183], v[80:83]
	v_mfma_f32_16x16x32_f16 v[76:79], v[132:135], v[188:191], v[76:79]
	v_mfma_f32_16x16x32_f16 v[72:75], v[148:151], v[188:191], v[72:75]
	s_waitcnt lgkmcnt(0)
	v_mfma_f32_16x16x32_f16 v[68:71], v[132:135], v[196:199], v[68:71]
	v_mfma_f32_16x16x32_f16 v[60:63], v[148:151], v[196:199], v[60:63]
	v_mfma_f32_16x16x32_f16 v[28:31], v[152:155], v[168:171], v[28:31]
	v_mfma_f32_16x16x32_f16 v[24:27], v[160:163], v[168:171], v[24:27]
	v_mfma_f32_16x16x32_f16 v[20:23], v[152:155], v[176:179], v[20:23]
	v_mfma_f32_16x16x32_f16 v[16:19], v[160:163], v[176:179], v[16:19]
	v_mfma_f32_16x16x32_f16 v[12:15], v[152:155], v[184:187], v[12:15]
	v_mfma_f32_16x16x32_f16 v[8:11], v[160:163], v[184:187], v[8:11]
	v_mfma_f32_16x16x32_f16 v[4:7], v[152:155], v[192:195], v[4:7]
	v_mfma_f32_16x16x32_f16 v[0:3], v[160:163], v[192:195], v[0:3]
	v_mfma_f32_16x16x32_f16 v[28:31], v[156:159], v[172:175], v[28:31]
	v_mfma_f32_16x16x32_f16 v[24:27], v[164:167], v[172:175], v[24:27]
	v_mfma_f32_16x16x32_f16 v[20:23], v[156:159], v[180:183], v[20:23]
	v_mfma_f32_16x16x32_f16 v[16:19], v[164:167], v[180:183], v[16:19]
	v_mfma_f32_16x16x32_f16 v[12:15], v[156:159], v[188:191], v[12:15]
	v_mfma_f32_16x16x32_f16 v[8:11], v[164:167], v[188:191], v[8:11]
	v_mfma_f32_16x16x32_f16 v[4:7], v[156:159], v[196:199], v[4:7]
	v_mfma_f32_16x16x32_f16 v[0:3], v[164:167], v[196:199], v[0:3]
	s_barrier
; #define PG8_STAGE(bufoff, gbase, voff) do { _Pragma("unroll") for (int _i = 0; _i < 2; ++_i) glds16_s((gbase), (voff)[_i], ldsb + (unsigned)((bufoff) + _i * 8192)); } while (0)
; #define PG8_LDA(dst, b, h) do { _Pragma("unroll") for (int m = 0; m < 4; ++m) _Pragma("unroll") for (int k = 0; k < 2; ++k) dst[m][k] = *(const LAS h16x8*)(lds + PG8_SA(b, h) + aoff + m * 2048 + k * 1024); } while (0)
; #define PG8_LDB(dst, b, h) do { _Pragma("unroll") for (int n = 0; n < 2; ++n) _Pragma("unroll") for (int k = 0; k < 2; ++k) dst[n][k] = *(const LAS h16x8*)(lds + PG8_SB(b, h) + boff + n * 2048 + k * 1024); } while (0)
; #define PG8_MMA(ai, bj, At, Bt) do { __builtin_amdgcn_s_setprio(1); _Pragma("unroll") for (int m = 0; m < 4; ++m) _Pragma("unroll") for (int n = 0; n < 2; ++n) _Pragma("unroll") for (int k = 0; k < 2; ++k) \
;         acc[ai][bj][m][n] = mma_step<I8>(Bt[n][k], At[m][k], acc[ai][bj][m][n]); __builtin_amdgcn_s_setprio(0); } while (0)
; #define PG8_WAIT_V(n) asm volatile("s_waitcnt vmcnt(" #n ")" ::: "memory")
; #define PG8_WAIT_L(n) asm volatile("s_waitcnt lgkmcnt(" #n ")" ::: "memory")
; #define PG8_BAR __builtin_amdgcn_s_barrier()
; #define PG8_SCHED __builtin_amdgcn_sched_barrier(0)
; __device__ __forceinline__ void glds16_s(const void* sbase, unsigned voff, unsigned lds_dst) {
;     unsigned keep;
;     asm volatile("s_mov_b32 %0, m0\n\ts_mov_b32 m0, %3\n\ts_nop 0\n\tglobal_load_lds_dwordx4 %1, %2\n\ts_mov_b32 m0, %0" : "=&s"(keep) : "v"(voff), "s"(sbase), "s"(lds_dst) : "memory");
; }
; template <class Prob, class Epi, bool I8 = false, bool ALIGN_EPI = true, bool SP2 = true>
; __device__ __forceinline__ void gemm_phase(LAS unsigned char* lds, int wave, const Prob& P, const Epi& E) {
;     ...
;             PG8_LDB(B0, 1, 0); PG8_LDB(B1, 1, 1); PG8_SCHED; PG8_LDA(At, 1, 0); PG8_STAGE(PG8_SA(0, 1), a2 + hstepA, voffA);
;             PG8_WAIT_V(8); PG8_WAIT_L(0); PG8_BAR; PG8_MMA(0, 0, At, B0); PG8_MMA(0, 1, At, B1); PG8_BAR; PG8_SCHED;
;             PG8_LDA(At, 1, 1); PG8_STAGE(PG8_SB(1, 0), b3, voffB); PG8_STAGE(PG8_SB(1, 1), b3 + hstepB, voffB); PG8_STAGE(PG8_SA(1, 0), a3, voffA);
;             PG8_WAIT_V(8); PG8_WAIT_L(0); PG8_BAR; PG8_MMA(1, 0, At, B0); PG8_MMA(1, 1, At, B1); PG8_BAR; PG8_SCHED;
	v_add_u32_e32 v140, 0x18000, v146
	ds_read_b128 v[128:131], v140
	ds_read_b128 v[132:135], v140 offset:1024
	ds_read_b128 v[136:139], v140 offset:2048
	ds_read_b128 v[148:151], v140 offset:3072
	v_add_u32_e32 v140, 0x1c000, v146
	ds_read_b128 v[152:155], v140
	ds_read_b128 v[156:159], v140 offset:1024
	ds_read_b128 v[160:163], v140 offset:2048
	ds_read_b128 v[164:167], v140 offset:3072
	ds_read_b128 v[168:171], v147 offset:32768
	ds_read_b128 v[172:175], v147 offset:33792
	ds_read_b128 v[176:179], v147 offset:34816
	ds_read_b128 v[180:183], v147 offset:35840
	ds_read_b128 v[184:187], v147 offset:36864
	ds_read_b128 v[188:191], v147 offset:37888
	ds_read_b128 v[192:195], v147 offset:38912
	ds_read_b128 v[196:199], v147 offset:39936
	s_add_u32 s4, s46, 0x80000
	s_addc_u32 s5, s47, 0
	s_mov_b32 m0, s60
	s_nop 0
	global_load_lds_dwordx4 v142, s[4:5]
	s_mov_b32 m0, s61
	s_nop 0
	global_load_lds_dwordx4 v144, s[4:5]
	s_waitcnt vmcnt(8)
	s_waitcnt lgkmcnt(0)
	s_barrier
	s_waitcnt lgkmcnt(7)
	v_mfma_f32_16x16x32_f16 v[124:127], v[128:131], v[168:171], v[124:127]
	v_mfma_f32_16x16x32_f16 v[120:123], v[136:139], v[168:171], v[120:123]
	s_waitcnt lgkmcnt(5)
	v_mfma_f32_16x16x32_f16 v[116:119], v[128:131], v[176:179], v[116:119]
	v_mfma_f32_16x16x32_f16 v[112:115], v[136:139], v[176:179], v[112:115]
	s_waitcnt lgkmcnt(3)
	v_mfma_f32_16x16x32_f16 v[108:111], v[128:131], v[184:187], v[108:111]
	v_mfma_f32_16x16x32_f16 v[104:107], v[136:139], v[184:187], v[104:107]
	s_waitcnt lgkmcnt(1)
	v_mfma_f32_16x16x32_f16 v[100:103], v[128:131], v[192:195], v[100:103]
	v_mfma_f32_16x16x32_f16 v[96:99], v[136:139], v[192:195], v[96:99]
	v_mfma_f32_16x16x32_f16 v[124:127], v[132:135], v[172:175], v[124:127]
	v_mfma_f32_16x16x32_f16 v[120:123], v[148:151], v[172:175], v[120:123]
	v_mfma_f32_16x16x32_f16 v[116:119], v[132:135], v[180:183], v[116:119]
	v_mfma_f32_16x16x32_f16 v[112:115], v[148:151], v[180:183], v[112:115]
	v_mfma_f32_16x16x32_f16 v[108:111], v[132:135], v[188:191], v[108:111]
	v_mfma_f32_16x16x32_f16 v[104:107], v[148:151], v[188:191], v[104:107]
	s_waitcnt lgkmcnt(0)
	v_mfma_f32_16x16x32_f16 v[100:103], v[132:135], v[196:199], v[100:103]
	v_mfma_f32_16x16x32_f16 v[96:99], v[148:151], v[196:199], v[96:99]
	v_mfma_f32_16x16x32_f16 v[64:67], v[152:155], v[168:171], v[64:67]
	v_mfma_f32_16x16x32_f16 v[56:59], v[160:163], v[168:171], v[56:59]
	v_mfma_f32_16x16x32_f16 v[52:55], v[152:155], v[176:179], v[52:55]
	v_mfma_f32_16x16x32_f16 v[48:51], v[160:163], v[176:179], v[48:51]
	v_mfma_f32_16x16x32_f16 v[44:47], v[152:155], v[184:187], v[44:47]
	v_mfma_f32_16x16x32_f16 v[40:43], v[160:163], v[184:187], v[40:43]
	v_mfma_f32_16x16x32_f16 v[36:39], v[152:155], v[192:195], v[36:39]
	v_mfma_f32_16x16x32_f16 v[32:35], v[160:163], v[192:195], v[32:35]
	v_mfma_f32_16x16x32_f16 v[64:67], v[156:159], v[172:175], v[64:67]
	v_mfma_f32_16x16x32_f16 v[56:59], v[164:167], v[172:175], v[56:59]
	v_mfma_f32_16x16x32_f16 v[52:55], v[156:159], v[180:183], v[52:55]
	v_mfma_f32_16x16x32_f16 v[48:51], v[164:167], v[180:183], v[48:51]
	v_mfma_f32_16x16x32_f16 v[44:47], v[156:159], v[188:191], v[44:47]
	v_mfma_f32_16x16x32_f16 v[40:43], v[164:167], v[188:191], v[40:43]
	v_mfma_f32_16x16x32_f16 v[36:39], v[156:159], v[196:199], v[36:39]
	v_mfma_f32_16x16x32_f16 v[32:35], v[164:167], v[196:199], v[32:35]
	s_barrier
	ds_read_b128 v[168:171], v147 offset:49152
	ds_read_b128 v[172:175], v147 offset:50176
	ds_read_b128 v[176:179], v147 offset:51200
	ds_read_b128 v[180:183], v147 offset:52224
	ds_read_b128 v[184:187], v147 offset:53248
	ds_read_b128 v[188:191], v147 offset:54272
	ds_read_b128 v[192:195], v147 offset:55296
	ds_read_b128 v[196:199], v147 offset:56320
	s_add_u32 s4, s44, 0x80
	s_addc_u32 s5, s45, 0
	s_mov_b32 m0, s64
	s_nop 0
	global_load_lds_dwordx4 v143, s[4:5]
	s_mov_b32 m0, s68
	s_nop 0
	global_load_lds_dwordx4 v145, s[4:5]
	s_add_u32 s4, s44, 0x80080
	s_addc_u32 s5, s45, 0
	s_mov_b32 m0, s73
	s_nop 0
	global_load_lds_dwordx4 v143, s[4:5]
	s_mov_b32 m0, s74
	s_nop 0
	global_load_lds_dwordx4 v145, s[4:5]
	s_mov_b32 m0, s69
	s_nop 0
	global_load_lds_dwordx4 v142, s[42:43]
	s_mov_b32 m0, s72
	s_nop 0
	global_load_lds_dwordx4 v144, s[42:43]
	s_waitcnt vmcnt(8)
	s_waitcnt lgkmcnt(0)
	s_barrier
; #define PG8_MMA(ai, bj, At, Bt) do { __builtin_amdgcn_s_setprio(1); _Pragma("unroll") for (int m = 0; m < 4; ++m) _Pragma("unroll") for (int n = 0; n < 2; ++n) _Pragma("unroll") for (int k = 0; k < 2; ++k) \
;         acc[ai][bj][m][n] = mma_step<I8>(Bt[n][k], At[m][k], acc[ai][bj][m][n]); __builtin_amdgcn_s_setprio(0); } while (0)
; #define PG8_WAIT_V(n) asm volatile("s_waitcnt vmcnt(" #n ")" ::: "memory")
; #define PG8_WAIT_L(n) asm volatile("s_waitcnt lgkmcnt(" #n ")" ::: "memory")
; #define PG8_BAR __builtin_amdgcn_s_barrier()
; #define PG8_SCHED __builtin_amdgcn_sched_barrier(0)
; template <class Prob, class Epi, bool I8 = false, bool ALIGN_EPI = true, bool SP2 = true>
; __device__ __forceinline__ void gemm_phase(LAS unsigned char* lds, int wave, const Prob& P, const Epi& E) {
;     ...
;             PG8_WAIT_V(8); PG8_WAIT_L(0); PG8_BAR; PG8_MMA(1, 0, At, B0); PG8_MMA(1, 1, At, B1); PG8_BAR; PG8_SCHED;
;     __device__ __forceinline__ void operator()(Acc& acc, const Unit& u, int wr, int wc, int fr, int fq, LAS unsigned char* lds, int tid) const {
;     ...
;             for (int ai = 0; ai < 2; ++ai) {
;                 h16x8 xv[4];
;                 f32x2 st[4]; float rs[4];
; #pragma unroll
;                 for (int m = 0; m < 4; ++m) { const unsigned row = u.pm * 256 + ai * 128 + wr * 64 + m * 16 + fr; xv[m] = *(const h16x8*)(X + (size_t)row * D + colt);
;                     if constexpr (LNX) st[m] = *(const f32x2*)((const char*)stats + (row << 3));
;                     if constexpr (I8) rs[m] = *(const float*)((const char*)sa + (row << 2)); }
	s_waitcnt lgkmcnt(7)
	v_mfma_f32_16x16x32_f16 v[92:95], v[128:131], v[168:171], v[92:95]
	v_mfma_f32_16x16x32_f16 v[88:91], v[136:139], v[168:171], v[88:91]
	s_waitcnt lgkmcnt(5)
	v_mfma_f32_16x16x32_f16 v[84:87], v[128:131], v[176:179], v[84:87]
	v_mfma_f32_16x16x32_f16 v[80:83], v[136:139], v[176:179], v[80:83]
	s_waitcnt lgkmcnt(3)
	v_mfma_f32_16x16x32_f16 v[76:79], v[128:131], v[184:187], v[76:79]
	v_mfma_f32_16x16x32_f16 v[72:75], v[136:139], v[184:187], v[72:75]
	s_waitcnt lgkmcnt(1)
	v_mfma_f32_16x16x32_f16 v[68:71], v[128:131], v[192:195], v[68:71]
	v_mfma_f32_16x16x32_f16 v[60:63], v[136:139], v[192:195], v[60:63]
	v_mfma_f32_16x16x32_f16 v[92:95], v[132:135], v[172:175], v[92:95]
	v_mfma_f32_16x16x32_f16 v[88:91], v[148:151], v[172:175], v[88:91]
	v_mfma_f32_16x16x32_f16 v[84:87], v[132:135], v[180:183], v[84:87]
	v_mfma_f32_16x16x32_f16 v[80:83], v[148:151], v[180:183], v[80:83]
	v_mfma_f32_16x16x32_f16 v[76:79], v[132:135], v[188:191], v[76:79]
	v_mfma_f32_16x16x32_f16 v[72:75], v[148:151], v[188:191], v[72:75]
	s_waitcnt lgkmcnt(0)
	v_mfma_f32_16x16x32_f16 v[68:71], v[132:135], v[196:199], v[68:71]
	v_mfma_f32_16x16x32_f16 v[60:63], v[148:151], v[196:199], v[60:63]
	v_mfma_f32_16x16x32_f16 v[28:31], v[152:155], v[168:171], v[28:31]
	v_mfma_f32_16x16x32_f16 v[24:27], v[160:163], v[168:171], v[24:27]
	v_mfma_f32_16x16x32_f16 v[20:23], v[152:155], v[176:179], v[20:23]
	v_mfma_f32_16x16x32_f16 v[16:19], v[160:163], v[176:179], v[16:19]
	v_mfma_f32_16x16x32_f16 v[12:15], v[152:155], v[184:187], v[12:15]
	v_mfma_f32_16x16x32_f16 v[8:11], v[160:163], v[184:187], v[8:11]
	v_mfma_f32_16x16x32_f16 v[4:7], v[152:155], v[192:195], v[4:7]
	v_mfma_f32_16x16x32_f16 v[0:3], v[160:163], v[192:195], v[0:3]
	v_mfma_f32_16x16x32_f16 v[28:31], v[156:159], v[172:175], v[28:31]
	v_mfma_f32_16x16x32_f16 v[24:27], v[164:167], v[172:175], v[24:27]
	v_mfma_f32_16x16x32_f16 v[20:23], v[156:159], v[180:183], v[20:23]
	v_mfma_f32_16x16x32_f16 v[16:19], v[164:167], v[180:183], v[16:19]
	v_mfma_f32_16x16x32_f16 v[12:15], v[156:159], v[188:191], v[12:15]
	v_mfma_f32_16x16x32_f16 v[8:11], v[164:167], v[188:191], v[8:11]
	v_mfma_f32_16x16x32_f16 v[4:7], v[156:159], v[196:199], v[4:7]
	v_mfma_f32_16x16x32_f16 v[0:3], v[164:167], v[196:199], v[0:3]
	s_barrier
	s_add_i32 s1, s1, 2
	s_add_u32 s85, s85, 0x100
	s_addc_u32 s86, s86, 0
	s_add_u32 s87, s87, 0x100
	s_addc_u32 s0, s0, 0
	s_add_u32 s40, s40, 0x100
	s_addc_u32 s41, s41, 0
	s_cmp_gt_u32 s1, 29
	s_cbranch_scc0 .LBB0_863
	v_mbcnt_lo_u32_b32 v128, -1, 0
	v_mbcnt_hi_u32_b32 v128, -1, v128
	s_lshl_b32 s0, s82, 8
	s_lshl_b32 s1, s81, 8
	v_lshrrev_b32_e32 v129, 1, v128
	s_add_i32 s1, s1, s62
	v_and_or_b32 v129, v129, 24, s0
	v_and_or_b32 v130, v128, 15, s1
	v_or_b32_e32 v129, s63, v129
	v_lshlrev_b32_e32 v130, 12, v130
	v_lshl_add_u32 v128, v129, 1, v130
	v_add_u32_e32 v129, 0x10000, v128
	v_add_u32_e32 v130, 0x20000, v128
	v_add_u32_e32 v131, 0x30000, v128
	v_add_u32_e32 v132, 0x80000, v128
	v_add_u32_e32 v133, 0x90000, v128
	v_add_u32_e32 v134, 0xa0000, v128
	v_add_u32_e32 v135, 0xb0000, v128
	global_load_dwordx4 v[148:151], v128, s[54:55]
	global_load_dwordx4 v[152:155], v129, s[54:55]
	global_load_dwordx4 v[156:159], v130, s[54:55]
	global_load_dwordx4 v[160:163], v131, s[54:55]
	global_load_dwordx4 v[164:167], v132, s[54:55]
	global_load_dwordx4 v[168:171], v133, s[54:55]
	global_load_dwordx4 v[172:175], v134, s[54:55]
	global_load_dwordx4 v[176:179], v135, s[54:55]
	global_load_dwordx4 v[180:183], v128, s[54:55] offset:256
	global_load_dwordx4 v[184:187], v129, s[54:55] offset:256
	global_load_dwordx4 v[188:191], v130, s[54:55] offset:256
	global_load_dwordx4 v[192:195], v131, s[54:55] offset:256
	global_load_dwordx4 v[196:199], v132, s[54:55] offset:256
	global_load_dwordx4 v[200:203], v133, s[54:55] offset:256
	global_load_dwordx4 v[204:207], v134, s[54:55] offset:256
	global_load_dwordx4 v[212:215], v135, s[54:55] offset:256
	s_and_b64 vcc, exec, s[16:17]
	s_cbranch_vccz .LBB0_866
	s_barrier

; #define PG8_WAIT_V(n) asm volatile("s_waitcnt vmcnt(" #n ")" ::: "memory")
; template <class Prob, class Epi, bool I8 = false, bool ALIGN_EPI = true, bool SP2 = true>
; __device__ __forceinline__ void gemm_phase(LAS unsigned char* lds, int wave, const Prob& P, const Epi& E) {
;     const int tid_ = wave * 64 + mk_lane();
;     const int tid = tid_, wid = __builtin_amdgcn_readfirstlane(tid >> 6), lane = tid & 63, wr = wid >> 2, wc = wid & 3, fr = lane & 15, fq = lane >> 4;
;     const int K = P.K, nt = K / BK;
;     unsigned voffA[2], voffB[2];
; #pragma unroll
;     for (int i = 0; i < 2; ++i) { int R, C; stage_rc(tid * 16 + i * 8192, R, C); const int Rb = (R & ~31) + perm32(R & 31);
;         voffA[i] = P.a_rowoff(R) + (unsigned)C * 2u; voffB[i] = P.b_rowoff(Rb) + (unsigned)C * 2u; }
;     const size_t kstep = (size_t)(BK * 2);
;     const size_t hstepA = P.a_hstep(), hstepB = P.b_hstep();
;     const unsigned ldsw = (unsigned)wid * 1024u;
;     const unsigned ldsb = (unsigned)(size_t)lds + ldsw;
;     const int aoff = lds_byte(wr * 64 + fr, fq * 8), boff = lds_byte(wc * 32 + fr, fq * 8);
;     ...
;     Unit cur, nxt; int ui = 0;
;     if (!P.next(0, cur)) return;
;     Acc acc;
; #pragma unroll
;     for (int a = 0; a < 2; ++a)
; #pragma unroll
;         for (int b = 0; b < 2; ++b)
; #pragma unroll
;             for (int m = 0; m < 4; ++m)
; #pragma unroll
;                 for (int n = 0; n < 2; ++n) acc[a][b][m][n] = (f32x4){0.f, 0.f, 0.f, 0.f};
;     h16x8 At[4][2], B0[2][2], B1[2][2];
;     const char* cA = P.a_tile(cur); const char* cB = P.b_tile(cur);
;     if constexpr (SP2) {
;         PG8_STAGE(PG8_SB(0, 0), cB, voffB); PG8_STAGE(PG8_SB(0, 1), cB + hstepB, voffB); PG8_STAGE(PG8_SA(0, 0), cA, voffA); PG8_STAGE(PG8_SA(0, 1), cA + hstepA, voffA);
;         if (wr == 1) PG8_BAR;
;         PG8_WAIT_V(2); PG8_BAR;
;         PG8_STAGE(PG8_SB(1, 0), cB + kstep, voffB); PG8_STAGE(PG8_SA(1, 0), cA + kstep, voffA); PG8_STAGE(PG8_SB(1, 1), cB + hstepB + kstep, voffB);
;         PG8_WAIT_V(6); PG8_BAR;
;     __device__ unsigned a_rowoff(int R) const { return (unsigned)(64 * R + 65 * (R & 1)) * (unsigned)lda * 2u; }
;     __device__ unsigned b_rowoff(int R) const { return (unsigned)R * (unsigned)ldb * 2u; }
;     __device__ size_t a_hstep() const { return (size_t)64 * 128 * lda * 2; }
;     __device__ size_t b_hstep() const { return (size_t)128 * ldb * 2; }
.LBB0_986:
	s_add_u32 s26, s30, 0x240000
	v_readlane_b32 s0, v255, 1
	s_addc_u32 s27, s31, 0
	s_mul_i32 s0, s0, 0x1600000
	s_add_u32 s0, s30, s0
	s_addc_u32 s1, s31, 0
	s_add_u32 s79, s0, 0x57200000
	s_addc_u32 s40, s1, 0
	s_add_u32 s41, s30, 0x51200000
	s_addc_u32 s19, s31, 0
	v_readlane_b32 s0, v254, 42
	v_readlane_b32 s4, v252, 13
	s_waitcnt lgkmcnt(0)
	s_barrier
	s_add_u32 s38, s30, 0x2000000
	v_mbcnt_lo_u32_b32 v0, -1, 0
	v_mbcnt_hi_u32_b32 v0, -1, v0
	v_readlane_b32 s5, v252, 14
	v_add_u32_e32 v1, s0, v0
	s_addc_u32 s39, s31, 0
	v_readfirstlane_b32 s0, v1
	s_and_b64 vcc, exec, s[4:5]
	s_cbranch_vccz .LBB0_1002
	v_ashrrev_i32_e32 v3, 31, v1
	v_lshrrev_b32_e32 v3, 26, v3
	v_lshlrev_b32_e32 v2, 4, v1
	v_add_u32_e32 v3, v1, v3
	v_bfe_i32 v1, v1, 27, 1
	v_lshrrev_b32_e32 v1, 22, v1
	v_add_u32_e32 v1, v2, v1
	v_and_b32_e32 v1, 0xfffffc00, v1
	v_sub_u32_e32 v1, v2, v1
	v_lshrrev_b32_e32 v4, 4, v1
	v_bitop3_b32 v1, v4, v1, 32 bitop3:0x6c
	v_ashrrev_i32_e32 v5, 31, v1
	v_ashrrev_i32_e32 v3, 6, v3
	v_lshrrev_b32_e32 v5, 26, v5
	v_lshlrev_b32_e32 v4, 3, v3
	v_add_u32_e32 v5, v1, v5
	v_and_b32_e32 v4, -16, v4
	v_ashrrev_i32_e32 v6, 6, v5
	v_add_u32_e32 v4, v6, v4
	v_and_b32_e32 v5, 0xc0, v5
	v_sub_u32_e32 v1, v1, v5
	v_mov_b32_e32 v9, 1
	v_lshlrev_b32_e32 v5, 1, v4
	v_lshrrev_b32_e32 v7, 2, v4
	v_and_b32_e32 v8, 3, v6
	s_mov_b32 s2, 0x1fffe0
	v_lshlrev_b32_e32 v3, 5, v3
	v_ashrrev_i16_sdwa v1, v9, sext(v1) dst_sel:DWORD dst_unused:UNUSED_PAD src0_sel:DWORD src1_sel:BYTE_0
	v_and_b32_e32 v5, 24, v5
	v_and_b32_e32 v7, 4, v7
	v_and_or_b32 v8, v4, s2, v8
	v_and_b32_e32 v6, 1, v6
	v_and_b32_e32 v3, 32, v3
	v_bfe_i32 v1, v1, 0, 16
	v_or3_b32 v5, v8, v7, v5
	v_cmp_eq_u32_e32 vcc, 1, v6
	v_mov_b32_e32 v8, 0x20800
	v_lshlrev_b32_e32 v4, 17, v4
	v_cndmask_b32_e32 v6, 0, v8, vcc
	v_add_lshl_u32 v1, v3, v1, 1
	v_add3_u32 v129, v4, v6, v1
	v_lshl_add_u32 v130, v5, 11, v1
	v_add_u32_e32 v1, 0x2000, v2
	v_ashrrev_i32_e32 v2, 31, v1
	v_lshrrev_b32_e32 v2, 22, v2
	v_add_u32_e32 v2, v1, v2
	v_ashrrev_i32_e32 v2, 10, v2
	v_mul_i32_i24_e32 v3, 0x400, v2
	v_sub_u32_e32 v1, v1, v3
	v_readlane_b32 s4, v252, 21
	v_lshrrev_b32_e32 v3, 4, v1
	v_readlane_b32 s5, v252, 22
	s_add_u32 s44, s79, s4
	v_bitop3_b32 v1, v3, v1, 32 bitop3:0x6c
	s_addc_u32 s45, s40, s5
	v_readlane_b32 s4, v252, 17
	v_ashrrev_i32_e32 v4, 31, v1
	v_readlane_b32 s5, v252, 18
	s_add_u32 s4, s41, s4
	v_lshrrev_b32_e32 v4, 26, v4
	s_addc_u32 s5, s19, s5
	v_lshlrev_b32_e32 v3, 3, v2
	v_add_u32_e32 v4, v1, v4
	s_add_u32 s50, s4, 0xfffff800
	v_and_b32_e32 v3, -16, v3
	v_ashrrev_i32_e32 v5, 6, v4
	s_addc_u32 s51, s5, -1
	v_add_u32_e32 v3, v5, v3
	v_and_b32_e32 v7, 3, v5
	s_ashr_i32 s16, s0, 6
	v_and_or_b32 v7, v3, s2, v7
	s_lshl_b32 s2, s16, 10
	s_ashr_i32 s1, s0, 8
	v_and_b32_e32 v4, 0xc0, v4
	s_add_i32 s2, s2, 0
	v_sub_u32_e32 v1, v1, v4
	s_add_u32 s14, s4, 0xfff800
	v_lshlrev_b32_e32 v2, 5, v2
	v_ashrrev_i16_sdwa v1, v9, sext(v1) dst_sel:DWORD dst_unused:UNUSED_PAD src0_sel:DWORD src1_sel:BYTE_0
	v_lshlrev_b32_e32 v4, 1, v3
	v_lshrrev_b32_e32 v6, 2, v3
	s_addc_u32 s15, s5, 0
	v_and_b32_e32 v2, 32, v2
	v_bfe_i32 v1, v1, 0, 16
	v_and_b32_e32 v4, 24, v4
	v_and_b32_e32 v6, 4, v6
	s_add_u32 s22, s44, 0x40000
	v_or3_b32 v4, v7, v6, v4
	v_add_lshl_u32 v1, v2, v1, 1
	s_addc_u32 s23, s45, 0
	s_add_i32 s62, s2, 0x10000
	s_mov_b32 m0, s62
	s_nop 0
	global_load_lds_dwordx4 v130, s[44:45]
	v_lshl_add_u32 v132, v4, 11, v1
	s_add_i32 s63, s2, 0x12000
	s_mov_b32 m0, s63
	s_nop 0
	global_load_lds_dwordx4 v132, s[44:45]
	v_and_b32_e32 v5, 1, v5
	s_add_i32 s64, s2, 0x14000
	s_mov_b32 m0, s64
	s_nop 0
	global_load_lds_dwordx4 v130, s[22:23]
	v_cmp_eq_u32_e32 vcc, 1, v5
	s_add_i32 s68, s2, 0x16000
	s_mov_b32 m0, s68
	s_nop 0
	global_load_lds_dwordx4 v132, s[22:23]
	v_lshlrev_b32_e32 v3, 17, v3
	v_cndmask_b32_e32 v5, 0, v8, vcc
	s_mov_b32 m0, s2
	s_nop 0
	global_load_lds_dwordx4 v129, s[50:51]
	v_add3_u32 v131, v3, v5, v1
	s_add_i32 s69, s2, 0x2000
	s_mov_b32 m0, s69
	s_nop 0
	global_load_lds_dwordx4 v131, s[50:51]
	s_add_i32 s72, s2, 0x4000
	s_mov_b32 m0, s72
	s_nop 0
	global_load_lds_dwordx4 v129, s[14:15]
	s_add_i32 s73, s2, 0x6000
	s_mov_b32 m0, s73
	s_nop 0
	global_load_lds_dwordx4 v131, s[14:15]
	s_cmp_eq_u32 s1, 1
	s_cselect_b64 s[14:15], -1, 0
	s_setprio 1
	s_cmp_lg_u32 s1, 1
	s_cbranch_scc1 .LBB0_989
	s_barrier
	s_setprio 0
.LBB0_989:
	s_add_u32 s22, s44, 0x80
	s_addc_u32 s23, s45, 0
	s_add_u32 s4, s4, 0xfffff880
	s_addc_u32 s5, s5, -1
	s_add_u32 s28, s44, 0x40080
	v_and_b32_e32 v1, 48, v0
	v_lshlrev_b32_e32 v2, 6, v0
	s_movk_i32 s6, 0x3c0
	v_lshlrev_b32_e32 v0, 2, v0
	s_addc_u32 s29, s45, 0
	s_lshl_b32 s74, s1, 6
	s_lshl_b32 s1, s1, 13
	v_and_or_b32 v1, v2, s6, v1
	v_and_b32_e32 v0, 32, v0
	v_bitop3_b32 v2, v1, s1, v0 bitop3:0xde
	s_lshl_b32 s1, s16, 5
	s_and_b32 s75, s1, 0x60
	s_lshl_b32 s1, s75, 7
	v_bitop3_b32 v0, s1, v1, v0 bitop3:0xf6
	s_waitcnt vmcnt(2)
	s_barrier
	s_add_i32 s76, s2, 0x18000
	s_mov_b32 m0, s76
	s_nop 0
	global_load_lds_dwordx4 v130, s[22:23]
	s_add_i32 s77, s2, 0x1a000
	s_mov_b32 m0, s77
	s_nop 0
	global_load_lds_dwordx4 v132, s[22:23]
	s_add_i32 s80, s2, 0x8000
	s_mov_b32 m0, s80
	s_nop 0
	global_load_lds_dwordx4 v129, s[4:5]
	s_add_i32 s81, s2, 0xa000
	s_mov_b32 m0, s81
	s_nop 0
	global_load_lds_dwordx4 v131, s[4:5]
	s_add_i32 s82, s2, 0x1c000
	s_mov_b32 m0, s82
	s_nop 0
	global_load_lds_dwordx4 v130, s[28:29]
	s_add_i32 s83, s2, 0x1e000
	s_mov_b32 m0, s83
	s_nop 0
	global_load_lds_dwordx4 v132, s[28:29]
	s_add_i32 s84, s2, 0xc000
	s_cmpk_lt_u32 s0, 0x100
	v_readlane_b32 s0, v252, 19
	s_waitcnt vmcnt(6)
	v_readlane_b32 s1, v252, 20
	s_mov_b32 s87, s0
	v_readlane_b32 s0, v252, 15
	s_cselect_b64 s[16:17], -1, 0
	s_add_i32 s85, s2, 0xe000
	s_mov_b32 s86, 0
	v_add_u32_e32 v133, 0, v0
	v_add_u32_e32 v134, 0, v2
	s_mov_b32 s88, s0
	s_barrier
	v_readlane_b32 s1, v252, 16
	s_branch .LBB0_992

; #define PG8_STAGE(bufoff, gbase, voff) do { _Pragma("unroll") for (int _i = 0; _i < 2; ++_i) glds16_s((gbase), (voff)[_i], ldsb + (unsigned)((bufoff) + _i * 8192)); } while (0)
; #define PG8_LDA(dst, b, h) do { _Pragma("unroll") for (int m = 0; m < 4; ++m) _Pragma("unroll") for (int k = 0; k < 2; ++k) dst[m][k] = *(const LAS h16x8*)(lds + PG8_SA(b, h) + aoff + m * 2048 + k * 1024); } while (0)
; #define PG8_LDB(dst, b, h) do { _Pragma("unroll") for (int n = 0; n < 2; ++n) _Pragma("unroll") for (int k = 0; k < 2; ++k) dst[n][k] = *(const LAS h16x8*)(lds + PG8_SB(b, h) + boff + n * 2048 + k * 1024); } while (0)
; #define PG8_MMA(ai, bj, At, Bt) do { __builtin_amdgcn_s_setprio(1); _Pragma("unroll") for (int m = 0; m < 4; ++m) _Pragma("unroll") for (int n = 0; n < 2; ++n) _Pragma("unroll") for (int k = 0; k < 2; ++k) \
;         acc[ai][bj][m][n] = mma_step<I8>(Bt[n][k], At[m][k], acc[ai][bj][m][n]); __builtin_amdgcn_s_setprio(0); } while (0)
; #define PG8_WAIT_V(n) asm volatile("s_waitcnt vmcnt(" #n ")" ::: "memory")
; #define PG8_WAIT_L(n) asm volatile("s_waitcnt lgkmcnt(" #n ")" ::: "memory")
; #define PG8_BAR __builtin_amdgcn_s_barrier()
; #define PG8_SCHED __builtin_amdgcn_sched_barrier(0)
; template <class Prob, class Epi, bool I8 = false, bool ALIGN_EPI = true, bool SP2 = true>
; __device__ __forceinline__ void gemm_phase(LAS unsigned char* lds, int wave, const Prob& P, const Epi& E) {
;     ...
;             PG8_LDB(B0, 0, 0); PG8_LDB(B1, 0, 1); PG8_SCHED; PG8_LDA(At, 0, 0); PG8_STAGE(PG8_SA(1, 1), a1 + hstepA, voffA);
;             PG8_WAIT_V(8); PG8_WAIT_L(0); PG8_BAR; PG8_MMA(0, 0, At, B0); PG8_MMA(0, 1, At, B1); PG8_BAR; PG8_SCHED;
;             PG8_LDA(At, 0, 1); PG8_STAGE(PG8_SB(0, 0), b2, voffB); PG8_STAGE(PG8_SB(0, 1), b2 + hstepB, voffB); PG8_STAGE(PG8_SA(0, 0), a2, voffA);
;             PG8_WAIT_V(8); PG8_WAIT_L(0); PG8_BAR; PG8_MMA(1, 0, At, B0); PG8_MMA(1, 1, At, B1); PG8_BAR; PG8_SCHED;
.Lpeel_995:
	v_add_u32_e32 v128, 0x10000, v133
	ds_read_b128 v[136:139], v128
	ds_read_b128 v[140:143], v128 offset:1024
	ds_read_b128 v[144:147], v128 offset:2048
	ds_read_b128 v[148:151], v128 offset:3072
	v_add_u32_e32 v128, 0x14000, v133
	ds_read_b128 v[152:155], v128
	ds_read_b128 v[156:159], v128 offset:1024
	ds_read_b128 v[160:163], v128 offset:2048
	ds_read_b128 v[164:167], v128 offset:3072
	s_cmp_eq_u32 s1, 12
	s_cselect_b32 s60, s89, s91
	s_cselect_b32 s61, s29, s92
	s_cselect_b32 s56, s90, s93
	s_cselect_b32 s57, s23, s0
	s_add_u32 s50, s60, 0x80
	s_addc_u32 s51, s61, 0
	ds_read_b128 v[168:171], v134
	ds_read_b128 v[172:175], v134 offset:1024
	ds_read_b128 v[176:179], v134 offset:2048
	ds_read_b128 v[180:183], v134 offset:3072
	ds_read_b128 v[184:187], v134 offset:4096
	ds_read_b128 v[188:191], v134 offset:5120
	ds_read_b128 v[192:195], v134 offset:6144
	ds_read_b128 v[196:199], v134 offset:7168
	s_mov_b32 m0, s84
	s_nop 0
	global_load_lds_dwordx4 v129, s[44:45]
	s_mov_b32 m0, s85
	s_nop 0
	global_load_lds_dwordx4 v131, s[44:45]
	s_waitcnt vmcnt(8)
	s_waitcnt lgkmcnt(0)
	s_barrier
	s_waitcnt lgkmcnt(7)
	v_mfma_i32_16x16x64_i8 v[16:19], v[136:139], v[168:171], 0
	v_mfma_i32_16x16x64_i8 v[20:23], v[144:147], v[168:171], 0
	s_waitcnt lgkmcnt(5)
	v_mfma_i32_16x16x64_i8 v[48:51], v[136:139], v[176:179], 0
	v_mfma_i32_16x16x64_i8 v[52:55], v[144:147], v[176:179], 0
	s_waitcnt lgkmcnt(3)
	v_mfma_i32_16x16x64_i8 v[72:75], v[136:139], v[184:187], 0
	v_mfma_i32_16x16x64_i8 v[76:79], v[144:147], v[184:187], 0
	s_waitcnt lgkmcnt(1)
	v_mfma_i32_16x16x64_i8 v[96:99], v[136:139], v[192:195], 0
	v_mfma_i32_16x16x64_i8 v[100:103], v[144:147], v[192:195], 0
	v_mfma_i32_16x16x64_i8 v[16:19], v[140:143], v[172:175], v[16:19]
	v_mfma_i32_16x16x64_i8 v[20:23], v[148:151], v[172:175], v[20:23]
	v_mfma_i32_16x16x64_i8 v[48:51], v[140:143], v[180:183], v[48:51]
	v_mfma_i32_16x16x64_i8 v[52:55], v[148:151], v[180:183], v[52:55]
	v_mfma_i32_16x16x64_i8 v[72:75], v[140:143], v[188:191], v[72:75]
	v_mfma_i32_16x16x64_i8 v[76:79], v[148:151], v[188:191], v[76:79]
	s_waitcnt lgkmcnt(0)
	v_mfma_i32_16x16x64_i8 v[96:99], v[140:143], v[196:199], v[96:99]
	v_mfma_i32_16x16x64_i8 v[100:103], v[148:151], v[196:199], v[100:103]
	v_mfma_i32_16x16x64_i8 v[24:27], v[152:155], v[168:171], 0
	v_mfma_i32_16x16x64_i8 v[28:31], v[160:163], v[168:171], 0
	v_mfma_i32_16x16x64_i8 v[56:59], v[152:155], v[176:179], 0
	v_mfma_i32_16x16x64_i8 v[60:63], v[160:163], v[176:179], 0
	v_mfma_i32_16x16x64_i8 v[80:83], v[152:155], v[184:187], 0
	v_mfma_i32_16x16x64_i8 v[84:87], v[160:163], v[184:187], 0
	v_mfma_i32_16x16x64_i8 v[104:107], v[152:155], v[192:195], 0
	v_mfma_i32_16x16x64_i8 v[108:111], v[160:163], v[192:195], 0
	v_mfma_i32_16x16x64_i8 v[24:27], v[156:159], v[172:175], v[24:27]
	v_mfma_i32_16x16x64_i8 v[28:31], v[164:167], v[172:175], v[28:31]
	v_mfma_i32_16x16x64_i8 v[56:59], v[156:159], v[180:183], v[56:59]
	v_mfma_i32_16x16x64_i8 v[60:63], v[164:167], v[180:183], v[60:63]
	v_mfma_i32_16x16x64_i8 v[80:83], v[156:159], v[188:191], v[80:83]
	v_mfma_i32_16x16x64_i8 v[84:87], v[164:167], v[188:191], v[84:87]
	v_mfma_i32_16x16x64_i8 v[104:107], v[156:159], v[196:199], v[104:107]
	v_mfma_i32_16x16x64_i8 v[108:111], v[164:167], v[196:199], v[108:111]
	s_barrier
	ds_read_b128 v[168:171], v134 offset:16384
	ds_read_b128 v[172:175], v134 offset:17408
	ds_read_b128 v[176:179], v134 offset:18432
	ds_read_b128 v[180:183], v134 offset:19456
	ds_read_b128 v[184:187], v134 offset:20480
	ds_read_b128 v[188:191], v134 offset:21504
	ds_read_b128 v[192:195], v134 offset:22528
	ds_read_b128 v[196:199], v134 offset:23552
	s_mov_b32 m0, s62
	s_nop 0
	global_load_lds_dwordx4 v130, s[56:57]
	s_mov_b32 m0, s63
	s_nop 0
	global_load_lds_dwordx4 v132, s[56:57]
	s_add_u32 s4, s56, 0x40000
	s_addc_u32 s5, s57, 0
	s_mov_b32 m0, s64
	s_nop 0
	global_load_lds_dwordx4 v130, s[4:5]
	s_mov_b32 m0, s68
	s_nop 0
	global_load_lds_dwordx4 v132, s[4:5]
	s_mov_b32 m0, s2
	s_nop 0
	global_load_lds_dwordx4 v129, s[60:61]
	s_mov_b32 m0, s69
	s_nop 0
	global_load_lds_dwordx4 v131, s[60:61]
	s_waitcnt vmcnt(8)
	s_waitcnt lgkmcnt(0)
	s_barrier
	s_waitcnt lgkmcnt(7)
	v_mfma_i32_16x16x64_i8 v[124:127], v[136:139], v[168:171], 0
	v_mfma_i32_16x16x64_i8 v[120:123], v[144:147], v[168:171], 0
	s_waitcnt lgkmcnt(5)
	v_mfma_i32_16x16x64_i8 v[92:95], v[136:139], v[176:179], 0
	v_mfma_i32_16x16x64_i8 v[88:91], v[144:147], v[176:179], 0
	s_waitcnt lgkmcnt(3)
	v_mfma_i32_16x16x64_i8 v[44:47], v[136:139], v[184:187], 0
	v_mfma_i32_16x16x64_i8 v[40:43], v[144:147], v[184:187], 0
	s_waitcnt lgkmcnt(1)
	v_mfma_i32_16x16x64_i8 v[12:15], v[136:139], v[192:195], 0
	v_mfma_i32_16x16x64_i8 v[8:11], v[144:147], v[192:195], 0
	v_mfma_i32_16x16x64_i8 v[124:127], v[140:143], v[172:175], v[124:127]
	v_mfma_i32_16x16x64_i8 v[120:123], v[148:151], v[172:175], v[120:123]
	v_mfma_i32_16x16x64_i8 v[92:95], v[140:143], v[180:183], v[92:95]
	v_mfma_i32_16x16x64_i8 v[88:91], v[148:151], v[180:183], v[88:91]
	v_mfma_i32_16x16x64_i8 v[44:47], v[140:143], v[188:191], v[44:47]
	v_mfma_i32_16x16x64_i8 v[40:43], v[148:151], v[188:191], v[40:43]
	s_waitcnt lgkmcnt(0)
	v_mfma_i32_16x16x64_i8 v[12:15], v[140:143], v[196:199], v[12:15]
	v_mfma_i32_16x16x64_i8 v[8:11], v[148:151], v[196:199], v[8:11]
	v_mfma_i32_16x16x64_i8 v[116:119], v[152:155], v[168:171], 0
	v_mfma_i32_16x16x64_i8 v[112:115], v[160:163], v[168:171], 0
	v_mfma_i32_16x16x64_i8 v[68:71], v[152:155], v[176:179], 0
	v_mfma_i32_16x16x64_i8 v[64:67], v[160:163], v[176:179], 0
	v_mfma_i32_16x16x64_i8 v[36:39], v[152:155], v[184:187], 0
	v_mfma_i32_16x16x64_i8 v[32:35], v[160:163], v[184:187], 0
	v_mfma_i32_16x16x64_i8 v[4:7], v[152:155], v[192:195], 0
	v_mfma_i32_16x16x64_i8 v[0:3], v[160:163], v[192:195], 0
	v_mfma_i32_16x16x64_i8 v[116:119], v[156:159], v[172:175], v[116:119]
	v_mfma_i32_16x16x64_i8 v[112:115], v[164:167], v[172:175], v[112:115]
	v_mfma_i32_16x16x64_i8 v[68:71], v[156:159], v[180:183], v[68:71]
	v_mfma_i32_16x16x64_i8 v[64:67], v[164:167], v[180:183], v[64:67]
	v_mfma_i32_16x16x64_i8 v[36:39], v[156:159], v[188:191], v[36:39]
	v_mfma_i32_16x16x64_i8 v[32:35], v[164:167], v[188:191], v[32:35]
	v_mfma_i32_16x16x64_i8 v[4:7], v[156:159], v[196:199], v[4:7]
	v_mfma_i32_16x16x64_i8 v[0:3], v[164:167], v[196:199], v[0:3]
	s_barrier
; #define PG8_STAGE(bufoff, gbase, voff) do { _Pragma("unroll") for (int _i = 0; _i < 2; ++_i) glds16_s((gbase), (voff)[_i], ldsb + (unsigned)((bufoff) + _i * 8192)); } while (0)
; #define PG8_LDA(dst, b, h) do { _Pragma("unroll") for (int m = 0; m < 4; ++m) _Pragma("unroll") for (int k = 0; k < 2; ++k) dst[m][k] = *(const LAS h16x8*)(lds + PG8_SA(b, h) + aoff + m * 2048 + k * 1024); } while (0)
; #define PG8_LDB(dst, b, h) do { _Pragma("unroll") for (int n = 0; n < 2; ++n) _Pragma("unroll") for (int k = 0; k < 2; ++k) dst[n][k] = *(const LAS h16x8*)(lds + PG8_SB(b, h) + boff + n * 2048 + k * 1024); } while (0)
; #define PG8_MMA(ai, bj, At, Bt) do { __builtin_amdgcn_s_setprio(1); _Pragma("unroll") for (int m = 0; m < 4; ++m) _Pragma("unroll") for (int n = 0; n < 2; ++n) _Pragma("unroll") for (int k = 0; k < 2; ++k) \
;         acc[ai][bj][m][n] = mma_step<I8>(Bt[n][k], At[m][k], acc[ai][bj][m][n]); __builtin_amdgcn_s_setprio(0); } while (0)
; #define PG8_WAIT_V(n) asm volatile("s_waitcnt vmcnt(" #n ")" ::: "memory")
; #define PG8_WAIT_L(n) asm volatile("s_waitcnt lgkmcnt(" #n ")" ::: "memory")
; #define PG8_BAR __builtin_amdgcn_s_barrier()
; #define PG8_SCHED __builtin_amdgcn_sched_barrier(0)
; template <class Prob, class Epi, bool I8 = false, bool ALIGN_EPI = true, bool SP2 = true>
; __device__ __forceinline__ void gemm_phase(LAS unsigned char* lds, int wave, const Prob& P, const Epi& E) {
;     ...
;             PG8_LDB(B0, 1, 0); PG8_LDB(B1, 1, 1); PG8_SCHED; PG8_LDA(At, 1, 0); PG8_STAGE(PG8_SA(0, 1), a2 + hstepA, voffA);
;             PG8_WAIT_V(8); PG8_WAIT_L(0); PG8_BAR; PG8_MMA(0, 0, At, B0); PG8_MMA(0, 1, At, B1); PG8_BAR; PG8_SCHED;
;             PG8_LDA(At, 1, 1); PG8_STAGE(PG8_SB(1, 0), b3, voffB); PG8_STAGE(PG8_SB(1, 1), b3 + hstepB, voffB); PG8_STAGE(PG8_SA(1, 0), a3, voffA);
;             PG8_WAIT_V(8); PG8_WAIT_L(0); PG8_BAR; PG8_MMA(1, 0, At, B0); PG8_MMA(1, 1, At, B1); PG8_BAR; PG8_SCHED;
	v_add_u32_e32 v128, 0x18000, v133
	ds_read_b128 v[136:139], v128
	ds_read_b128 v[140:143], v128 offset:1024
	ds_read_b128 v[144:147], v128 offset:2048
	ds_read_b128 v[148:151], v128 offset:3072
	v_add_u32_e32 v128, 0x1c000, v133
	ds_read_b128 v[152:155], v128
	ds_read_b128 v[156:159], v128 offset:1024
	ds_read_b128 v[160:163], v128 offset:2048
	ds_read_b128 v[164:167], v128 offset:3072
	ds_read_b128 v[168:171], v134 offset:32768
	ds_read_b128 v[172:175], v134 offset:33792
	ds_read_b128 v[176:179], v134 offset:34816
	ds_read_b128 v[180:183], v134 offset:35840
	ds_read_b128 v[184:187], v134 offset:36864
	ds_read_b128 v[188:191], v134 offset:37888
	ds_read_b128 v[192:195], v134 offset:38912
	ds_read_b128 v[196:199], v134 offset:39936
	s_add_u32 s4, s60, 0x1000000
	s_addc_u32 s5, s61, 0
	s_mov_b32 m0, s72
	s_nop 0
	global_load_lds_dwordx4 v129, s[4:5]
	s_mov_b32 m0, s73
	s_nop 0
	global_load_lds_dwordx4 v131, s[4:5]
	s_waitcnt vmcnt(8)
	s_waitcnt lgkmcnt(0)
	s_barrier
	s_waitcnt lgkmcnt(7)
	v_mfma_i32_16x16x64_i8 v[16:19], v[136:139], v[168:171], v[16:19]
	v_mfma_i32_16x16x64_i8 v[20:23], v[144:147], v[168:171], v[20:23]
	s_waitcnt lgkmcnt(5)
	v_mfma_i32_16x16x64_i8 v[48:51], v[136:139], v[176:179], v[48:51]
	v_mfma_i32_16x16x64_i8 v[52:55], v[144:147], v[176:179], v[52:55]
	s_waitcnt lgkmcnt(3)
	v_mfma_i32_16x16x64_i8 v[72:75], v[136:139], v[184:187], v[72:75]
	v_mfma_i32_16x16x64_i8 v[76:79], v[144:147], v[184:187], v[76:79]
	s_waitcnt lgkmcnt(1)
	v_mfma_i32_16x16x64_i8 v[96:99], v[136:139], v[192:195], v[96:99]
	v_mfma_i32_16x16x64_i8 v[100:103], v[144:147], v[192:195], v[100:103]
	v_mfma_i32_16x16x64_i8 v[16:19], v[140:143], v[172:175], v[16:19]
	v_mfma_i32_16x16x64_i8 v[20:23], v[148:151], v[172:175], v[20:23]
	v_mfma_i32_16x16x64_i8 v[48:51], v[140:143], v[180:183], v[48:51]
	v_mfma_i32_16x16x64_i8 v[52:55], v[148:151], v[180:183], v[52:55]
	v_mfma_i32_16x16x64_i8 v[72:75], v[140:143], v[188:191], v[72:75]
	v_mfma_i32_16x16x64_i8 v[76:79], v[148:151], v[188:191], v[76:79]
	s_waitcnt lgkmcnt(0)
	v_mfma_i32_16x16x64_i8 v[96:99], v[140:143], v[196:199], v[96:99]
	v_mfma_i32_16x16x64_i8 v[100:103], v[148:151], v[196:199], v[100:103]
	v_mfma_i32_16x16x64_i8 v[24:27], v[152:155], v[168:171], v[24:27]
	v_mfma_i32_16x16x64_i8 v[28:31], v[160:163], v[168:171], v[28:31]
	v_mfma_i32_16x16x64_i8 v[56:59], v[152:155], v[176:179], v[56:59]
	v_mfma_i32_16x16x64_i8 v[60:63], v[160:163], v[176:179], v[60:63]
	v_mfma_i32_16x16x64_i8 v[80:83], v[152:155], v[184:187], v[80:83]
	v_mfma_i32_16x16x64_i8 v[84:87], v[160:163], v[184:187], v[84:87]
	v_mfma_i32_16x16x64_i8 v[104:107], v[152:155], v[192:195], v[104:107]
	v_mfma_i32_16x16x64_i8 v[108:111], v[160:163], v[192:195], v[108:111]
	v_mfma_i32_16x16x64_i8 v[24:27], v[156:159], v[172:175], v[24:27]
	v_mfma_i32_16x16x64_i8 v[28:31], v[164:167], v[172:175], v[28:31]
	v_mfma_i32_16x16x64_i8 v[56:59], v[156:159], v[180:183], v[56:59]
	v_mfma_i32_16x16x64_i8 v[60:63], v[164:167], v[180:183], v[60:63]
	v_mfma_i32_16x16x64_i8 v[80:83], v[156:159], v[188:191], v[80:83]
	v_mfma_i32_16x16x64_i8 v[84:87], v[164:167], v[188:191], v[84:87]
	v_mfma_i32_16x16x64_i8 v[104:107], v[156:159], v[196:199], v[104:107]
	v_mfma_i32_16x16x64_i8 v[108:111], v[164:167], v[196:199], v[108:111]
	s_barrier
	ds_read_b128 v[168:171], v134 offset:49152
	ds_read_b128 v[172:175], v134 offset:50176
	ds_read_b128 v[176:179], v134 offset:51200
	ds_read_b128 v[180:183], v134 offset:52224
	ds_read_b128 v[184:187], v134 offset:53248
	ds_read_b128 v[188:191], v134 offset:54272
	ds_read_b128 v[192:195], v134 offset:55296
	ds_read_b128 v[196:199], v134 offset:56320
	s_add_u32 s4, s56, 0x80
	s_addc_u32 s5, s57, 0
	s_mov_b32 m0, s76
	s_nop 0
	global_load_lds_dwordx4 v130, s[4:5]
	s_mov_b32 m0, s77
	s_nop 0
	global_load_lds_dwordx4 v132, s[4:5]
	s_add_u32 s4, s56, 0x40080
	s_addc_u32 s5, s57, 0
	s_mov_b32 m0, s82
	s_nop 0
	global_load_lds_dwordx4 v130, s[4:5]
	s_mov_b32 m0, s83
	s_nop 0
	global_load_lds_dwordx4 v132, s[4:5]
	s_mov_b32 m0, s80
	s_nop 0
	global_load_lds_dwordx4 v129, s[50:51]
	s_mov_b32 m0, s81
	s_nop 0
	global_load_lds_dwordx4 v131, s[50:51]
	s_waitcnt vmcnt(8)
	s_waitcnt lgkmcnt(0)
	s_barrier
	s_waitcnt lgkmcnt(7)
	v_mfma_i32_16x16x64_i8 v[124:127], v[136:139], v[168:171], v[124:127]
	v_mfma_i32_16x16x64_i8 v[120:123], v[144:147], v[168:171], v[120:123]
	s_waitcnt lgkmcnt(5)
	v_mfma_i32_16x16x64_i8 v[92:95], v[136:139], v[176:179], v[92:95]
	v_mfma_i32_16x16x64_i8 v[88:91], v[144:147], v[176:179], v[88:91]
	s_waitcnt lgkmcnt(3)
	v_mfma_i32_16x16x64_i8 v[44:47], v[136:139], v[184:187], v[44:47]
	v_mfma_i32_16x16x64_i8 v[40:43], v[144:147], v[184:187], v[40:43]
	s_waitcnt lgkmcnt(1)
	v_mfma_i32_16x16x64_i8 v[12:15], v[136:139], v[192:195], v[12:15]
	v_mfma_i32_16x16x64_i8 v[8:11], v[144:147], v[192:195], v[8:11]
	v_mfma_i32_16x16x64_i8 v[124:127], v[140:143], v[172:175], v[124:127]
	v_mfma_i32_16x16x64_i8 v[120:123], v[148:151], v[172:175], v[120:123]
	v_mfma_i32_16x16x64_i8 v[92:95], v[140:143], v[180:183], v[92:95]
	v_mfma_i32_16x16x64_i8 v[88:91], v[148:151], v[180:183], v[88:91]
	v_mfma_i32_16x16x64_i8 v[44:47], v[140:143], v[188:191], v[44:47]
	v_mfma_i32_16x16x64_i8 v[40:43], v[148:151], v[188:191], v[40:43]
	s_waitcnt lgkmcnt(0)
	v_mfma_i32_16x16x64_i8 v[12:15], v[140:143], v[196:199], v[12:15]
	v_mfma_i32_16x16x64_i8 v[8:11], v[148:151], v[196:199], v[8:11]
	v_mfma_i32_16x16x64_i8 v[116:119], v[152:155], v[168:171], v[116:119]
	v_mfma_i32_16x16x64_i8 v[112:115], v[160:163], v[168:171], v[112:115]
	v_mfma_i32_16x16x64_i8 v[68:71], v[152:155], v[176:179], v[68:71]
	v_mfma_i32_16x16x64_i8 v[64:67], v[160:163], v[176:179], v[64:67]
	v_mfma_i32_16x16x64_i8 v[36:39], v[152:155], v[184:187], v[36:39]
	v_mfma_i32_16x16x64_i8 v[32:35], v[160:163], v[184:187], v[32:35]
	v_mfma_i32_16x16x64_i8 v[4:7], v[152:155], v[192:195], v[4:7]
	v_mfma_i32_16x16x64_i8 v[0:3], v[160:163], v[192:195], v[0:3]
	v_mfma_i32_16x16x64_i8 v[116:119], v[156:159], v[172:175], v[116:119]
	v_mfma_i32_16x16x64_i8 v[112:115], v[164:167], v[172:175], v[112:115]
	v_mfma_i32_16x16x64_i8 v[68:71], v[156:159], v[180:183], v[68:71]
	v_mfma_i32_16x16x64_i8 v[64:67], v[164:167], v[180:183], v[64:67]
	v_mfma_i32_16x16x64_i8 v[36:39], v[156:159], v[188:191], v[36:39]
	v_mfma_i32_16x16x64_i8 v[32:35], v[164:167], v[188:191], v[32:35]
	v_mfma_i32_16x16x64_i8 v[4:7], v[156:159], v[196:199], v[4:7]
	v_mfma_i32_16x16x64_i8 v[0:3], v[164:167], v[196:199], v[0:3]
	s_barrier
	s_add_i32 s1, s1, 2
	s_add_u32 s91, s91, 0x100
	s_addc_u32 s92, s92, 0
	s_add_u32 s93, s93, 0x100
	s_addc_u32 s0, s0, 0
	s_add_u32 s44, s44, 0x100
	s_addc_u32 s45, s45, 0
	s_cmp_gt_u32 s1, 13
; #define PG8_STAGE(bufoff, gbase, voff) do { _Pragma("unroll") for (int _i = 0; _i < 2; ++_i) glds16_s((gbase), (voff)[_i], ldsb + (unsigned)((bufoff) + _i * 8192)); } while (0)
; #define PG8_LDA(dst, b, h) do { _Pragma("unroll") for (int m = 0; m < 4; ++m) _Pragma("unroll") for (int k = 0; k < 2; ++k) dst[m][k] = *(const LAS h16x8*)(lds + PG8_SA(b, h) + aoff + m * 2048 + k * 1024); } while (0)
; #define PG8_LDB(dst, b, h) do { _Pragma("unroll") for (int n = 0; n < 2; ++n) _Pragma("unroll") for (int k = 0; k < 2; ++k) dst[n][k] = *(const LAS h16x8*)(lds + PG8_SB(b, h) + boff + n * 2048 + k * 1024); } while (0)
; #define PG8_MMA(ai, bj, At, Bt) do { __builtin_amdgcn_s_setprio(1); _Pragma("unroll") for (int m = 0; m < 4; ++m) _Pragma("unroll") for (int n = 0; n < 2; ++n) _Pragma("unroll") for (int k = 0; k < 2; ++k) \
;         acc[ai][bj][m][n] = mma_step<I8>(Bt[n][k], At[m][k], acc[ai][bj][m][n]); __builtin_amdgcn_s_setprio(0); } while (0)
; #define PG8_WAIT_V(n) asm volatile("s_waitcnt vmcnt(" #n ")" ::: "memory")
; #define PG8_WAIT_L(n) asm volatile("s_waitcnt lgkmcnt(" #n ")" ::: "memory")
; #define PG8_BAR __builtin_amdgcn_s_barrier()
; #define PG8_SCHED __builtin_amdgcn_sched_barrier(0)
; template <class Prob, class Epi, bool I8 = false, bool ALIGN_EPI = true, bool SP2 = true>
; __device__ __forceinline__ void gemm_phase(LAS unsigned char* lds, int wave, const Prob& P, const Epi& E) {
;     ...
;             PG8_LDB(B0, 0, 0); PG8_LDB(B1, 0, 1); PG8_SCHED; PG8_LDA(At, 0, 0); PG8_STAGE(PG8_SA(1, 1), a1 + hstepA, voffA);
;             PG8_WAIT_V(8); PG8_WAIT_L(0); PG8_BAR; PG8_MMA(0, 0, At, B0); PG8_MMA(0, 1, At, B1); PG8_BAR; PG8_SCHED;
;             PG8_LDA(At, 0, 1); PG8_STAGE(PG8_SB(0, 0), b2, voffB); PG8_STAGE(PG8_SB(0, 1), b2 + hstepB, voffB); PG8_STAGE(PG8_SA(0, 0), a2, voffA);
;             PG8_WAIT_V(8); PG8_WAIT_L(0); PG8_BAR; PG8_MMA(1, 0, At, B0); PG8_MMA(1, 1, At, B1); PG8_BAR; PG8_SCHED;
.LBB0_995:
	v_add_u32_e32 v128, 0x10000, v133
	ds_read_b128 v[136:139], v128
	ds_read_b128 v[140:143], v128 offset:1024
	ds_read_b128 v[144:147], v128 offset:2048
	ds_read_b128 v[148:151], v128 offset:3072
	v_add_u32_e32 v128, 0x14000, v133
	ds_read_b128 v[152:155], v128
	ds_read_b128 v[156:159], v128 offset:1024
	ds_read_b128 v[160:163], v128 offset:2048
	ds_read_b128 v[164:167], v128 offset:3072
	s_cmp_eq_u32 s1, 12
	s_cselect_b32 s60, s89, s91
	s_cselect_b32 s61, s29, s92
	s_cselect_b32 s56, s90, s93
	s_cselect_b32 s57, s23, s0
	s_add_u32 s50, s60, 0x80
	s_addc_u32 s51, s61, 0
	ds_read_b128 v[168:171], v134
	ds_read_b128 v[172:175], v134 offset:1024
	ds_read_b128 v[176:179], v134 offset:2048
	ds_read_b128 v[180:183], v134 offset:3072
	ds_read_b128 v[184:187], v134 offset:4096
	ds_read_b128 v[188:191], v134 offset:5120
	ds_read_b128 v[192:195], v134 offset:6144
	ds_read_b128 v[196:199], v134 offset:7168
	s_mov_b32 m0, s84
	s_nop 0
	global_load_lds_dwordx4 v129, s[44:45]
	s_mov_b32 m0, s85
	s_nop 0
	global_load_lds_dwordx4 v131, s[44:45]
	s_waitcnt vmcnt(8)
	s_waitcnt lgkmcnt(0)
	s_barrier
	s_waitcnt lgkmcnt(7)
	v_mfma_i32_16x16x64_i8 v[16:19], v[136:139], v[168:171], v[16:19]
	v_mfma_i32_16x16x64_i8 v[20:23], v[144:147], v[168:171], v[20:23]
	s_waitcnt lgkmcnt(5)
	v_mfma_i32_16x16x64_i8 v[48:51], v[136:139], v[176:179], v[48:51]
	v_mfma_i32_16x16x64_i8 v[52:55], v[144:147], v[176:179], v[52:55]
	s_waitcnt lgkmcnt(3)
	v_mfma_i32_16x16x64_i8 v[72:75], v[136:139], v[184:187], v[72:75]
	v_mfma_i32_16x16x64_i8 v[76:79], v[144:147], v[184:187], v[76:79]
	s_waitcnt lgkmcnt(1)
	v_mfma_i32_16x16x64_i8 v[96:99], v[136:139], v[192:195], v[96:99]
	v_mfma_i32_16x16x64_i8 v[100:103], v[144:147], v[192:195], v[100:103]
	v_mfma_i32_16x16x64_i8 v[16:19], v[140:143], v[172:175], v[16:19]
	v_mfma_i32_16x16x64_i8 v[20:23], v[148:151], v[172:175], v[20:23]
	v_mfma_i32_16x16x64_i8 v[48:51], v[140:143], v[180:183], v[48:51]
	v_mfma_i32_16x16x64_i8 v[52:55], v[148:151], v[180:183], v[52:55]
	v_mfma_i32_16x16x64_i8 v[72:75], v[140:143], v[188:191], v[72:75]
	v_mfma_i32_16x16x64_i8 v[76:79], v[148:151], v[188:191], v[76:79]
	s_waitcnt lgkmcnt(0)
	v_mfma_i32_16x16x64_i8 v[96:99], v[140:143], v[196:199], v[96:99]
	v_mfma_i32_16x16x64_i8 v[100:103], v[148:151], v[196:199], v[100:103]
	v_mfma_i32_16x16x64_i8 v[24:27], v[152:155], v[168:171], v[24:27]
	v_mfma_i32_16x16x64_i8 v[28:31], v[160:163], v[168:171], v[28:31]
	v_mfma_i32_16x16x64_i8 v[56:59], v[152:155], v[176:179], v[56:59]
	v_mfma_i32_16x16x64_i8 v[60:63], v[160:163], v[176:179], v[60:63]
	v_mfma_i32_16x16x64_i8 v[80:83], v[152:155], v[184:187], v[80:83]
	v_mfma_i32_16x16x64_i8 v[84:87], v[160:163], v[184:187], v[84:87]
	v_mfma_i32_16x16x64_i8 v[104:107], v[152:155], v[192:195], v[104:107]
	v_mfma_i32_16x16x64_i8 v[108:111], v[160:163], v[192:195], v[108:111]
	v_mfma_i32_16x16x64_i8 v[24:27], v[156:159], v[172:175], v[24:27]
	v_mfma_i32_16x16x64_i8 v[28:31], v[164:167], v[172:175], v[28:31]
	v_mfma_i32_16x16x64_i8 v[56:59], v[156:159], v[180:183], v[56:59]
	v_mfma_i32_16x16x64_i8 v[60:63], v[164:167], v[180:183], v[60:63]
	v_mfma_i32_16x16x64_i8 v[80:83], v[156:159], v[188:191], v[80:83]
	v_mfma_i32_16x16x64_i8 v[84:87], v[164:167], v[188:191], v[84:87]
	v_mfma_i32_16x16x64_i8 v[104:107], v[156:159], v[196:199], v[104:107]
	v_mfma_i32_16x16x64_i8 v[108:111], v[164:167], v[196:199], v[108:111]
	s_barrier
	ds_read_b128 v[168:171], v134 offset:16384
	ds_read_b128 v[172:175], v134 offset:17408
	ds_read_b128 v[176:179], v134 offset:18432
	ds_read_b128 v[180:183], v134 offset:19456
	ds_read_b128 v[184:187], v134 offset:20480
	ds_read_b128 v[188:191], v134 offset:21504
	ds_read_b128 v[192:195], v134 offset:22528
	ds_read_b128 v[196:199], v134 offset:23552
	s_mov_b32 m0, s62
	s_nop 0
	global_load_lds_dwordx4 v130, s[56:57]
	s_mov_b32 m0, s63
	s_nop 0
	global_load_lds_dwordx4 v132, s[56:57]
	s_add_u32 s4, s56, 0x40000
	s_addc_u32 s5, s57, 0
	s_mov_b32 m0, s64
	s_nop 0
	global_load_lds_dwordx4 v130, s[4:5]
	s_mov_b32 m0, s68
	s_nop 0
	global_load_lds_dwordx4 v132, s[4:5]
	s_mov_b32 m0, s2
	s_nop 0
	global_load_lds_dwordx4 v129, s[60:61]
	s_mov_b32 m0, s69
	s_nop 0
	global_load_lds_dwordx4 v131, s[60:61]
	s_waitcnt vmcnt(8)
	s_waitcnt lgkmcnt(0)
	s_barrier
	s_waitcnt lgkmcnt(7)
	v_mfma_i32_16x16x64_i8 v[124:127], v[136:139], v[168:171], v[124:127]
	v_mfma_i32_16x16x64_i8 v[120:123], v[144:147], v[168:171], v[120:123]
	s_waitcnt lgkmcnt(5)
	v_mfma_i32_16x16x64_i8 v[92:95], v[136:139], v[176:179], v[92:95]
	v_mfma_i32_16x16x64_i8 v[88:91], v[144:147], v[176:179], v[88:91]
	s_waitcnt lgkmcnt(3)
	v_mfma_i32_16x16x64_i8 v[44:47], v[136:139], v[184:187], v[44:47]
	v_mfma_i32_16x16x64_i8 v[40:43], v[144:147], v[184:187], v[40:43]
	s_waitcnt lgkmcnt(1)
	v_mfma_i32_16x16x64_i8 v[12:15], v[136:139], v[192:195], v[12:15]
	v_mfma_i32_16x16x64_i8 v[8:11], v[144:147], v[192:195], v[8:11]
	v_mfma_i32_16x16x64_i8 v[124:127], v[140:143], v[172:175], v[124:127]
	v_mfma_i32_16x16x64_i8 v[120:123], v[148:151], v[172:175], v[120:123]
	v_mfma_i32_16x16x64_i8 v[92:95], v[140:143], v[180:183], v[92:95]
	v_mfma_i32_16x16x64_i8 v[88:91], v[148:151], v[180:183], v[88:91]
	v_mfma_i32_16x16x64_i8 v[44:47], v[140:143], v[188:191], v[44:47]
	v_mfma_i32_16x16x64_i8 v[40:43], v[148:151], v[188:191], v[40:43]
	s_waitcnt lgkmcnt(0)
	v_mfma_i32_16x16x64_i8 v[12:15], v[140:143], v[196:199], v[12:15]
	v_mfma_i32_16x16x64_i8 v[8:11], v[148:151], v[196:199], v[8:11]
	v_mfma_i32_16x16x64_i8 v[116:119], v[152:155], v[168:171], v[116:119]
	v_mfma_i32_16x16x64_i8 v[112:115], v[160:163], v[168:171], v[112:115]
	v_mfma_i32_16x16x64_i8 v[68:71], v[152:155], v[176:179], v[68:71]
	v_mfma_i32_16x16x64_i8 v[64:67], v[160:163], v[176:179], v[64:67]
	v_mfma_i32_16x16x64_i8 v[36:39], v[152:155], v[184:187], v[36:39]
	v_mfma_i32_16x16x64_i8 v[32:35], v[160:163], v[184:187], v[32:35]
	v_mfma_i32_16x16x64_i8 v[4:7], v[152:155], v[192:195], v[4:7]
	v_mfma_i32_16x16x64_i8 v[0:3], v[160:163], v[192:195], v[0:3]
	v_mfma_i32_16x16x64_i8 v[116:119], v[156:159], v[172:175], v[116:119]
	v_mfma_i32_16x16x64_i8 v[112:115], v[164:167], v[172:175], v[112:115]
	v_mfma_i32_16x16x64_i8 v[68:71], v[156:159], v[180:183], v[68:71]
	v_mfma_i32_16x16x64_i8 v[64:67], v[164:167], v[180:183], v[64:67]
	v_mfma_i32_16x16x64_i8 v[36:39], v[156:159], v[188:191], v[36:39]
	v_mfma_i32_16x16x64_i8 v[32:35], v[164:167], v[188:191], v[32:35]
	v_mfma_i32_16x16x64_i8 v[4:7], v[156:159], v[196:199], v[4:7]
	v_mfma_i32_16x16x64_i8 v[0:3], v[164:167], v[196:199], v[0:3]
	s_barrier
; #define PG8_STAGE(bufoff, gbase, voff) do { _Pragma("unroll") for (int _i = 0; _i < 2; ++_i) glds16_s((gbase), (voff)[_i], ldsb + (unsigned)((bufoff) + _i * 8192)); } while (0)
; #define PG8_LDA(dst, b, h) do { _Pragma("unroll") for (int m = 0; m < 4; ++m) _Pragma("unroll") for (int k = 0; k < 2; ++k) dst[m][k] = *(const LAS h16x8*)(lds + PG8_SA(b, h) + aoff + m * 2048 + k * 1024); } while (0)
; #define PG8_LDB(dst, b, h) do { _Pragma("unroll") for (int n = 0; n < 2; ++n) _Pragma("unroll") for (int k = 0; k < 2; ++k) dst[n][k] = *(const LAS h16x8*)(lds + PG8_SB(b, h) + boff + n * 2048 + k * 1024); } while (0)
; #define PG8_MMA(ai, bj, At, Bt) do { __builtin_amdgcn_s_setprio(1); _Pragma("unroll") for (int m = 0; m < 4; ++m) _Pragma("unroll") for (int n = 0; n < 2; ++n) _Pragma("unroll") for (int k = 0; k < 2; ++k) \
;         acc[ai][bj][m][n] = mma_step<I8>(Bt[n][k], At[m][k], acc[ai][bj][m][n]); __builtin_amdgcn_s_setprio(0); } while (0)
; #define PG8_WAIT_V(n) asm volatile("s_waitcnt vmcnt(" #n ")" ::: "memory")
; #define PG8_WAIT_L(n) asm volatile("s_waitcnt lgkmcnt(" #n ")" ::: "memory")
; #define PG8_BAR __builtin_amdgcn_s_barrier()
; #define PG8_SCHED __builtin_amdgcn_sched_barrier(0)
; template <class Prob, class Epi, bool I8 = false, bool ALIGN_EPI = true, bool SP2 = true>
; __device__ __forceinline__ void gemm_phase(LAS unsigned char* lds, int wave, const Prob& P, const Epi& E) {
;     ...
;             PG8_LDB(B0, 1, 0); PG8_LDB(B1, 1, 1); PG8_SCHED; PG8_LDA(At, 1, 0); PG8_STAGE(PG8_SA(0, 1), a2 + hstepA, voffA);
;             PG8_WAIT_V(8); PG8_WAIT_L(0); PG8_BAR; PG8_MMA(0, 0, At, B0); PG8_MMA(0, 1, At, B1); PG8_BAR; PG8_SCHED;
;             PG8_LDA(At, 1, 1); PG8_STAGE(PG8_SB(1, 0), b3, voffB); PG8_STAGE(PG8_SB(1, 1), b3 + hstepB, voffB); PG8_STAGE(PG8_SA(1, 0), a3, voffA);
;             PG8_WAIT_V(8); PG8_WAIT_L(0); PG8_BAR; PG8_MMA(1, 0, At, B0); PG8_MMA(1, 1, At, B1); PG8_BAR; PG8_SCHED;
;     ...
;         if constexpr (ALIGN_EPI) { if (wr == 0) PG8_BAR; }
	v_add_u32_e32 v128, 0x18000, v133
	ds_read_b128 v[136:139], v128
	ds_read_b128 v[140:143], v128 offset:1024
	ds_read_b128 v[144:147], v128 offset:2048
	ds_read_b128 v[148:151], v128 offset:3072
	v_add_u32_e32 v128, 0x1c000, v133
	ds_read_b128 v[152:155], v128
	ds_read_b128 v[156:159], v128 offset:1024
	ds_read_b128 v[160:163], v128 offset:2048
	ds_read_b128 v[164:167], v128 offset:3072
	ds_read_b128 v[168:171], v134 offset:32768
	ds_read_b128 v[172:175], v134 offset:33792
	ds_read_b128 v[176:179], v134 offset:34816
	ds_read_b128 v[180:183], v134 offset:35840
	ds_read_b128 v[184:187], v134 offset:36864
	ds_read_b128 v[188:191], v134 offset:37888
	ds_read_b128 v[192:195], v134 offset:38912
	ds_read_b128 v[196:199], v134 offset:39936
	s_add_u32 s4, s60, 0x1000000
	s_addc_u32 s5, s61, 0
	s_mov_b32 m0, s72
	s_nop 0
	global_load_lds_dwordx4 v129, s[4:5]
	s_mov_b32 m0, s73
	s_nop 0
	global_load_lds_dwordx4 v131, s[4:5]
	s_waitcnt vmcnt(8)
	s_waitcnt lgkmcnt(0)
	s_barrier
	s_waitcnt lgkmcnt(7)
	v_mfma_i32_16x16x64_i8 v[16:19], v[136:139], v[168:171], v[16:19]
	v_mfma_i32_16x16x64_i8 v[20:23], v[144:147], v[168:171], v[20:23]
	s_waitcnt lgkmcnt(5)
	v_mfma_i32_16x16x64_i8 v[48:51], v[136:139], v[176:179], v[48:51]
	v_mfma_i32_16x16x64_i8 v[52:55], v[144:147], v[176:179], v[52:55]
	s_waitcnt lgkmcnt(3)
	v_mfma_i32_16x16x64_i8 v[72:75], v[136:139], v[184:187], v[72:75]
	v_mfma_i32_16x16x64_i8 v[76:79], v[144:147], v[184:187], v[76:79]
	s_waitcnt lgkmcnt(1)
	v_mfma_i32_16x16x64_i8 v[96:99], v[136:139], v[192:195], v[96:99]
	v_mfma_i32_16x16x64_i8 v[100:103], v[144:147], v[192:195], v[100:103]
	v_mfma_i32_16x16x64_i8 v[16:19], v[140:143], v[172:175], v[16:19]
	v_mfma_i32_16x16x64_i8 v[20:23], v[148:151], v[172:175], v[20:23]
	v_mfma_i32_16x16x64_i8 v[48:51], v[140:143], v[180:183], v[48:51]
	v_mfma_i32_16x16x64_i8 v[52:55], v[148:151], v[180:183], v[52:55]
	v_mfma_i32_16x16x64_i8 v[72:75], v[140:143], v[188:191], v[72:75]
	v_mfma_i32_16x16x64_i8 v[76:79], v[148:151], v[188:191], v[76:79]
	s_waitcnt lgkmcnt(0)
	v_mfma_i32_16x16x64_i8 v[96:99], v[140:143], v[196:199], v[96:99]
	v_mfma_i32_16x16x64_i8 v[100:103], v[148:151], v[196:199], v[100:103]
	v_mfma_i32_16x16x64_i8 v[24:27], v[152:155], v[168:171], v[24:27]
	v_mfma_i32_16x16x64_i8 v[28:31], v[160:163], v[168:171], v[28:31]
	v_mfma_i32_16x16x64_i8 v[56:59], v[152:155], v[176:179], v[56:59]
	v_mfma_i32_16x16x64_i8 v[60:63], v[160:163], v[176:179], v[60:63]
	v_mfma_i32_16x16x64_i8 v[80:83], v[152:155], v[184:187], v[80:83]
	v_mfma_i32_16x16x64_i8 v[84:87], v[160:163], v[184:187], v[84:87]
	v_mfma_i32_16x16x64_i8 v[104:107], v[152:155], v[192:195], v[104:107]
	v_mfma_i32_16x16x64_i8 v[108:111], v[160:163], v[192:195], v[108:111]
	v_mfma_i32_16x16x64_i8 v[24:27], v[156:159], v[172:175], v[24:27]
	v_mfma_i32_16x16x64_i8 v[28:31], v[164:167], v[172:175], v[28:31]
	v_mfma_i32_16x16x64_i8 v[56:59], v[156:159], v[180:183], v[56:59]
	v_mfma_i32_16x16x64_i8 v[60:63], v[164:167], v[180:183], v[60:63]
	v_mfma_i32_16x16x64_i8 v[80:83], v[156:159], v[188:191], v[80:83]
	v_mfma_i32_16x16x64_i8 v[84:87], v[164:167], v[188:191], v[84:87]
	v_mfma_i32_16x16x64_i8 v[104:107], v[156:159], v[196:199], v[104:107]
	v_mfma_i32_16x16x64_i8 v[108:111], v[164:167], v[196:199], v[108:111]
	s_barrier
	ds_read_b128 v[168:171], v134 offset:49152
	ds_read_b128 v[172:175], v134 offset:50176
	ds_read_b128 v[176:179], v134 offset:51200
	ds_read_b128 v[180:183], v134 offset:52224
	ds_read_b128 v[184:187], v134 offset:53248
	ds_read_b128 v[188:191], v134 offset:54272
	ds_read_b128 v[192:195], v134 offset:55296
	ds_read_b128 v[196:199], v134 offset:56320
	s_add_u32 s4, s56, 0x80
	s_addc_u32 s5, s57, 0
	s_mov_b32 m0, s76
	s_nop 0
	global_load_lds_dwordx4 v130, s[4:5]
	s_mov_b32 m0, s77
	s_nop 0
	global_load_lds_dwordx4 v132, s[4:5]
	s_add_u32 s4, s56, 0x40080
	s_addc_u32 s5, s57, 0
	s_mov_b32 m0, s82
	s_nop 0
	global_load_lds_dwordx4 v130, s[4:5]
	s_mov_b32 m0, s83
	s_nop 0
	global_load_lds_dwordx4 v132, s[4:5]
	s_mov_b32 m0, s80
	s_nop 0
	global_load_lds_dwordx4 v129, s[50:51]
	s_mov_b32 m0, s81
	s_nop 0
	global_load_lds_dwordx4 v131, s[50:51]
	s_waitcnt vmcnt(8)
	s_waitcnt lgkmcnt(0)
	s_barrier
	s_waitcnt lgkmcnt(7)
	v_mfma_i32_16x16x64_i8 v[124:127], v[136:139], v[168:171], v[124:127]
	v_mfma_i32_16x16x64_i8 v[120:123], v[144:147], v[168:171], v[120:123]
	s_waitcnt lgkmcnt(5)
	v_mfma_i32_16x16x64_i8 v[92:95], v[136:139], v[176:179], v[92:95]
	v_mfma_i32_16x16x64_i8 v[88:91], v[144:147], v[176:179], v[88:91]
	s_waitcnt lgkmcnt(3)
	v_mfma_i32_16x16x64_i8 v[44:47], v[136:139], v[184:187], v[44:47]
	v_mfma_i32_16x16x64_i8 v[40:43], v[144:147], v[184:187], v[40:43]
	s_waitcnt lgkmcnt(1)
	v_mfma_i32_16x16x64_i8 v[12:15], v[136:139], v[192:195], v[12:15]
	v_mfma_i32_16x16x64_i8 v[8:11], v[144:147], v[192:195], v[8:11]
	v_mfma_i32_16x16x64_i8 v[124:127], v[140:143], v[172:175], v[124:127]
	v_mfma_i32_16x16x64_i8 v[120:123], v[148:151], v[172:175], v[120:123]
	v_mfma_i32_16x16x64_i8 v[92:95], v[140:143], v[180:183], v[92:95]
	v_mfma_i32_16x16x64_i8 v[88:91], v[148:151], v[180:183], v[88:91]
	v_mfma_i32_16x16x64_i8 v[44:47], v[140:143], v[188:191], v[44:47]
	v_mfma_i32_16x16x64_i8 v[40:43], v[148:151], v[188:191], v[40:43]
	s_waitcnt lgkmcnt(0)
	v_mfma_i32_16x16x64_i8 v[12:15], v[140:143], v[196:199], v[12:15]
	v_mfma_i32_16x16x64_i8 v[8:11], v[148:151], v[196:199], v[8:11]
	v_mfma_i32_16x16x64_i8 v[116:119], v[152:155], v[168:171], v[116:119]
	v_mfma_i32_16x16x64_i8 v[112:115], v[160:163], v[168:171], v[112:115]
	v_mfma_i32_16x16x64_i8 v[68:71], v[152:155], v[176:179], v[68:71]
	v_mfma_i32_16x16x64_i8 v[64:67], v[160:163], v[176:179], v[64:67]
	v_mfma_i32_16x16x64_i8 v[36:39], v[152:155], v[184:187], v[36:39]
	v_mfma_i32_16x16x64_i8 v[32:35], v[160:163], v[184:187], v[32:35]
	v_mfma_i32_16x16x64_i8 v[4:7], v[152:155], v[192:195], v[4:7]
	v_mfma_i32_16x16x64_i8 v[0:3], v[160:163], v[192:195], v[0:3]
	v_mfma_i32_16x16x64_i8 v[116:119], v[156:159], v[172:175], v[116:119]
	v_mfma_i32_16x16x64_i8 v[112:115], v[164:167], v[172:175], v[112:115]
	v_mfma_i32_16x16x64_i8 v[68:71], v[156:159], v[180:183], v[68:71]
	v_mfma_i32_16x16x64_i8 v[64:67], v[164:167], v[180:183], v[64:67]
	v_mfma_i32_16x16x64_i8 v[36:39], v[156:159], v[188:191], v[36:39]
	v_mfma_i32_16x16x64_i8 v[32:35], v[164:167], v[188:191], v[32:35]
	v_mfma_i32_16x16x64_i8 v[4:7], v[156:159], v[196:199], v[4:7]
	v_mfma_i32_16x16x64_i8 v[0:3], v[164:167], v[196:199], v[0:3]
	s_barrier
	s_add_i32 s1, s1, 2
	s_add_u32 s91, s91, 0x100
	s_addc_u32 s92, s92, 0
	s_add_u32 s93, s93, 0x100
	s_addc_u32 s0, s0, 0
	s_add_u32 s44, s44, 0x100
	s_addc_u32 s45, s45, 0
	s_cmp_gt_u32 s1, 13
	s_cbranch_scc0 .LBB0_995
	s_and_b64 vcc, exec, s[16:17]
	s_cbranch_vccz .LBB0_998
	s_barrier

; template <class Prob, class Epi, bool I8 = false, bool ALIGN_EPI = true, bool SP2 = true>
; __device__ __forceinline__ void gemm_phase(LAS unsigned char* lds, int wave, const Prob& P, const Epi& E) {
;     const int tid_ = wave * 64 + mk_lane();
;     const int tid = tid_, wid = __builtin_amdgcn_readfirstlane(tid >> 6), lane = tid & 63, wr = wid >> 2, wc = wid & 3, fr = lane & 15, fq = lane >> 4;
;     const int K = P.K, nt = K / BK;
;     unsigned voffA[2], voffB[2];
; #pragma unroll
;     for (int i = 0; i < 2; ++i) { int R, C; stage_rc(tid * 16 + i * 8192, R, C); const int Rb = (R & ~31) + perm32(R & 31);
;         voffA[i] = P.a_rowoff(R) + (unsigned)C * 2u; voffB[i] = P.b_rowoff(Rb) + (unsigned)C * 2u; }
;     const size_t kstep = (size_t)(BK * 2);
;     const size_t hstepA = P.a_hstep(), hstepB = P.b_hstep();
;     const unsigned ldsw = (unsigned)wid * 1024u;
;     const unsigned ldsb = (unsigned)(size_t)lds + ldsw;
;     const int aoff = lds_byte(wr * 64 + fr, fq * 8), boff = lds_byte(wc * 32 + fr, fq * 8);
;     ...
;     Unit cur, nxt; int ui = 0;
;     if (!P.next(0, cur)) return;
;     Acc acc;
; #pragma unroll
;     for (int a = 0; a < 2; ++a)
; #pragma unroll
;         for (int b = 0; b < 2; ++b)
; #pragma unroll
;             for (int m = 0; m < 4; ++m)
; #pragma unroll
;                 for (int n = 0; n < 2; ++n) acc[a][b][m][n] = (f32x4){0.f, 0.f, 0.f, 0.f};
;     h16x8 At[4][2], B0[2][2], B1[2][2];
;     const char* cA = P.a_tile(cur); const char* cB = P.b_tile(cur);
;     if constexpr (SP2) {
;         PG8_STAGE(PG8_SB(0, 0), cB, voffB); PG8_STAGE(PG8_SB(0, 1), cB + hstepB, voffB); PG8_STAGE(PG8_SA(0, 0), cA, voffA); PG8_STAGE(PG8_SA(0, 1), cA + hstepA, voffA);
;         if (wr == 1) PG8_BAR;
;         PG8_WAIT_V(2); PG8_BAR;
;         PG8_STAGE(PG8_SB(1, 0), cB + kstep, voffB); PG8_STAGE(PG8_SA(1, 0), cA + kstep, voffA); PG8_STAGE(PG8_SB(1, 1), cB + hstepB + kstep, voffB);
;         PG8_WAIT_V(6); PG8_BAR;
;     __device__ bool next(int i, Unit& u) const { return S.next(i, u); }
;     __device__ unsigned a_rowoff(int R) const { const int r = upmap ? (128 * (R >> 6) + 8 * (R & 15) + ((R >> 4) & 3)) : R; return (unsigned)r * (unsigned)lda * 2u; }
;     __device__ unsigned b_rowoff(int R) const { return (unsigned)R * (unsigned)ldb * 2u; }
;     __device__ size_t a_hstep() const { return (size_t)(upmap ? 4 : 128) * lda * 2; }
.LBB0_1056:
	v_readlane_b32 s0, v254, 42
	v_readlane_b32 s4, v252, 23
	s_waitcnt lgkmcnt(0)
	s_barrier
	s_add_u32 s14, s30, 0x2d200000
	v_mbcnt_lo_u32_b32 v0, -1, 0
	v_mbcnt_hi_u32_b32 v0, -1, v0
	v_readlane_b32 s5, v252, 24
	v_add_u32_e32 v1, s0, v0
	s_addc_u32 s15, s31, 0
	v_readfirstlane_b32 s0, v1
	s_and_b64 vcc, exec, s[4:5]
	s_cbranch_vccz .LBB0_1088
	v_ashrrev_i32_e32 v3, 31, v1
	v_lshrrev_b32_e32 v3, 26, v3
	v_lshlrev_b32_e32 v2, 4, v1
	v_add_u32_e32 v3, v1, v3
	v_bfe_i32 v1, v1, 27, 1
	v_lshrrev_b32_e32 v1, 22, v1
	v_add_u32_e32 v1, v2, v1
	v_and_b32_e32 v1, 0xfffffc00, v1
	v_sub_u32_e32 v1, v2, v1
	v_lshrrev_b32_e32 v4, 4, v1
	v_bitop3_b32 v1, v4, v1, 32 bitop3:0x6c
	v_ashrrev_i32_e32 v5, 31, v1
	v_ashrrev_i32_e32 v3, 6, v3
	v_lshrrev_b32_e32 v5, 26, v5
	v_lshlrev_b32_e32 v4, 3, v3
	v_add_u32_e32 v5, v1, v5
	v_and_b32_e32 v4, -16, v4
	v_ashrrev_i32_e32 v6, 6, v5
	v_add_u32_e32 v4, v6, v4
	v_and_b32_e32 v5, 0xc0, v5
	v_sub_u32_e32 v1, v1, v5
	v_lshlrev_b32_e32 v5, 1, v4
	v_lshrrev_b32_e32 v8, 2, v4
	v_and_b32_e32 v6, 3, v6
	s_mov_b32 s1, 0x1fffe0
	v_mov_b32_e32 v9, 1
	v_and_b32_e32 v7, 24, v5
	v_and_b32_e32 v8, 4, v8
	v_and_or_b32 v6, v4, s1, v6
	v_lshlrev_b32_e32 v3, 5, v3
	v_ashrrev_i16_sdwa v1, v9, sext(v1) dst_sel:DWORD dst_unused:UNUSED_PAD src0_sel:DWORD src1_sel:BYTE_0
	v_or3_b32 v6, v6, v8, v7
	v_lshlrev_b32_e32 v7, 3, v4
	v_and_b32_e32 v3, 32, v3
	v_bfe_i32 v1, v1, 0, 16
	v_and_b32_e32 v5, 0x1fff80, v5
	v_and_b32_e32 v7, 0x78, v7
	v_bfe_u32 v4, v4, 4, 2
	v_or3_b32 v4, v5, v7, v4
	v_add_lshl_u32 v1, v3, v1, 1
	v_lshl_add_u32 v250, v4, 11, v1
	v_lshl_add_u32 v217, v6, 11, v1
	v_add_u32_e32 v1, 0x2000, v2
	v_ashrrev_i32_e32 v2, 31, v1
	v_lshrrev_b32_e32 v2, 22, v2
	v_add_u32_e32 v2, v1, v2
	v_ashrrev_i32_e32 v2, 10, v2
	v_mul_i32_i24_e32 v3, 0x400, v2
	v_sub_u32_e32 v1, v1, v3
	v_lshrrev_b32_e32 v3, 4, v1
	v_bitop3_b32 v1, v3, v1, 32 bitop3:0x6c
	v_ashrrev_i32_e32 v4, 31, v1
	v_lshrrev_b32_e32 v4, 26, v4
	v_lshlrev_b32_e32 v3, 3, v2
	v_add_u32_e32 v4, v1, v4
	v_and_b32_e32 v3, -16, v3
	v_ashrrev_i32_e32 v5, 6, v4
	v_add_u32_e32 v3, v5, v3
	v_and_b32_e32 v5, 3, v5
	v_and_b32_e32 v4, 0xc0, v4
	v_and_or_b32 v5, v3, s1, v5
	s_ashr_i32 s1, s0, 6
	v_sub_u32_e32 v1, v1, v4
	s_lshl_b32 s2, s1, 10
	s_ashr_i32 s64, s0, 8
	v_lshlrev_b32_e32 v2, 5, v2
	v_ashrrev_i16_sdwa v1, v9, sext(v1) dst_sel:DWORD dst_unused:UNUSED_PAD src0_sel:DWORD src1_sel:BYTE_0
	v_lshlrev_b32_e32 v4, 1, v3
	v_lshrrev_b32_e32 v7, 2, v3
	s_add_i32 s72, s2, 0
	v_readlane_b32 s4, v252, 48
	v_and_b32_e32 v2, 32, v2
	v_bfe_i32 v1, v1, 0, 16
	v_and_b32_e32 v6, 24, v4
	v_and_b32_e32 v7, 4, v7
	v_readlane_b32 s5, v252, 49
	s_add_u32 s44, s79, s4
	v_or3_b32 v5, v5, v7, v6
	v_add_lshl_u32 v1, v2, v1, 1
	s_addc_u32 s45, s40, s5
	s_add_i32 s73, s72, 0x10000
	s_mov_b32 m0, s73
	s_nop 0
	global_load_lds_dwordx4 v217, s[44:45]
	s_add_i32 s74, s72, 0x12000
	v_lshl_add_u32 v248, v5, 11, v1
	s_mov_b32 m0, s74
	s_nop 0
	global_load_lds_dwordx4 v248, s[44:45]
	s_add_u32 s4, s44, 0x40000
	s_addc_u32 s5, s45, 0
	s_add_i32 s75, s72, 0x14000
	s_mov_b32 m0, s75
	s_nop 0
	global_load_lds_dwordx4 v217, s[4:5]
	v_lshlrev_b32_e32 v6, 3, v3
	s_add_i32 s80, s72, 0x16000
	s_mov_b32 m0, s80
	s_nop 0
	global_load_lds_dwordx4 v248, s[4:5]
	v_readlane_b32 s4, v252, 56
	v_and_b32_e32 v4, 0x1fff80, v4
	v_and_b32_e32 v6, 0x78, v6
	v_bfe_u32 v3, v3, 4, 2
	v_readlane_b32 s5, v252, 57
	s_add_u32 s60, s41, s4
	v_or3_b32 v3, v4, v6, v3
	s_addc_u32 s61, s19, s5
	s_mov_b32 m0, s72
	s_nop 0
	global_load_lds_dwordx4 v250, s[60:61]
	s_add_i32 s81, s72, 0x2000
	v_lshl_add_u32 v247, v3, 11, v1
	s_mov_b32 m0, s81
	s_nop 0
	global_load_lds_dwordx4 v247, s[60:61]
	s_add_u32 s4, s60, 0x2000
	s_addc_u32 s5, s61, 0
	s_add_i32 s82, s72, 0x4000
	s_mov_b32 m0, s82
	s_nop 0
	global_load_lds_dwordx4 v250, s[4:5]
	s_add_i32 s83, s72, 0x6000
	s_mov_b32 m0, s83
	s_nop 0
	global_load_lds_dwordx4 v247, s[4:5]
	s_cmp_eq_u32 s64, 1
	s_cselect_b64 s[16:17], -1, 0
	s_setprio 1
	s_cmp_lg_u32 s64, 1
	s_cbranch_scc1 .LBB0_1059
	s_barrier
	s_setprio 0
.LBB0_1059:
	v_readlane_b32 s6, v255, 1
	v_readlane_b32 s84, v251, 4
	s_mul_i32 s2, s6, 0x8400
	v_readlane_b32 s86, v251, 6
	v_readlane_b32 s87, v251, 7
	s_lshl_b64 s[4:5], s[2:3], 2
	s_mov_b64 s[46:47], s[86:87]
	s_add_u32 s22, s46, s4
	v_and_b32_e32 v1, 15, v0
	v_and_b32_e32 v2, 48, v0
	v_lshlrev_b32_e32 v0, 2, v0
	s_addc_u32 s23, s47, s5
	v_lshl_or_b32 v1, v1, 6, v2
	s_lshl_b32 s2, s64, 13
	v_and_b32_e32 v0, 32, v0
	s_lshl_b32 s1, s1, 5
	v_bitop3_b32 v2, v1, s2, v0 bitop3:0xde
	s_and_b32 s84, s1, 0x60
	s_mul_i32 s2, s6, 0x2c00
	s_lshl_b32 s1, s84, 7
	s_lshl_b64 s[4:5], s[2:3], 2
	v_bitop3_b32 v0, s1, v1, v0 bitop3:0xf6
	s_add_u32 s1, s30, s4
	s_addc_u32 s2, s31, s5
	s_add_u32 s28, s1, 0x200000
	s_addc_u32 s29, s2, 0
	v_readlane_b32 s85, v251, 5
	s_add_u32 s4, s44, 0x80
	s_waitcnt vmcnt(2)
	s_barrier
	s_addc_u32 s5, s45, 0
	s_add_i32 s2, s72, 0x18000
	s_mov_b32 m0, s2
	s_nop 0
	global_load_lds_dwordx4 v217, s[4:5]
	s_add_i32 s85, s72, 0x1a000
	s_mov_b32 m0, s85
	s_nop 0
	global_load_lds_dwordx4 v248, s[4:5]
	s_add_u32 s4, s60, 0x80
	s_addc_u32 s5, s61, 0
	s_add_i32 s86, s72, 0x8000
	s_mov_b32 m0, s86
	s_nop 0
	global_load_lds_dwordx4 v250, s[4:5]
	s_add_i32 s87, s72, 0xa000
	v_readlane_b32 s88, v251, 8
	s_mov_b32 m0, s87
	s_nop 0
	global_load_lds_dwordx4 v247, s[4:5]
	s_add_u32 s4, s44, 0x40080
	v_readlane_b32 s89, v251, 9
	s_addc_u32 s5, s45, 0
	s_add_i32 s88, s72, 0x1c000
	s_mov_b32 m0, s88
	s_nop 0
	global_load_lds_dwordx4 v217, s[4:5]
	v_readlane_b32 s90, v251, 10
	s_add_i32 s89, s72, 0x1e000
	s_mov_b32 m0, s89
	s_nop 0
	global_load_lds_dwordx4 v248, s[4:5]
	s_waitcnt vmcnt(6)
	s_add_i32 s90, s72, 0xc000
	v_readlane_b32 s91, v251, 11
	s_cmpk_lt_u32 s0, 0x100
	v_readlane_b32 s0, v252, 54
	s_cselect_b64 s[46:47], -1, 0
	s_lshl_b32 s91, s64, 7
	s_add_i32 s92, s72, 0xe000
	s_mov_b32 s93, 0
	v_add_u32_e32 v210, 0, v0
	v_add_u32_e32 v211, 0, v2
	v_readlane_b32 s94, v252, 35
	s_mov_b32 s95, s0
	s_barrier
	v_readlane_b32 s1, v252, 55
	s_branch .LBB0_1062

; #define PG8_STAGE(bufoff, gbase, voff) do { _Pragma("unroll") for (int _i = 0; _i < 2; ++_i) glds16_s((gbase), (voff)[_i], ldsb + (unsigned)((bufoff) + _i * 8192)); } while (0)
; #define PG8_LDA(dst, b, h) do { _Pragma("unroll") for (int m = 0; m < 4; ++m) _Pragma("unroll") for (int k = 0; k < 2; ++k) dst[m][k] = *(const LAS h16x8*)(lds + PG8_SA(b, h) + aoff + m * 2048 + k * 1024); } while (0)
; #define PG8_LDB(dst, b, h) do { _Pragma("unroll") for (int n = 0; n < 2; ++n) _Pragma("unroll") for (int k = 0; k < 2; ++k) dst[n][k] = *(const LAS h16x8*)(lds + PG8_SB(b, h) + boff + n * 2048 + k * 1024); } while (0)
; #define PG8_MMA(ai, bj, At, Bt) do { __builtin_amdgcn_s_setprio(1); _Pragma("unroll") for (int m = 0; m < 4; ++m) _Pragma("unroll") for (int n = 0; n < 2; ++n) _Pragma("unroll") for (int k = 0; k < 2; ++k) \
;         acc[ai][bj][m][n] = mma_step<I8>(Bt[n][k], At[m][k], acc[ai][bj][m][n]); __builtin_amdgcn_s_setprio(0); } while (0)
; #define PG8_WAIT_V(n) asm volatile("s_waitcnt vmcnt(" #n ")" ::: "memory")
; #define PG8_WAIT_L(n) asm volatile("s_waitcnt lgkmcnt(" #n ")" ::: "memory")
; #define PG8_BAR __builtin_amdgcn_s_barrier()
; #define PG8_SCHED __builtin_amdgcn_sched_barrier(0)
; template <class Prob, class Epi, bool I8 = false, bool ALIGN_EPI = true, bool SP2 = true>
; __device__ __forceinline__ void gemm_phase(LAS unsigned char* lds, int wave, const Prob& P, const Epi& E) {
;     ...
;             PG8_LDB(B0, 0, 0); PG8_LDB(B1, 0, 1); PG8_SCHED; PG8_LDA(At, 0, 0); PG8_STAGE(PG8_SA(1, 1), a1 + hstepA, voffA);
;             PG8_WAIT_V(8); PG8_WAIT_L(0); PG8_BAR; PG8_MMA(0, 0, At, B0); PG8_MMA(0, 1, At, B1); PG8_BAR; PG8_SCHED;
;             PG8_LDA(At, 0, 1); PG8_STAGE(PG8_SB(0, 0), b2, voffB); PG8_STAGE(PG8_SB(0, 1), b2 + hstepB, voffB); PG8_STAGE(PG8_SA(0, 0), a2, voffA);
;             PG8_WAIT_V(8); PG8_WAIT_L(0); PG8_BAR; PG8_MMA(1, 0, At, B0); PG8_MMA(1, 1, At, B1); PG8_BAR; PG8_SCHED;
.Lpeel_1065:
	v_add_u32_e32 v124, 0x10000, v210
	v_add_u32_e32 v140, 0x14000, v210
	ds_read_b128 v[104:107], v124
	ds_read_b128 v[112:115], v124 offset:1024
	ds_read_b128 v[120:123], v124 offset:2048
	ds_read_b128 v[124:127], v124 offset:3072
	ds_read_b128 v[128:131], v140
	ds_read_b128 v[132:135], v140 offset:1024
	ds_read_b128 v[136:139], v140 offset:2048
	ds_read_b128 v[140:143], v140 offset:3072
	s_cmp_eq_u32 s4, 12
	s_cselect_b32 s62, s96, vcc_lo
	s_cselect_b32 s63, s51, vcc_hi
	s_cselect_b32 s68, s97, s0
	s_cselect_b32 s69, s49, s1
	s_add_u32 s60, s62, 0x80
	s_addc_u32 s61, s63, 0
	ds_read_b128 v[144:147], v211
	ds_read_b128 v[164:167], v211 offset:1024
	ds_read_b128 v[168:171], v211 offset:2048
	ds_read_b128 v[172:175], v211 offset:3072
	ds_read_b128 v[176:179], v211 offset:4096
	ds_read_b128 v[180:183], v211 offset:5120
	ds_read_b128 v[184:187], v211 offset:6144
	ds_read_b128 v[188:191], v211 offset:7168
	s_mov_b32 m0, s90
	s_nop 0
	global_load_lds_dwordx4 v250, s[44:45]
	s_mov_b32 m0, s92
	s_nop 0
	global_load_lds_dwordx4 v247, s[44:45]
	s_waitcnt vmcnt(8)
	s_waitcnt lgkmcnt(0)
	s_barrier
	s_waitcnt lgkmcnt(7)
	v_mfma_i32_16x16x64_i8 v[160:163], v[104:107], v[144:147], 0
	v_mfma_i32_16x16x64_i8 v[152:155], v[120:123], v[144:147], 0
	s_waitcnt lgkmcnt(5)
	v_mfma_i32_16x16x64_i8 v[52:55], v[104:107], v[168:171], 0
	v_mfma_i32_16x16x64_i8 v[80:83], v[120:123], v[168:171], 0
	s_waitcnt lgkmcnt(3)
	v_mfma_i32_16x16x64_i8 v[48:51], v[104:107], v[176:179], 0
	v_mfma_i32_16x16x64_i8 v[72:75], v[120:123], v[176:179], 0
	s_waitcnt lgkmcnt(1)
	v_mfma_i32_16x16x64_i8 v[44:47], v[104:107], v[184:187], 0
	v_mfma_i32_16x16x64_i8 v[68:71], v[120:123], v[184:187], 0
	v_mfma_i32_16x16x64_i8 v[160:163], v[112:115], v[164:167], v[160:163]
	v_mfma_i32_16x16x64_i8 v[152:155], v[124:127], v[164:167], v[152:155]
	v_mfma_i32_16x16x64_i8 v[52:55], v[112:115], v[172:175], v[52:55]
	v_mfma_i32_16x16x64_i8 v[80:83], v[124:127], v[172:175], v[80:83]
	v_mfma_i32_16x16x64_i8 v[48:51], v[112:115], v[180:183], v[48:51]
	v_mfma_i32_16x16x64_i8 v[72:75], v[124:127], v[180:183], v[72:75]
	s_waitcnt lgkmcnt(0)
	v_mfma_i32_16x16x64_i8 v[44:47], v[112:115], v[188:191], v[44:47]
	v_mfma_i32_16x16x64_i8 v[68:71], v[124:127], v[188:191], v[68:71]
	v_mfma_i32_16x16x64_i8 v[116:119], v[128:131], v[144:147], 0
	v_mfma_i32_16x16x64_i8 v[28:31], v[136:139], v[144:147], 0
	v_mfma_i32_16x16x64_i8 v[100:103], v[128:131], v[168:171], 0
	v_mfma_i32_16x16x64_i8 v[24:27], v[136:139], v[168:171], 0
	v_mfma_i32_16x16x64_i8 v[96:99], v[128:131], v[176:179], 0
	v_mfma_i32_16x16x64_i8 v[20:23], v[136:139], v[176:179], 0
	v_mfma_i32_16x16x64_i8 v[92:95], v[128:131], v[184:187], 0
	v_mfma_i32_16x16x64_i8 v[16:19], v[136:139], v[184:187], 0
	v_mfma_i32_16x16x64_i8 v[116:119], v[132:135], v[164:167], v[116:119]
	v_mfma_i32_16x16x64_i8 v[28:31], v[140:143], v[164:167], v[28:31]
	v_mfma_i32_16x16x64_i8 v[100:103], v[132:135], v[172:175], v[100:103]
	v_mfma_i32_16x16x64_i8 v[24:27], v[140:143], v[172:175], v[24:27]
	v_mfma_i32_16x16x64_i8 v[96:99], v[132:135], v[180:183], v[96:99]
	v_mfma_i32_16x16x64_i8 v[20:23], v[140:143], v[180:183], v[20:23]
	v_mfma_i32_16x16x64_i8 v[92:95], v[132:135], v[188:191], v[92:95]
	v_mfma_i32_16x16x64_i8 v[16:19], v[140:143], v[188:191], v[16:19]
	s_barrier
	ds_read_b128 v[144:147], v211 offset:16384
	ds_read_b128 v[164:167], v211 offset:17408
	ds_read_b128 v[168:171], v211 offset:18432
	ds_read_b128 v[172:175], v211 offset:19456
	ds_read_b128 v[176:179], v211 offset:20480
	ds_read_b128 v[180:183], v211 offset:21504
	ds_read_b128 v[184:187], v211 offset:22528
	ds_read_b128 v[188:191], v211 offset:23552
	s_mov_b32 m0, s73
	s_nop 0
	global_load_lds_dwordx4 v217, s[68:69]
	s_add_u32 s6, s68, 0x40000
	s_mov_b32 m0, s74
	s_nop 0
	global_load_lds_dwordx4 v248, s[68:69]
	s_addc_u32 s7, s69, 0
	s_mov_b32 m0, s75
	s_nop 0
	global_load_lds_dwordx4 v217, s[6:7]
	s_mov_b32 m0, s80
	s_nop 0
	global_load_lds_dwordx4 v248, s[6:7]
	s_mov_b32 m0, s72
	s_nop 0
	global_load_lds_dwordx4 v250, s[62:63]
	s_mov_b32 m0, s81
	s_nop 0
	global_load_lds_dwordx4 v247, s[62:63]
	s_waitcnt vmcnt(8)
	s_waitcnt lgkmcnt(0)
	s_barrier
	s_waitcnt lgkmcnt(7)
	v_mfma_i32_16x16x64_i8 v[40:43], v[104:107], v[144:147], 0
	v_mfma_i32_16x16x64_i8 v[64:67], v[120:123], v[144:147], 0
	s_waitcnt lgkmcnt(5)
	v_mfma_i32_16x16x64_i8 v[36:39], v[104:107], v[168:171], 0
	v_mfma_i32_16x16x64_i8 v[60:63], v[120:123], v[168:171], 0
	s_waitcnt lgkmcnt(3)
	v_mfma_i32_16x16x64_i8 v[32:35], v[104:107], v[176:179], 0
	v_mfma_i32_16x16x64_i8 v[56:59], v[120:123], v[176:179], 0
	s_waitcnt lgkmcnt(1)
	v_mfma_i32_16x16x64_i8 v[104:107], v[104:107], v[184:187], 0
	v_mfma_i32_16x16x64_i8 v[40:43], v[112:115], v[164:167], v[40:43]
	v_mfma_i32_16x16x64_i8 v[64:67], v[124:127], v[164:167], v[64:67]
	v_mfma_i32_16x16x64_i8 v[36:39], v[112:115], v[172:175], v[36:39]
	v_mfma_i32_16x16x64_i8 v[60:63], v[124:127], v[172:175], v[60:63]
	v_mfma_i32_16x16x64_i8 v[32:35], v[112:115], v[180:183], v[32:35]
	v_mfma_i32_16x16x64_i8 v[56:59], v[124:127], v[180:183], v[56:59]
	s_waitcnt lgkmcnt(0)
	v_mfma_i32_16x16x64_i8 v[104:107], v[112:115], v[188:191], v[104:107]
	v_mfma_i32_16x16x64_i8 v[112:115], v[120:123], v[184:187], 0
	v_mfma_i32_16x16x64_i8 v[112:115], v[124:127], v[188:191], v[112:115]
	v_mfma_i32_16x16x64_i8 v[88:91], v[128:131], v[144:147], 0
	v_mfma_i32_16x16x64_i8 v[12:15], v[136:139], v[144:147], 0
	v_mfma_i32_16x16x64_i8 v[84:87], v[128:131], v[168:171], 0
	v_mfma_i32_16x16x64_i8 v[8:11], v[136:139], v[168:171], 0
	v_mfma_i32_16x16x64_i8 v[76:79], v[128:131], v[176:179], 0
	v_mfma_i32_16x16x64_i8 v[4:7], v[136:139], v[176:179], 0
	v_mfma_i32_16x16x64_i8 v[108:111], v[128:131], v[184:187], 0
	v_mfma_i32_16x16x64_i8 v[0:3], v[136:139], v[184:187], 0
	v_mfma_i32_16x16x64_i8 v[88:91], v[132:135], v[164:167], v[88:91]
	v_mfma_i32_16x16x64_i8 v[12:15], v[140:143], v[164:167], v[12:15]
	v_mfma_i32_16x16x64_i8 v[84:87], v[132:135], v[172:175], v[84:87]
	v_mfma_i32_16x16x64_i8 v[8:11], v[140:143], v[172:175], v[8:11]
	v_mfma_i32_16x16x64_i8 v[76:79], v[132:135], v[180:183], v[76:79]
	v_mfma_i32_16x16x64_i8 v[4:7], v[140:143], v[180:183], v[4:7]
	v_mfma_i32_16x16x64_i8 v[108:111], v[132:135], v[188:191], v[108:111]
	v_mfma_i32_16x16x64_i8 v[0:3], v[140:143], v[188:191], v[0:3]
	s_barrier
; #define PG8_STAGE(bufoff, gbase, voff) do { _Pragma("unroll") for (int _i = 0; _i < 2; ++_i) glds16_s((gbase), (voff)[_i], ldsb + (unsigned)((bufoff) + _i * 8192)); } while (0)
; #define PG8_LDA(dst, b, h) do { _Pragma("unroll") for (int m = 0; m < 4; ++m) _Pragma("unroll") for (int k = 0; k < 2; ++k) dst[m][k] = *(const LAS h16x8*)(lds + PG8_SA(b, h) + aoff + m * 2048 + k * 1024); } while (0)
; #define PG8_LDB(dst, b, h) do { _Pragma("unroll") for (int n = 0; n < 2; ++n) _Pragma("unroll") for (int k = 0; k < 2; ++k) dst[n][k] = *(const LAS h16x8*)(lds + PG8_SB(b, h) + boff + n * 2048 + k * 1024); } while (0)
; #define PG8_MMA(ai, bj, At, Bt) do { __builtin_amdgcn_s_setprio(1); _Pragma("unroll") for (int m = 0; m < 4; ++m) _Pragma("unroll") for (int n = 0; n < 2; ++n) _Pragma("unroll") for (int k = 0; k < 2; ++k) \
;         acc[ai][bj][m][n] = mma_step<I8>(Bt[n][k], At[m][k], acc[ai][bj][m][n]); __builtin_amdgcn_s_setprio(0); } while (0)
; #define PG8_WAIT_V(n) asm volatile("s_waitcnt vmcnt(" #n ")" ::: "memory")
; #define PG8_WAIT_L(n) asm volatile("s_waitcnt lgkmcnt(" #n ")" ::: "memory")
; #define PG8_BAR __builtin_amdgcn_s_barrier()
; #define PG8_SCHED __builtin_amdgcn_sched_barrier(0)
; template <class Prob, class Epi, bool I8 = false, bool ALIGN_EPI = true, bool SP2 = true>
; __device__ __forceinline__ void gemm_phase(LAS unsigned char* lds, int wave, const Prob& P, const Epi& E) {
;     ...
;             PG8_LDB(B0, 1, 0); PG8_LDB(B1, 1, 1); PG8_SCHED; PG8_LDA(At, 1, 0); PG8_STAGE(PG8_SA(0, 1), a2 + hstepA, voffA);
;             PG8_WAIT_V(8); PG8_WAIT_L(0); PG8_BAR; PG8_MMA(0, 0, At, B0); PG8_MMA(0, 1, At, B1); PG8_BAR; PG8_SCHED;
;             PG8_LDA(At, 1, 1); PG8_STAGE(PG8_SB(1, 0), b3, voffB); PG8_STAGE(PG8_SB(1, 1), b3 + hstepB, voffB); PG8_STAGE(PG8_SA(1, 0), a3, voffA);
;             PG8_WAIT_V(8); PG8_WAIT_L(0); PG8_BAR; PG8_MMA(1, 0, At, B0); PG8_MMA(1, 1, At, B1); PG8_BAR; PG8_SCHED;
	v_add_u32_e32 v132, 0x18000, v210
	v_add_u32_e32 v148, 0x1c000, v210
	ds_read_b128 v[120:123], v132
	ds_read_b128 v[124:127], v132 offset:1024
	ds_read_b128 v[128:131], v132 offset:2048
	ds_read_b128 v[132:135], v132 offset:3072
	ds_read_b128 v[136:139], v148
	ds_read_b128 v[140:143], v148 offset:1024
	ds_read_b128 v[144:147], v148 offset:2048
	ds_read_b128 v[164:167], v148 offset:3072
	ds_read_b128 v[148:151], v211 offset:32768
	ds_read_b128 v[156:159], v211 offset:33792
	ds_read_b128 v[168:171], v211 offset:34816
	ds_read_b128 v[172:175], v211 offset:35840
	ds_read_b128 v[176:179], v211 offset:36864
	ds_read_b128 v[180:183], v211 offset:37888
	ds_read_b128 v[184:187], v211 offset:38912
	ds_read_b128 v[188:191], v211 offset:39936
	s_add_u32 s6, s62, 0x2000
	s_addc_u32 s7, s63, 0
	s_mov_b32 m0, s82
	s_nop 0
	global_load_lds_dwordx4 v250, s[6:7]
	s_mov_b32 m0, s83
	s_nop 0
	global_load_lds_dwordx4 v247, s[6:7]
	s_waitcnt vmcnt(8)
	s_waitcnt lgkmcnt(0)
	s_barrier
	s_waitcnt lgkmcnt(7)
	v_mfma_i32_16x16x64_i8 v[160:163], v[120:123], v[148:151], v[160:163]
	v_mfma_i32_16x16x64_i8 v[152:155], v[128:131], v[148:151], v[152:155]
	s_waitcnt lgkmcnt(5)
	v_mfma_i32_16x16x64_i8 v[52:55], v[120:123], v[168:171], v[52:55]
	v_mfma_i32_16x16x64_i8 v[80:83], v[128:131], v[168:171], v[80:83]
	s_waitcnt lgkmcnt(3)
	v_mfma_i32_16x16x64_i8 v[48:51], v[120:123], v[176:179], v[48:51]
	v_mfma_i32_16x16x64_i8 v[72:75], v[128:131], v[176:179], v[72:75]
	s_waitcnt lgkmcnt(1)
	v_mfma_i32_16x16x64_i8 v[44:47], v[120:123], v[184:187], v[44:47]
	v_mfma_i32_16x16x64_i8 v[68:71], v[128:131], v[184:187], v[68:71]
	v_mfma_i32_16x16x64_i8 v[160:163], v[124:127], v[156:159], v[160:163]
	v_mfma_i32_16x16x64_i8 v[152:155], v[132:135], v[156:159], v[152:155]
	v_mfma_i32_16x16x64_i8 v[52:55], v[124:127], v[172:175], v[52:55]
	v_mfma_i32_16x16x64_i8 v[80:83], v[132:135], v[172:175], v[80:83]
	v_mfma_i32_16x16x64_i8 v[48:51], v[124:127], v[180:183], v[48:51]
	v_mfma_i32_16x16x64_i8 v[72:75], v[132:135], v[180:183], v[72:75]
	s_waitcnt lgkmcnt(0)
	v_mfma_i32_16x16x64_i8 v[44:47], v[124:127], v[188:191], v[44:47]
	v_mfma_i32_16x16x64_i8 v[68:71], v[132:135], v[188:191], v[68:71]
	v_mfma_i32_16x16x64_i8 v[116:119], v[136:139], v[148:151], v[116:119]
	v_mfma_i32_16x16x64_i8 v[28:31], v[144:147], v[148:151], v[28:31]
	v_mfma_i32_16x16x64_i8 v[100:103], v[136:139], v[168:171], v[100:103]
	v_mfma_i32_16x16x64_i8 v[24:27], v[144:147], v[168:171], v[24:27]
	v_mfma_i32_16x16x64_i8 v[96:99], v[136:139], v[176:179], v[96:99]
	v_mfma_i32_16x16x64_i8 v[20:23], v[144:147], v[176:179], v[20:23]
	v_mfma_i32_16x16x64_i8 v[92:95], v[136:139], v[184:187], v[92:95]
	v_mfma_i32_16x16x64_i8 v[16:19], v[144:147], v[184:187], v[16:19]
	v_mfma_i32_16x16x64_i8 v[116:119], v[140:143], v[156:159], v[116:119]
	v_mfma_i32_16x16x64_i8 v[28:31], v[164:167], v[156:159], v[28:31]
	v_mfma_i32_16x16x64_i8 v[100:103], v[140:143], v[172:175], v[100:103]
	v_mfma_i32_16x16x64_i8 v[24:27], v[164:167], v[172:175], v[24:27]
	v_mfma_i32_16x16x64_i8 v[96:99], v[140:143], v[180:183], v[96:99]
	v_mfma_i32_16x16x64_i8 v[20:23], v[164:167], v[180:183], v[20:23]
	v_mfma_i32_16x16x64_i8 v[92:95], v[140:143], v[188:191], v[92:95]
	v_mfma_i32_16x16x64_i8 v[16:19], v[164:167], v[188:191], v[16:19]
	s_barrier
	ds_read_b128 v[168:171], v211 offset:49152
	ds_read_b128 v[172:175], v211 offset:50176
	ds_read_b128 v[176:179], v211 offset:51200
	ds_read_b128 v[180:183], v211 offset:52224
	ds_read_b128 v[184:187], v211 offset:53248
	ds_read_b128 v[188:191], v211 offset:54272
	ds_read_b128 v[192:195], v211 offset:55296
	ds_read_b128 v[196:199], v211 offset:56320
	s_add_u32 s6, s68, 0x80
	s_addc_u32 s7, s69, 0
	s_mov_b32 m0, s2
	s_nop 0
	global_load_lds_dwordx4 v217, s[6:7]
	s_mov_b32 m0, s85
	s_nop 0
	global_load_lds_dwordx4 v248, s[6:7]
	s_add_u32 s6, s68, 0x40080
	s_addc_u32 s7, s69, 0
	s_mov_b32 m0, s88
	s_nop 0
	global_load_lds_dwordx4 v217, s[6:7]
	s_mov_b32 m0, s89
	s_nop 0
	global_load_lds_dwordx4 v248, s[6:7]
	s_mov_b32 m0, s86
	s_nop 0
	global_load_lds_dwordx4 v250, s[60:61]
	s_mov_b32 m0, s87
	s_nop 0
	global_load_lds_dwordx4 v247, s[60:61]
	s_waitcnt vmcnt(8)
	s_waitcnt lgkmcnt(0)
	s_barrier
	s_waitcnt lgkmcnt(1)
	v_mfma_i32_16x16x64_i8 v[104:107], v[120:123], v[192:195], v[104:107]
	v_mfma_i32_16x16x64_i8 v[40:43], v[120:123], v[168:171], v[40:43]
	v_mfma_i32_16x16x64_i8 v[64:67], v[128:131], v[168:171], v[64:67]
	v_mfma_i32_16x16x64_i8 v[36:39], v[120:123], v[176:179], v[36:39]
	v_mfma_i32_16x16x64_i8 v[60:63], v[128:131], v[176:179], v[60:63]
	v_mfma_i32_16x16x64_i8 v[32:35], v[120:123], v[184:187], v[32:35]
	v_mfma_i32_16x16x64_i8 v[56:59], v[128:131], v[184:187], v[56:59]
	s_waitcnt lgkmcnt(0)
	v_mfma_i32_16x16x64_i8 v[156:159], v[124:127], v[196:199], v[104:107]
	v_mfma_i32_16x16x64_i8 v[104:107], v[128:131], v[192:195], v[112:115]
	v_mfma_i32_16x16x64_i8 v[40:43], v[124:127], v[172:175], v[40:43]
	v_mfma_i32_16x16x64_i8 v[64:67], v[132:135], v[172:175], v[64:67]
	v_mfma_i32_16x16x64_i8 v[36:39], v[124:127], v[180:183], v[36:39]
	v_mfma_i32_16x16x64_i8 v[60:63], v[132:135], v[180:183], v[60:63]
	v_mfma_i32_16x16x64_i8 v[32:35], v[124:127], v[188:191], v[32:35]
	v_mfma_i32_16x16x64_i8 v[56:59], v[132:135], v[188:191], v[56:59]
	v_mfma_i32_16x16x64_i8 v[148:151], v[132:135], v[196:199], v[104:107]
	v_mfma_i32_16x16x64_i8 v[88:91], v[136:139], v[168:171], v[88:91]
	v_mfma_i32_16x16x64_i8 v[12:15], v[144:147], v[168:171], v[12:15]
	v_mfma_i32_16x16x64_i8 v[84:87], v[136:139], v[176:179], v[84:87]
	v_mfma_i32_16x16x64_i8 v[8:11], v[144:147], v[176:179], v[8:11]
	v_mfma_i32_16x16x64_i8 v[76:79], v[136:139], v[184:187], v[76:79]
	v_mfma_i32_16x16x64_i8 v[4:7], v[144:147], v[184:187], v[4:7]
	v_mfma_i32_16x16x64_i8 v[104:107], v[136:139], v[192:195], v[108:111]
	v_mfma_i32_16x16x64_i8 v[0:3], v[144:147], v[192:195], v[0:3]
	v_mfma_i32_16x16x64_i8 v[88:91], v[140:143], v[172:175], v[88:91]
	v_mfma_i32_16x16x64_i8 v[12:15], v[164:167], v[172:175], v[12:15]
	v_mfma_i32_16x16x64_i8 v[84:87], v[140:143], v[180:183], v[84:87]
	v_mfma_i32_16x16x64_i8 v[8:11], v[164:167], v[180:183], v[8:11]
	v_mfma_i32_16x16x64_i8 v[76:79], v[140:143], v[188:191], v[76:79]
	v_mfma_i32_16x16x64_i8 v[4:7], v[164:167], v[188:191], v[4:7]
	v_mfma_i32_16x16x64_i8 v[108:111], v[140:143], v[196:199], v[104:107]
	v_mfma_i32_16x16x64_i8 v[0:3], v[164:167], v[196:199], v[0:3]
	s_barrier
	s_add_i32 s4, s4, 2
	s_add_u32 vcc_lo, vcc_lo, 0x100
	s_addc_u32 vcc_hi, vcc_hi, 0
	s_add_u32 s0, s0, 0x100
	s_addc_u32 s1, s1, 0
	s_add_u32 s44, s44, 0x100
	s_addc_u32 s45, s45, 0
	s_cmp_gt_u32 s4, 13
; #define PG8_STAGE(bufoff, gbase, voff) do { _Pragma("unroll") for (int _i = 0; _i < 2; ++_i) glds16_s((gbase), (voff)[_i], ldsb + (unsigned)((bufoff) + _i * 8192)); } while (0)
; #define PG8_LDA(dst, b, h) do { _Pragma("unroll") for (int m = 0; m < 4; ++m) _Pragma("unroll") for (int k = 0; k < 2; ++k) dst[m][k] = *(const LAS h16x8*)(lds + PG8_SA(b, h) + aoff + m * 2048 + k * 1024); } while (0)
; #define PG8_LDB(dst, b, h) do { _Pragma("unroll") for (int n = 0; n < 2; ++n) _Pragma("unroll") for (int k = 0; k < 2; ++k) dst[n][k] = *(const LAS h16x8*)(lds + PG8_SB(b, h) + boff + n * 2048 + k * 1024); } while (0)
; #define PG8_MMA(ai, bj, At, Bt) do { __builtin_amdgcn_s_setprio(1); _Pragma("unroll") for (int m = 0; m < 4; ++m) _Pragma("unroll") for (int n = 0; n < 2; ++n) _Pragma("unroll") for (int k = 0; k < 2; ++k) \
;         acc[ai][bj][m][n] = mma_step<I8>(Bt[n][k], At[m][k], acc[ai][bj][m][n]); __builtin_amdgcn_s_setprio(0); } while (0)
; #define PG8_WAIT_V(n) asm volatile("s_waitcnt vmcnt(" #n ")" ::: "memory")
; #define PG8_WAIT_L(n) asm volatile("s_waitcnt lgkmcnt(" #n ")" ::: "memory")
; #define PG8_BAR __builtin_amdgcn_s_barrier()
; #define PG8_SCHED __builtin_amdgcn_sched_barrier(0)
; template <class Prob, class Epi, bool I8 = false, bool ALIGN_EPI = true, bool SP2 = true>
; __device__ __forceinline__ void gemm_phase(LAS unsigned char* lds, int wave, const Prob& P, const Epi& E) {
;     ...
;             PG8_LDB(B0, 0, 0); PG8_LDB(B1, 0, 1); PG8_SCHED; PG8_LDA(At, 0, 0); PG8_STAGE(PG8_SA(1, 1), a1 + hstepA, voffA);
;             PG8_WAIT_V(8); PG8_WAIT_L(0); PG8_BAR; PG8_MMA(0, 0, At, B0); PG8_MMA(0, 1, At, B1); PG8_BAR; PG8_SCHED;
;             PG8_LDA(At, 0, 1); PG8_STAGE(PG8_SB(0, 0), b2, voffB); PG8_STAGE(PG8_SB(0, 1), b2 + hstepB, voffB); PG8_STAGE(PG8_SA(0, 0), a2, voffA);
;             PG8_WAIT_V(8); PG8_WAIT_L(0); PG8_BAR; PG8_MMA(1, 0, At, B0); PG8_MMA(1, 1, At, B1); PG8_BAR; PG8_SCHED;
.LBB0_1065:
	v_add_u32_e32 v124, 0x10000, v210
	v_add_u32_e32 v140, 0x14000, v210
	ds_read_b128 v[104:107], v124
	ds_read_b128 v[112:115], v124 offset:1024
	ds_read_b128 v[120:123], v124 offset:2048
	ds_read_b128 v[124:127], v124 offset:3072
	ds_read_b128 v[128:131], v140
	ds_read_b128 v[132:135], v140 offset:1024
	ds_read_b128 v[136:139], v140 offset:2048
	ds_read_b128 v[140:143], v140 offset:3072
	s_cmp_eq_u32 s4, 12
	s_cselect_b32 s62, s96, vcc_lo
	s_cselect_b32 s63, s51, vcc_hi
	s_cselect_b32 s68, s97, s0
	s_cselect_b32 s69, s49, s1
	s_add_u32 s60, s62, 0x80
	s_addc_u32 s61, s63, 0
	ds_read_b128 v[144:147], v211
	ds_read_b128 v[164:167], v211 offset:1024
	ds_read_b128 v[168:171], v211 offset:2048
	ds_read_b128 v[172:175], v211 offset:3072
	ds_read_b128 v[176:179], v211 offset:4096
	ds_read_b128 v[180:183], v211 offset:5120
	ds_read_b128 v[184:187], v211 offset:6144
	ds_read_b128 v[188:191], v211 offset:7168
	s_mov_b32 m0, s90
	s_nop 0
	global_load_lds_dwordx4 v250, s[44:45]
	s_mov_b32 m0, s92
	s_nop 0
	global_load_lds_dwordx4 v247, s[44:45]
	s_waitcnt vmcnt(8)
	s_waitcnt lgkmcnt(0)
	s_barrier
	s_waitcnt lgkmcnt(7)
	v_mfma_i32_16x16x64_i8 v[160:163], v[104:107], v[144:147], v[160:163]
	v_mfma_i32_16x16x64_i8 v[152:155], v[120:123], v[144:147], v[152:155]
	s_waitcnt lgkmcnt(5)
	v_mfma_i32_16x16x64_i8 v[52:55], v[104:107], v[168:171], v[52:55]
	v_mfma_i32_16x16x64_i8 v[80:83], v[120:123], v[168:171], v[80:83]
	s_waitcnt lgkmcnt(3)
	v_mfma_i32_16x16x64_i8 v[48:51], v[104:107], v[176:179], v[48:51]
	v_mfma_i32_16x16x64_i8 v[72:75], v[120:123], v[176:179], v[72:75]
	s_waitcnt lgkmcnt(1)
	v_mfma_i32_16x16x64_i8 v[44:47], v[104:107], v[184:187], v[44:47]
	v_mfma_i32_16x16x64_i8 v[68:71], v[120:123], v[184:187], v[68:71]
	v_mfma_i32_16x16x64_i8 v[160:163], v[112:115], v[164:167], v[160:163]
	v_mfma_i32_16x16x64_i8 v[152:155], v[124:127], v[164:167], v[152:155]
	v_mfma_i32_16x16x64_i8 v[52:55], v[112:115], v[172:175], v[52:55]
	v_mfma_i32_16x16x64_i8 v[80:83], v[124:127], v[172:175], v[80:83]
	v_mfma_i32_16x16x64_i8 v[48:51], v[112:115], v[180:183], v[48:51]
	v_mfma_i32_16x16x64_i8 v[72:75], v[124:127], v[180:183], v[72:75]
	s_waitcnt lgkmcnt(0)
	v_mfma_i32_16x16x64_i8 v[44:47], v[112:115], v[188:191], v[44:47]
	v_mfma_i32_16x16x64_i8 v[68:71], v[124:127], v[188:191], v[68:71]
	v_mfma_i32_16x16x64_i8 v[116:119], v[128:131], v[144:147], v[116:119]
	v_mfma_i32_16x16x64_i8 v[28:31], v[136:139], v[144:147], v[28:31]
	v_mfma_i32_16x16x64_i8 v[100:103], v[128:131], v[168:171], v[100:103]
	v_mfma_i32_16x16x64_i8 v[24:27], v[136:139], v[168:171], v[24:27]
	v_mfma_i32_16x16x64_i8 v[96:99], v[128:131], v[176:179], v[96:99]
	v_mfma_i32_16x16x64_i8 v[20:23], v[136:139], v[176:179], v[20:23]
	v_mfma_i32_16x16x64_i8 v[92:95], v[128:131], v[184:187], v[92:95]
	v_mfma_i32_16x16x64_i8 v[16:19], v[136:139], v[184:187], v[16:19]
	v_mfma_i32_16x16x64_i8 v[116:119], v[132:135], v[164:167], v[116:119]
	v_mfma_i32_16x16x64_i8 v[28:31], v[140:143], v[164:167], v[28:31]
	v_mfma_i32_16x16x64_i8 v[100:103], v[132:135], v[172:175], v[100:103]
	v_mfma_i32_16x16x64_i8 v[24:27], v[140:143], v[172:175], v[24:27]
	v_mfma_i32_16x16x64_i8 v[96:99], v[132:135], v[180:183], v[96:99]
	v_mfma_i32_16x16x64_i8 v[20:23], v[140:143], v[180:183], v[20:23]
	v_mfma_i32_16x16x64_i8 v[92:95], v[132:135], v[188:191], v[92:95]
	v_mfma_i32_16x16x64_i8 v[16:19], v[140:143], v[188:191], v[16:19]
	s_barrier
	ds_read_b128 v[144:147], v211 offset:16384
	ds_read_b128 v[164:167], v211 offset:17408
	ds_read_b128 v[168:171], v211 offset:18432
	ds_read_b128 v[172:175], v211 offset:19456
	ds_read_b128 v[176:179], v211 offset:20480
	ds_read_b128 v[180:183], v211 offset:21504
	ds_read_b128 v[184:187], v211 offset:22528
	ds_read_b128 v[188:191], v211 offset:23552
	s_mov_b32 m0, s73
	s_nop 0
	global_load_lds_dwordx4 v217, s[68:69]
	s_add_u32 s6, s68, 0x40000
	s_mov_b32 m0, s74
	s_nop 0
	global_load_lds_dwordx4 v248, s[68:69]
	s_addc_u32 s7, s69, 0
	s_mov_b32 m0, s75
	s_nop 0
	global_load_lds_dwordx4 v217, s[6:7]
	s_mov_b32 m0, s80
	s_nop 0
	global_load_lds_dwordx4 v248, s[6:7]
	s_mov_b32 m0, s72
	s_nop 0
	global_load_lds_dwordx4 v250, s[62:63]
	s_mov_b32 m0, s81
	s_nop 0
	global_load_lds_dwordx4 v247, s[62:63]
	s_waitcnt vmcnt(8)
	s_waitcnt lgkmcnt(0)
	s_barrier
	s_waitcnt lgkmcnt(7)
	v_mfma_i32_16x16x64_i8 v[40:43], v[104:107], v[144:147], v[40:43]
	v_mfma_i32_16x16x64_i8 v[64:67], v[120:123], v[144:147], v[64:67]
	s_waitcnt lgkmcnt(5)
	v_mfma_i32_16x16x64_i8 v[36:39], v[104:107], v[168:171], v[36:39]
	v_mfma_i32_16x16x64_i8 v[60:63], v[120:123], v[168:171], v[60:63]
	s_waitcnt lgkmcnt(3)
	v_mfma_i32_16x16x64_i8 v[32:35], v[104:107], v[176:179], v[32:35]
	v_mfma_i32_16x16x64_i8 v[56:59], v[120:123], v[176:179], v[56:59]
	s_waitcnt lgkmcnt(1)
	v_mfma_i32_16x16x64_i8 v[104:107], v[104:107], v[184:187], v[156:159]
	v_mfma_i32_16x16x64_i8 v[40:43], v[112:115], v[164:167], v[40:43]
	v_mfma_i32_16x16x64_i8 v[64:67], v[124:127], v[164:167], v[64:67]
	v_mfma_i32_16x16x64_i8 v[36:39], v[112:115], v[172:175], v[36:39]
	v_mfma_i32_16x16x64_i8 v[60:63], v[124:127], v[172:175], v[60:63]
	v_mfma_i32_16x16x64_i8 v[32:35], v[112:115], v[180:183], v[32:35]
	v_mfma_i32_16x16x64_i8 v[56:59], v[124:127], v[180:183], v[56:59]
	s_waitcnt lgkmcnt(0)
	v_mfma_i32_16x16x64_i8 v[104:107], v[112:115], v[188:191], v[104:107]
	v_mfma_i32_16x16x64_i8 v[112:115], v[120:123], v[184:187], v[148:151]
	v_mfma_i32_16x16x64_i8 v[112:115], v[124:127], v[188:191], v[112:115]
	v_mfma_i32_16x16x64_i8 v[88:91], v[128:131], v[144:147], v[88:91]
	v_mfma_i32_16x16x64_i8 v[12:15], v[136:139], v[144:147], v[12:15]
	v_mfma_i32_16x16x64_i8 v[84:87], v[128:131], v[168:171], v[84:87]
	v_mfma_i32_16x16x64_i8 v[8:11], v[136:139], v[168:171], v[8:11]
	v_mfma_i32_16x16x64_i8 v[76:79], v[128:131], v[176:179], v[76:79]
	v_mfma_i32_16x16x64_i8 v[4:7], v[136:139], v[176:179], v[4:7]
	v_mfma_i32_16x16x64_i8 v[108:111], v[128:131], v[184:187], v[108:111]
	v_mfma_i32_16x16x64_i8 v[0:3], v[136:139], v[184:187], v[0:3]
	v_mfma_i32_16x16x64_i8 v[88:91], v[132:135], v[164:167], v[88:91]
	v_mfma_i32_16x16x64_i8 v[12:15], v[140:143], v[164:167], v[12:15]
	v_mfma_i32_16x16x64_i8 v[84:87], v[132:135], v[172:175], v[84:87]
	v_mfma_i32_16x16x64_i8 v[8:11], v[140:143], v[172:175], v[8:11]
	v_mfma_i32_16x16x64_i8 v[76:79], v[132:135], v[180:183], v[76:79]
	v_mfma_i32_16x16x64_i8 v[4:7], v[140:143], v[180:183], v[4:7]
	v_mfma_i32_16x16x64_i8 v[108:111], v[132:135], v[188:191], v[108:111]
	v_mfma_i32_16x16x64_i8 v[0:3], v[140:143], v[188:191], v[0:3]
	s_barrier
; #define PG8_STAGE(bufoff, gbase, voff) do { _Pragma("unroll") for (int _i = 0; _i < 2; ++_i) glds16_s((gbase), (voff)[_i], ldsb + (unsigned)((bufoff) + _i * 8192)); } while (0)
; #define PG8_LDA(dst, b, h) do { _Pragma("unroll") for (int m = 0; m < 4; ++m) _Pragma("unroll") for (int k = 0; k < 2; ++k) dst[m][k] = *(const LAS h16x8*)(lds + PG8_SA(b, h) + aoff + m * 2048 + k * 1024); } while (0)
; #define PG8_LDB(dst, b, h) do { _Pragma("unroll") for (int n = 0; n < 2; ++n) _Pragma("unroll") for (int k = 0; k < 2; ++k) dst[n][k] = *(const LAS h16x8*)(lds + PG8_SB(b, h) + boff + n * 2048 + k * 1024); } while (0)
; #define PG8_MMA(ai, bj, At, Bt) do { __builtin_amdgcn_s_setprio(1); _Pragma("unroll") for (int m = 0; m < 4; ++m) _Pragma("unroll") for (int n = 0; n < 2; ++n) _Pragma("unroll") for (int k = 0; k < 2; ++k) \
;         acc[ai][bj][m][n] = mma_step<I8>(Bt[n][k], At[m][k], acc[ai][bj][m][n]); __builtin_amdgcn_s_setprio(0); } while (0)
; #define PG8_WAIT_V(n) asm volatile("s_waitcnt vmcnt(" #n ")" ::: "memory")
; #define PG8_WAIT_L(n) asm volatile("s_waitcnt lgkmcnt(" #n ")" ::: "memory")
; #define PG8_BAR __builtin_amdgcn_s_barrier()
; #define PG8_SCHED __builtin_amdgcn_sched_barrier(0)
; template <class Prob, class Epi, bool I8 = false, bool ALIGN_EPI = true, bool SP2 = true>
; __device__ __forceinline__ void gemm_phase(LAS unsigned char* lds, int wave, const Prob& P, const Epi& E) {
;     ...
;             PG8_LDB(B0, 1, 0); PG8_LDB(B1, 1, 1); PG8_SCHED; PG8_LDA(At, 1, 0); PG8_STAGE(PG8_SA(0, 1), a2 + hstepA, voffA);
;             PG8_WAIT_V(8); PG8_WAIT_L(0); PG8_BAR; PG8_MMA(0, 0, At, B0); PG8_MMA(0, 1, At, B1); PG8_BAR; PG8_SCHED;
;             PG8_LDA(At, 1, 1); PG8_STAGE(PG8_SB(1, 0), b3, voffB); PG8_STAGE(PG8_SB(1, 1), b3 + hstepB, voffB); PG8_STAGE(PG8_SA(1, 0), a3, voffA);
;             PG8_WAIT_V(8); PG8_WAIT_L(0); PG8_BAR; PG8_MMA(1, 0, At, B0); PG8_MMA(1, 1, At, B1); PG8_BAR; PG8_SCHED;
;     ...
;         if constexpr (ALIGN_EPI) { if (wr == 0) PG8_BAR; }
; __device__ __forceinline__ float silu_f(float x) { return x * __builtin_amdgcn_rcpf(1.0f + __expf(-x)); }
	v_add_u32_e32 v132, 0x18000, v210
	v_add_u32_e32 v148, 0x1c000, v210
	ds_read_b128 v[120:123], v132
	ds_read_b128 v[124:127], v132 offset:1024
	ds_read_b128 v[128:131], v132 offset:2048
	ds_read_b128 v[132:135], v132 offset:3072
	ds_read_b128 v[136:139], v148
	ds_read_b128 v[140:143], v148 offset:1024
	ds_read_b128 v[144:147], v148 offset:2048
	ds_read_b128 v[164:167], v148 offset:3072
	ds_read_b128 v[148:151], v211 offset:32768
	ds_read_b128 v[156:159], v211 offset:33792
	ds_read_b128 v[168:171], v211 offset:34816
	ds_read_b128 v[172:175], v211 offset:35840
	ds_read_b128 v[176:179], v211 offset:36864
	ds_read_b128 v[180:183], v211 offset:37888
	ds_read_b128 v[184:187], v211 offset:38912
	ds_read_b128 v[188:191], v211 offset:39936
	s_add_u32 s6, s62, 0x2000
	s_addc_u32 s7, s63, 0
	s_mov_b32 m0, s82
	s_nop 0
	global_load_lds_dwordx4 v250, s[6:7]
	s_mov_b32 m0, s83
	s_nop 0
	global_load_lds_dwordx4 v247, s[6:7]
	s_waitcnt vmcnt(8)
	s_waitcnt lgkmcnt(0)
	s_barrier
	s_waitcnt lgkmcnt(7)
	v_mfma_i32_16x16x64_i8 v[160:163], v[120:123], v[148:151], v[160:163]
	v_mfma_i32_16x16x64_i8 v[152:155], v[128:131], v[148:151], v[152:155]
	s_waitcnt lgkmcnt(5)
	v_mfma_i32_16x16x64_i8 v[52:55], v[120:123], v[168:171], v[52:55]
	v_mfma_i32_16x16x64_i8 v[80:83], v[128:131], v[168:171], v[80:83]
	s_waitcnt lgkmcnt(3)
	v_mfma_i32_16x16x64_i8 v[48:51], v[120:123], v[176:179], v[48:51]
	v_mfma_i32_16x16x64_i8 v[72:75], v[128:131], v[176:179], v[72:75]
	s_waitcnt lgkmcnt(1)
	v_mfma_i32_16x16x64_i8 v[44:47], v[120:123], v[184:187], v[44:47]
	v_mfma_i32_16x16x64_i8 v[68:71], v[128:131], v[184:187], v[68:71]
	v_mfma_i32_16x16x64_i8 v[160:163], v[124:127], v[156:159], v[160:163]
	v_mfma_i32_16x16x64_i8 v[152:155], v[132:135], v[156:159], v[152:155]
	v_mfma_i32_16x16x64_i8 v[52:55], v[124:127], v[172:175], v[52:55]
	v_mfma_i32_16x16x64_i8 v[80:83], v[132:135], v[172:175], v[80:83]
	v_mfma_i32_16x16x64_i8 v[48:51], v[124:127], v[180:183], v[48:51]
	v_mfma_i32_16x16x64_i8 v[72:75], v[132:135], v[180:183], v[72:75]
	s_waitcnt lgkmcnt(0)
	v_mfma_i32_16x16x64_i8 v[44:47], v[124:127], v[188:191], v[44:47]
	v_mfma_i32_16x16x64_i8 v[68:71], v[132:135], v[188:191], v[68:71]
	v_mfma_i32_16x16x64_i8 v[116:119], v[136:139], v[148:151], v[116:119]
	v_mfma_i32_16x16x64_i8 v[28:31], v[144:147], v[148:151], v[28:31]
	v_mfma_i32_16x16x64_i8 v[100:103], v[136:139], v[168:171], v[100:103]
	v_mfma_i32_16x16x64_i8 v[24:27], v[144:147], v[168:171], v[24:27]
	v_mfma_i32_16x16x64_i8 v[96:99], v[136:139], v[176:179], v[96:99]
	v_mfma_i32_16x16x64_i8 v[20:23], v[144:147], v[176:179], v[20:23]
	v_mfma_i32_16x16x64_i8 v[92:95], v[136:139], v[184:187], v[92:95]
	v_mfma_i32_16x16x64_i8 v[16:19], v[144:147], v[184:187], v[16:19]
	v_mfma_i32_16x16x64_i8 v[116:119], v[140:143], v[156:159], v[116:119]
	v_mfma_i32_16x16x64_i8 v[28:31], v[164:167], v[156:159], v[28:31]
	v_mfma_i32_16x16x64_i8 v[100:103], v[140:143], v[172:175], v[100:103]
	v_mfma_i32_16x16x64_i8 v[24:27], v[164:167], v[172:175], v[24:27]
	v_mfma_i32_16x16x64_i8 v[96:99], v[140:143], v[180:183], v[96:99]
	v_mfma_i32_16x16x64_i8 v[20:23], v[164:167], v[180:183], v[20:23]
	v_mfma_i32_16x16x64_i8 v[92:95], v[140:143], v[188:191], v[92:95]
	v_mfma_i32_16x16x64_i8 v[16:19], v[164:167], v[188:191], v[16:19]
	s_barrier
	ds_read_b128 v[168:171], v211 offset:49152
	ds_read_b128 v[172:175], v211 offset:50176
	ds_read_b128 v[176:179], v211 offset:51200
	ds_read_b128 v[180:183], v211 offset:52224
	ds_read_b128 v[184:187], v211 offset:53248
	ds_read_b128 v[188:191], v211 offset:54272
	ds_read_b128 v[192:195], v211 offset:55296
	ds_read_b128 v[196:199], v211 offset:56320
	s_add_u32 s6, s68, 0x80
	s_addc_u32 s7, s69, 0
	s_mov_b32 m0, s2
	s_nop 0
	global_load_lds_dwordx4 v217, s[6:7]
	s_mov_b32 m0, s85
	s_nop 0
	global_load_lds_dwordx4 v248, s[6:7]
	s_add_u32 s6, s68, 0x40080
	s_addc_u32 s7, s69, 0
	s_mov_b32 m0, s88
	s_nop 0
	global_load_lds_dwordx4 v217, s[6:7]
	s_mov_b32 m0, s89
	s_nop 0
	global_load_lds_dwordx4 v248, s[6:7]
	s_mov_b32 m0, s86
	s_nop 0
	global_load_lds_dwordx4 v250, s[60:61]
	s_mov_b32 m0, s87
	s_nop 0
	global_load_lds_dwordx4 v247, s[60:61]
	s_waitcnt vmcnt(8)
	s_waitcnt lgkmcnt(0)
	s_barrier
	s_waitcnt lgkmcnt(1)
	v_mfma_i32_16x16x64_i8 v[104:107], v[120:123], v[192:195], v[104:107]
	v_mfma_i32_16x16x64_i8 v[40:43], v[120:123], v[168:171], v[40:43]
	v_mfma_i32_16x16x64_i8 v[64:67], v[128:131], v[168:171], v[64:67]
	v_mfma_i32_16x16x64_i8 v[36:39], v[120:123], v[176:179], v[36:39]
	v_mfma_i32_16x16x64_i8 v[60:63], v[128:131], v[176:179], v[60:63]
	v_mfma_i32_16x16x64_i8 v[32:35], v[120:123], v[184:187], v[32:35]
	v_mfma_i32_16x16x64_i8 v[56:59], v[128:131], v[184:187], v[56:59]
	s_waitcnt lgkmcnt(0)
	v_mfma_i32_16x16x64_i8 v[156:159], v[124:127], v[196:199], v[104:107]
	v_mfma_i32_16x16x64_i8 v[104:107], v[128:131], v[192:195], v[112:115]
	v_mfma_i32_16x16x64_i8 v[40:43], v[124:127], v[172:175], v[40:43]
	v_mfma_i32_16x16x64_i8 v[64:67], v[132:135], v[172:175], v[64:67]
	v_mfma_i32_16x16x64_i8 v[36:39], v[124:127], v[180:183], v[36:39]
	v_mfma_i32_16x16x64_i8 v[60:63], v[132:135], v[180:183], v[60:63]
	v_mfma_i32_16x16x64_i8 v[32:35], v[124:127], v[188:191], v[32:35]
	v_mfma_i32_16x16x64_i8 v[56:59], v[132:135], v[188:191], v[56:59]
	v_mfma_i32_16x16x64_i8 v[148:151], v[132:135], v[196:199], v[104:107]
	v_mfma_i32_16x16x64_i8 v[88:91], v[136:139], v[168:171], v[88:91]
	v_mfma_i32_16x16x64_i8 v[12:15], v[144:147], v[168:171], v[12:15]
	v_mfma_i32_16x16x64_i8 v[84:87], v[136:139], v[176:179], v[84:87]
	v_mfma_i32_16x16x64_i8 v[8:11], v[144:147], v[176:179], v[8:11]
	v_mfma_i32_16x16x64_i8 v[76:79], v[136:139], v[184:187], v[76:79]
	v_mfma_i32_16x16x64_i8 v[4:7], v[144:147], v[184:187], v[4:7]
	v_mfma_i32_16x16x64_i8 v[104:107], v[136:139], v[192:195], v[108:111]
	v_mfma_i32_16x16x64_i8 v[0:3], v[144:147], v[192:195], v[0:3]
	v_mfma_i32_16x16x64_i8 v[88:91], v[140:143], v[172:175], v[88:91]
	v_mfma_i32_16x16x64_i8 v[12:15], v[164:167], v[172:175], v[12:15]
	v_mfma_i32_16x16x64_i8 v[84:87], v[140:143], v[180:183], v[84:87]
	v_mfma_i32_16x16x64_i8 v[8:11], v[164:167], v[180:183], v[8:11]
	v_mfma_i32_16x16x64_i8 v[76:79], v[140:143], v[188:191], v[76:79]
	v_mfma_i32_16x16x64_i8 v[4:7], v[164:167], v[188:191], v[4:7]
	v_mfma_i32_16x16x64_i8 v[108:111], v[140:143], v[196:199], v[104:107]
	v_mfma_i32_16x16x64_i8 v[0:3], v[164:167], v[196:199], v[0:3]
	s_barrier
	s_add_i32 s4, s4, 2
	s_add_u32 vcc_lo, vcc_lo, 0x100
	s_addc_u32 vcc_hi, vcc_hi, 0
	s_add_u32 s0, s0, 0x100
	s_addc_u32 s1, s1, 0
	s_add_u32 s44, s44, 0x100
	s_addc_u32 s45, s45, 0
	s_cmp_gt_u32 s4, 13
	s_cbranch_scc0 .LBB0_1065
	s_mov_b32 s100, 0xbfb8aa3b
	s_mov_b32 s101, 0
	s_and_b64 vcc, exec, s[46:47]
	s_cbranch_vccz .LBB0_1068
	s_barrier

; template <class Prob, class Epi, bool I8 = false, bool ALIGN_EPI = true, bool SP2 = true>
; __device__ __forceinline__ void gemm_phase(LAS unsigned char* lds, int wave, const Prob& P, const Epi& E) {
;     const int tid_ = wave * 64 + mk_lane();
;     const int tid = tid_, wid = __builtin_amdgcn_readfirstlane(tid >> 6), lane = tid & 63, wr = wid >> 2, wc = wid & 3, fr = lane & 15, fq = lane >> 4;
;     const int K = P.K, nt = K / BK;
;     unsigned voffA[2], voffB[2];
; #pragma unroll
;     for (int i = 0; i < 2; ++i) { int R, C; stage_rc(tid * 16 + i * 8192, R, C); const int Rb = (R & ~31) + perm32(R & 31);
;         voffA[i] = P.a_rowoff(R) + (unsigned)C * 2u; voffB[i] = P.b_rowoff(Rb) + (unsigned)C * 2u; }
;     const size_t kstep = (size_t)(BK * 2);
;     const size_t hstepA = P.a_hstep(), hstepB = P.b_hstep();
;     const unsigned ldsw = (unsigned)wid * 1024u;
;     const unsigned ldsb = (unsigned)(size_t)lds + ldsw;
;     const int aoff = lds_byte(wr * 64 + fr, fq * 8), boff = lds_byte(wc * 32 + fr, fq * 8);
;     ...
;     Unit cur, nxt; int ui = 0;
;     if (!P.next(0, cur)) return;
;     Acc acc;
; #pragma unroll
;     for (int a = 0; a < 2; ++a)
; #pragma unroll
;         for (int b = 0; b < 2; ++b)
; #pragma unroll
;             for (int m = 0; m < 4; ++m)
; #pragma unroll
;                 for (int n = 0; n < 2; ++n) acc[a][b][m][n] = (f32x4){0.f, 0.f, 0.f, 0.f};
;     h16x8 At[4][2], B0[2][2], B1[2][2];
;     const char* cA = P.a_tile(cur); const char* cB = P.b_tile(cur);
;     if constexpr (SP2) {
;         PG8_STAGE(PG8_SB(0, 0), cB, voffB); PG8_STAGE(PG8_SB(0, 1), cB + hstepB, voffB); PG8_STAGE(PG8_SA(0, 0), cA, voffA); PG8_STAGE(PG8_SA(0, 1), cA + hstepA, voffA);
;         if (wr == 1) PG8_BAR;
;         PG8_WAIT_V(2); PG8_BAR;
;         PG8_STAGE(PG8_SB(1, 0), cB + kstep, voffB); PG8_STAGE(PG8_SA(1, 0), cA + kstep, voffA); PG8_STAGE(PG8_SB(1, 1), cB + hstepB + kstep, voffB);
;         PG8_WAIT_V(6); PG8_BAR;
;     __device__ bool next(int i, Unit& u) const { return S.next(i, u); }
;     __device__ unsigned a_rowoff(int R) const { const int r = upmap ? (128 * (R >> 6) + 8 * (R & 15) + ((R >> 4) & 3)) : R; return (unsigned)r * (unsigned)lda * 2u; }
;     __device__ unsigned b_rowoff(int R) const { return (unsigned)R * (unsigned)ldb * 2u; }
;     __device__ size_t a_hstep() const { return (size_t)(upmap ? 4 : 128) * lda * 2; }
.LBB0_1203:
	v_readlane_b32 s0, v254, 42
	v_readlane_b32 s4, v254, 43
	s_waitcnt lgkmcnt(0)
	s_barrier
	v_mbcnt_lo_u32_b32 v0, -1, 0
	v_mbcnt_hi_u32_b32 v0, -1, v0
	v_readlane_b32 s5, v254, 44
	v_add_u32_e32 v1, s0, v0
	s_and_b64 vcc, exec, s[4:5]
	v_readfirstlane_b32 s0, v1
	s_cbranch_vccz .LBB0_1223
	v_ashrrev_i32_e32 v2, 31, v1
	v_lshrrev_b32_e32 v2, 26, v2
	v_lshlrev_b32_e32 v3, 4, v1
	v_add_u32_e32 v2, v1, v2
	v_bfe_i32 v1, v1, 27, 1
	v_lshrrev_b32_e32 v1, 22, v1
	v_add_u32_e32 v1, v3, v1
	v_and_b32_e32 v1, 0xfffffc00, v1
	v_sub_u32_e32 v1, v3, v1
	v_lshrrev_b32_e32 v4, 4, v1
	v_bitop3_b32 v1, v4, v1, 32 bitop3:0x6c
	v_ashrrev_i32_e32 v5, 31, v1
	v_lshrrev_b32_e32 v5, 26, v5
	v_ashrrev_i32_e32 v2, 6, v2
	v_add_u32_e32 v5, v1, v5
	v_readlane_b32 s1, v255, 1
	v_lshlrev_b32_e32 v4, 3, v2
	v_ashrrev_i32_e32 v6, 6, v5
	v_and_b32_e32 v5, 0xc0, v5
	s_mul_i32 s1, s1, 0xb00000
	v_and_b32_e32 v4, -16, v4
	v_sub_u32_e32 v1, v1, v5
	v_mov_b32_e32 v8, 1
	s_add_u32 s1, s30, s1
	v_add_u32_e32 v4, v6, v4
	v_lshlrev_b32_e32 v2, 5, v2
	v_ashrrev_i16_sdwa v1, v8, sext(v1) dst_sel:DWORD dst_unused:UNUSED_PAD src0_sel:DWORD src1_sel:BYTE_0
	s_addc_u32 s4, s31, 0
	v_and_b32_e32 v2, 32, v2
	v_bfe_i32 v1, v1, 0, 16
	v_lshlrev_b32_e32 v5, 1, v4
	v_lshrrev_b32_e32 v7, 2, v4
	v_and_b32_e32 v6, 3, v6
	s_mov_b32 s7, 0x7fffe0
	s_add_u32 s2, s1, 0xba00000
	v_and_b32_e32 v5, 24, v5
	v_and_b32_e32 v7, 4, v7
	v_and_or_b32 v6, v4, s7, v6
	v_add_lshl_u32 v2, v2, v1, 1
	s_movk_i32 s6, 0x1600
	s_addc_u32 s19, s4, 0
	v_or3_b32 v5, v6, v7, v5
	v_mad_u64_u32 v[160:161], s[4:5], v4, s6, v[2:3]
	v_add_u32_e32 v1, 0x2000, v3
	v_mad_u32_u24 v161, v5, s6, v2
	v_ashrrev_i32_e32 v2, 31, v1
	v_lshrrev_b32_e32 v2, 22, v2
	v_add_u32_e32 v2, v1, v2
	v_ashrrev_i32_e32 v2, 10, v2
	v_mul_i32_i24_e32 v3, 0x400, v2
	v_sub_u32_e32 v1, v1, v3
	v_lshrrev_b32_e32 v3, 4, v1
	v_bitop3_b32 v1, v3, v1, 32 bitop3:0x6c
	v_ashrrev_i32_e32 v4, 31, v1
	v_lshrrev_b32_e32 v4, 26, v4
	v_add_u32_e32 v4, v1, v4
	v_ashrrev_i32_e32 v5, 6, v4
	v_and_b32_e32 v4, 0xc0, v4
	v_lshlrev_b32_e32 v3, 3, v2
	v_sub_u32_e32 v1, v1, v4
	v_and_b32_e32 v3, -16, v3
	v_lshlrev_b32_e32 v2, 5, v2
	v_ashrrev_i16_sdwa v1, v8, sext(v1) dst_sel:DWORD dst_unused:UNUSED_PAD src0_sel:DWORD src1_sel:BYTE_0
	v_add_u32_e32 v3, v5, v3
	v_and_b32_e32 v2, 32, v2
	v_bfe_i32 v1, v1, 0, 16
	v_lshlrev_b32_e32 v4, 1, v3
	v_lshrrev_b32_e32 v6, 2, v3
	v_and_b32_e32 v5, 3, v5
	v_add_lshl_u32 v2, v2, v1, 1
	v_and_b32_e32 v4, 24, v4
	v_and_b32_e32 v6, 4, v6
	v_and_or_b32 v5, v3, s7, v5
	v_mad_u64_u32 v[162:163], s[4:5], v3, s6, v[2:3]
	v_or3_b32 v4, v5, v6, v4
	s_ashr_i32 s4, s0, 6
	v_mad_u32_u24 v163, v4, s6, v2
	s_lshl_b32 s5, s4, 10
	v_readlane_b32 s6, v252, 31
	s_ashr_i32 s1, s0, 8
	s_add_i32 s40, s5, 0
	s_mul_i32 s5, s6, 0x160000
	s_add_u32 s14, s2, s5
	s_mul_hi_i32 s5, s6, 0x160000
	s_addc_u32 s15, s19, s5
	s_add_i32 s41, s40, 0x10000
	s_mov_b32 m0, s41
	s_nop 0
	global_load_lds_dwordx4 v161, s[14:15]
	s_add_i32 s62, s40, 0x12000
	s_mov_b32 m0, s62
	s_nop 0
	global_load_lds_dwordx4 v163, s[14:15]
	s_add_u32 s6, s14, 0xb0000
	s_addc_u32 s7, s15, 0
	s_add_i32 s63, s40, 0x14000
	s_mov_b32 m0, s63
	s_nop 0
	global_load_lds_dwordx4 v161, s[6:7]
	s_add_i32 s64, s40, 0x16000
	s_mov_b32 m0, s64
	s_nop 0
	global_load_lds_dwordx4 v163, s[6:7]
	v_readlane_b32 s6, v252, 42
	v_readlane_b32 s7, v252, 43
	s_mov_b32 m0, s40
	s_nop 0
	global_load_lds_dwordx4 v160, s[6:7]
	s_add_i32 s68, s40, 0x2000
	s_mov_b32 m0, s68
	s_nop 0
	global_load_lds_dwordx4 v162, s[6:7]
	v_readlane_b32 s6, v252, 40
	s_add_i32 s69, s40, 0x4000
	v_readlane_b32 s7, v252, 41
	s_mov_b32 m0, s69
	s_nop 0
	global_load_lds_dwordx4 v160, s[6:7]
	s_add_i32 s76, s40, 0x6000
	s_mov_b32 m0, s76
	s_nop 0
	global_load_lds_dwordx4 v162, s[6:7]
	s_cmp_eq_u32 s1, 1
	s_cselect_b64 s[16:17], -1, 0
	s_setprio 1
	s_cmp_lg_u32 s1, 1
	s_cbranch_scc1 .LBB0_1206
	s_barrier
	s_setprio 0
.LBB0_1206:
	v_readlane_b32 s80, v251, 16
	v_readlane_b32 s81, v251, 17
	v_readlane_b32 s82, v251, 18
	v_readlane_b32 s83, v251, 19
	v_readlane_b32 s92, v251, 28
	v_readlane_b32 s93, v251, 29
	v_readlane_b32 s94, v251, 30
	v_readlane_b32 s95, v251, 31
	s_mov_b64 s[80:81], s[92:93]
	s_mov_b64 s[82:83], s[94:95]
	v_readlane_b32 s6, v255, 2
	v_readlane_b32 s7, v255, 3
	s_add_u32 s22, s82, s6
	s_addc_u32 s23, s83, s7
	s_add_u32 s5, s30, s6
	s_addc_u32 s6, s31, s7
	s_add_u32 s26, s5, 0x232000
	v_and_b32_e32 v1, 48, v0
	v_lshlrev_b32_e32 v2, 6, v0
	s_movk_i32 s5, 0x3c0
	v_lshlrev_b32_e32 v0, 2, v0
	s_addc_u32 s27, s6, 0
	s_lshl_b32 s77, s1, 6
	s_lshl_b32 s1, s1, 13
	v_and_or_b32 v1, v2, s5, v1
	v_and_b32_e32 v0, 32, v0
	v_bitop3_b32 v2, v1, s1, v0 bitop3:0xde
	s_lshl_b32 s1, s4, 5
	s_and_b32 s79, s1, 0x60
	s_lshl_b32 s1, s79, 7
	s_add_u32 s28, s30, 0x280000
	s_addc_u32 s29, s31, 0
	s_add_u32 s46, s30, 0x1b00000
	s_addc_u32 s47, s31, 0
	s_add_u32 s4, s14, 0x80
	v_bitop3_b32 v0, s1, v1, v0 bitop3:0xf6
	s_waitcnt vmcnt(2)
	s_barrier
	s_addc_u32 s5, s15, 0
	s_add_i32 s80, s40, 0x18000
	s_mov_b32 m0, s80
	s_nop 0
	global_load_lds_dwordx4 v161, s[4:5]
	s_add_i32 s81, s40, 0x1a000
	s_mov_b32 m0, s81
	s_nop 0
	global_load_lds_dwordx4 v163, s[4:5]
	v_readlane_b32 s4, v252, 44
	s_add_i32 s82, s40, 0x8000
	v_readlane_b32 s5, v252, 45
	s_mov_b32 m0, s82
	s_nop 0
	global_load_lds_dwordx4 v160, s[4:5]
	s_add_i32 s83, s40, 0xa000
	v_readlane_b32 s84, v251, 20
	s_mov_b32 m0, s83
	s_nop 0
	global_load_lds_dwordx4 v162, s[4:5]
	s_add_u32 s4, s14, 0xb0080
	v_readlane_b32 s85, v251, 21
	s_addc_u32 s5, s15, 0
	s_add_i32 s84, s40, 0x1c000
	s_mov_b32 m0, s84
	s_nop 0
	global_load_lds_dwordx4 v161, s[4:5]
	v_readlane_b32 s86, v251, 22
	s_add_i32 s85, s40, 0x1e000
	s_mov_b32 m0, s85
	s_nop 0
	global_load_lds_dwordx4 v163, s[4:5]
	s_waitcnt vmcnt(6)
	s_add_i32 s86, s40, 0xc000
	v_readlane_b32 s87, v251, 23
	v_readlane_b32 s88, v251, 24
	s_cmpk_lt_u32 s0, 0x100
	v_readlane_b32 s0, v252, 36
	v_readlane_b32 s44, v252, 42
	v_readlane_b32 s89, v251, 25
	v_readlane_b32 s90, v251, 26
	s_cselect_b64 s[48:49], -1, 0
	s_add_i32 s87, s40, 0xe000
	s_mov_b32 s88, 0
	v_add_u32_e32 v179, 0, v0
	v_add_u32_e32 v185, 0, v2
	v_readlane_b32 s73, v252, 31
	s_mov_b32 s72, s0
	v_readlane_b32 s45, v252, 43
	v_readlane_b32 s91, v251, 27
	s_barrier
	v_readlane_b32 s1, v252, 37
	s_branch .LBB0_1209

; #define PG8_STAGE(bufoff, gbase, voff) do { _Pragma("unroll") for (int _i = 0; _i < 2; ++_i) glds16_s((gbase), (voff)[_i], ldsb + (unsigned)((bufoff) + _i * 8192)); } while (0)
; #define PG8_LDA(dst, b, h) do { _Pragma("unroll") for (int m = 0; m < 4; ++m) _Pragma("unroll") for (int k = 0; k < 2; ++k) dst[m][k] = *(const LAS h16x8*)(lds + PG8_SA(b, h) + aoff + m * 2048 + k * 1024); } while (0)
; #define PG8_LDB(dst, b, h) do { _Pragma("unroll") for (int n = 0; n < 2; ++n) _Pragma("unroll") for (int k = 0; k < 2; ++k) dst[n][k] = *(const LAS h16x8*)(lds + PG8_SB(b, h) + boff + n * 2048 + k * 1024); } while (0)
; #define PG8_MMA(ai, bj, At, Bt) do { __builtin_amdgcn_s_setprio(1); _Pragma("unroll") for (int m = 0; m < 4; ++m) _Pragma("unroll") for (int n = 0; n < 2; ++n) _Pragma("unroll") for (int k = 0; k < 2; ++k) \
;         acc[ai][bj][m][n] = mma_step<I8>(Bt[n][k], At[m][k], acc[ai][bj][m][n]); __builtin_amdgcn_s_setprio(0); } while (0)
; #define PG8_WAIT_V(n) asm volatile("s_waitcnt vmcnt(" #n ")" ::: "memory")
; #define PG8_WAIT_L(n) asm volatile("s_waitcnt lgkmcnt(" #n ")" ::: "memory")
; #define PG8_BAR __builtin_amdgcn_s_barrier()
; #define PG8_SCHED __builtin_amdgcn_sched_barrier(0)
; template <class Prob, class Epi, bool I8 = false, bool ALIGN_EPI = true, bool SP2 = true>
; __device__ __forceinline__ void gemm_phase(LAS unsigned char* lds, int wave, const Prob& P, const Epi& E) {
;     ...
;             PG8_LDB(B0, 0, 0); PG8_LDB(B1, 0, 1); PG8_SCHED; PG8_LDA(At, 0, 0); PG8_STAGE(PG8_SA(1, 1), a1 + hstepA, voffA);
;             PG8_WAIT_V(8); PG8_WAIT_L(0); PG8_BAR; PG8_MMA(0, 0, At, B0); PG8_MMA(0, 1, At, B1); PG8_BAR; PG8_SCHED;
;             PG8_LDA(At, 0, 1); PG8_STAGE(PG8_SB(0, 0), b2, voffB); PG8_STAGE(PG8_SB(0, 1), b2 + hstepB, voffB); PG8_STAGE(PG8_SA(0, 0), a2, voffA);
;             PG8_WAIT_V(8); PG8_WAIT_L(0); PG8_BAR; PG8_MMA(1, 0, At, B0); PG8_MMA(1, 1, At, B1); PG8_BAR; PG8_SCHED;
.Lpeel_1216:
	v_add_u32_e32 v140, 0x10000, v179
	v_add_u32_e32 v156, 0x14000, v179
	ds_read_b128 v[100:103], v140
	ds_read_b128 v[108:111], v140 offset:1024
	ds_read_b128 v[136:139], v140 offset:2048
	ds_read_b128 v[140:143], v140 offset:3072
	ds_read_b128 v[144:147], v156
	ds_read_b128 v[148:151], v156 offset:1024
	ds_read_b128 v[152:155], v156 offset:2048
	ds_read_b128 v[156:159], v156 offset:3072
	s_cmp_eq_u32 s4, 40
	s_cselect_b32 s60, s38, s74
	s_cselect_b32 s61, s39, s75
	s_cselect_b32 s56, s50, s0
	s_cselect_b32 s57, s51, s1
	s_add_u32 s44, s60, 0x80
	s_addc_u32 s45, s61, 0
	ds_read_b128 v[164:167], v185
	ds_read_b128 v[168:171], v185 offset:1024
	ds_read_b128 v[172:175], v185 offset:2048
	ds_read_b128 v[180:183], v185 offset:3072
	ds_read_b128 v[186:189], v185 offset:4096
	ds_read_b128 v[190:193], v185 offset:5120
	ds_read_b128 v[194:197], v185 offset:6144
	ds_read_b128 v[198:201], v185 offset:7168
	s_mov_b32 m0, s86
	s_nop 0
	global_load_lds_dwordx4 v160, s[14:15]
	s_mov_b32 m0, s87
	s_nop 0
	global_load_lds_dwordx4 v162, s[14:15]
	s_waitcnt vmcnt(8)
	s_waitcnt lgkmcnt(0)
	s_barrier
	s_waitcnt lgkmcnt(7)
	v_mfma_i32_16x16x64_i8 v[132:135], v[100:103], v[164:167], 0
	v_mfma_i32_16x16x64_i8 v[128:131], v[136:139], v[164:167], 0
	s_waitcnt lgkmcnt(5)
	v_mfma_i32_16x16x64_i8 v[124:127], v[100:103], v[172:175], 0
	v_mfma_i32_16x16x64_i8 v[120:123], v[136:139], v[172:175], 0
	s_waitcnt lgkmcnt(3)
	v_mfma_i32_16x16x64_i8 v[116:119], v[100:103], v[186:189], 0
	v_mfma_i32_16x16x64_i8 v[112:115], v[136:139], v[186:189], 0
	s_waitcnt lgkmcnt(1)
	v_mfma_i32_16x16x64_i8 v[104:107], v[100:103], v[194:197], 0
	v_mfma_i32_16x16x64_i8 v[96:99], v[136:139], v[194:197], 0
	v_mfma_i32_16x16x64_i8 v[132:135], v[108:111], v[168:171], v[132:135]
	v_mfma_i32_16x16x64_i8 v[128:131], v[140:143], v[168:171], v[128:131]
	v_mfma_i32_16x16x64_i8 v[124:127], v[108:111], v[180:183], v[124:127]
	v_mfma_i32_16x16x64_i8 v[120:123], v[140:143], v[180:183], v[120:123]
	v_mfma_i32_16x16x64_i8 v[116:119], v[108:111], v[190:193], v[116:119]
	v_mfma_i32_16x16x64_i8 v[112:115], v[140:143], v[190:193], v[112:115]
	s_waitcnt lgkmcnt(0)
	v_mfma_i32_16x16x64_i8 v[104:107], v[108:111], v[198:201], v[104:107]
	v_mfma_i32_16x16x64_i8 v[96:99], v[140:143], v[198:201], v[96:99]
	v_mfma_i32_16x16x64_i8 v[60:63], v[144:147], v[164:167], 0
	v_mfma_i32_16x16x64_i8 v[56:59], v[152:155], v[164:167], 0
	v_mfma_i32_16x16x64_i8 v[52:55], v[144:147], v[172:175], 0
	v_mfma_i32_16x16x64_i8 v[48:51], v[152:155], v[172:175], 0
	v_mfma_i32_16x16x64_i8 v[44:47], v[144:147], v[186:189], 0
	v_mfma_i32_16x16x64_i8 v[40:43], v[152:155], v[186:189], 0
	v_mfma_i32_16x16x64_i8 v[36:39], v[144:147], v[194:197], 0
	v_mfma_i32_16x16x64_i8 v[32:35], v[152:155], v[194:197], 0
	v_mfma_i32_16x16x64_i8 v[60:63], v[148:151], v[168:171], v[60:63]
	v_mfma_i32_16x16x64_i8 v[56:59], v[156:159], v[168:171], v[56:59]
	v_mfma_i32_16x16x64_i8 v[52:55], v[148:151], v[180:183], v[52:55]
	v_mfma_i32_16x16x64_i8 v[48:51], v[156:159], v[180:183], v[48:51]
	v_mfma_i32_16x16x64_i8 v[44:47], v[148:151], v[190:193], v[44:47]
	v_mfma_i32_16x16x64_i8 v[40:43], v[156:159], v[190:193], v[40:43]
	v_mfma_i32_16x16x64_i8 v[36:39], v[148:151], v[198:201], v[36:39]
	v_mfma_i32_16x16x64_i8 v[32:35], v[156:159], v[198:201], v[32:35]
	s_barrier
	ds_read_b128 v[164:167], v185 offset:16384
	ds_read_b128 v[168:171], v185 offset:17408
	ds_read_b128 v[172:175], v185 offset:18432
	ds_read_b128 v[180:183], v185 offset:19456
	ds_read_b128 v[186:189], v185 offset:20480
	ds_read_b128 v[190:193], v185 offset:21504
	ds_read_b128 v[194:197], v185 offset:22528
	ds_read_b128 v[198:201], v185 offset:23552
	s_mov_b32 m0, s41
	s_nop 0
	global_load_lds_dwordx4 v161, s[56:57]
	s_add_u32 s6, s56, 0xb0000
	s_mov_b32 m0, s62
	s_nop 0
	global_load_lds_dwordx4 v163, s[56:57]
	s_addc_u32 s7, s57, 0
	s_mov_b32 m0, s63
	s_nop 0
	global_load_lds_dwordx4 v161, s[6:7]
	s_mov_b32 m0, s64
	s_nop 0
	global_load_lds_dwordx4 v163, s[6:7]
	s_mov_b32 m0, s40
	s_nop 0
	global_load_lds_dwordx4 v160, s[60:61]
	s_mov_b32 m0, s68
	s_nop 0
	global_load_lds_dwordx4 v162, s[60:61]
	s_waitcnt vmcnt(8)
	s_waitcnt lgkmcnt(0)
	s_barrier
	s_waitcnt lgkmcnt(7)
	v_mfma_i32_16x16x64_i8 v[92:95], v[100:103], v[164:167], 0
	v_mfma_i32_16x16x64_i8 v[88:91], v[136:139], v[164:167], 0
	s_waitcnt lgkmcnt(5)
	v_mfma_i32_16x16x64_i8 v[84:87], v[100:103], v[172:175], 0
	v_mfma_i32_16x16x64_i8 v[80:83], v[136:139], v[172:175], 0
	s_waitcnt lgkmcnt(3)
	v_mfma_i32_16x16x64_i8 v[76:79], v[100:103], v[186:189], 0
	v_mfma_i32_16x16x64_i8 v[72:75], v[136:139], v[186:189], 0
	s_waitcnt lgkmcnt(1)
	v_mfma_i32_16x16x64_i8 v[68:71], v[100:103], v[194:197], 0
	v_mfma_i32_16x16x64_i8 v[64:67], v[136:139], v[194:197], 0
	v_mfma_i32_16x16x64_i8 v[92:95], v[108:111], v[168:171], v[92:95]
	v_mfma_i32_16x16x64_i8 v[88:91], v[140:143], v[168:171], v[88:91]
	v_mfma_i32_16x16x64_i8 v[84:87], v[108:111], v[180:183], v[84:87]
	v_mfma_i32_16x16x64_i8 v[80:83], v[140:143], v[180:183], v[80:83]
	v_mfma_i32_16x16x64_i8 v[76:79], v[108:111], v[190:193], v[76:79]
	v_mfma_i32_16x16x64_i8 v[72:75], v[140:143], v[190:193], v[72:75]
	s_waitcnt lgkmcnt(0)
	v_mfma_i32_16x16x64_i8 v[68:71], v[108:111], v[198:201], v[68:71]
	v_mfma_i32_16x16x64_i8 v[64:67], v[140:143], v[198:201], v[64:67]
	v_mfma_i32_16x16x64_i8 v[28:31], v[144:147], v[164:167], 0
	v_mfma_i32_16x16x64_i8 v[24:27], v[152:155], v[164:167], 0
	v_mfma_i32_16x16x64_i8 v[20:23], v[144:147], v[172:175], 0
	v_mfma_i32_16x16x64_i8 v[16:19], v[152:155], v[172:175], 0
	v_mfma_i32_16x16x64_i8 v[12:15], v[144:147], v[186:189], 0
	v_mfma_i32_16x16x64_i8 v[8:11], v[152:155], v[186:189], 0
	v_mfma_i32_16x16x64_i8 v[4:7], v[144:147], v[194:197], 0
	v_mfma_i32_16x16x64_i8 v[0:3], v[152:155], v[194:197], 0
	v_mfma_i32_16x16x64_i8 v[28:31], v[148:151], v[168:171], v[28:31]
	v_mfma_i32_16x16x64_i8 v[24:27], v[156:159], v[168:171], v[24:27]
	v_mfma_i32_16x16x64_i8 v[20:23], v[148:151], v[180:183], v[20:23]
	v_mfma_i32_16x16x64_i8 v[16:19], v[156:159], v[180:183], v[16:19]
	v_mfma_i32_16x16x64_i8 v[12:15], v[148:151], v[190:193], v[12:15]
	v_mfma_i32_16x16x64_i8 v[8:11], v[156:159], v[190:193], v[8:11]
	v_mfma_i32_16x16x64_i8 v[4:7], v[148:151], v[198:201], v[4:7]
	v_mfma_i32_16x16x64_i8 v[0:3], v[156:159], v[198:201], v[0:3]
	s_barrier
; #define PG8_STAGE(bufoff, gbase, voff) do { _Pragma("unroll") for (int _i = 0; _i < 2; ++_i) glds16_s((gbase), (voff)[_i], ldsb + (unsigned)((bufoff) + _i * 8192)); } while (0)
; #define PG8_LDA(dst, b, h) do { _Pragma("unroll") for (int m = 0; m < 4; ++m) _Pragma("unroll") for (int k = 0; k < 2; ++k) dst[m][k] = *(const LAS h16x8*)(lds + PG8_SA(b, h) + aoff + m * 2048 + k * 1024); } while (0)
; #define PG8_LDB(dst, b, h) do { _Pragma("unroll") for (int n = 0; n < 2; ++n) _Pragma("unroll") for (int k = 0; k < 2; ++k) dst[n][k] = *(const LAS h16x8*)(lds + PG8_SB(b, h) + boff + n * 2048 + k * 1024); } while (0)
; #define PG8_MMA(ai, bj, At, Bt) do { __builtin_amdgcn_s_setprio(1); _Pragma("unroll") for (int m = 0; m < 4; ++m) _Pragma("unroll") for (int n = 0; n < 2; ++n) _Pragma("unroll") for (int k = 0; k < 2; ++k) \
;         acc[ai][bj][m][n] = mma_step<I8>(Bt[n][k], At[m][k], acc[ai][bj][m][n]); __builtin_amdgcn_s_setprio(0); } while (0)
; #define PG8_WAIT_V(n) asm volatile("s_waitcnt vmcnt(" #n ")" ::: "memory")
; #define PG8_WAIT_L(n) asm volatile("s_waitcnt lgkmcnt(" #n ")" ::: "memory")
; #define PG8_BAR __builtin_amdgcn_s_barrier()
; #define PG8_SCHED __builtin_amdgcn_sched_barrier(0)
; template <class Prob, class Epi, bool I8 = false, bool ALIGN_EPI = true, bool SP2 = true>
; __device__ __forceinline__ void gemm_phase(LAS unsigned char* lds, int wave, const Prob& P, const Epi& E) {
;     ...
;             PG8_LDB(B0, 1, 0); PG8_LDB(B1, 1, 1); PG8_SCHED; PG8_LDA(At, 1, 0); PG8_STAGE(PG8_SA(0, 1), a2 + hstepA, voffA);
;             PG8_WAIT_V(8); PG8_WAIT_L(0); PG8_BAR; PG8_MMA(0, 0, At, B0); PG8_MMA(0, 1, At, B1); PG8_BAR; PG8_SCHED;
;             PG8_LDA(At, 1, 1); PG8_STAGE(PG8_SB(1, 0), b3, voffB); PG8_STAGE(PG8_SB(1, 1), b3 + hstepB, voffB); PG8_STAGE(PG8_SA(1, 0), a3, voffA);
;             PG8_WAIT_V(8); PG8_WAIT_L(0); PG8_BAR; PG8_MMA(1, 0, At, B0); PG8_MMA(1, 1, At, B1); PG8_BAR; PG8_SCHED;
	v_add_u32_e32 v140, 0x18000, v179
	v_add_u32_e32 v156, 0x1c000, v179
	ds_read_b128 v[100:103], v140
	ds_read_b128 v[108:111], v140 offset:1024
	ds_read_b128 v[136:139], v140 offset:2048
	ds_read_b128 v[140:143], v140 offset:3072
	ds_read_b128 v[144:147], v156
	ds_read_b128 v[148:151], v156 offset:1024
	ds_read_b128 v[152:155], v156 offset:2048
	ds_read_b128 v[156:159], v156 offset:3072
	ds_read_b128 v[164:167], v185 offset:32768
	ds_read_b128 v[168:171], v185 offset:33792
	ds_read_b128 v[172:175], v185 offset:34816
	ds_read_b128 v[180:183], v185 offset:35840
	ds_read_b128 v[186:189], v185 offset:36864
	ds_read_b128 v[190:193], v185 offset:37888
	ds_read_b128 v[194:197], v185 offset:38912
	ds_read_b128 v[198:201], v185 offset:39936
	s_add_u32 s6, s60, 0xb0000
	s_addc_u32 s7, s61, 0
	s_mov_b32 m0, s69
	s_nop 0
	global_load_lds_dwordx4 v160, s[6:7]
	s_mov_b32 m0, s76
	s_nop 0
	global_load_lds_dwordx4 v162, s[6:7]
	s_waitcnt vmcnt(8)
	s_waitcnt lgkmcnt(0)
	s_barrier
	s_waitcnt lgkmcnt(7)
	v_mfma_i32_16x16x64_i8 v[132:135], v[100:103], v[164:167], v[132:135]
	v_mfma_i32_16x16x64_i8 v[128:131], v[136:139], v[164:167], v[128:131]
	s_waitcnt lgkmcnt(5)
	v_mfma_i32_16x16x64_i8 v[124:127], v[100:103], v[172:175], v[124:127]
	v_mfma_i32_16x16x64_i8 v[120:123], v[136:139], v[172:175], v[120:123]
	s_waitcnt lgkmcnt(3)
	v_mfma_i32_16x16x64_i8 v[116:119], v[100:103], v[186:189], v[116:119]
	v_mfma_i32_16x16x64_i8 v[112:115], v[136:139], v[186:189], v[112:115]
	s_waitcnt lgkmcnt(1)
	v_mfma_i32_16x16x64_i8 v[104:107], v[100:103], v[194:197], v[104:107]
	v_mfma_i32_16x16x64_i8 v[96:99], v[136:139], v[194:197], v[96:99]
	v_mfma_i32_16x16x64_i8 v[132:135], v[108:111], v[168:171], v[132:135]
	v_mfma_i32_16x16x64_i8 v[128:131], v[140:143], v[168:171], v[128:131]
	v_mfma_i32_16x16x64_i8 v[124:127], v[108:111], v[180:183], v[124:127]
	v_mfma_i32_16x16x64_i8 v[120:123], v[140:143], v[180:183], v[120:123]
	v_mfma_i32_16x16x64_i8 v[116:119], v[108:111], v[190:193], v[116:119]
	v_mfma_i32_16x16x64_i8 v[112:115], v[140:143], v[190:193], v[112:115]
	s_waitcnt lgkmcnt(0)
	v_mfma_i32_16x16x64_i8 v[104:107], v[108:111], v[198:201], v[104:107]
	v_mfma_i32_16x16x64_i8 v[96:99], v[140:143], v[198:201], v[96:99]
	v_mfma_i32_16x16x64_i8 v[60:63], v[144:147], v[164:167], v[60:63]
	v_mfma_i32_16x16x64_i8 v[56:59], v[152:155], v[164:167], v[56:59]
	v_mfma_i32_16x16x64_i8 v[52:55], v[144:147], v[172:175], v[52:55]
	v_mfma_i32_16x16x64_i8 v[48:51], v[152:155], v[172:175], v[48:51]
	v_mfma_i32_16x16x64_i8 v[44:47], v[144:147], v[186:189], v[44:47]
	v_mfma_i32_16x16x64_i8 v[40:43], v[152:155], v[186:189], v[40:43]
	v_mfma_i32_16x16x64_i8 v[36:39], v[144:147], v[194:197], v[36:39]
	v_mfma_i32_16x16x64_i8 v[32:35], v[152:155], v[194:197], v[32:35]
	v_mfma_i32_16x16x64_i8 v[60:63], v[148:151], v[168:171], v[60:63]
	v_mfma_i32_16x16x64_i8 v[56:59], v[156:159], v[168:171], v[56:59]
	v_mfma_i32_16x16x64_i8 v[52:55], v[148:151], v[180:183], v[52:55]
	v_mfma_i32_16x16x64_i8 v[48:51], v[156:159], v[180:183], v[48:51]
	v_mfma_i32_16x16x64_i8 v[44:47], v[148:151], v[190:193], v[44:47]
	v_mfma_i32_16x16x64_i8 v[40:43], v[156:159], v[190:193], v[40:43]
	v_mfma_i32_16x16x64_i8 v[36:39], v[148:151], v[198:201], v[36:39]
	v_mfma_i32_16x16x64_i8 v[32:35], v[156:159], v[198:201], v[32:35]
	s_barrier
	ds_read_b128 v[164:167], v185 offset:49152
	ds_read_b128 v[168:171], v185 offset:50176
	ds_read_b128 v[172:175], v185 offset:51200
	ds_read_b128 v[180:183], v185 offset:52224
	ds_read_b128 v[186:189], v185 offset:53248
	ds_read_b128 v[190:193], v185 offset:54272
	ds_read_b128 v[194:197], v185 offset:55296
	ds_read_b128 v[198:201], v185 offset:56320
	s_add_u32 s6, s56, 0x80
	s_addc_u32 s7, s57, 0
	s_mov_b32 m0, s80
	s_nop 0
	global_load_lds_dwordx4 v161, s[6:7]
	s_mov_b32 m0, s81
	s_nop 0
	global_load_lds_dwordx4 v163, s[6:7]
	s_add_u32 s6, s56, 0xb0080
	s_addc_u32 s7, s57, 0
	s_mov_b32 m0, s84
	s_nop 0
	global_load_lds_dwordx4 v161, s[6:7]
	s_mov_b32 m0, s85
	s_nop 0
	global_load_lds_dwordx4 v163, s[6:7]
	s_mov_b32 m0, s82
	s_nop 0
	global_load_lds_dwordx4 v160, s[44:45]
	s_mov_b32 m0, s83
	s_nop 0
	global_load_lds_dwordx4 v162, s[44:45]
	s_waitcnt vmcnt(8)
	s_waitcnt lgkmcnt(0)
	s_barrier
	s_waitcnt lgkmcnt(7)
	v_mfma_i32_16x16x64_i8 v[92:95], v[100:103], v[164:167], v[92:95]
	v_mfma_i32_16x16x64_i8 v[88:91], v[136:139], v[164:167], v[88:91]
	s_waitcnt lgkmcnt(5)
	v_mfma_i32_16x16x64_i8 v[84:87], v[100:103], v[172:175], v[84:87]
	v_mfma_i32_16x16x64_i8 v[80:83], v[136:139], v[172:175], v[80:83]
	s_waitcnt lgkmcnt(3)
	v_mfma_i32_16x16x64_i8 v[76:79], v[100:103], v[186:189], v[76:79]
	v_mfma_i32_16x16x64_i8 v[72:75], v[136:139], v[186:189], v[72:75]
	s_waitcnt lgkmcnt(1)
	v_mfma_i32_16x16x64_i8 v[68:71], v[100:103], v[194:197], v[68:71]
	v_mfma_i32_16x16x64_i8 v[64:67], v[136:139], v[194:197], v[64:67]
	v_mfma_i32_16x16x64_i8 v[92:95], v[108:111], v[168:171], v[92:95]
	v_mfma_i32_16x16x64_i8 v[88:91], v[140:143], v[168:171], v[88:91]
	v_mfma_i32_16x16x64_i8 v[84:87], v[108:111], v[180:183], v[84:87]
	v_mfma_i32_16x16x64_i8 v[80:83], v[140:143], v[180:183], v[80:83]
	v_mfma_i32_16x16x64_i8 v[76:79], v[108:111], v[190:193], v[76:79]
	v_mfma_i32_16x16x64_i8 v[72:75], v[140:143], v[190:193], v[72:75]
	s_waitcnt lgkmcnt(0)
	v_mfma_i32_16x16x64_i8 v[68:71], v[108:111], v[198:201], v[68:71]
	v_mfma_i32_16x16x64_i8 v[64:67], v[140:143], v[198:201], v[64:67]
	v_mfma_i32_16x16x64_i8 v[28:31], v[144:147], v[164:167], v[28:31]
	v_mfma_i32_16x16x64_i8 v[24:27], v[152:155], v[164:167], v[24:27]
	v_mfma_i32_16x16x64_i8 v[20:23], v[144:147], v[172:175], v[20:23]
	v_mfma_i32_16x16x64_i8 v[16:19], v[152:155], v[172:175], v[16:19]
	v_mfma_i32_16x16x64_i8 v[12:15], v[144:147], v[186:189], v[12:15]
	v_mfma_i32_16x16x64_i8 v[8:11], v[152:155], v[186:189], v[8:11]
	v_mfma_i32_16x16x64_i8 v[4:7], v[144:147], v[194:197], v[4:7]
	v_mfma_i32_16x16x64_i8 v[0:3], v[152:155], v[194:197], v[0:3]
	v_mfma_i32_16x16x64_i8 v[28:31], v[148:151], v[168:171], v[28:31]
	v_mfma_i32_16x16x64_i8 v[24:27], v[156:159], v[168:171], v[24:27]
	v_mfma_i32_16x16x64_i8 v[20:23], v[148:151], v[180:183], v[20:23]
	v_mfma_i32_16x16x64_i8 v[16:19], v[156:159], v[180:183], v[16:19]
	v_mfma_i32_16x16x64_i8 v[12:15], v[148:151], v[190:193], v[12:15]
	v_mfma_i32_16x16x64_i8 v[8:11], v[156:159], v[190:193], v[8:11]
	v_mfma_i32_16x16x64_i8 v[4:7], v[148:151], v[198:201], v[4:7]
	v_mfma_i32_16x16x64_i8 v[0:3], v[156:159], v[198:201], v[0:3]
	s_barrier
	s_add_i32 s4, s4, 2
	s_add_u32 s74, s74, 0x100
	s_addc_u32 s75, s75, 0
	s_add_u32 s0, s0, 0x100
	s_addc_u32 s1, s1, 0
	s_add_u32 s14, s14, 0x100
	s_addc_u32 s15, s15, 0
	s_cmp_gt_u32 s4, 41
; #define PG8_STAGE(bufoff, gbase, voff) do { _Pragma("unroll") for (int _i = 0; _i < 2; ++_i) glds16_s((gbase), (voff)[_i], ldsb + (unsigned)((bufoff) + _i * 8192)); } while (0)
; #define PG8_LDA(dst, b, h) do { _Pragma("unroll") for (int m = 0; m < 4; ++m) _Pragma("unroll") for (int k = 0; k < 2; ++k) dst[m][k] = *(const LAS h16x8*)(lds + PG8_SA(b, h) + aoff + m * 2048 + k * 1024); } while (0)
; #define PG8_LDB(dst, b, h) do { _Pragma("unroll") for (int n = 0; n < 2; ++n) _Pragma("unroll") for (int k = 0; k < 2; ++k) dst[n][k] = *(const LAS h16x8*)(lds + PG8_SB(b, h) + boff + n * 2048 + k * 1024); } while (0)
; #define PG8_MMA(ai, bj, At, Bt) do { __builtin_amdgcn_s_setprio(1); _Pragma("unroll") for (int m = 0; m < 4; ++m) _Pragma("unroll") for (int n = 0; n < 2; ++n) _Pragma("unroll") for (int k = 0; k < 2; ++k) \
;         acc[ai][bj][m][n] = mma_step<I8>(Bt[n][k], At[m][k], acc[ai][bj][m][n]); __builtin_amdgcn_s_setprio(0); } while (0)
; #define PG8_WAIT_V(n) asm volatile("s_waitcnt vmcnt(" #n ")" ::: "memory")
; #define PG8_WAIT_L(n) asm volatile("s_waitcnt lgkmcnt(" #n ")" ::: "memory")
; #define PG8_BAR __builtin_amdgcn_s_barrier()
; #define PG8_SCHED __builtin_amdgcn_sched_barrier(0)
; template <class Prob, class Epi, bool I8 = false, bool ALIGN_EPI = true, bool SP2 = true>
; __device__ __forceinline__ void gemm_phase(LAS unsigned char* lds, int wave, const Prob& P, const Epi& E) {
;     ...
;             PG8_LDB(B0, 0, 0); PG8_LDB(B1, 0, 1); PG8_SCHED; PG8_LDA(At, 0, 0); PG8_STAGE(PG8_SA(1, 1), a1 + hstepA, voffA);
;             PG8_WAIT_V(8); PG8_WAIT_L(0); PG8_BAR; PG8_MMA(0, 0, At, B0); PG8_MMA(0, 1, At, B1); PG8_BAR; PG8_SCHED;
;             PG8_LDA(At, 0, 1); PG8_STAGE(PG8_SB(0, 0), b2, voffB); PG8_STAGE(PG8_SB(0, 1), b2 + hstepB, voffB); PG8_STAGE(PG8_SA(0, 0), a2, voffA);
;             PG8_WAIT_V(8); PG8_WAIT_L(0); PG8_BAR; PG8_MMA(1, 0, At, B0); PG8_MMA(1, 1, At, B1); PG8_BAR; PG8_SCHED;
.LBB0_1216:
	v_add_u32_e32 v140, 0x10000, v179
	v_add_u32_e32 v156, 0x14000, v179
	ds_read_b128 v[100:103], v140
	ds_read_b128 v[108:111], v140 offset:1024
	ds_read_b128 v[136:139], v140 offset:2048
	ds_read_b128 v[140:143], v140 offset:3072
	ds_read_b128 v[144:147], v156
	ds_read_b128 v[148:151], v156 offset:1024
	ds_read_b128 v[152:155], v156 offset:2048
	ds_read_b128 v[156:159], v156 offset:3072
	s_cmp_eq_u32 s4, 40
	s_cselect_b32 s60, s38, s74
	s_cselect_b32 s61, s39, s75
	s_cselect_b32 s56, s50, s0
	s_cselect_b32 s57, s51, s1
	s_add_u32 s44, s60, 0x80
	s_addc_u32 s45, s61, 0
	ds_read_b128 v[164:167], v185
	ds_read_b128 v[168:171], v185 offset:1024
	ds_read_b128 v[172:175], v185 offset:2048
	ds_read_b128 v[180:183], v185 offset:3072
	ds_read_b128 v[186:189], v185 offset:4096
	ds_read_b128 v[190:193], v185 offset:5120
	ds_read_b128 v[194:197], v185 offset:6144
	ds_read_b128 v[198:201], v185 offset:7168
	s_mov_b32 m0, s86
	s_nop 0
	global_load_lds_dwordx4 v160, s[14:15]
	s_mov_b32 m0, s87
	s_nop 0
	global_load_lds_dwordx4 v162, s[14:15]
	s_waitcnt vmcnt(8)
	s_waitcnt lgkmcnt(0)
	s_barrier
	s_waitcnt lgkmcnt(7)
	v_mfma_i32_16x16x64_i8 v[132:135], v[100:103], v[164:167], v[132:135]
	v_mfma_i32_16x16x64_i8 v[128:131], v[136:139], v[164:167], v[128:131]
	s_waitcnt lgkmcnt(5)
	v_mfma_i32_16x16x64_i8 v[124:127], v[100:103], v[172:175], v[124:127]
	v_mfma_i32_16x16x64_i8 v[120:123], v[136:139], v[172:175], v[120:123]
	s_waitcnt lgkmcnt(3)
	v_mfma_i32_16x16x64_i8 v[116:119], v[100:103], v[186:189], v[116:119]
	v_mfma_i32_16x16x64_i8 v[112:115], v[136:139], v[186:189], v[112:115]
	s_waitcnt lgkmcnt(1)
	v_mfma_i32_16x16x64_i8 v[104:107], v[100:103], v[194:197], v[104:107]
	v_mfma_i32_16x16x64_i8 v[96:99], v[136:139], v[194:197], v[96:99]
	v_mfma_i32_16x16x64_i8 v[132:135], v[108:111], v[168:171], v[132:135]
	v_mfma_i32_16x16x64_i8 v[128:131], v[140:143], v[168:171], v[128:131]
	v_mfma_i32_16x16x64_i8 v[124:127], v[108:111], v[180:183], v[124:127]
	v_mfma_i32_16x16x64_i8 v[120:123], v[140:143], v[180:183], v[120:123]
	v_mfma_i32_16x16x64_i8 v[116:119], v[108:111], v[190:193], v[116:119]
	v_mfma_i32_16x16x64_i8 v[112:115], v[140:143], v[190:193], v[112:115]
	s_waitcnt lgkmcnt(0)
	v_mfma_i32_16x16x64_i8 v[104:107], v[108:111], v[198:201], v[104:107]
	v_mfma_i32_16x16x64_i8 v[96:99], v[140:143], v[198:201], v[96:99]
	v_mfma_i32_16x16x64_i8 v[60:63], v[144:147], v[164:167], v[60:63]
	v_mfma_i32_16x16x64_i8 v[56:59], v[152:155], v[164:167], v[56:59]
	v_mfma_i32_16x16x64_i8 v[52:55], v[144:147], v[172:175], v[52:55]
	v_mfma_i32_16x16x64_i8 v[48:51], v[152:155], v[172:175], v[48:51]
	v_mfma_i32_16x16x64_i8 v[44:47], v[144:147], v[186:189], v[44:47]
	v_mfma_i32_16x16x64_i8 v[40:43], v[152:155], v[186:189], v[40:43]
	v_mfma_i32_16x16x64_i8 v[36:39], v[144:147], v[194:197], v[36:39]
	v_mfma_i32_16x16x64_i8 v[32:35], v[152:155], v[194:197], v[32:35]
	v_mfma_i32_16x16x64_i8 v[60:63], v[148:151], v[168:171], v[60:63]
	v_mfma_i32_16x16x64_i8 v[56:59], v[156:159], v[168:171], v[56:59]
	v_mfma_i32_16x16x64_i8 v[52:55], v[148:151], v[180:183], v[52:55]
	v_mfma_i32_16x16x64_i8 v[48:51], v[156:159], v[180:183], v[48:51]
	v_mfma_i32_16x16x64_i8 v[44:47], v[148:151], v[190:193], v[44:47]
	v_mfma_i32_16x16x64_i8 v[40:43], v[156:159], v[190:193], v[40:43]
	v_mfma_i32_16x16x64_i8 v[36:39], v[148:151], v[198:201], v[36:39]
	v_mfma_i32_16x16x64_i8 v[32:35], v[156:159], v[198:201], v[32:35]
	s_barrier
	ds_read_b128 v[164:167], v185 offset:16384
	ds_read_b128 v[168:171], v185 offset:17408
	ds_read_b128 v[172:175], v185 offset:18432
	ds_read_b128 v[180:183], v185 offset:19456
	ds_read_b128 v[186:189], v185 offset:20480
	ds_read_b128 v[190:193], v185 offset:21504
	ds_read_b128 v[194:197], v185 offset:22528
	ds_read_b128 v[198:201], v185 offset:23552
	s_mov_b32 m0, s41
	s_nop 0
	global_load_lds_dwordx4 v161, s[56:57]
	s_add_u32 s6, s56, 0xb0000
	s_mov_b32 m0, s62
	s_nop 0
	global_load_lds_dwordx4 v163, s[56:57]
	s_addc_u32 s7, s57, 0
	s_mov_b32 m0, s63
	s_nop 0
	global_load_lds_dwordx4 v161, s[6:7]
	s_mov_b32 m0, s64
	s_nop 0
	global_load_lds_dwordx4 v163, s[6:7]
	s_mov_b32 m0, s40
	s_nop 0
	global_load_lds_dwordx4 v160, s[60:61]
	s_mov_b32 m0, s68
	s_nop 0
	global_load_lds_dwordx4 v162, s[60:61]
	s_waitcnt vmcnt(8)
	s_waitcnt lgkmcnt(0)
	s_barrier
	s_waitcnt lgkmcnt(7)
	v_mfma_i32_16x16x64_i8 v[92:95], v[100:103], v[164:167], v[92:95]
	v_mfma_i32_16x16x64_i8 v[88:91], v[136:139], v[164:167], v[88:91]
	s_waitcnt lgkmcnt(5)
	v_mfma_i32_16x16x64_i8 v[84:87], v[100:103], v[172:175], v[84:87]
	v_mfma_i32_16x16x64_i8 v[80:83], v[136:139], v[172:175], v[80:83]
	s_waitcnt lgkmcnt(3)
	v_mfma_i32_16x16x64_i8 v[76:79], v[100:103], v[186:189], v[76:79]
	v_mfma_i32_16x16x64_i8 v[72:75], v[136:139], v[186:189], v[72:75]
	s_waitcnt lgkmcnt(1)
	v_mfma_i32_16x16x64_i8 v[68:71], v[100:103], v[194:197], v[68:71]
	v_mfma_i32_16x16x64_i8 v[64:67], v[136:139], v[194:197], v[64:67]
	v_mfma_i32_16x16x64_i8 v[92:95], v[108:111], v[168:171], v[92:95]
	v_mfma_i32_16x16x64_i8 v[88:91], v[140:143], v[168:171], v[88:91]
	v_mfma_i32_16x16x64_i8 v[84:87], v[108:111], v[180:183], v[84:87]
	v_mfma_i32_16x16x64_i8 v[80:83], v[140:143], v[180:183], v[80:83]
	v_mfma_i32_16x16x64_i8 v[76:79], v[108:111], v[190:193], v[76:79]
	v_mfma_i32_16x16x64_i8 v[72:75], v[140:143], v[190:193], v[72:75]
	s_waitcnt lgkmcnt(0)
	v_mfma_i32_16x16x64_i8 v[68:71], v[108:111], v[198:201], v[68:71]
	v_mfma_i32_16x16x64_i8 v[64:67], v[140:143], v[198:201], v[64:67]
	v_mfma_i32_16x16x64_i8 v[28:31], v[144:147], v[164:167], v[28:31]
	v_mfma_i32_16x16x64_i8 v[24:27], v[152:155], v[164:167], v[24:27]
	v_mfma_i32_16x16x64_i8 v[20:23], v[144:147], v[172:175], v[20:23]
	v_mfma_i32_16x16x64_i8 v[16:19], v[152:155], v[172:175], v[16:19]
	v_mfma_i32_16x16x64_i8 v[12:15], v[144:147], v[186:189], v[12:15]
	v_mfma_i32_16x16x64_i8 v[8:11], v[152:155], v[186:189], v[8:11]
	v_mfma_i32_16x16x64_i8 v[4:7], v[144:147], v[194:197], v[4:7]
	v_mfma_i32_16x16x64_i8 v[0:3], v[152:155], v[194:197], v[0:3]
	v_mfma_i32_16x16x64_i8 v[28:31], v[148:151], v[168:171], v[28:31]
	v_mfma_i32_16x16x64_i8 v[24:27], v[156:159], v[168:171], v[24:27]
	v_mfma_i32_16x16x64_i8 v[20:23], v[148:151], v[180:183], v[20:23]
	v_mfma_i32_16x16x64_i8 v[16:19], v[156:159], v[180:183], v[16:19]
	v_mfma_i32_16x16x64_i8 v[12:15], v[148:151], v[190:193], v[12:15]
	v_mfma_i32_16x16x64_i8 v[8:11], v[156:159], v[190:193], v[8:11]
	v_mfma_i32_16x16x64_i8 v[4:7], v[148:151], v[198:201], v[4:7]
	v_mfma_i32_16x16x64_i8 v[0:3], v[156:159], v[198:201], v[0:3]
	s_barrier
; #define PG8_STAGE(bufoff, gbase, voff) do { _Pragma("unroll") for (int _i = 0; _i < 2; ++_i) glds16_s((gbase), (voff)[_i], ldsb + (unsigned)((bufoff) + _i * 8192)); } while (0)
; #define PG8_LDA(dst, b, h) do { _Pragma("unroll") for (int m = 0; m < 4; ++m) _Pragma("unroll") for (int k = 0; k < 2; ++k) dst[m][k] = *(const LAS h16x8*)(lds + PG8_SA(b, h) + aoff + m * 2048 + k * 1024); } while (0)
; #define PG8_LDB(dst, b, h) do { _Pragma("unroll") for (int n = 0; n < 2; ++n) _Pragma("unroll") for (int k = 0; k < 2; ++k) dst[n][k] = *(const LAS h16x8*)(lds + PG8_SB(b, h) + boff + n * 2048 + k * 1024); } while (0)
; #define PG8_MMA(ai, bj, At, Bt) do { __builtin_amdgcn_s_setprio(1); _Pragma("unroll") for (int m = 0; m < 4; ++m) _Pragma("unroll") for (int n = 0; n < 2; ++n) _Pragma("unroll") for (int k = 0; k < 2; ++k) \
;         acc[ai][bj][m][n] = mma_step<I8>(Bt[n][k], At[m][k], acc[ai][bj][m][n]); __builtin_amdgcn_s_setprio(0); } while (0)
; #define PG8_WAIT_V(n) asm volatile("s_waitcnt vmcnt(" #n ")" ::: "memory")
; #define PG8_WAIT_L(n) asm volatile("s_waitcnt lgkmcnt(" #n ")" ::: "memory")
; #define PG8_BAR __builtin_amdgcn_s_barrier()
; #define PG8_SCHED __builtin_amdgcn_sched_barrier(0)
; template <class Prob, class Epi, bool I8 = false, bool ALIGN_EPI = true, bool SP2 = true>
; __device__ __forceinline__ void gemm_phase(LAS unsigned char* lds, int wave, const Prob& P, const Epi& E) {
;     ...
;             PG8_LDB(B0, 1, 0); PG8_LDB(B1, 1, 1); PG8_SCHED; PG8_LDA(At, 1, 0); PG8_STAGE(PG8_SA(0, 1), a2 + hstepA, voffA);
;             PG8_WAIT_V(8); PG8_WAIT_L(0); PG8_BAR; PG8_MMA(0, 0, At, B0); PG8_MMA(0, 1, At, B1); PG8_BAR; PG8_SCHED;
;             PG8_LDA(At, 1, 1); PG8_STAGE(PG8_SB(1, 0), b3, voffB); PG8_STAGE(PG8_SB(1, 1), b3 + hstepB, voffB); PG8_STAGE(PG8_SA(1, 0), a3, voffA);
;             PG8_WAIT_V(8); PG8_WAIT_L(0); PG8_BAR; PG8_MMA(1, 0, At, B0); PG8_MMA(1, 1, At, B1); PG8_BAR; PG8_SCHED;
;     ...
;         if constexpr (ALIGN_EPI) { if (wr == 0) PG8_BAR; }
	v_add_u32_e32 v140, 0x18000, v179
	v_add_u32_e32 v156, 0x1c000, v179
	ds_read_b128 v[100:103], v140
	ds_read_b128 v[108:111], v140 offset:1024
	ds_read_b128 v[136:139], v140 offset:2048
	ds_read_b128 v[140:143], v140 offset:3072
	ds_read_b128 v[144:147], v156
	ds_read_b128 v[148:151], v156 offset:1024
	ds_read_b128 v[152:155], v156 offset:2048
	ds_read_b128 v[156:159], v156 offset:3072
	ds_read_b128 v[164:167], v185 offset:32768
	ds_read_b128 v[168:171], v185 offset:33792
	ds_read_b128 v[172:175], v185 offset:34816
	ds_read_b128 v[180:183], v185 offset:35840
	ds_read_b128 v[186:189], v185 offset:36864
	ds_read_b128 v[190:193], v185 offset:37888
	ds_read_b128 v[194:197], v185 offset:38912
	ds_read_b128 v[198:201], v185 offset:39936
	s_add_u32 s6, s60, 0xb0000
	s_addc_u32 s7, s61, 0
	s_mov_b32 m0, s69
	s_nop 0
	global_load_lds_dwordx4 v160, s[6:7]
	s_mov_b32 m0, s76
	s_nop 0
	global_load_lds_dwordx4 v162, s[6:7]
	s_waitcnt vmcnt(8)
	s_waitcnt lgkmcnt(0)
	s_barrier
	s_waitcnt lgkmcnt(7)
	v_mfma_i32_16x16x64_i8 v[132:135], v[100:103], v[164:167], v[132:135]
	v_mfma_i32_16x16x64_i8 v[128:131], v[136:139], v[164:167], v[128:131]
	s_waitcnt lgkmcnt(5)
	v_mfma_i32_16x16x64_i8 v[124:127], v[100:103], v[172:175], v[124:127]
	v_mfma_i32_16x16x64_i8 v[120:123], v[136:139], v[172:175], v[120:123]
	s_waitcnt lgkmcnt(3)
	v_mfma_i32_16x16x64_i8 v[116:119], v[100:103], v[186:189], v[116:119]
	v_mfma_i32_16x16x64_i8 v[112:115], v[136:139], v[186:189], v[112:115]
	s_waitcnt lgkmcnt(1)
	v_mfma_i32_16x16x64_i8 v[104:107], v[100:103], v[194:197], v[104:107]
	v_mfma_i32_16x16x64_i8 v[96:99], v[136:139], v[194:197], v[96:99]
	v_mfma_i32_16x16x64_i8 v[132:135], v[108:111], v[168:171], v[132:135]
	v_mfma_i32_16x16x64_i8 v[128:131], v[140:143], v[168:171], v[128:131]
	v_mfma_i32_16x16x64_i8 v[124:127], v[108:111], v[180:183], v[124:127]
	v_mfma_i32_16x16x64_i8 v[120:123], v[140:143], v[180:183], v[120:123]
	v_mfma_i32_16x16x64_i8 v[116:119], v[108:111], v[190:193], v[116:119]
	v_mfma_i32_16x16x64_i8 v[112:115], v[140:143], v[190:193], v[112:115]
	s_waitcnt lgkmcnt(0)
	v_mfma_i32_16x16x64_i8 v[104:107], v[108:111], v[198:201], v[104:107]
	v_mfma_i32_16x16x64_i8 v[96:99], v[140:143], v[198:201], v[96:99]
	v_mfma_i32_16x16x64_i8 v[60:63], v[144:147], v[164:167], v[60:63]
	v_mfma_i32_16x16x64_i8 v[56:59], v[152:155], v[164:167], v[56:59]
	v_mfma_i32_16x16x64_i8 v[52:55], v[144:147], v[172:175], v[52:55]
	v_mfma_i32_16x16x64_i8 v[48:51], v[152:155], v[172:175], v[48:51]
	v_mfma_i32_16x16x64_i8 v[44:47], v[144:147], v[186:189], v[44:47]
	v_mfma_i32_16x16x64_i8 v[40:43], v[152:155], v[186:189], v[40:43]
	v_mfma_i32_16x16x64_i8 v[36:39], v[144:147], v[194:197], v[36:39]
	v_mfma_i32_16x16x64_i8 v[32:35], v[152:155], v[194:197], v[32:35]
	v_mfma_i32_16x16x64_i8 v[60:63], v[148:151], v[168:171], v[60:63]
	v_mfma_i32_16x16x64_i8 v[56:59], v[156:159], v[168:171], v[56:59]
	v_mfma_i32_16x16x64_i8 v[52:55], v[148:151], v[180:183], v[52:55]
	v_mfma_i32_16x16x64_i8 v[48:51], v[156:159], v[180:183], v[48:51]
	v_mfma_i32_16x16x64_i8 v[44:47], v[148:151], v[190:193], v[44:47]
	v_mfma_i32_16x16x64_i8 v[40:43], v[156:159], v[190:193], v[40:43]
	v_mfma_i32_16x16x64_i8 v[36:39], v[148:151], v[198:201], v[36:39]
	v_mfma_i32_16x16x64_i8 v[32:35], v[156:159], v[198:201], v[32:35]
	s_barrier
	ds_read_b128 v[164:167], v185 offset:49152
	ds_read_b128 v[168:171], v185 offset:50176
	ds_read_b128 v[172:175], v185 offset:51200
	ds_read_b128 v[180:183], v185 offset:52224
	ds_read_b128 v[186:189], v185 offset:53248
	ds_read_b128 v[190:193], v185 offset:54272
	ds_read_b128 v[194:197], v185 offset:55296
	ds_read_b128 v[198:201], v185 offset:56320
	s_add_u32 s6, s56, 0x80
	s_addc_u32 s7, s57, 0
	s_mov_b32 m0, s80
	s_nop 0
	global_load_lds_dwordx4 v161, s[6:7]
	s_mov_b32 m0, s81
	s_nop 0
	global_load_lds_dwordx4 v163, s[6:7]
	s_add_u32 s6, s56, 0xb0080
	s_addc_u32 s7, s57, 0
	s_mov_b32 m0, s84
	s_nop 0
	global_load_lds_dwordx4 v161, s[6:7]
	s_mov_b32 m0, s85
	s_nop 0
	global_load_lds_dwordx4 v163, s[6:7]
	s_mov_b32 m0, s82
	s_nop 0
	global_load_lds_dwordx4 v160, s[44:45]
	s_mov_b32 m0, s83
	s_nop 0
	global_load_lds_dwordx4 v162, s[44:45]
	s_waitcnt vmcnt(8)
	s_waitcnt lgkmcnt(0)
	s_barrier
	s_waitcnt lgkmcnt(7)
	v_mfma_i32_16x16x64_i8 v[92:95], v[100:103], v[164:167], v[92:95]
	v_mfma_i32_16x16x64_i8 v[88:91], v[136:139], v[164:167], v[88:91]
	s_waitcnt lgkmcnt(5)
	v_mfma_i32_16x16x64_i8 v[84:87], v[100:103], v[172:175], v[84:87]
	v_mfma_i32_16x16x64_i8 v[80:83], v[136:139], v[172:175], v[80:83]
	s_waitcnt lgkmcnt(3)
	v_mfma_i32_16x16x64_i8 v[76:79], v[100:103], v[186:189], v[76:79]
	v_mfma_i32_16x16x64_i8 v[72:75], v[136:139], v[186:189], v[72:75]
	s_waitcnt lgkmcnt(1)
	v_mfma_i32_16x16x64_i8 v[68:71], v[100:103], v[194:197], v[68:71]
	v_mfma_i32_16x16x64_i8 v[64:67], v[136:139], v[194:197], v[64:67]
	v_mfma_i32_16x16x64_i8 v[92:95], v[108:111], v[168:171], v[92:95]
	v_mfma_i32_16x16x64_i8 v[88:91], v[140:143], v[168:171], v[88:91]
	v_mfma_i32_16x16x64_i8 v[84:87], v[108:111], v[180:183], v[84:87]
	v_mfma_i32_16x16x64_i8 v[80:83], v[140:143], v[180:183], v[80:83]
	v_mfma_i32_16x16x64_i8 v[76:79], v[108:111], v[190:193], v[76:79]
	v_mfma_i32_16x16x64_i8 v[72:75], v[140:143], v[190:193], v[72:75]
	s_waitcnt lgkmcnt(0)
	v_mfma_i32_16x16x64_i8 v[68:71], v[108:111], v[198:201], v[68:71]
	v_mfma_i32_16x16x64_i8 v[64:67], v[140:143], v[198:201], v[64:67]
	v_mfma_i32_16x16x64_i8 v[28:31], v[144:147], v[164:167], v[28:31]
	v_mfma_i32_16x16x64_i8 v[24:27], v[152:155], v[164:167], v[24:27]
	v_mfma_i32_16x16x64_i8 v[20:23], v[144:147], v[172:175], v[20:23]
	v_mfma_i32_16x16x64_i8 v[16:19], v[152:155], v[172:175], v[16:19]
	v_mfma_i32_16x16x64_i8 v[12:15], v[144:147], v[186:189], v[12:15]
	v_mfma_i32_16x16x64_i8 v[8:11], v[152:155], v[186:189], v[8:11]
	v_mfma_i32_16x16x64_i8 v[4:7], v[144:147], v[194:197], v[4:7]
	v_mfma_i32_16x16x64_i8 v[0:3], v[152:155], v[194:197], v[0:3]
	v_mfma_i32_16x16x64_i8 v[28:31], v[148:151], v[168:171], v[28:31]
	v_mfma_i32_16x16x64_i8 v[24:27], v[156:159], v[168:171], v[24:27]
	v_mfma_i32_16x16x64_i8 v[20:23], v[148:151], v[180:183], v[20:23]
	v_mfma_i32_16x16x64_i8 v[16:19], v[156:159], v[180:183], v[16:19]
	v_mfma_i32_16x16x64_i8 v[12:15], v[148:151], v[190:193], v[12:15]
	v_mfma_i32_16x16x64_i8 v[8:11], v[156:159], v[190:193], v[8:11]
	v_mfma_i32_16x16x64_i8 v[4:7], v[148:151], v[198:201], v[4:7]
	v_mfma_i32_16x16x64_i8 v[0:3], v[156:159], v[198:201], v[0:3]
	s_barrier
	s_add_i32 s4, s4, 2
	s_add_u32 s74, s74, 0x100
	s_addc_u32 s75, s75, 0
	s_add_u32 s0, s0, 0x100
	s_addc_u32 s1, s1, 0
	s_add_u32 s14, s14, 0x100
	s_addc_u32 s15, s15, 0
	s_cmp_gt_u32 s4, 41
	s_cbranch_scc0 .LBB0_1216
	s_and_b64 vcc, exec, s[48:49]
	s_cbranch_vccz .LBB0_1219
	s_barrier
